# residual GEMM epilogues (7 instances): the (mean, rstd) pair of a row loaded once per row instead of once per fragment, stores left in flight (vmcnt(1) instead of vmcnt(0))
# baseline (speedup 1.0000x reference)
.LBB0_1179:
	v_lshl_add_u32 v174, s38, 8, v153
	v_mul_hi_i32 v129, v174, s64
	v_lshrrev_b32_e32 v130, 31, v129
	v_ashrrev_i32_e32 v129, 11, v129
	v_add_u32_e32 v134, v129, v130
	v_mad_i32_i24 v129, v134, s65, v174
	v_lshl_add_u32 v130, v134, 13, v202
	v_lshlrev_b32_e32 v131, 8, v134
	v_cmp_gt_i32_e32 vcc, s52, v129
	v_readlane_b32 s16, v254, 28
	v_readlane_b32 s20, v254, 32
	v_cndmask_b32_e32 v130, v130, v131, vcc
	v_add_u32_e32 v130, v130, v129
	v_readlane_b32 s21, v254, 33
	v_lshl_or_b32 v128, s39, 8, v182
	v_mov_b32_e32 v204, s71
	v_mov_b32_e32 v203, s21
	v_mov_b32_e32 v205, s20
	v_mov_b32_e32 v206, s70
	v_ashrrev_i32_e32 v131, 31, v130
	v_cndmask_b32_e32 v133, v203, v204, vcc
	v_cndmask_b32_e32 v132, v205, v206, vcc
	v_lshlrev_b64 v[130:131], 12, v[130:131]
	v_ashrrev_i32_e32 v129, 31, v128
	v_lshl_add_u64 v[130:131], v[132:133], 0, v[130:131]
	v_lshlrev_b64 v[172:173], 2, v[128:129]
	v_ashrrev_i32_e32 v175, 31, v174
	v_lshl_add_u64 v[180:181], v[130:131], 0, v[172:173]
	v_lshl_add_u64 v[176:177], v[174:175], 3, s[62:63]
	v_readlane_b32 s68, v254, 59
	global_load_dwordx4 v[208:211], v[180:181], off
	global_load_dwordx4 v[224:227], v[180:181], off offset:64
	global_load_dwordx2 v[232:233], v[176:177], off
	v_cndmask_b32_e64 v128, v134, 4, vcc
	v_readlane_b32 s80, v255, 7
	v_readlane_b32 s81, v255, 8
	v_readlane_b32 s82, v255, 9
	v_readlane_b32 s83, v255, 10
	v_mul_hi_i32_i24_e32 v129, 0x6000, v128
	v_lshl_add_u64 v[168:169], s[80:81], 0, v[172:173]
	v_lshl_add_u64 v[170:171], s[82:83], 0, v[172:173]
	v_mul_i32_i24_e32 v128, 0x6000, v128
	global_load_dwordx4 v[212:215], v[168:169], off
	global_load_dwordx4 v[216:219], v[170:171], off
	v_lshl_add_u64 v[128:129], s[0:1], 0, v[128:129]
	v_lshl_add_u64 v[234:235], v[128:129], 0, v[172:173]
	global_load_dwordx4 v[220:223], v[234:235], off
	v_or_b32_e32 v236, 16, v174
	v_mul_hi_i32 v128, v236, s64
	v_lshrrev_b32_e32 v129, 31, v128
	v_ashrrev_i32_e32 v128, 11, v128
	v_add_u32_e32 v175, v128, v129
	v_mad_i32_i24 v128, v175, s65, v236
	v_lshl_add_u32 v129, v175, 13, v202
	v_lshlrev_b32_e32 v130, 8, v175
	v_cmp_gt_i32_e32 vcc, s52, v128
	v_ashrrev_i32_e32 v237, 31, v236
	s_mov_b64 s[4:5], -1
	v_cndmask_b32_e32 v129, v129, v130, vcc
	v_add_u32_e32 v128, v129, v128
	v_ashrrev_i32_e32 v129, 31, v128
	v_cndmask_b32_e32 v131, v203, v204, vcc
	v_cndmask_b32_e32 v130, v205, v206, vcc
	v_lshlrev_b64 v[128:129], 12, v[128:129]
	v_lshl_add_u64 v[128:129], v[130:131], 0, v[128:129]
	v_lshl_add_u64 v[178:179], v[128:129], 0, v[172:173]
	global_load_dwordx4 v[228:231], v[178:179], off
	global_load_dwordx4 v[136:139], v[178:179], off offset:64
	global_load_dwordx4 v[132:135], v[178:179], off offset:512
	global_load_dwordx4 v[128:131], v[178:179], off offset:576
	v_readlane_b32 s17, v254, 29
	v_readlane_b32 s18, v254, 30
	v_readlane_b32 s19, v254, 31
	v_readlane_b32 s22, v254, 34
	v_readlane_b32 s23, v254, 35
	v_readlane_b32 s69, v254, 60
	v_readlane_b32 s70, v254, 61
	v_readlane_b32 s71, v254, 62
	v_readlane_b32 s72, v254, 63
	v_readlane_b32 s73, v255, 0
	v_readlane_b32 s74, v255, 1
	v_readlane_b32 s75, v255, 2
	v_readlane_b32 s76, v255, 3
	v_readlane_b32 s77, v255, 4
	v_readlane_b32 s78, v255, 5
	v_readlane_b32 s79, v255, 6
	s_waitcnt vmcnt(0)
	v_sub_f32_e32 v211, v211, v232
	v_sub_f32_e32 v210, v210, v232
	v_sub_f32_e32 v209, v209, v232
	v_sub_f32_e32 v208, v208, v232
	v_pk_mul_f32 v[208:209], v[208:209], v[232:233] op_sel:[0,1]
	v_pk_mul_f32 v[210:211], v[210:211], v[232:233] op_sel:[0,1]
	v_pk_fma_f32 v[208:209], v[212:213], v[208:209], v[216:217]
	v_pk_fma_f32 v[210:211], v[214:215], v[210:211], v[218:219]
	v_pk_mul_f32 v[208:209], v[208:209], s[42:43] op_sel_hi:[1,0]
	v_pk_mul_f32 v[210:211], v[210:211], s[42:43] op_sel_hi:[1,0]
	v_pk_fma_f32 v[124:125], v[124:125], v[220:221], v[208:209]
	v_pk_fma_f32 v[126:127], v[126:127], v[222:223], v[210:211]
	global_store_dwordx4 v[180:181], v[124:127], off
	s_nop 0
	s_nop 0
	global_load_dwordx4 v[124:127], v[168:169], off offset:64
	global_load_dwordx4 v[208:211], v[170:171], off offset:64
	global_load_dwordx4 v[212:215], v[234:235], off offset:64
	global_load_dwordx4 v[216:219], v[180:181], off offset:512
	s_waitcnt vmcnt(4)
	v_mov_b32_e32 v220, v232
	v_mov_b32_e32 v221, v233
	v_sub_f32_e32 v223, v227, v220
	v_sub_f32_e32 v222, v226, v220
	v_sub_f32_e32 v225, v225, v220
	v_sub_f32_e32 v224, v224, v220
	v_pk_mul_f32 v[224:225], v[224:225], v[220:221] op_sel:[0,1]
	v_pk_mul_f32 v[220:221], v[222:223], v[220:221] op_sel:[0,1]
	s_waitcnt vmcnt(2)
	v_pk_fma_f32 v[124:125], v[124:125], v[224:225], v[208:209]
	v_pk_fma_f32 v[126:127], v[126:127], v[220:221], v[210:211]
	v_pk_mul_f32 v[124:125], v[124:125], s[42:43] op_sel_hi:[1,0]
	v_pk_mul_f32 v[126:127], v[126:127], s[42:43] op_sel_hi:[1,0]
	s_waitcnt vmcnt(1)
	v_pk_fma_f32 v[120:121], v[120:121], v[212:213], v[124:125]
	v_pk_fma_f32 v[122:123], v[122:123], v[214:215], v[126:127]
	global_store_dwordx4 v[180:181], v[120:123], off offset:64
	s_nop 0
	s_nop 0
	global_load_dwordx4 v[120:123], v[168:169], off offset:512
	global_load_dwordx4 v[124:127], v[170:171], off offset:512
	global_load_dwordx4 v[208:211], v[234:235], off offset:512
	global_load_dwordx4 v[212:215], v[180:181], off offset:576
	v_lshl_add_u64 v[224:225], v[236:237], 3, s[62:63]
	v_or_b32_e32 v226, 32, v174
	v_ashrrev_i32_e32 v227, 31, v226
	s_waitcnt vmcnt(4)
	v_mov_b32_e32 v220, v232
	v_mov_b32_e32 v221, v233
	v_sub_f32_e32 v219, v219, v220
	v_sub_f32_e32 v218, v218, v220
	v_sub_f32_e32 v217, v217, v220
	v_sub_f32_e32 v216, v216, v220
	v_pk_mul_f32 v[216:217], v[216:217], v[220:221] op_sel:[0,1]
	v_pk_mul_f32 v[218:219], v[218:219], v[220:221] op_sel:[0,1]
	s_waitcnt vmcnt(2)
	v_pk_fma_f32 v[120:121], v[120:121], v[216:217], v[124:125]
	v_pk_fma_f32 v[122:123], v[122:123], v[218:219], v[126:127]
	v_pk_mul_f32 v[120:121], v[120:121], s[42:43] op_sel_hi:[1,0]
	v_pk_mul_f32 v[122:123], v[122:123], s[42:43] op_sel_hi:[1,0]
	s_waitcnt vmcnt(1)
	v_pk_fma_f32 v[116:117], v[116:117], v[208:209], v[120:121]
	v_pk_fma_f32 v[118:119], v[118:119], v[210:211], v[122:123]
	global_store_dwordx4 v[180:181], v[116:119], off offset:512
	s_nop 0
	s_nop 0
	global_load_dwordx4 v[116:119], v[168:169], off offset:576
	global_load_dwordx4 v[120:123], v[170:171], off offset:576
	global_load_dwordx4 v[124:127], v[234:235], off offset:576
	s_waitcnt vmcnt(3)
	v_mov_b32_e32 v208, v232
	v_mov_b32_e32 v209, v233
	v_sub_f32_e32 v211, v215, v208
	v_sub_f32_e32 v210, v214, v208
	v_sub_f32_e32 v213, v213, v208
	v_sub_f32_e32 v212, v212, v208
	v_pk_mul_f32 v[212:213], v[212:213], v[208:209] op_sel:[0,1]
	v_pk_mul_f32 v[208:209], v[210:211], v[208:209] op_sel:[0,1]
	s_waitcnt vmcnt(1)
	v_pk_fma_f32 v[116:117], v[116:117], v[212:213], v[120:121]
	v_pk_fma_f32 v[118:119], v[118:119], v[208:209], v[122:123]
	v_pk_mul_f32 v[116:117], v[116:117], s[42:43] op_sel_hi:[1,0]
	v_pk_mul_f32 v[118:119], v[118:119], s[42:43] op_sel_hi:[1,0]
	s_waitcnt vmcnt(0)
	v_pk_fma_f32 v[112:113], v[112:113], v[124:125], v[116:117]
	v_pk_fma_f32 v[114:115], v[114:115], v[126:127], v[118:119]
	global_store_dwordx4 v[180:181], v[112:115], off offset:576
	global_load_dwordx2 v[126:127], v[224:225], off
	global_load_dwordx4 v[208:211], v[168:169], off
	global_load_dwordx4 v[212:215], v[170:171], off
	v_cndmask_b32_e64 v112, v175, 4, vcc
	v_mul_hi_i32_i24_e32 v113, 0x6000, v112
	v_mul_i32_i24_e32 v112, 0x6000, v112
	v_lshl_add_u64 v[112:113], s[0:1], 0, v[112:113]
	v_lshl_add_u64 v[180:181], v[112:113], 0, v[172:173]
	global_load_dwordx4 v[216:219], v[180:181], off
	v_mul_hi_i32 v112, v226, s64
	v_lshrrev_b32_e32 v113, 31, v112
	v_ashrrev_i32_e32 v112, 11, v112
	v_add_u32_e32 v175, v112, v113
	v_mad_i32_i24 v112, v175, s65, v226
	v_lshl_add_u32 v113, v175, 13, v202
	v_lshlrev_b32_e32 v114, 8, v175
	v_cmp_gt_i32_e32 vcc, s52, v112
	s_waitcnt vmcnt(3)
	v_mov_b32_e32 v232, v126
	v_mov_b32_e32 v233, v127
	v_sub_f32_e32 v231, v231, v126
	v_cndmask_b32_e32 v113, v113, v114, vcc
	v_add_u32_e32 v112, v113, v112
	v_sub_f32_e32 v230, v230, v126
	v_sub_f32_e32 v229, v229, v126
	v_sub_f32_e32 v228, v228, v126
	v_ashrrev_i32_e32 v113, 31, v112
	v_pk_mul_f32 v[228:229], v[228:229], v[126:127] op_sel:[0,1]
	v_pk_mul_f32 v[126:127], v[230:231], v[126:127] op_sel:[0,1]
	v_cndmask_b32_e32 v115, v203, v204, vcc
	v_cndmask_b32_e32 v114, v205, v206, vcc
	v_lshlrev_b64 v[112:113], 12, v[112:113]
	s_waitcnt vmcnt(1)
	v_pk_fma_f32 v[126:127], v[210:211], v[126:127], v[214:215]
	v_pk_fma_f32 v[208:209], v[208:209], v[228:229], v[212:213]
	v_lshl_add_u64 v[112:113], v[114:115], 0, v[112:113]
	v_pk_mul_f32 v[208:209], v[208:209], s[42:43] op_sel_hi:[1,0]
	v_pk_mul_f32 v[126:127], v[126:127], s[42:43] op_sel_hi:[1,0]
	v_lshl_add_u64 v[124:125], v[112:113], 0, v[172:173]
	s_waitcnt vmcnt(0)
	v_pk_fma_f32 v[110:111], v[110:111], v[218:219], v[126:127]
	v_pk_fma_f32 v[108:109], v[108:109], v[216:217], v[208:209]
	global_load_dwordx4 v[220:223], v[124:125], off
	global_load_dwordx4 v[120:123], v[124:125], off offset:64
	global_load_dwordx4 v[116:119], v[124:125], off offset:512
	global_load_dwordx4 v[112:115], v[124:125], off offset:576
	s_nop 0
	global_store_dwordx4 v[178:179], v[108:111], off
	s_nop 0
	s_nop 0
	global_load_dwordx4 v[108:111], v[168:169], off offset:64
	global_load_dwordx4 v[208:211], v[170:171], off offset:64
	global_load_dwordx4 v[212:215], v[180:181], off offset:64
	s_waitcnt vmcnt(3)
	v_mov_b32_e32 v126, v232
	v_mov_b32_e32 v127, v233
	v_sub_f32_e32 v139, v139, v126
	v_sub_f32_e32 v138, v138, v126
	v_sub_f32_e32 v137, v137, v126
	v_sub_f32_e32 v136, v136, v126
	v_pk_mul_f32 v[136:137], v[136:137], v[126:127] op_sel:[0,1]
	v_pk_mul_f32 v[126:127], v[138:139], v[126:127] op_sel:[0,1]
	s_waitcnt vmcnt(1)
	v_pk_fma_f32 v[108:109], v[108:109], v[136:137], v[208:209]
	v_pk_fma_f32 v[110:111], v[110:111], v[126:127], v[210:211]
	v_pk_mul_f32 v[108:109], v[108:109], s[42:43] op_sel_hi:[1,0]
	v_pk_mul_f32 v[110:111], v[110:111], s[42:43] op_sel_hi:[1,0]
	s_waitcnt vmcnt(0)
	v_pk_fma_f32 v[104:105], v[104:105], v[212:213], v[108:109]
	v_pk_fma_f32 v[106:107], v[106:107], v[214:215], v[110:111]
	global_store_dwordx4 v[178:179], v[104:107], off offset:64
	s_nop 0
	s_nop 0
	global_load_dwordx4 v[104:107], v[168:169], off offset:512
	global_load_dwordx4 v[108:111], v[170:171], off offset:512
	global_load_dwordx4 v[136:139], v[180:181], off offset:512
	v_or_b32_e32 v210, 48, v174
	v_ashrrev_i32_e32 v211, 31, v210
	s_waitcnt vmcnt(3)
	v_mov_b32_e32 v126, v232
	v_mov_b32_e32 v127, v233
	v_sub_f32_e32 v135, v135, v126
	v_sub_f32_e32 v134, v134, v126
	v_sub_f32_e32 v133, v133, v126
	v_sub_f32_e32 v132, v132, v126
	v_pk_mul_f32 v[132:133], v[132:133], v[126:127] op_sel:[0,1]
	v_pk_mul_f32 v[126:127], v[134:135], v[126:127] op_sel:[0,1]
	s_waitcnt vmcnt(1)
	v_pk_fma_f32 v[104:105], v[104:105], v[132:133], v[108:109]
	v_pk_fma_f32 v[106:107], v[106:107], v[126:127], v[110:111]
	v_pk_mul_f32 v[104:105], v[104:105], s[42:43] op_sel_hi:[1,0]
	v_pk_mul_f32 v[106:107], v[106:107], s[42:43] op_sel_hi:[1,0]
	s_waitcnt vmcnt(0)
	v_pk_fma_f32 v[100:101], v[100:101], v[136:137], v[104:105]
	v_pk_fma_f32 v[102:103], v[102:103], v[138:139], v[106:107]
	global_store_dwordx4 v[178:179], v[100:103], off offset:512
	s_nop 0
	s_nop 0
	global_load_dwordx4 v[100:103], v[168:169], off offset:576
	global_load_dwordx4 v[104:107], v[170:171], off offset:576
	global_load_dwordx4 v[108:111], v[180:181], off offset:576
	v_lshl_add_u64 v[138:139], v[226:227], 3, s[62:63]
	s_waitcnt vmcnt(3)
	v_mov_b32_e32 v126, v232
	v_mov_b32_e32 v127, v233
	v_sub_f32_e32 v131, v131, v126
	v_sub_f32_e32 v130, v130, v126
	v_sub_f32_e32 v129, v129, v126
	v_sub_f32_e32 v128, v128, v126
	v_pk_mul_f32 v[128:129], v[128:129], v[126:127] op_sel:[0,1]
	v_pk_mul_f32 v[126:127], v[130:131], v[126:127] op_sel:[0,1]
	s_waitcnt vmcnt(1)
	v_pk_fma_f32 v[100:101], v[100:101], v[128:129], v[104:105]
	v_pk_fma_f32 v[102:103], v[102:103], v[126:127], v[106:107]
	v_pk_mul_f32 v[100:101], v[100:101], s[42:43] op_sel_hi:[1,0]
	v_pk_mul_f32 v[102:103], v[102:103], s[42:43] op_sel_hi:[1,0]
	s_waitcnt vmcnt(0)
	v_pk_fma_f32 v[96:97], v[96:97], v[108:109], v[100:101]
	v_pk_fma_f32 v[98:99], v[98:99], v[110:111], v[102:103]
	global_store_dwordx4 v[178:179], v[96:99], off offset:576
	global_load_dwordx2 v[110:111], v[138:139], off
	global_load_dwordx4 v[126:129], v[168:169], off
	global_load_dwordx4 v[130:133], v[170:171], off
	v_cndmask_b32_e64 v96, v175, 4, vcc
	v_mul_hi_i32_i24_e32 v97, 0x6000, v96
	v_mul_i32_i24_e32 v96, 0x6000, v96
	v_lshl_add_u64 v[96:97], s[0:1], 0, v[96:97]
	v_lshl_add_u64 v[208:209], v[96:97], 0, v[172:173]
	global_load_dwordx4 v[134:137], v[208:209], off
	v_mul_hi_i32 v96, v210, s64
	v_lshrrev_b32_e32 v97, 31, v96
	v_ashrrev_i32_e32 v96, 11, v96
	v_add_u32_e32 v175, v96, v97
	v_mad_i32_i24 v96, v175, s65, v210
	v_lshl_add_u32 v97, v175, 13, v202
	v_lshlrev_b32_e32 v98, 8, v175
	v_cmp_gt_i32_e32 vcc, s52, v96
	s_waitcnt vmcnt(3)
	v_mov_b32_e32 v216, v110
	v_mov_b32_e32 v217, v111
	v_sub_f32_e32 v213, v223, v110
	v_cndmask_b32_e32 v97, v97, v98, vcc
	v_add_u32_e32 v96, v97, v96
	v_sub_f32_e32 v212, v222, v110
	v_sub_f32_e32 v215, v221, v110
	v_sub_f32_e32 v214, v220, v110
	v_ashrrev_i32_e32 v97, 31, v96
	v_pk_mul_f32 v[214:215], v[214:215], v[110:111] op_sel:[0,1]
	v_pk_mul_f32 v[110:111], v[212:213], v[110:111] op_sel:[0,1]
	v_cndmask_b32_e32 v99, v203, v204, vcc
	v_cndmask_b32_e32 v98, v205, v206, vcc
	v_lshlrev_b64 v[96:97], 12, v[96:97]
	s_waitcnt vmcnt(1)
	v_pk_fma_f32 v[110:111], v[128:129], v[110:111], v[132:133]
	v_pk_fma_f32 v[126:127], v[126:127], v[214:215], v[130:131]
	v_lshl_add_u64 v[96:97], v[98:99], 0, v[96:97]
	v_pk_mul_f32 v[126:127], v[126:127], s[42:43] op_sel_hi:[1,0]
	v_pk_mul_f32 v[110:111], v[110:111], s[42:43] op_sel_hi:[1,0]
	v_lshl_add_u64 v[108:109], v[96:97], 0, v[172:173]
	s_waitcnt vmcnt(0)
	v_pk_fma_f32 v[94:95], v[94:95], v[136:137], v[110:111]
	v_pk_fma_f32 v[92:93], v[92:93], v[134:135], v[126:127]
	global_load_dwordx4 v[178:181], v[108:109], off
	global_load_dwordx4 v[104:107], v[108:109], off offset:64
	global_load_dwordx4 v[100:103], v[108:109], off offset:512
	global_load_dwordx4 v[96:99], v[108:109], off offset:576
	s_nop 0
	global_store_dwordx4 v[124:125], v[92:95], off
	s_nop 0
	s_nop 0
	global_load_dwordx4 v[92:95], v[168:169], off offset:64
	global_load_dwordx4 v[126:129], v[170:171], off offset:64
	global_load_dwordx4 v[130:133], v[208:209], off offset:64
	s_waitcnt vmcnt(3)
	v_mov_b32_e32 v110, v216
	v_mov_b32_e32 v111, v217
	v_sub_f32_e32 v123, v123, v110
	v_sub_f32_e32 v122, v122, v110
	v_sub_f32_e32 v121, v121, v110
	v_sub_f32_e32 v120, v120, v110
	v_pk_mul_f32 v[120:121], v[120:121], v[110:111] op_sel:[0,1]
	v_pk_mul_f32 v[110:111], v[122:123], v[110:111] op_sel:[0,1]
	s_waitcnt vmcnt(1)
	v_pk_fma_f32 v[92:93], v[92:93], v[120:121], v[126:127]
	v_pk_fma_f32 v[94:95], v[94:95], v[110:111], v[128:129]
	v_pk_mul_f32 v[92:93], v[92:93], s[42:43] op_sel_hi:[1,0]
	v_pk_mul_f32 v[94:95], v[94:95], s[42:43] op_sel_hi:[1,0]
	s_waitcnt vmcnt(0)
	v_pk_fma_f32 v[88:89], v[88:89], v[130:131], v[92:93]
	v_pk_fma_f32 v[90:91], v[90:91], v[132:133], v[94:95]
	global_store_dwordx4 v[124:125], v[88:91], off offset:64
	s_nop 0
	s_nop 0
	global_load_dwordx4 v[88:91], v[168:169], off offset:512
	global_load_dwordx4 v[92:95], v[170:171], off offset:512
	global_load_dwordx4 v[120:123], v[208:209], off offset:512
	v_lshl_add_u64 v[126:127], v[210:211], 3, s[62:63]
	s_waitcnt vmcnt(3)
	v_mov_b32_e32 v110, v216
	v_mov_b32_e32 v111, v217
	v_sub_f32_e32 v119, v119, v110
	v_sub_f32_e32 v118, v118, v110
	v_sub_f32_e32 v117, v117, v110
	v_sub_f32_e32 v116, v116, v110
	v_pk_mul_f32 v[116:117], v[116:117], v[110:111] op_sel:[0,1]
	v_pk_mul_f32 v[110:111], v[118:119], v[110:111] op_sel:[0,1]
	s_waitcnt vmcnt(1)
	v_pk_fma_f32 v[88:89], v[88:89], v[116:117], v[92:93]
	v_pk_fma_f32 v[90:91], v[90:91], v[110:111], v[94:95]
	v_pk_mul_f32 v[88:89], v[88:89], s[42:43] op_sel_hi:[1,0]
	v_pk_mul_f32 v[90:91], v[90:91], s[42:43] op_sel_hi:[1,0]
	s_waitcnt vmcnt(0)
	v_pk_fma_f32 v[84:85], v[84:85], v[120:121], v[88:89]
	v_pk_fma_f32 v[86:87], v[86:87], v[122:123], v[90:91]
	global_store_dwordx4 v[124:125], v[84:87], off offset:512
	s_nop 0
	s_nop 0
	global_load_dwordx4 v[84:87], v[168:169], off offset:576
	global_load_dwordx4 v[88:91], v[170:171], off offset:576
	global_load_dwordx4 v[92:95], v[208:209], off offset:576
	s_waitcnt vmcnt(3)
	v_mov_b32_e32 v110, v216
	v_mov_b32_e32 v111, v217
	v_sub_f32_e32 v115, v115, v110
	v_sub_f32_e32 v114, v114, v110
	v_sub_f32_e32 v113, v113, v110
	v_sub_f32_e32 v112, v112, v110
	v_pk_mul_f32 v[112:113], v[112:113], v[110:111] op_sel:[0,1]
	v_pk_mul_f32 v[110:111], v[114:115], v[110:111] op_sel:[0,1]
	s_waitcnt vmcnt(1)
	v_pk_fma_f32 v[84:85], v[84:85], v[112:113], v[88:89]
	v_pk_fma_f32 v[86:87], v[86:87], v[110:111], v[90:91]
	v_pk_mul_f32 v[84:85], v[84:85], s[42:43] op_sel_hi:[1,0]
	v_pk_mul_f32 v[86:87], v[86:87], s[42:43] op_sel_hi:[1,0]
	s_waitcnt vmcnt(0)
	v_pk_fma_f32 v[80:81], v[80:81], v[92:93], v[84:85]
	v_pk_fma_f32 v[82:83], v[82:83], v[94:95], v[86:87]
	global_store_dwordx4 v[124:125], v[80:83], off offset:576
	global_load_dwordx2 v[94:95], v[126:127], off
	global_load_dwordx4 v[110:113], v[168:169], off
	global_load_dwordx4 v[114:117], v[170:171], off
	v_cndmask_b32_e64 v80, v175, 4, vcc
	v_mul_hi_i32_i24_e32 v81, 0x6000, v80
	v_mul_i32_i24_e32 v80, 0x6000, v80
	v_lshl_add_u64 v[80:81], s[0:1], 0, v[80:81]
	v_lshl_add_u64 v[128:129], v[80:81], 0, v[172:173]
	global_load_dwordx4 v[118:121], v[128:129], off
	v_add_u32_e32 v80, 0x80, v174
	v_mul_hi_i32 v81, v80, s64
	v_lshrrev_b32_e32 v82, 31, v81
	v_ashrrev_i32_e32 v81, 11, v81
	v_add_u32_e32 v134, v81, v82
	v_mad_i32_i24 v80, v134, s65, v80
	v_lshl_add_u32 v81, v134, 13, v202
	v_lshlrev_b32_e32 v82, 8, v134
	v_cmp_gt_i32_e32 vcc, s52, v80
	s_waitcnt vmcnt(3)
	v_mov_b32_e32 v136, v94
	v_mov_b32_e32 v137, v95
	v_sub_f32_e32 v131, v181, v94
	v_cndmask_b32_e32 v81, v81, v82, vcc
	v_add_u32_e32 v80, v81, v80
	v_sub_f32_e32 v130, v180, v94
	v_sub_f32_e32 v133, v179, v94
	v_sub_f32_e32 v132, v178, v94
	v_ashrrev_i32_e32 v81, 31, v80
	v_pk_mul_f32 v[132:133], v[132:133], v[94:95] op_sel:[0,1]
	v_pk_mul_f32 v[94:95], v[130:131], v[94:95] op_sel:[0,1]
	v_cndmask_b32_e32 v83, v203, v204, vcc
	v_cndmask_b32_e32 v82, v205, v206, vcc
	v_lshlrev_b64 v[80:81], 12, v[80:81]
	s_waitcnt vmcnt(1)
	v_pk_fma_f32 v[94:95], v[112:113], v[94:95], v[116:117]
	v_pk_fma_f32 v[110:111], v[110:111], v[132:133], v[114:115]
	v_lshl_add_u64 v[80:81], v[82:83], 0, v[80:81]
	v_pk_mul_f32 v[110:111], v[110:111], s[42:43] op_sel_hi:[1,0]
	v_pk_mul_f32 v[94:95], v[94:95], s[42:43] op_sel_hi:[1,0]
	v_lshl_add_u64 v[92:93], v[80:81], 0, v[172:173]
	s_waitcnt vmcnt(0)
	v_pk_fma_f32 v[78:79], v[78:79], v[120:121], v[94:95]
	v_pk_fma_f32 v[76:77], v[76:77], v[118:119], v[110:111]
	global_load_dwordx4 v[122:125], v[92:93], off
	global_load_dwordx4 v[88:91], v[92:93], off offset:64
	global_load_dwordx4 v[84:87], v[92:93], off offset:512
	global_load_dwordx4 v[80:83], v[92:93], off offset:576
	s_nop 0
	global_store_dwordx4 v[108:109], v[76:79], off
	s_nop 0
	s_nop 0
	global_load_dwordx4 v[76:79], v[168:169], off offset:64
	global_load_dwordx4 v[110:113], v[170:171], off offset:64
	global_load_dwordx4 v[114:117], v[128:129], off offset:64
	s_waitcnt vmcnt(3)
	v_mov_b32_e32 v94, v136
	v_mov_b32_e32 v95, v137
	v_sub_f32_e32 v107, v107, v94
	v_sub_f32_e32 v106, v106, v94
	v_sub_f32_e32 v105, v105, v94
	v_sub_f32_e32 v104, v104, v94
	v_pk_mul_f32 v[104:105], v[104:105], v[94:95] op_sel:[0,1]
	v_pk_mul_f32 v[94:95], v[106:107], v[94:95] op_sel:[0,1]
	s_waitcnt vmcnt(1)
	v_pk_fma_f32 v[76:77], v[76:77], v[104:105], v[110:111]
	v_pk_fma_f32 v[78:79], v[78:79], v[94:95], v[112:113]
	v_pk_mul_f32 v[76:77], v[76:77], s[42:43] op_sel_hi:[1,0]
	v_pk_mul_f32 v[78:79], v[78:79], s[42:43] op_sel_hi:[1,0]
	s_waitcnt vmcnt(0)
	v_pk_fma_f32 v[72:73], v[72:73], v[114:115], v[76:77]
	v_pk_fma_f32 v[74:75], v[74:75], v[116:117], v[78:79]
	global_store_dwordx4 v[108:109], v[72:75], off offset:64
	s_nop 0
	s_nop 0
	global_load_dwordx4 v[72:75], v[168:169], off offset:512
	global_load_dwordx4 v[76:79], v[170:171], off offset:512
	global_load_dwordx4 v[104:107], v[128:129], off offset:512
	v_add_u32_e32 v112, 0x90, v174
	v_ashrrev_i32_e32 v113, 31, v112
	s_waitcnt vmcnt(3)
	v_mov_b32_e32 v94, v136
	v_mov_b32_e32 v95, v137
	v_sub_f32_e32 v103, v103, v94
	v_sub_f32_e32 v102, v102, v94
	v_sub_f32_e32 v101, v101, v94
	v_sub_f32_e32 v100, v100, v94
	v_pk_mul_f32 v[100:101], v[100:101], v[94:95] op_sel:[0,1]
	v_pk_mul_f32 v[94:95], v[102:103], v[94:95] op_sel:[0,1]
	s_waitcnt vmcnt(1)
	v_pk_fma_f32 v[72:73], v[72:73], v[100:101], v[76:77]
	v_pk_fma_f32 v[74:75], v[74:75], v[94:95], v[78:79]
	v_pk_mul_f32 v[72:73], v[72:73], s[42:43] op_sel_hi:[1,0]
	v_pk_mul_f32 v[74:75], v[74:75], s[42:43] op_sel_hi:[1,0]
	s_waitcnt vmcnt(0)
	v_pk_fma_f32 v[68:69], v[68:69], v[104:105], v[72:73]
	v_pk_fma_f32 v[70:71], v[70:71], v[106:107], v[74:75]
	global_store_dwordx4 v[108:109], v[68:71], off offset:512
	s_nop 0
	s_nop 0
	global_load_dwordx4 v[68:71], v[168:169], off offset:576
	global_load_dwordx4 v[72:75], v[170:171], off offset:576
	global_load_dwordx4 v[76:79], v[128:129], off offset:576
	s_waitcnt vmcnt(3)
	v_mov_b32_e32 v94, v136
	v_mov_b32_e32 v95, v137
	v_sub_f32_e32 v99, v99, v94
	v_sub_f32_e32 v98, v98, v94
	v_sub_f32_e32 v97, v97, v94
	v_sub_f32_e32 v96, v96, v94
	v_pk_mul_f32 v[96:97], v[96:97], v[94:95] op_sel:[0,1]
	v_pk_mul_f32 v[94:95], v[98:99], v[94:95] op_sel:[0,1]
	s_waitcnt vmcnt(1)
	v_pk_fma_f32 v[68:69], v[68:69], v[96:97], v[72:73]
	v_pk_fma_f32 v[70:71], v[70:71], v[94:95], v[74:75]
	v_pk_mul_f32 v[68:69], v[68:69], s[42:43] op_sel_hi:[1,0]
	v_pk_mul_f32 v[70:71], v[70:71], s[42:43] op_sel_hi:[1,0]
	s_waitcnt vmcnt(0)
	v_pk_fma_f32 v[64:65], v[64:65], v[76:77], v[68:69]
	v_pk_fma_f32 v[66:67], v[66:67], v[78:79], v[70:71]
	global_store_dwordx4 v[108:109], v[64:67], off offset:576
	global_load_dwordx2 v[78:79], v[176:177], off offset:1024
	global_load_dwordx4 v[94:97], v[168:169], off
	global_load_dwordx4 v[98:101], v[170:171], off
	v_cndmask_b32_e64 v64, v134, 4, vcc
	v_mul_hi_i32_i24_e32 v65, 0x6000, v64
	v_mul_i32_i24_e32 v64, 0x6000, v64
	v_lshl_add_u64 v[64:65], s[0:1], 0, v[64:65]
	v_lshl_add_u64 v[110:111], v[64:65], 0, v[172:173]
	global_load_dwordx4 v[102:105], v[110:111], off
	v_mul_hi_i32 v64, v112, s64
	v_lshrrev_b32_e32 v65, 31, v64
	v_ashrrev_i32_e32 v64, 11, v64
	v_add_u32_e32 v118, v64, v65
	v_mad_i32_i24 v64, v118, s65, v112
	v_lshl_add_u32 v65, v118, 13, v202
	v_lshlrev_b32_e32 v66, 8, v118
	v_cmp_gt_i32_e32 vcc, s52, v64
	s_waitcnt vmcnt(3)
	v_sub_f32_e32 v115, v125, v78
	v_cndmask_b32_e32 v65, v65, v66, vcc
	v_add_u32_e32 v64, v65, v64
	v_sub_f32_e32 v114, v124, v78
	v_sub_f32_e32 v117, v123, v78
	v_sub_f32_e32 v116, v122, v78
	v_ashrrev_i32_e32 v65, 31, v64
	v_pk_mul_f32 v[116:117], v[116:117], v[78:79] op_sel:[0,1]
	v_pk_mul_f32 v[78:79], v[114:115], v[78:79] op_sel:[0,1]
	v_cndmask_b32_e32 v67, v203, v204, vcc
	v_cndmask_b32_e32 v66, v205, v206, vcc
	v_lshlrev_b64 v[64:65], 12, v[64:65]
	s_waitcnt vmcnt(1)
	v_pk_fma_f32 v[78:79], v[96:97], v[78:79], v[100:101]
	v_pk_fma_f32 v[94:95], v[94:95], v[116:117], v[98:99]
	v_lshl_add_u64 v[64:65], v[66:67], 0, v[64:65]
	v_pk_mul_f32 v[94:95], v[94:95], s[42:43] op_sel_hi:[1,0]
	v_pk_mul_f32 v[78:79], v[78:79], s[42:43] op_sel_hi:[1,0]
	v_lshl_add_u64 v[76:77], v[64:65], 0, v[172:173]
	s_waitcnt vmcnt(0)
	v_pk_fma_f32 v[62:63], v[62:63], v[104:105], v[78:79]
	v_pk_fma_f32 v[60:61], v[60:61], v[102:103], v[94:95]
	global_load_dwordx4 v[106:109], v[76:77], off
	global_load_dwordx4 v[72:75], v[76:77], off offset:64
	global_load_dwordx4 v[68:71], v[76:77], off offset:512
	global_load_dwordx4 v[64:67], v[76:77], off offset:576
	s_nop 0
	global_store_dwordx4 v[92:93], v[60:63], off
	global_load_dwordx2 v[78:79], v[176:177], off offset:1024
	s_nop 0
	global_load_dwordx4 v[60:63], v[168:169], off offset:64
	global_load_dwordx4 v[94:97], v[170:171], off offset:64
	global_load_dwordx4 v[98:101], v[110:111], off offset:64
	s_waitcnt vmcnt(3)
	v_sub_f32_e32 v91, v91, v78
	v_sub_f32_e32 v90, v90, v78
	v_sub_f32_e32 v89, v89, v78
	v_sub_f32_e32 v88, v88, v78
	v_pk_mul_f32 v[88:89], v[88:89], v[78:79] op_sel:[0,1]
	v_pk_mul_f32 v[78:79], v[90:91], v[78:79] op_sel:[0,1]
	s_waitcnt vmcnt(1)
	v_pk_fma_f32 v[60:61], v[60:61], v[88:89], v[94:95]
	v_pk_fma_f32 v[62:63], v[62:63], v[78:79], v[96:97]
	v_pk_mul_f32 v[60:61], v[60:61], s[42:43] op_sel_hi:[1,0]
	v_pk_mul_f32 v[62:63], v[62:63], s[42:43] op_sel_hi:[1,0]
	s_waitcnt vmcnt(0)
	v_pk_fma_f32 v[56:57], v[56:57], v[98:99], v[60:61]
	v_pk_fma_f32 v[58:59], v[58:59], v[100:101], v[62:63]
	global_store_dwordx4 v[92:93], v[56:59], off offset:64
	global_load_dwordx2 v[78:79], v[176:177], off offset:1024
	s_nop 0
	global_load_dwordx4 v[56:59], v[168:169], off offset:512
	global_load_dwordx4 v[60:63], v[170:171], off offset:512
	global_load_dwordx4 v[88:91], v[110:111], off offset:512
	v_lshl_add_u64 v[94:95], v[112:113], 3, s[62:63]
	v_add_u32_e32 v98, 0xa0, v174
	v_ashrrev_i32_e32 v99, 31, v98
	s_waitcnt vmcnt(3)
	v_sub_f32_e32 v87, v87, v78
	v_sub_f32_e32 v86, v86, v78
	v_sub_f32_e32 v85, v85, v78
	v_sub_f32_e32 v84, v84, v78
	v_pk_mul_f32 v[84:85], v[84:85], v[78:79] op_sel:[0,1]
	v_pk_mul_f32 v[78:79], v[86:87], v[78:79] op_sel:[0,1]
	s_waitcnt vmcnt(1)
	v_pk_fma_f32 v[56:57], v[56:57], v[84:85], v[60:61]
	v_pk_fma_f32 v[58:59], v[58:59], v[78:79], v[62:63]
	v_pk_mul_f32 v[56:57], v[56:57], s[42:43] op_sel_hi:[1,0]
	v_pk_mul_f32 v[58:59], v[58:59], s[42:43] op_sel_hi:[1,0]
	s_waitcnt vmcnt(0)
	v_pk_fma_f32 v[52:53], v[52:53], v[88:89], v[56:57]
	v_pk_fma_f32 v[54:55], v[54:55], v[90:91], v[58:59]
	global_store_dwordx4 v[92:93], v[52:55], off offset:512
	global_load_dwordx2 v[78:79], v[176:177], off offset:1024
	s_nop 0
	global_load_dwordx4 v[52:55], v[168:169], off offset:576
	global_load_dwordx4 v[56:59], v[170:171], off offset:576
	global_load_dwordx4 v[60:63], v[110:111], off offset:576
	s_waitcnt vmcnt(3)
	v_sub_f32_e32 v83, v83, v78
	v_sub_f32_e32 v82, v82, v78
	v_sub_f32_e32 v81, v81, v78
	v_sub_f32_e32 v80, v80, v78
	v_pk_mul_f32 v[80:81], v[80:81], v[78:79] op_sel:[0,1]
	v_pk_mul_f32 v[78:79], v[82:83], v[78:79] op_sel:[0,1]
	s_waitcnt vmcnt(1)
	v_pk_fma_f32 v[52:53], v[52:53], v[80:81], v[56:57]
	v_pk_fma_f32 v[54:55], v[54:55], v[78:79], v[58:59]
	v_pk_mul_f32 v[52:53], v[52:53], s[42:43] op_sel_hi:[1,0]
	v_pk_mul_f32 v[54:55], v[54:55], s[42:43] op_sel_hi:[1,0]
	s_waitcnt vmcnt(0)
	v_pk_fma_f32 v[48:49], v[48:49], v[60:61], v[52:53]
	v_pk_fma_f32 v[50:51], v[50:51], v[62:63], v[54:55]
	global_store_dwordx4 v[92:93], v[48:51], off offset:576
	global_load_dwordx2 v[62:63], v[94:95], off
	global_load_dwordx4 v[78:81], v[168:169], off
	global_load_dwordx4 v[82:85], v[170:171], off
	v_cndmask_b32_e64 v48, v118, 4, vcc
	v_mul_hi_i32_i24_e32 v49, 0x6000, v48
	v_mul_i32_i24_e32 v48, 0x6000, v48
	v_lshl_add_u64 v[48:49], s[0:1], 0, v[48:49]
	v_lshl_add_u64 v[96:97], v[48:49], 0, v[172:173]
	global_load_dwordx4 v[86:89], v[96:97], off
	v_mul_hi_i32 v48, v98, s64
	v_lshrrev_b32_e32 v49, 31, v48
	v_ashrrev_i32_e32 v48, 11, v48
	v_add_u32_e32 v104, v48, v49
	v_mad_i32_i24 v48, v104, s65, v98
	v_lshl_add_u32 v49, v104, 13, v202
	v_lshlrev_b32_e32 v50, 8, v104
	v_cmp_gt_i32_e32 vcc, s52, v48
	s_waitcnt vmcnt(3)
	v_mov_b32_e32 v128, v62
	v_mov_b32_e32 v129, v63
	v_sub_f32_e32 v101, v109, v62
	v_cndmask_b32_e32 v49, v49, v50, vcc
	v_add_u32_e32 v48, v49, v48
	v_sub_f32_e32 v100, v108, v62
	v_sub_f32_e32 v103, v107, v62
	v_sub_f32_e32 v102, v106, v62
	v_ashrrev_i32_e32 v49, 31, v48
	v_pk_mul_f32 v[102:103], v[102:103], v[62:63] op_sel:[0,1]
	v_pk_mul_f32 v[62:63], v[100:101], v[62:63] op_sel:[0,1]
	v_cndmask_b32_e32 v51, v203, v204, vcc
	v_cndmask_b32_e32 v50, v205, v206, vcc
	v_lshlrev_b64 v[48:49], 12, v[48:49]
	s_waitcnt vmcnt(1)
	v_pk_fma_f32 v[62:63], v[80:81], v[62:63], v[84:85]
	v_pk_fma_f32 v[78:79], v[78:79], v[102:103], v[82:83]
	v_lshl_add_u64 v[48:49], v[50:51], 0, v[48:49]
	v_pk_mul_f32 v[78:79], v[78:79], s[42:43] op_sel_hi:[1,0]
	v_pk_mul_f32 v[62:63], v[62:63], s[42:43] op_sel_hi:[1,0]
	v_lshl_add_u64 v[60:61], v[48:49], 0, v[172:173]
	s_waitcnt vmcnt(0)
	v_pk_fma_f32 v[46:47], v[46:47], v[88:89], v[62:63]
	v_pk_fma_f32 v[44:45], v[44:45], v[86:87], v[78:79]
	global_load_dwordx4 v[90:93], v[60:61], off
	global_load_dwordx4 v[56:59], v[60:61], off offset:64
	global_load_dwordx4 v[52:55], v[60:61], off offset:512
	global_load_dwordx4 v[48:51], v[60:61], off offset:576
	s_nop 0
	global_store_dwordx4 v[76:77], v[44:47], off
	s_nop 0
	s_nop 0
	global_load_dwordx4 v[44:47], v[168:169], off offset:64
	global_load_dwordx4 v[78:81], v[170:171], off offset:64
	global_load_dwordx4 v[82:85], v[96:97], off offset:64
	s_waitcnt vmcnt(3)
	v_mov_b32_e32 v62, v128
	v_mov_b32_e32 v63, v129
	v_sub_f32_e32 v75, v75, v62
	v_sub_f32_e32 v74, v74, v62
	v_sub_f32_e32 v73, v73, v62
	v_sub_f32_e32 v72, v72, v62
	v_pk_mul_f32 v[72:73], v[72:73], v[62:63] op_sel:[0,1]
	v_pk_mul_f32 v[62:63], v[74:75], v[62:63] op_sel:[0,1]
	s_waitcnt vmcnt(1)
	v_pk_fma_f32 v[44:45], v[44:45], v[72:73], v[78:79]
	v_pk_fma_f32 v[46:47], v[46:47], v[62:63], v[80:81]
	v_pk_mul_f32 v[44:45], v[44:45], s[42:43] op_sel_hi:[1,0]
	v_pk_mul_f32 v[46:47], v[46:47], s[42:43] op_sel_hi:[1,0]
	s_waitcnt vmcnt(0)
	v_pk_fma_f32 v[40:41], v[40:41], v[82:83], v[44:45]
	v_pk_fma_f32 v[42:43], v[42:43], v[84:85], v[46:47]
	global_store_dwordx4 v[76:77], v[40:43], off offset:64
	s_nop 0
	s_nop 0
	global_load_dwordx4 v[40:43], v[168:169], off offset:512
	global_load_dwordx4 v[44:47], v[170:171], off offset:512
	global_load_dwordx4 v[72:75], v[96:97], off offset:512
	v_lshl_add_u64 v[78:79], v[98:99], 3, s[62:63]
	v_add_u32_e32 v82, 0xb0, v174
	v_ashrrev_i32_e32 v83, 31, v82
	s_waitcnt vmcnt(3)
	v_mov_b32_e32 v62, v128
	v_mov_b32_e32 v63, v129
	v_sub_f32_e32 v71, v71, v62
	v_sub_f32_e32 v70, v70, v62
	v_sub_f32_e32 v69, v69, v62
	v_sub_f32_e32 v68, v68, v62
	v_pk_mul_f32 v[68:69], v[68:69], v[62:63] op_sel:[0,1]
	v_pk_mul_f32 v[62:63], v[70:71], v[62:63] op_sel:[0,1]
	s_waitcnt vmcnt(1)
	v_pk_fma_f32 v[40:41], v[40:41], v[68:69], v[44:45]
	v_pk_fma_f32 v[42:43], v[42:43], v[62:63], v[46:47]
	v_pk_mul_f32 v[40:41], v[40:41], s[42:43] op_sel_hi:[1,0]
	v_pk_mul_f32 v[42:43], v[42:43], s[42:43] op_sel_hi:[1,0]
	s_waitcnt vmcnt(0)
	v_pk_fma_f32 v[36:37], v[36:37], v[72:73], v[40:41]
	v_pk_fma_f32 v[38:39], v[38:39], v[74:75], v[42:43]
	global_store_dwordx4 v[76:77], v[36:39], off offset:512
	s_nop 0
	s_nop 0
	global_load_dwordx4 v[36:39], v[168:169], off offset:576
	global_load_dwordx4 v[40:43], v[170:171], off offset:576
	global_load_dwordx4 v[44:47], v[96:97], off offset:576
	s_waitcnt vmcnt(3)
	v_mov_b32_e32 v62, v128
	v_mov_b32_e32 v63, v129
	v_sub_f32_e32 v67, v67, v62
	v_sub_f32_e32 v66, v66, v62
	v_sub_f32_e32 v65, v65, v62
	v_sub_f32_e32 v64, v64, v62
	v_pk_mul_f32 v[64:65], v[64:65], v[62:63] op_sel:[0,1]
	v_pk_mul_f32 v[62:63], v[66:67], v[62:63] op_sel:[0,1]
	s_waitcnt vmcnt(1)
	v_pk_fma_f32 v[36:37], v[36:37], v[64:65], v[40:41]
	v_pk_fma_f32 v[38:39], v[38:39], v[62:63], v[42:43]
	v_pk_mul_f32 v[36:37], v[36:37], s[42:43] op_sel_hi:[1,0]
	v_pk_mul_f32 v[38:39], v[38:39], s[42:43] op_sel_hi:[1,0]
	s_waitcnt vmcnt(0)
	v_pk_fma_f32 v[32:33], v[32:33], v[44:45], v[36:37]
	v_pk_fma_f32 v[34:35], v[34:35], v[46:47], v[38:39]
	global_store_dwordx4 v[76:77], v[32:35], off offset:576
	global_load_dwordx2 v[46:47], v[78:79], off
	global_load_dwordx4 v[42:45], v[168:169], off
	global_load_dwordx4 v[62:65], v[170:171], off
	v_cndmask_b32_e64 v32, v104, 4, vcc
	v_mul_hi_i32_i24_e32 v33, 0x6000, v32
	v_mul_i32_i24_e32 v32, 0x6000, v32
	v_lshl_add_u64 v[32:33], s[0:1], 0, v[32:33]
	v_lshl_add_u64 v[80:81], v[32:33], 0, v[172:173]
	global_load_dwordx4 v[66:69], v[80:81], off
	v_mul_hi_i32 v32, v82, s64
	v_lshrrev_b32_e32 v33, 31, v32
	v_ashrrev_i32_e32 v32, 11, v32
	v_add_u32_e32 v88, v32, v33
	v_mad_i32_i24 v32, v88, s65, v82
	v_lshl_add_u32 v33, v88, 13, v202
	v_lshlrev_b32_e32 v34, 8, v88
	v_cmp_gt_i32_e32 vcc, s52, v32
	s_waitcnt vmcnt(3)
	v_mov_b32_e32 v128, v46
	v_mov_b32_e32 v129, v47
	v_sub_f32_e32 v85, v93, v46
	v_cndmask_b32_e32 v33, v33, v34, vcc
	v_add_u32_e32 v32, v33, v32
	v_sub_f32_e32 v84, v92, v46
	v_sub_f32_e32 v87, v91, v46
	v_sub_f32_e32 v86, v90, v46
	v_ashrrev_i32_e32 v33, 31, v32
	v_pk_mul_f32 v[86:87], v[86:87], v[46:47] op_sel:[0,1]
	v_pk_mul_f32 v[46:47], v[84:85], v[46:47] op_sel:[0,1]
	v_cndmask_b32_e32 v35, v203, v204, vcc
	v_cndmask_b32_e32 v34, v205, v206, vcc
	v_lshlrev_b64 v[32:33], 12, v[32:33]
	s_waitcnt vmcnt(1)
	v_pk_fma_f32 v[44:45], v[44:45], v[46:47], v[64:65]
	v_pk_fma_f32 v[42:43], v[42:43], v[86:87], v[62:63]
	v_lshl_add_u64 v[32:33], v[34:35], 0, v[32:33]
	v_pk_mul_f32 v[42:43], v[42:43], s[42:43] op_sel_hi:[1,0]
	v_pk_mul_f32 v[44:45], v[44:45], s[42:43] op_sel_hi:[1,0]
	v_lshl_add_u64 v[40:41], v[32:33], 0, v[172:173]
	s_waitcnt vmcnt(0)
	v_pk_fma_f32 v[30:31], v[30:31], v[68:69], v[44:45]
	v_pk_fma_f32 v[28:29], v[28:29], v[66:67], v[42:43]
	global_load_dwordx4 v[70:73], v[40:41], off
	global_load_dwordx4 v[74:77], v[40:41], off offset:64
	global_load_dwordx4 v[36:39], v[40:41], off offset:512
	global_load_dwordx4 v[32:35], v[40:41], off offset:576
	s_nop 0
	global_store_dwordx4 v[60:61], v[28:31], off
	s_nop 0
	s_nop 0
	global_load_dwordx4 v[28:31], v[168:169], off offset:64
	global_load_dwordx4 v[42:45], v[170:171], off offset:64
	global_load_dwordx4 v[62:65], v[80:81], off offset:64
	s_waitcnt vmcnt(3)
	v_mov_b32_e32 v46, v128
	v_mov_b32_e32 v47, v129
	v_sub_f32_e32 v59, v59, v46
	v_sub_f32_e32 v58, v58, v46
	v_sub_f32_e32 v57, v57, v46
	v_sub_f32_e32 v56, v56, v46
	v_pk_mul_f32 v[56:57], v[56:57], v[46:47] op_sel:[0,1]
	v_pk_mul_f32 v[46:47], v[58:59], v[46:47] op_sel:[0,1]
	s_waitcnt vmcnt(1)
	v_pk_fma_f32 v[28:29], v[28:29], v[56:57], v[42:43]
	v_pk_fma_f32 v[30:31], v[30:31], v[46:47], v[44:45]
	v_pk_mul_f32 v[28:29], v[28:29], s[42:43] op_sel_hi:[1,0]
	v_pk_mul_f32 v[30:31], v[30:31], s[42:43] op_sel_hi:[1,0]
	s_waitcnt vmcnt(0)
	v_pk_fma_f32 v[24:25], v[24:25], v[62:63], v[28:29]
	v_pk_fma_f32 v[26:27], v[26:27], v[64:65], v[30:31]
	global_store_dwordx4 v[60:61], v[24:27], off offset:64
	s_nop 0
	s_nop 0
	global_load_dwordx4 v[24:27], v[168:169], off offset:512
	global_load_dwordx4 v[28:31], v[170:171], off offset:512
	global_load_dwordx4 v[42:45], v[80:81], off offset:512
	s_waitcnt vmcnt(3)
	v_mov_b32_e32 v46, v128
	v_mov_b32_e32 v47, v129
	v_sub_f32_e32 v55, v55, v46
	v_sub_f32_e32 v54, v54, v46
	v_sub_f32_e32 v53, v53, v46
	v_sub_f32_e32 v52, v52, v46
	v_pk_mul_f32 v[52:53], v[52:53], v[46:47] op_sel:[0,1]
	v_pk_mul_f32 v[46:47], v[54:55], v[46:47] op_sel:[0,1]
	s_waitcnt vmcnt(1)
	v_pk_fma_f32 v[24:25], v[24:25], v[52:53], v[28:29]
	v_pk_fma_f32 v[26:27], v[26:27], v[46:47], v[30:31]
	v_pk_mul_f32 v[24:25], v[24:25], s[42:43] op_sel_hi:[1,0]
	v_pk_mul_f32 v[26:27], v[26:27], s[42:43] op_sel_hi:[1,0]
	s_waitcnt vmcnt(0)
	v_pk_fma_f32 v[20:21], v[20:21], v[42:43], v[24:25]
	v_pk_fma_f32 v[22:23], v[22:23], v[44:45], v[26:27]
	global_store_dwordx4 v[60:61], v[20:23], off offset:512
	s_nop 0
	s_nop 0
	global_load_dwordx4 v[20:23], v[168:169], off offset:576
	global_load_dwordx4 v[24:27], v[170:171], off offset:576
	global_load_dwordx4 v[28:31], v[80:81], off offset:576
	v_lshl_add_u64 v[44:45], v[82:83], 3, s[62:63]
	s_waitcnt vmcnt(3)
	v_mov_b32_e32 v42, v128
	v_mov_b32_e32 v43, v129
	v_sub_f32_e32 v47, v51, v42
	v_sub_f32_e32 v46, v50, v42
	v_sub_f32_e32 v49, v49, v42
	v_sub_f32_e32 v48, v48, v42
	v_pk_mul_f32 v[48:49], v[48:49], v[42:43] op_sel:[0,1]
	v_pk_mul_f32 v[42:43], v[46:47], v[42:43] op_sel:[0,1]
	s_waitcnt vmcnt(1)
	v_pk_fma_f32 v[20:21], v[20:21], v[48:49], v[24:25]
	v_pk_fma_f32 v[22:23], v[22:23], v[42:43], v[26:27]
	v_pk_mul_f32 v[20:21], v[20:21], s[42:43] op_sel_hi:[1,0]
	v_pk_mul_f32 v[22:23], v[22:23], s[42:43] op_sel_hi:[1,0]
	s_waitcnt vmcnt(0)
	v_pk_fma_f32 v[16:17], v[16:17], v[28:29], v[20:21]
	v_pk_fma_f32 v[18:19], v[18:19], v[30:31], v[22:23]
	global_store_dwordx4 v[60:61], v[16:19], off offset:576
	global_load_dwordx2 v[28:29], v[44:45], off
	v_cndmask_b32_e64 v24, v88, 4, vcc
	v_mul_hi_i32_i24_e32 v25, 0x6000, v24
	v_mul_i32_i24_e32 v24, 0x6000, v24
	global_load_dwordx4 v[16:19], v[168:169], off
	global_load_dwordx4 v[20:23], v[170:171], off
	v_lshl_add_u64 v[24:25], s[0:1], 0, v[24:25]
	v_lshl_add_u64 v[30:31], v[24:25], 0, v[172:173]
	global_load_dwordx4 v[24:27], v[30:31], off
	s_and_b64 vcc, exec, s[10:11]
	s_waitcnt vmcnt(3)
	v_mov_b32_e32 v128, v28
	v_mov_b32_e32 v129, v29
	v_sub_f32_e32 v43, v73, v28
	v_sub_f32_e32 v42, v72, v28
	v_sub_f32_e32 v47, v71, v28
	v_sub_f32_e32 v46, v70, v28
	v_pk_mul_f32 v[46:47], v[46:47], v[28:29] op_sel:[0,1]
	v_pk_mul_f32 v[28:29], v[42:43], v[28:29] op_sel:[0,1]
	s_waitcnt vmcnt(1)
	v_pk_fma_f32 v[16:17], v[16:17], v[46:47], v[20:21]
	v_pk_fma_f32 v[18:19], v[18:19], v[28:29], v[22:23]
	v_pk_mul_f32 v[16:17], v[16:17], s[42:43] op_sel_hi:[1,0]
	v_pk_mul_f32 v[18:19], v[18:19], s[42:43] op_sel_hi:[1,0]
	s_waitcnt vmcnt(0)
	v_pk_fma_f32 v[12:13], v[12:13], v[24:25], v[16:17]
	v_pk_fma_f32 v[14:15], v[14:15], v[26:27], v[18:19]
	global_store_dwordx4 v[40:41], v[12:15], off
	s_nop 0
	s_nop 0
	global_load_dwordx4 v[12:15], v[168:169], off offset:64
	global_load_dwordx4 v[16:19], v[170:171], off offset:64
	global_load_dwordx4 v[20:23], v[30:31], off offset:64
	s_waitcnt vmcnt(3)
	v_mov_b32_e32 v24, v128
	v_mov_b32_e32 v25, v129
	v_sub_f32_e32 v27, v77, v24
	v_sub_f32_e32 v26, v76, v24
	v_sub_f32_e32 v29, v75, v24
	v_sub_f32_e32 v28, v74, v24
	v_pk_mul_f32 v[28:29], v[28:29], v[24:25] op_sel:[0,1]
	v_pk_mul_f32 v[24:25], v[26:27], v[24:25] op_sel:[0,1]
	s_waitcnt vmcnt(1)
	v_pk_fma_f32 v[12:13], v[12:13], v[28:29], v[16:17]
	v_pk_fma_f32 v[14:15], v[14:15], v[24:25], v[18:19]
	v_pk_mul_f32 v[12:13], v[12:13], s[42:43] op_sel_hi:[1,0]
	v_pk_mul_f32 v[14:15], v[14:15], s[42:43] op_sel_hi:[1,0]
	s_waitcnt vmcnt(0)
	v_pk_fma_f32 v[8:9], v[8:9], v[20:21], v[12:13]
	v_pk_fma_f32 v[10:11], v[10:11], v[22:23], v[14:15]
	global_store_dwordx4 v[40:41], v[8:11], off offset:64
	s_nop 0
	s_nop 0
	global_load_dwordx4 v[8:11], v[168:169], off offset:512
	global_load_dwordx4 v[12:15], v[170:171], off offset:512
	global_load_dwordx4 v[16:19], v[30:31], off offset:512
	s_waitcnt vmcnt(3)
	v_mov_b32_e32 v20, v128
	v_mov_b32_e32 v21, v129
	v_sub_f32_e32 v23, v39, v20
	v_sub_f32_e32 v22, v38, v20
	v_sub_f32_e32 v25, v37, v20
	v_sub_f32_e32 v24, v36, v20
	v_pk_mul_f32 v[24:25], v[24:25], v[20:21] op_sel:[0,1]
	v_pk_mul_f32 v[20:21], v[22:23], v[20:21] op_sel:[0,1]
	s_waitcnt vmcnt(1)
	v_pk_fma_f32 v[8:9], v[8:9], v[24:25], v[12:13]
	v_pk_fma_f32 v[10:11], v[10:11], v[20:21], v[14:15]
	v_pk_mul_f32 v[8:9], v[8:9], s[42:43] op_sel_hi:[1,0]
	v_pk_mul_f32 v[10:11], v[10:11], s[42:43] op_sel_hi:[1,0]
	s_waitcnt vmcnt(0)
	v_pk_fma_f32 v[4:5], v[4:5], v[16:17], v[8:9]
	v_pk_fma_f32 v[6:7], v[6:7], v[18:19], v[10:11]
	global_store_dwordx4 v[40:41], v[4:7], off offset:512
	s_nop 0
	s_nop 0
	global_load_dwordx4 v[4:7], v[168:169], off offset:576
	global_load_dwordx4 v[8:11], v[170:171], off offset:576
	global_load_dwordx4 v[12:15], v[30:31], off offset:576
	s_waitcnt vmcnt(3)
	v_mov_b32_e32 v16, v128
	v_mov_b32_e32 v17, v129
	v_sub_f32_e32 v19, v35, v16
	v_sub_f32_e32 v18, v34, v16
	v_sub_f32_e32 v21, v33, v16
	v_sub_f32_e32 v20, v32, v16
	v_pk_mul_f32 v[20:21], v[20:21], v[16:17] op_sel:[0,1]
	v_pk_mul_f32 v[16:17], v[18:19], v[16:17] op_sel:[0,1]
	s_waitcnt vmcnt(1)
	v_pk_fma_f32 v[4:5], v[4:5], v[20:21], v[8:9]
	v_pk_fma_f32 v[6:7], v[6:7], v[16:17], v[10:11]
	v_pk_mul_f32 v[4:5], v[4:5], s[42:43] op_sel_hi:[1,0]
	v_pk_mul_f32 v[6:7], v[6:7], s[42:43] op_sel_hi:[1,0]
	s_waitcnt vmcnt(0)
	v_pk_fma_f32 v[0:1], v[0:1], v[12:13], v[4:5]
	v_pk_fma_f32 v[2:3], v[2:3], v[14:15], v[6:7]
	global_store_dwordx4 v[40:41], v[0:3], off offset:576
	s_cbranch_vccnz .LBB0_1164
	s_andn2_b64 vcc, exec, s[8:9]
	s_cbranch_vccnz .LBB0_1163
	s_barrier
	s_branch .LBB0_1163

.LBB0_1769:
	v_lshl_add_u32 v186, s64, 8, v153
	v_mul_hi_i32 v128, v186, s76
	v_lshrrev_b32_e32 v129, 31, v128
	v_ashrrev_i32_e32 v128, 11, v128
	v_add_u32_e32 v132, v128, v129
	v_mad_i32_i24 v128, v132, s77, v186
	v_lshl_add_u32 v129, v132, 13, v215
	v_lshlrev_b32_e32 v130, 8, v132
	v_cmp_gt_i32_e32 vcc, s52, v128
	v_readlane_b32 s16, v254, 28
	v_readlane_b32 s20, v254, 32
	v_cndmask_b32_e32 v129, v129, v130, vcc
	v_add_u32_e32 v128, v129, v128
	v_readlane_b32 s21, v254, 33
	v_lshl_or_b32 v232, s66, 8, v198
	v_mov_b32_e32 v217, s71
	v_mov_b32_e32 v216, s21
	v_mov_b32_e32 v218, s20
	v_mov_b32_e32 v219, s70
	v_ashrrev_i32_e32 v129, 31, v128
	v_cndmask_b32_e32 v131, v216, v217, vcc
	v_cndmask_b32_e32 v130, v218, v219, vcc
	v_lshlrev_b64 v[128:129], 12, v[128:129]
	v_ashrrev_i32_e32 v233, 31, v232
	v_lshl_add_u64 v[128:129], v[130:131], 0, v[128:129]
	v_lshlrev_b64 v[172:173], 2, v[232:233]
	v_ashrrev_i32_e32 v187, 31, v186
	v_lshl_add_u64 v[192:193], v[128:129], 0, v[172:173]
	v_lshl_add_u64 v[188:189], v[186:187], 3, s[62:63]
	global_load_dwordx4 v[178:181], v[192:193], off
	global_load_dwordx4 v[228:231], v[192:193], off offset:64
	global_load_dwordx2 v[234:235], v[188:189], off
	v_cndmask_b32_e64 v128, v132, 4, vcc
	v_mul_hi_i32_i24_e32 v129, 0x6000, v128
	v_lshl_add_u64 v[174:175], s[10:11], 0, v[172:173]
	v_lshl_add_u64 v[176:177], s[12:13], 0, v[172:173]
	v_mul_i32_i24_e32 v128, 0x6000, v128
	global_load_dwordx4 v[182:185], v[174:175], off
	global_load_dwordx4 v[220:223], v[176:177], off
	v_lshl_add_u64 v[128:129], s[0:1], 0, v[128:129]
	v_lshl_add_u64 v[236:237], v[128:129], 0, v[172:173]
	global_load_dwordx4 v[224:227], v[236:237], off
	v_or_b32_e32 v240, 16, v186
	v_mul_hi_i32 v128, v240, s76
	v_lshrrev_b32_e32 v129, 31, v128
	v_ashrrev_i32_e32 v128, 11, v128
	v_add_u32_e32 v187, v128, v129
	v_mad_i32_i24 v128, v187, s77, v240
	v_lshl_add_u32 v129, v187, 13, v215
	v_lshlrev_b32_e32 v130, 8, v187
	v_cmp_gt_i32_e32 vcc, s52, v128
	v_or_b32_e32 v238, 16, v232
	v_ashrrev_i32_e32 v239, 31, v238
	v_cndmask_b32_e32 v129, v129, v130, vcc
	v_add_u32_e32 v128, v129, v128
	v_ashrrev_i32_e32 v129, 31, v128
	v_cndmask_b32_e32 v131, v216, v217, vcc
	v_cndmask_b32_e32 v130, v218, v219, vcc
	v_lshlrev_b64 v[128:129], 12, v[128:129]
	v_lshl_add_u64 v[128:129], v[130:131], 0, v[128:129]
	v_lshl_add_u64 v[190:191], v[128:129], 0, v[172:173]
	global_load_dwordx4 v[140:143], v[190:191], off
	global_load_dwordx4 v[136:139], v[190:191], off offset:64
	global_load_dwordx4 v[132:135], v[190:191], off offset:512
	global_load_dwordx4 v[128:131], v[190:191], off offset:576
	v_ashrrev_i32_e32 v241, 31, v240
	v_or_b32_e32 v242, 32, v186
	v_ashrrev_i32_e32 v243, 31, v242
	s_mov_b64 s[4:5], -1
	v_readlane_b32 s17, v254, 29
	v_readlane_b32 s18, v254, 30
	v_readlane_b32 s19, v254, 31
	v_readlane_b32 s22, v254, 34
	v_readlane_b32 s23, v254, 35
	s_waitcnt vmcnt(0)
	v_sub_f32_e32 v181, v181, v234
	v_sub_f32_e32 v180, v180, v234
	v_sub_f32_e32 v179, v179, v234
	v_sub_f32_e32 v178, v178, v234
	v_pk_mul_f32 v[178:179], v[178:179], v[234:235] op_sel:[0,1]
	v_pk_mul_f32 v[180:181], v[180:181], v[234:235] op_sel:[0,1]
	v_pk_fma_f32 v[178:179], v[182:183], v[178:179], v[220:221]
	v_pk_fma_f32 v[180:181], v[184:185], v[180:181], v[222:223]
	v_pk_mul_f32 v[178:179], v[178:179], s[44:45] op_sel_hi:[1,0]
	v_pk_mul_f32 v[180:181], v[180:181], s[44:45] op_sel_hi:[1,0]
	v_pk_fma_f32 v[124:125], v[124:125], v[224:225], v[178:179]
	v_pk_fma_f32 v[126:127], v[126:127], v[226:227], v[180:181]
	global_store_dwordx4 v[192:193], v[124:127], off
	s_nop 0
	s_waitcnt vmcnt(1)
	v_sub_f32_e32 v231, v231, v234
	v_lshlrev_b64 v[126:127], 2, v[238:239]
	v_lshl_add_u64 v[124:125], s[10:11], 0, v[126:127]
	v_lshl_add_u64 v[126:127], s[12:13], 0, v[126:127]
	global_load_dwordx4 v[178:181], v[124:125], off
	global_load_dwordx4 v[182:185], v[126:127], off
	global_load_dwordx4 v[220:223], v[236:237], off offset:64
	v_sub_f32_e32 v230, v230, v234
	v_sub_f32_e32 v229, v229, v234
	v_sub_f32_e32 v228, v228, v234
	v_pk_mul_f32 v[228:229], v[228:229], v[234:235] op_sel:[0,1]
	v_pk_mul_f32 v[230:231], v[230:231], v[234:235] op_sel:[0,1]
	v_or_b32_e32 v238, 0x80, v232
	global_load_dwordx4 v[224:227], v[192:193], off offset:512
	v_ashrrev_i32_e32 v239, 31, v238
	v_or_b32_e32 v232, 0x90, v232
	v_ashrrev_i32_e32 v233, 31, v232
	s_waitcnt vmcnt(2)
	v_pk_fma_f32 v[180:181], v[180:181], v[230:231], v[184:185]
	v_pk_fma_f32 v[178:179], v[178:179], v[228:229], v[182:183]
	v_pk_mul_f32 v[180:181], v[180:181], s[44:45] op_sel_hi:[1,0]
	v_pk_mul_f32 v[178:179], v[178:179], s[44:45] op_sel_hi:[1,0]
	s_waitcnt vmcnt(1)
	v_pk_fma_f32 v[122:123], v[122:123], v[222:223], v[180:181]
	v_pk_fma_f32 v[120:121], v[120:121], v[220:221], v[178:179]
	global_store_dwordx4 v[192:193], v[120:123], off offset:64
	s_nop 0
	s_waitcnt vmcnt(1)
	v_sub_f32_e32 v227, v227, v234
	v_lshlrev_b64 v[120:121], 2, v[238:239]
	v_lshl_add_u64 v[178:179], s[10:11], 0, v[120:121]
	v_lshl_add_u64 v[180:181], s[12:13], 0, v[120:121]
	global_load_dwordx4 v[120:123], v[178:179], off
	global_load_dwordx4 v[182:185], v[180:181], off
	global_load_dwordx4 v[220:223], v[236:237], off offset:512
	v_sub_f32_e32 v226, v226, v234
	v_sub_f32_e32 v225, v225, v234
	v_sub_f32_e32 v224, v224, v234
	v_pk_mul_f32 v[224:225], v[224:225], v[234:235] op_sel:[0,1]
	v_pk_mul_f32 v[226:227], v[226:227], v[234:235] op_sel:[0,1]
	global_load_dwordx4 v[228:231], v[192:193], off offset:576
	s_waitcnt vmcnt(2)
	v_pk_fma_f32 v[122:123], v[122:123], v[226:227], v[184:185]
	v_pk_fma_f32 v[120:121], v[120:121], v[224:225], v[182:183]
	v_pk_mul_f32 v[122:123], v[122:123], s[44:45] op_sel_hi:[1,0]
	v_pk_mul_f32 v[120:121], v[120:121], s[44:45] op_sel_hi:[1,0]
	s_waitcnt vmcnt(1)
	v_pk_fma_f32 v[118:119], v[118:119], v[222:223], v[122:123]
	v_pk_fma_f32 v[116:117], v[116:117], v[220:221], v[120:121]
	global_store_dwordx4 v[192:193], v[116:119], off offset:512
	s_nop 0
	s_waitcnt vmcnt(1)
	v_mov_b32_e32 v224, v234
	v_mov_b32_e32 v225, v235
	v_sub_f32_e32 v227, v231, v224
	v_lshlrev_b64 v[116:117], 2, v[232:233]
	v_lshl_add_u64 v[182:183], s[10:11], 0, v[116:117]
	v_lshl_add_u64 v[184:185], s[12:13], 0, v[116:117]
	global_load_dwordx4 v[116:119], v[182:183], off
	global_load_dwordx4 v[120:123], v[184:185], off
	global_load_dwordx4 v[220:223], v[236:237], off offset:576
	v_sub_f32_e32 v226, v230, v224
	v_sub_f32_e32 v229, v229, v224
	v_sub_f32_e32 v228, v228, v224
	v_pk_mul_f32 v[228:229], v[228:229], v[224:225] op_sel:[0,1]
	v_pk_mul_f32 v[224:225], v[226:227], v[224:225] op_sel:[0,1]
	v_lshl_add_u64 v[236:237], v[240:241], 3, s[62:63]
	s_waitcnt vmcnt(1)
	v_pk_fma_f32 v[118:119], v[118:119], v[224:225], v[122:123]
	v_pk_fma_f32 v[116:117], v[116:117], v[228:229], v[120:121]
	v_pk_mul_f32 v[118:119], v[118:119], s[44:45] op_sel_hi:[1,0]
	v_pk_mul_f32 v[116:117], v[116:117], s[44:45] op_sel_hi:[1,0]
	s_waitcnt vmcnt(0)
	v_pk_fma_f32 v[114:115], v[114:115], v[222:223], v[118:119]
	v_pk_fma_f32 v[112:113], v[112:113], v[220:221], v[116:117]
	global_store_dwordx4 v[192:193], v[112:115], off offset:576
	global_load_dwordx2 v[238:239], v[236:237], off
	global_load_dwordx4 v[220:223], v[174:175], off
	global_load_dwordx4 v[224:227], v[176:177], off
	v_cndmask_b32_e64 v112, v187, 4, vcc
	v_mul_hi_i32_i24_e32 v113, 0x6000, v112
	v_mul_i32_i24_e32 v112, 0x6000, v112
	v_lshl_add_u64 v[112:113], s[0:1], 0, v[112:113]
	v_lshl_add_u64 v[240:241], v[112:113], 0, v[172:173]
	global_load_dwordx4 v[228:231], v[240:241], off
	v_mul_hi_i32 v112, v242, s76
	v_lshrrev_b32_e32 v113, 31, v112
	v_ashrrev_i32_e32 v112, 11, v112
	v_add_u32_e32 v187, v112, v113
	v_mad_i32_i24 v112, v187, s77, v242
	v_lshl_add_u32 v113, v187, 13, v215
	v_lshlrev_b32_e32 v114, 8, v187
	v_cmp_gt_i32_e32 vcc, s52, v112
	s_waitcnt vmcnt(3)
	v_sub_f32_e32 v143, v143, v238
	v_cndmask_b32_e32 v113, v113, v114, vcc
	v_add_u32_e32 v112, v113, v112
	v_sub_f32_e32 v142, v142, v238
	v_sub_f32_e32 v141, v141, v238
	v_sub_f32_e32 v140, v140, v238
	v_ashrrev_i32_e32 v113, 31, v112
	v_pk_mul_f32 v[140:141], v[140:141], v[238:239] op_sel:[0,1]
	v_pk_mul_f32 v[142:143], v[142:143], v[238:239] op_sel:[0,1]
	v_cndmask_b32_e32 v115, v216, v217, vcc
	v_cndmask_b32_e32 v114, v218, v219, vcc
	v_lshlrev_b64 v[112:113], 12, v[112:113]
	s_waitcnt vmcnt(1)
	v_pk_fma_f32 v[142:143], v[222:223], v[142:143], v[226:227]
	v_pk_fma_f32 v[140:141], v[220:221], v[140:141], v[224:225]
	v_lshl_add_u64 v[112:113], v[114:115], 0, v[112:113]
	v_pk_mul_f32 v[140:141], v[140:141], s[44:45] op_sel_hi:[1,0]
	v_pk_mul_f32 v[142:143], v[142:143], s[44:45] op_sel_hi:[1,0]
	v_lshl_add_u64 v[192:193], v[112:113], 0, v[172:173]
	s_waitcnt vmcnt(0)
	v_pk_fma_f32 v[110:111], v[110:111], v[230:231], v[142:143]
	v_pk_fma_f32 v[108:109], v[108:109], v[228:229], v[140:141]
	global_load_dwordx4 v[232:235], v[192:193], off
	global_load_dwordx4 v[120:123], v[192:193], off offset:64
	global_load_dwordx4 v[116:119], v[192:193], off offset:512
	global_load_dwordx4 v[112:115], v[192:193], off offset:576
	s_nop 0
	global_store_dwordx4 v[190:191], v[108:111], off
	s_nop 0
	s_nop 0
	global_load_dwordx4 v[108:111], v[124:125], off
	global_load_dwordx4 v[140:143], v[126:127], off
	global_load_dwordx4 v[220:223], v[240:241], off offset:64
	s_waitcnt vmcnt(3)
	v_mov_b32_e32 v224, v238
	v_mov_b32_e32 v225, v239
	v_sub_f32_e32 v139, v139, v224
	v_sub_f32_e32 v138, v138, v224
	v_sub_f32_e32 v137, v137, v224
	v_sub_f32_e32 v136, v136, v224
	v_pk_mul_f32 v[136:137], v[136:137], v[224:225] op_sel:[0,1]
	v_pk_mul_f32 v[138:139], v[138:139], v[224:225] op_sel:[0,1]
	s_waitcnt vmcnt(1)
	v_pk_fma_f32 v[108:109], v[108:109], v[136:137], v[140:141]
	v_pk_fma_f32 v[110:111], v[110:111], v[138:139], v[142:143]
	v_pk_mul_f32 v[108:109], v[108:109], s[44:45] op_sel_hi:[1,0]
	v_pk_mul_f32 v[110:111], v[110:111], s[44:45] op_sel_hi:[1,0]
	s_waitcnt vmcnt(0)
	v_pk_fma_f32 v[104:105], v[104:105], v[220:221], v[108:109]
	v_pk_fma_f32 v[106:107], v[106:107], v[222:223], v[110:111]
	global_store_dwordx4 v[190:191], v[104:107], off offset:64
	s_nop 0
	s_nop 0
	global_load_dwordx4 v[104:107], v[178:179], off
	global_load_dwordx4 v[108:111], v[180:181], off
	global_load_dwordx4 v[136:139], v[240:241], off offset:512
	v_lshl_add_u64 v[220:221], v[242:243], 3, s[62:63]
	v_or_b32_e32 v222, 48, v186
	v_ashrrev_i32_e32 v223, 31, v222
	s_waitcnt vmcnt(3)
	v_mov_b32_e32 v140, v238
	v_mov_b32_e32 v141, v239
	v_sub_f32_e32 v135, v135, v140
	v_sub_f32_e32 v134, v134, v140
	v_sub_f32_e32 v133, v133, v140
	v_sub_f32_e32 v132, v132, v140
	v_pk_mul_f32 v[132:133], v[132:133], v[140:141] op_sel:[0,1]
	v_pk_mul_f32 v[134:135], v[134:135], v[140:141] op_sel:[0,1]
	s_waitcnt vmcnt(1)
	v_pk_fma_f32 v[104:105], v[104:105], v[132:133], v[108:109]
	v_pk_fma_f32 v[106:107], v[106:107], v[134:135], v[110:111]
	v_pk_mul_f32 v[104:105], v[104:105], s[44:45] op_sel_hi:[1,0]
	v_pk_mul_f32 v[106:107], v[106:107], s[44:45] op_sel_hi:[1,0]
	s_waitcnt vmcnt(0)
	v_pk_fma_f32 v[100:101], v[100:101], v[136:137], v[104:105]
	v_pk_fma_f32 v[102:103], v[102:103], v[138:139], v[106:107]
	global_store_dwordx4 v[190:191], v[100:103], off offset:512
	s_nop 0
	s_nop 0
	global_load_dwordx4 v[100:103], v[182:183], off
	global_load_dwordx4 v[104:107], v[184:185], off
	global_load_dwordx4 v[108:111], v[240:241], off offset:576
	s_waitcnt vmcnt(3)
	v_mov_b32_e32 v132, v238
	v_mov_b32_e32 v133, v239
	v_sub_f32_e32 v131, v131, v132
	v_sub_f32_e32 v130, v130, v132
	v_sub_f32_e32 v129, v129, v132
	v_sub_f32_e32 v128, v128, v132
	v_pk_mul_f32 v[128:129], v[128:129], v[132:133] op_sel:[0,1]
	v_pk_mul_f32 v[130:131], v[130:131], v[132:133] op_sel:[0,1]
	s_waitcnt vmcnt(1)
	v_pk_fma_f32 v[100:101], v[100:101], v[128:129], v[104:105]
	v_pk_fma_f32 v[102:103], v[102:103], v[130:131], v[106:107]
	v_pk_mul_f32 v[100:101], v[100:101], s[44:45] op_sel_hi:[1,0]
	v_pk_mul_f32 v[102:103], v[102:103], s[44:45] op_sel_hi:[1,0]
	s_waitcnt vmcnt(0)
	v_pk_fma_f32 v[96:97], v[96:97], v[108:109], v[100:101]
	v_pk_fma_f32 v[98:99], v[98:99], v[110:111], v[102:103]
	global_store_dwordx4 v[190:191], v[96:99], off offset:576
	global_load_dwordx2 v[110:111], v[220:221], off
	global_load_dwordx4 v[128:131], v[174:175], off
	global_load_dwordx4 v[132:135], v[176:177], off
	v_cndmask_b32_e64 v96, v187, 4, vcc
	v_mul_hi_i32_i24_e32 v97, 0x6000, v96
	v_mul_i32_i24_e32 v96, 0x6000, v96
	v_lshl_add_u64 v[96:97], s[0:1], 0, v[96:97]
	v_lshl_add_u64 v[190:191], v[96:97], 0, v[172:173]
	global_load_dwordx4 v[136:139], v[190:191], off
	v_mul_hi_i32 v96, v222, s76
	v_lshrrev_b32_e32 v97, 31, v96
	v_ashrrev_i32_e32 v96, 11, v96
	v_add_u32_e32 v187, v96, v97
	v_mad_i32_i24 v96, v187, s77, v222
	v_lshl_add_u32 v97, v187, 13, v215
	v_lshlrev_b32_e32 v98, 8, v187
	v_cmp_gt_i32_e32 vcc, s52, v96
	s_waitcnt vmcnt(3)
	v_mov_b32_e32 v228, v110
	v_mov_b32_e32 v229, v111
	v_sub_f32_e32 v225, v235, v110
	v_cndmask_b32_e32 v97, v97, v98, vcc
	v_add_u32_e32 v96, v97, v96
	v_sub_f32_e32 v224, v234, v110
	v_sub_f32_e32 v227, v233, v110
	v_sub_f32_e32 v226, v232, v110
	v_ashrrev_i32_e32 v97, 31, v96
	v_pk_mul_f32 v[226:227], v[226:227], v[110:111] op_sel:[0,1]
	v_pk_mul_f32 v[110:111], v[224:225], v[110:111] op_sel:[0,1]
	v_cndmask_b32_e32 v99, v216, v217, vcc
	v_cndmask_b32_e32 v98, v218, v219, vcc
	v_lshlrev_b64 v[96:97], 12, v[96:97]
	s_waitcnt vmcnt(1)
	v_pk_fma_f32 v[110:111], v[130:131], v[110:111], v[134:135]
	v_pk_fma_f32 v[128:129], v[128:129], v[226:227], v[132:133]
	v_lshl_add_u64 v[96:97], v[98:99], 0, v[96:97]
	v_pk_mul_f32 v[128:129], v[128:129], s[44:45] op_sel_hi:[1,0]
	v_pk_mul_f32 v[110:111], v[110:111], s[44:45] op_sel_hi:[1,0]
	v_lshl_add_u64 v[108:109], v[96:97], 0, v[172:173]
	s_waitcnt vmcnt(0)
	v_pk_fma_f32 v[94:95], v[94:95], v[138:139], v[110:111]
	v_pk_fma_f32 v[92:93], v[92:93], v[136:137], v[128:129]
	global_load_dwordx4 v[140:143], v[108:109], off
	global_load_dwordx4 v[104:107], v[108:109], off offset:64
	global_load_dwordx4 v[100:103], v[108:109], off offset:512
	global_load_dwordx4 v[96:99], v[108:109], off offset:576
	s_nop 0
	global_store_dwordx4 v[192:193], v[92:95], off
	s_nop 0
	s_nop 0
	global_load_dwordx4 v[92:95], v[124:125], off
	global_load_dwordx4 v[128:131], v[126:127], off
	global_load_dwordx4 v[132:135], v[190:191], off offset:64
	s_waitcnt vmcnt(3)
	v_mov_b32_e32 v110, v228
	v_mov_b32_e32 v111, v229
	v_sub_f32_e32 v123, v123, v110
	v_sub_f32_e32 v122, v122, v110
	v_sub_f32_e32 v121, v121, v110
	v_sub_f32_e32 v120, v120, v110
	v_pk_mul_f32 v[120:121], v[120:121], v[110:111] op_sel:[0,1]
	v_pk_mul_f32 v[110:111], v[122:123], v[110:111] op_sel:[0,1]
	s_waitcnt vmcnt(1)
	v_pk_fma_f32 v[92:93], v[92:93], v[120:121], v[128:129]
	v_pk_fma_f32 v[94:95], v[94:95], v[110:111], v[130:131]
	v_pk_mul_f32 v[92:93], v[92:93], s[44:45] op_sel_hi:[1,0]
	v_pk_mul_f32 v[94:95], v[94:95], s[44:45] op_sel_hi:[1,0]
	s_waitcnt vmcnt(0)
	v_pk_fma_f32 v[88:89], v[88:89], v[132:133], v[92:93]
	v_pk_fma_f32 v[90:91], v[90:91], v[134:135], v[94:95]
	global_store_dwordx4 v[192:193], v[88:91], off offset:64
	s_nop 0
	s_nop 0
	global_load_dwordx4 v[88:91], v[178:179], off
	global_load_dwordx4 v[92:95], v[180:181], off
	global_load_dwordx4 v[120:123], v[190:191], off offset:512
	s_waitcnt vmcnt(3)
	v_mov_b32_e32 v110, v228
	v_mov_b32_e32 v111, v229
	v_sub_f32_e32 v119, v119, v110
	v_sub_f32_e32 v118, v118, v110
	v_sub_f32_e32 v117, v117, v110
	v_sub_f32_e32 v116, v116, v110
	v_pk_mul_f32 v[116:117], v[116:117], v[110:111] op_sel:[0,1]
	v_pk_mul_f32 v[110:111], v[118:119], v[110:111] op_sel:[0,1]
	s_waitcnt vmcnt(1)
	v_pk_fma_f32 v[88:89], v[88:89], v[116:117], v[92:93]
	v_pk_fma_f32 v[90:91], v[90:91], v[110:111], v[94:95]
	v_pk_mul_f32 v[88:89], v[88:89], s[44:45] op_sel_hi:[1,0]
	v_pk_mul_f32 v[90:91], v[90:91], s[44:45] op_sel_hi:[1,0]
	s_waitcnt vmcnt(0)
	v_pk_fma_f32 v[84:85], v[84:85], v[120:121], v[88:89]
	v_pk_fma_f32 v[86:87], v[86:87], v[122:123], v[90:91]
	global_store_dwordx4 v[192:193], v[84:87], off offset:512
	s_nop 0
	s_nop 0
	global_load_dwordx4 v[84:87], v[182:183], off
	global_load_dwordx4 v[88:91], v[184:185], off
	global_load_dwordx4 v[92:95], v[190:191], off offset:576
	v_lshl_add_u64 v[122:123], v[222:223], 3, s[62:63]
	s_waitcnt vmcnt(3)
	v_mov_b32_e32 v110, v228
	v_mov_b32_e32 v111, v229
	v_sub_f32_e32 v115, v115, v110
	v_sub_f32_e32 v114, v114, v110
	v_sub_f32_e32 v113, v113, v110
	v_sub_f32_e32 v112, v112, v110
	v_pk_mul_f32 v[112:113], v[112:113], v[110:111] op_sel:[0,1]
	v_pk_mul_f32 v[110:111], v[114:115], v[110:111] op_sel:[0,1]
	s_waitcnt vmcnt(1)
	v_pk_fma_f32 v[84:85], v[84:85], v[112:113], v[88:89]
	v_pk_fma_f32 v[86:87], v[86:87], v[110:111], v[90:91]
	v_pk_mul_f32 v[84:85], v[84:85], s[44:45] op_sel_hi:[1,0]
	v_pk_mul_f32 v[86:87], v[86:87], s[44:45] op_sel_hi:[1,0]
	s_waitcnt vmcnt(0)
	v_pk_fma_f32 v[80:81], v[80:81], v[92:93], v[84:85]
	v_pk_fma_f32 v[82:83], v[82:83], v[94:95], v[86:87]
	global_store_dwordx4 v[192:193], v[80:83], off offset:576
	global_load_dwordx2 v[94:95], v[122:123], off
	global_load_dwordx4 v[110:113], v[174:175], off
	global_load_dwordx4 v[114:117], v[176:177], off
	v_cndmask_b32_e64 v80, v187, 4, vcc
	v_mul_hi_i32_i24_e32 v81, 0x6000, v80
	v_mul_i32_i24_e32 v80, 0x6000, v80
	v_lshl_add_u64 v[80:81], s[0:1], 0, v[80:81]
	v_lshl_add_u64 v[132:133], v[80:81], 0, v[172:173]
	global_load_dwordx4 v[118:121], v[132:133], off
	v_add_u32_e32 v80, 0x80, v186
	v_mul_hi_i32 v81, v80, s76
	v_lshrrev_b32_e32 v82, 31, v81
	v_ashrrev_i32_e32 v81, 11, v81
	v_add_u32_e32 v138, v81, v82
	v_mad_i32_i24 v80, v138, s77, v80
	v_lshl_add_u32 v81, v138, 13, v215
	v_lshlrev_b32_e32 v82, 8, v138
	v_cmp_gt_i32_e32 vcc, s52, v80
	s_waitcnt vmcnt(3)
	v_mov_b32_e32 v190, v94
	v_mov_b32_e32 v191, v95
	v_sub_f32_e32 v135, v143, v94
	v_cndmask_b32_e32 v81, v81, v82, vcc
	v_add_u32_e32 v80, v81, v80
	v_sub_f32_e32 v134, v142, v94
	v_sub_f32_e32 v137, v141, v94
	v_sub_f32_e32 v136, v140, v94
	v_ashrrev_i32_e32 v81, 31, v80
	v_pk_mul_f32 v[136:137], v[136:137], v[94:95] op_sel:[0,1]
	v_pk_mul_f32 v[94:95], v[134:135], v[94:95] op_sel:[0,1]
	v_cndmask_b32_e32 v83, v216, v217, vcc
	v_cndmask_b32_e32 v82, v218, v219, vcc
	v_lshlrev_b64 v[80:81], 12, v[80:81]
	s_waitcnt vmcnt(1)
	v_pk_fma_f32 v[94:95], v[112:113], v[94:95], v[116:117]
	v_pk_fma_f32 v[110:111], v[110:111], v[136:137], v[114:115]
	v_lshl_add_u64 v[80:81], v[82:83], 0, v[80:81]
	v_pk_mul_f32 v[110:111], v[110:111], s[44:45] op_sel_hi:[1,0]
	v_pk_mul_f32 v[94:95], v[94:95], s[44:45] op_sel_hi:[1,0]
	v_lshl_add_u64 v[92:93], v[80:81], 0, v[172:173]
	s_waitcnt vmcnt(0)
	v_pk_fma_f32 v[78:79], v[78:79], v[120:121], v[94:95]
	v_pk_fma_f32 v[76:77], v[76:77], v[118:119], v[110:111]
	global_load_dwordx4 v[128:131], v[92:93], off
	global_load_dwordx4 v[88:91], v[92:93], off offset:64
	global_load_dwordx4 v[84:87], v[92:93], off offset:512
	global_load_dwordx4 v[80:83], v[92:93], off offset:576
	s_nop 0
	global_store_dwordx4 v[108:109], v[76:79], off
	s_nop 0
	s_nop 0
	global_load_dwordx4 v[76:79], v[124:125], off
	global_load_dwordx4 v[110:113], v[126:127], off
	global_load_dwordx4 v[114:117], v[132:133], off offset:64
	s_waitcnt vmcnt(3)
	v_mov_b32_e32 v94, v190
	v_mov_b32_e32 v95, v191
	v_sub_f32_e32 v107, v107, v94
	v_sub_f32_e32 v106, v106, v94
	v_sub_f32_e32 v105, v105, v94
	v_sub_f32_e32 v104, v104, v94
	v_pk_mul_f32 v[104:105], v[104:105], v[94:95] op_sel:[0,1]
	v_pk_mul_f32 v[94:95], v[106:107], v[94:95] op_sel:[0,1]
	s_waitcnt vmcnt(1)
	v_pk_fma_f32 v[76:77], v[76:77], v[104:105], v[110:111]
	v_pk_fma_f32 v[78:79], v[78:79], v[94:95], v[112:113]
	v_pk_mul_f32 v[76:77], v[76:77], s[44:45] op_sel_hi:[1,0]
	v_pk_mul_f32 v[78:79], v[78:79], s[44:45] op_sel_hi:[1,0]
	s_waitcnt vmcnt(0)
	v_pk_fma_f32 v[72:73], v[72:73], v[114:115], v[76:77]
	v_pk_fma_f32 v[74:75], v[74:75], v[116:117], v[78:79]
	global_store_dwordx4 v[108:109], v[72:75], off offset:64
	s_nop 0
	s_nop 0
	global_load_dwordx4 v[72:75], v[178:179], off
	global_load_dwordx4 v[76:79], v[180:181], off
	global_load_dwordx4 v[104:107], v[132:133], off offset:512
	v_add_u32_e32 v112, 0x90, v186
	v_ashrrev_i32_e32 v113, 31, v112
	s_waitcnt vmcnt(3)
	v_mov_b32_e32 v94, v190
	v_mov_b32_e32 v95, v191
	v_sub_f32_e32 v103, v103, v94
	v_sub_f32_e32 v102, v102, v94
	v_sub_f32_e32 v101, v101, v94
	v_sub_f32_e32 v100, v100, v94
	v_pk_mul_f32 v[100:101], v[100:101], v[94:95] op_sel:[0,1]
	v_pk_mul_f32 v[94:95], v[102:103], v[94:95] op_sel:[0,1]
	s_waitcnt vmcnt(1)
	v_pk_fma_f32 v[72:73], v[72:73], v[100:101], v[76:77]
	v_pk_fma_f32 v[74:75], v[74:75], v[94:95], v[78:79]
	v_pk_mul_f32 v[72:73], v[72:73], s[44:45] op_sel_hi:[1,0]
	v_pk_mul_f32 v[74:75], v[74:75], s[44:45] op_sel_hi:[1,0]
	s_waitcnt vmcnt(0)
	v_pk_fma_f32 v[68:69], v[68:69], v[104:105], v[72:73]
	v_pk_fma_f32 v[70:71], v[70:71], v[106:107], v[74:75]
	global_store_dwordx4 v[108:109], v[68:71], off offset:512
	s_nop 0
	s_nop 0
	global_load_dwordx4 v[68:71], v[182:183], off
	global_load_dwordx4 v[72:75], v[184:185], off
	global_load_dwordx4 v[76:79], v[132:133], off offset:576
	s_waitcnt vmcnt(3)
	v_mov_b32_e32 v94, v190
	v_mov_b32_e32 v95, v191
	v_sub_f32_e32 v99, v99, v94
	v_sub_f32_e32 v98, v98, v94
	v_sub_f32_e32 v97, v97, v94
	v_sub_f32_e32 v96, v96, v94
	v_pk_mul_f32 v[96:97], v[96:97], v[94:95] op_sel:[0,1]
	v_pk_mul_f32 v[94:95], v[98:99], v[94:95] op_sel:[0,1]
	s_waitcnt vmcnt(1)
	v_pk_fma_f32 v[68:69], v[68:69], v[96:97], v[72:73]
	v_pk_fma_f32 v[70:71], v[70:71], v[94:95], v[74:75]
	v_pk_mul_f32 v[68:69], v[68:69], s[44:45] op_sel_hi:[1,0]
	v_pk_mul_f32 v[70:71], v[70:71], s[44:45] op_sel_hi:[1,0]
	s_waitcnt vmcnt(0)
	v_pk_fma_f32 v[64:65], v[64:65], v[76:77], v[68:69]
	v_pk_fma_f32 v[66:67], v[66:67], v[78:79], v[70:71]
	global_store_dwordx4 v[108:109], v[64:67], off offset:576
	global_load_dwordx2 v[78:79], v[188:189], off offset:1024
	global_load_dwordx4 v[94:97], v[174:175], off
	global_load_dwordx4 v[98:101], v[176:177], off
	v_cndmask_b32_e64 v64, v138, 4, vcc
	v_mul_hi_i32_i24_e32 v65, 0x6000, v64
	v_mul_i32_i24_e32 v64, 0x6000, v64
	v_lshl_add_u64 v[64:65], s[0:1], 0, v[64:65]
	v_lshl_add_u64 v[110:111], v[64:65], 0, v[172:173]
	global_load_dwordx4 v[102:105], v[110:111], off
	v_mul_hi_i32 v64, v112, s76
	v_lshrrev_b32_e32 v65, 31, v64
	v_ashrrev_i32_e32 v64, 11, v64
	v_add_u32_e32 v118, v64, v65
	v_mad_i32_i24 v64, v118, s77, v112
	v_lshl_add_u32 v65, v118, 13, v215
	v_lshlrev_b32_e32 v66, 8, v118
	v_cmp_gt_i32_e32 vcc, s52, v64
	s_waitcnt vmcnt(3)
	v_sub_f32_e32 v115, v131, v78
	v_cndmask_b32_e32 v65, v65, v66, vcc
	v_add_u32_e32 v64, v65, v64
	v_sub_f32_e32 v114, v130, v78
	v_sub_f32_e32 v117, v129, v78
	v_sub_f32_e32 v116, v128, v78
	v_ashrrev_i32_e32 v65, 31, v64
	v_pk_mul_f32 v[116:117], v[116:117], v[78:79] op_sel:[0,1]
	v_pk_mul_f32 v[78:79], v[114:115], v[78:79] op_sel:[0,1]
	v_cndmask_b32_e32 v67, v216, v217, vcc
	v_cndmask_b32_e32 v66, v218, v219, vcc
	v_lshlrev_b64 v[64:65], 12, v[64:65]
	s_waitcnt vmcnt(1)
	v_pk_fma_f32 v[78:79], v[96:97], v[78:79], v[100:101]
	v_pk_fma_f32 v[94:95], v[94:95], v[116:117], v[98:99]
	v_lshl_add_u64 v[64:65], v[66:67], 0, v[64:65]
	v_pk_mul_f32 v[94:95], v[94:95], s[44:45] op_sel_hi:[1,0]
	v_pk_mul_f32 v[78:79], v[78:79], s[44:45] op_sel_hi:[1,0]
	v_lshl_add_u64 v[76:77], v[64:65], 0, v[172:173]
	s_waitcnt vmcnt(0)
	v_pk_fma_f32 v[62:63], v[62:63], v[104:105], v[78:79]
	v_pk_fma_f32 v[60:61], v[60:61], v[102:103], v[94:95]
	global_load_dwordx4 v[106:109], v[76:77], off
	global_load_dwordx4 v[72:75], v[76:77], off offset:64
	global_load_dwordx4 v[68:71], v[76:77], off offset:512
	global_load_dwordx4 v[64:67], v[76:77], off offset:576
	s_nop 0
	global_store_dwordx4 v[92:93], v[60:63], off
	global_load_dwordx2 v[78:79], v[188:189], off offset:1024
	s_nop 0
	global_load_dwordx4 v[60:63], v[124:125], off
	global_load_dwordx4 v[94:97], v[126:127], off
	global_load_dwordx4 v[98:101], v[110:111], off offset:64
	s_waitcnt vmcnt(3)
	v_sub_f32_e32 v91, v91, v78
	v_sub_f32_e32 v90, v90, v78
	v_sub_f32_e32 v89, v89, v78
	v_sub_f32_e32 v88, v88, v78
	v_pk_mul_f32 v[88:89], v[88:89], v[78:79] op_sel:[0,1]
	v_pk_mul_f32 v[78:79], v[90:91], v[78:79] op_sel:[0,1]
	s_waitcnt vmcnt(1)
	v_pk_fma_f32 v[60:61], v[60:61], v[88:89], v[94:95]
	v_pk_fma_f32 v[62:63], v[62:63], v[78:79], v[96:97]
	v_pk_mul_f32 v[60:61], v[60:61], s[44:45] op_sel_hi:[1,0]
	v_pk_mul_f32 v[62:63], v[62:63], s[44:45] op_sel_hi:[1,0]
	s_waitcnt vmcnt(0)
	v_pk_fma_f32 v[56:57], v[56:57], v[98:99], v[60:61]
	v_pk_fma_f32 v[58:59], v[58:59], v[100:101], v[62:63]
	global_store_dwordx4 v[92:93], v[56:59], off offset:64
	global_load_dwordx2 v[78:79], v[188:189], off offset:1024
	s_nop 0
	global_load_dwordx4 v[56:59], v[178:179], off
	global_load_dwordx4 v[60:63], v[180:181], off
	global_load_dwordx4 v[88:91], v[110:111], off offset:512
	v_lshl_add_u64 v[94:95], v[112:113], 3, s[62:63]
	v_add_u32_e32 v98, 0xa0, v186
	v_ashrrev_i32_e32 v99, 31, v98
	s_waitcnt vmcnt(3)
	v_sub_f32_e32 v87, v87, v78
	v_sub_f32_e32 v86, v86, v78
	v_sub_f32_e32 v85, v85, v78
	v_sub_f32_e32 v84, v84, v78
	v_pk_mul_f32 v[84:85], v[84:85], v[78:79] op_sel:[0,1]
	v_pk_mul_f32 v[78:79], v[86:87], v[78:79] op_sel:[0,1]
	s_waitcnt vmcnt(1)
	v_pk_fma_f32 v[56:57], v[56:57], v[84:85], v[60:61]
	v_pk_fma_f32 v[58:59], v[58:59], v[78:79], v[62:63]
	v_pk_mul_f32 v[56:57], v[56:57], s[44:45] op_sel_hi:[1,0]
	v_pk_mul_f32 v[58:59], v[58:59], s[44:45] op_sel_hi:[1,0]
	s_waitcnt vmcnt(0)
	v_pk_fma_f32 v[52:53], v[52:53], v[88:89], v[56:57]
	v_pk_fma_f32 v[54:55], v[54:55], v[90:91], v[58:59]
	global_store_dwordx4 v[92:93], v[52:55], off offset:512
	global_load_dwordx2 v[78:79], v[188:189], off offset:1024
	s_nop 0
	global_load_dwordx4 v[52:55], v[182:183], off
	global_load_dwordx4 v[56:59], v[184:185], off
	global_load_dwordx4 v[60:63], v[110:111], off offset:576
	s_waitcnt vmcnt(3)
	v_sub_f32_e32 v83, v83, v78
	v_sub_f32_e32 v82, v82, v78
	v_sub_f32_e32 v81, v81, v78
	v_sub_f32_e32 v80, v80, v78
	v_pk_mul_f32 v[80:81], v[80:81], v[78:79] op_sel:[0,1]
	v_pk_mul_f32 v[78:79], v[82:83], v[78:79] op_sel:[0,1]
	s_waitcnt vmcnt(1)
	v_pk_fma_f32 v[52:53], v[52:53], v[80:81], v[56:57]
	v_pk_fma_f32 v[54:55], v[54:55], v[78:79], v[58:59]
	v_pk_mul_f32 v[52:53], v[52:53], s[44:45] op_sel_hi:[1,0]
	v_pk_mul_f32 v[54:55], v[54:55], s[44:45] op_sel_hi:[1,0]
	s_waitcnt vmcnt(0)
	v_pk_fma_f32 v[48:49], v[48:49], v[60:61], v[52:53]
	v_pk_fma_f32 v[50:51], v[50:51], v[62:63], v[54:55]
	global_store_dwordx4 v[92:93], v[48:51], off offset:576
	global_load_dwordx2 v[62:63], v[94:95], off
	global_load_dwordx4 v[78:81], v[174:175], off
	global_load_dwordx4 v[82:85], v[176:177], off
	v_cndmask_b32_e64 v48, v118, 4, vcc
	v_mul_hi_i32_i24_e32 v49, 0x6000, v48
	v_mul_i32_i24_e32 v48, 0x6000, v48
	v_lshl_add_u64 v[48:49], s[0:1], 0, v[48:49]
	v_lshl_add_u64 v[96:97], v[48:49], 0, v[172:173]
	global_load_dwordx4 v[86:89], v[96:97], off
	v_mul_hi_i32 v48, v98, s76
	v_lshrrev_b32_e32 v49, 31, v48
	v_ashrrev_i32_e32 v48, 11, v48
	v_add_u32_e32 v104, v48, v49
	v_mad_i32_i24 v48, v104, s77, v98
	v_lshl_add_u32 v49, v104, 13, v215
	v_lshlrev_b32_e32 v50, 8, v104
	v_cmp_gt_i32_e32 vcc, s52, v48
	s_waitcnt vmcnt(3)
	v_mov_b32_e32 v128, v62
	v_mov_b32_e32 v129, v63
	v_sub_f32_e32 v101, v109, v62
	v_cndmask_b32_e32 v49, v49, v50, vcc
	v_add_u32_e32 v48, v49, v48
	v_sub_f32_e32 v100, v108, v62
	v_sub_f32_e32 v103, v107, v62
	v_sub_f32_e32 v102, v106, v62
	v_ashrrev_i32_e32 v49, 31, v48
	v_pk_mul_f32 v[102:103], v[102:103], v[62:63] op_sel:[0,1]
	v_pk_mul_f32 v[62:63], v[100:101], v[62:63] op_sel:[0,1]
	v_cndmask_b32_e32 v51, v216, v217, vcc
	v_cndmask_b32_e32 v50, v218, v219, vcc
	v_lshlrev_b64 v[48:49], 12, v[48:49]
	s_waitcnt vmcnt(1)
	v_pk_fma_f32 v[62:63], v[80:81], v[62:63], v[84:85]
	v_pk_fma_f32 v[78:79], v[78:79], v[102:103], v[82:83]
	v_lshl_add_u64 v[48:49], v[50:51], 0, v[48:49]
	v_pk_mul_f32 v[78:79], v[78:79], s[44:45] op_sel_hi:[1,0]
	v_pk_mul_f32 v[62:63], v[62:63], s[44:45] op_sel_hi:[1,0]
	v_lshl_add_u64 v[60:61], v[48:49], 0, v[172:173]
	s_waitcnt vmcnt(0)
	v_pk_fma_f32 v[46:47], v[46:47], v[88:89], v[62:63]
	v_pk_fma_f32 v[44:45], v[44:45], v[86:87], v[78:79]
	global_load_dwordx4 v[90:93], v[60:61], off
	global_load_dwordx4 v[56:59], v[60:61], off offset:64
	global_load_dwordx4 v[52:55], v[60:61], off offset:512
	global_load_dwordx4 v[48:51], v[60:61], off offset:576
	s_nop 0
	global_store_dwordx4 v[76:77], v[44:47], off
	s_nop 0
	s_nop 0
	global_load_dwordx4 v[44:47], v[124:125], off
	global_load_dwordx4 v[78:81], v[126:127], off
	global_load_dwordx4 v[82:85], v[96:97], off offset:64
	s_waitcnt vmcnt(3)
	v_mov_b32_e32 v62, v128
	v_mov_b32_e32 v63, v129
	v_sub_f32_e32 v75, v75, v62
	v_sub_f32_e32 v74, v74, v62
	v_sub_f32_e32 v73, v73, v62
	v_sub_f32_e32 v72, v72, v62
	v_pk_mul_f32 v[72:73], v[72:73], v[62:63] op_sel:[0,1]
	v_pk_mul_f32 v[62:63], v[74:75], v[62:63] op_sel:[0,1]
	s_waitcnt vmcnt(1)
	v_pk_fma_f32 v[44:45], v[44:45], v[72:73], v[78:79]
	v_pk_fma_f32 v[46:47], v[46:47], v[62:63], v[80:81]
	v_pk_mul_f32 v[44:45], v[44:45], s[44:45] op_sel_hi:[1,0]
	v_pk_mul_f32 v[46:47], v[46:47], s[44:45] op_sel_hi:[1,0]
	s_waitcnt vmcnt(0)
	v_pk_fma_f32 v[40:41], v[40:41], v[82:83], v[44:45]
	v_pk_fma_f32 v[42:43], v[42:43], v[84:85], v[46:47]
	global_store_dwordx4 v[76:77], v[40:43], off offset:64
	s_nop 0
	s_nop 0
	global_load_dwordx4 v[40:43], v[178:179], off
	global_load_dwordx4 v[44:47], v[180:181], off
	global_load_dwordx4 v[72:75], v[96:97], off offset:512
	v_lshl_add_u64 v[78:79], v[98:99], 3, s[62:63]
	v_add_u32_e32 v82, 0xb0, v186
	v_ashrrev_i32_e32 v83, 31, v82
	s_waitcnt vmcnt(3)
	v_mov_b32_e32 v62, v128
	v_mov_b32_e32 v63, v129
	v_sub_f32_e32 v71, v71, v62
	v_sub_f32_e32 v70, v70, v62
	v_sub_f32_e32 v69, v69, v62
	v_sub_f32_e32 v68, v68, v62
	v_pk_mul_f32 v[68:69], v[68:69], v[62:63] op_sel:[0,1]
	v_pk_mul_f32 v[62:63], v[70:71], v[62:63] op_sel:[0,1]
	s_waitcnt vmcnt(1)
	v_pk_fma_f32 v[40:41], v[40:41], v[68:69], v[44:45]
	v_pk_fma_f32 v[42:43], v[42:43], v[62:63], v[46:47]
	v_pk_mul_f32 v[40:41], v[40:41], s[44:45] op_sel_hi:[1,0]
	v_pk_mul_f32 v[42:43], v[42:43], s[44:45] op_sel_hi:[1,0]
	s_waitcnt vmcnt(0)
	v_pk_fma_f32 v[36:37], v[36:37], v[72:73], v[40:41]
	v_pk_fma_f32 v[38:39], v[38:39], v[74:75], v[42:43]
	global_store_dwordx4 v[76:77], v[36:39], off offset:512
	s_nop 0
	s_nop 0
	global_load_dwordx4 v[36:39], v[182:183], off
	global_load_dwordx4 v[40:43], v[184:185], off
	global_load_dwordx4 v[44:47], v[96:97], off offset:576
	s_waitcnt vmcnt(3)
	v_mov_b32_e32 v62, v128
	v_mov_b32_e32 v63, v129
	v_sub_f32_e32 v67, v67, v62
	v_sub_f32_e32 v66, v66, v62
	v_sub_f32_e32 v65, v65, v62
	v_sub_f32_e32 v64, v64, v62
	v_pk_mul_f32 v[64:65], v[64:65], v[62:63] op_sel:[0,1]
	v_pk_mul_f32 v[62:63], v[66:67], v[62:63] op_sel:[0,1]
	s_waitcnt vmcnt(1)
	v_pk_fma_f32 v[36:37], v[36:37], v[64:65], v[40:41]
	v_pk_fma_f32 v[38:39], v[38:39], v[62:63], v[42:43]
	v_pk_mul_f32 v[36:37], v[36:37], s[44:45] op_sel_hi:[1,0]
	v_pk_mul_f32 v[38:39], v[38:39], s[44:45] op_sel_hi:[1,0]
	s_waitcnt vmcnt(0)
	v_pk_fma_f32 v[32:33], v[32:33], v[44:45], v[36:37]
	v_pk_fma_f32 v[34:35], v[34:35], v[46:47], v[38:39]
	global_store_dwordx4 v[76:77], v[32:35], off offset:576
	global_load_dwordx2 v[46:47], v[78:79], off
	global_load_dwordx4 v[42:45], v[174:175], off
	global_load_dwordx4 v[62:65], v[176:177], off
	v_cndmask_b32_e64 v32, v104, 4, vcc
	v_mul_hi_i32_i24_e32 v33, 0x6000, v32
	v_mul_i32_i24_e32 v32, 0x6000, v32
	v_lshl_add_u64 v[32:33], s[0:1], 0, v[32:33]
	v_lshl_add_u64 v[80:81], v[32:33], 0, v[172:173]
	global_load_dwordx4 v[66:69], v[80:81], off
	v_mul_hi_i32 v32, v82, s76
	v_lshrrev_b32_e32 v33, 31, v32
	v_ashrrev_i32_e32 v32, 11, v32
	v_add_u32_e32 v88, v32, v33
	v_mad_i32_i24 v32, v88, s77, v82
	v_lshl_add_u32 v33, v88, 13, v215
	v_lshlrev_b32_e32 v34, 8, v88
	v_cmp_gt_i32_e32 vcc, s52, v32
	s_waitcnt vmcnt(3)
	v_mov_b32_e32 v128, v46
	v_mov_b32_e32 v129, v47
	v_sub_f32_e32 v85, v93, v46
	v_cndmask_b32_e32 v33, v33, v34, vcc
	v_add_u32_e32 v32, v33, v32
	v_sub_f32_e32 v84, v92, v46
	v_sub_f32_e32 v87, v91, v46
	v_sub_f32_e32 v86, v90, v46
	v_ashrrev_i32_e32 v33, 31, v32
	v_pk_mul_f32 v[86:87], v[86:87], v[46:47] op_sel:[0,1]
	v_pk_mul_f32 v[46:47], v[84:85], v[46:47] op_sel:[0,1]
	v_cndmask_b32_e32 v35, v216, v217, vcc
	v_cndmask_b32_e32 v34, v218, v219, vcc
	v_lshlrev_b64 v[32:33], 12, v[32:33]
	s_waitcnt vmcnt(1)
	v_pk_fma_f32 v[44:45], v[44:45], v[46:47], v[64:65]
	v_pk_fma_f32 v[42:43], v[42:43], v[86:87], v[62:63]
	v_lshl_add_u64 v[32:33], v[34:35], 0, v[32:33]
	v_pk_mul_f32 v[42:43], v[42:43], s[44:45] op_sel_hi:[1,0]
	v_pk_mul_f32 v[44:45], v[44:45], s[44:45] op_sel_hi:[1,0]
	v_lshl_add_u64 v[40:41], v[32:33], 0, v[172:173]
	s_waitcnt vmcnt(0)
	v_pk_fma_f32 v[30:31], v[30:31], v[68:69], v[44:45]
	v_pk_fma_f32 v[28:29], v[28:29], v[66:67], v[42:43]
	global_load_dwordx4 v[70:73], v[40:41], off
	global_load_dwordx4 v[74:77], v[40:41], off offset:64
	global_load_dwordx4 v[36:39], v[40:41], off offset:512
	global_load_dwordx4 v[32:35], v[40:41], off offset:576
	s_nop 0
	global_store_dwordx4 v[60:61], v[28:31], off
	s_nop 0
	s_nop 0
	global_load_dwordx4 v[28:31], v[124:125], off
	global_load_dwordx4 v[42:45], v[126:127], off
	global_load_dwordx4 v[62:65], v[80:81], off offset:64
	s_waitcnt vmcnt(3)
	v_mov_b32_e32 v46, v128
	v_mov_b32_e32 v47, v129
	v_sub_f32_e32 v59, v59, v46
	v_sub_f32_e32 v58, v58, v46
	v_sub_f32_e32 v57, v57, v46
	v_sub_f32_e32 v56, v56, v46
	v_pk_mul_f32 v[56:57], v[56:57], v[46:47] op_sel:[0,1]
	v_pk_mul_f32 v[46:47], v[58:59], v[46:47] op_sel:[0,1]
	s_waitcnt vmcnt(1)
	v_pk_fma_f32 v[28:29], v[28:29], v[56:57], v[42:43]
	v_pk_fma_f32 v[30:31], v[30:31], v[46:47], v[44:45]
	v_pk_mul_f32 v[28:29], v[28:29], s[44:45] op_sel_hi:[1,0]
	v_pk_mul_f32 v[30:31], v[30:31], s[44:45] op_sel_hi:[1,0]
	s_waitcnt vmcnt(0)
	v_pk_fma_f32 v[24:25], v[24:25], v[62:63], v[28:29]
	v_pk_fma_f32 v[26:27], v[26:27], v[64:65], v[30:31]
	global_store_dwordx4 v[60:61], v[24:27], off offset:64
	s_nop 0
	s_nop 0
	global_load_dwordx4 v[24:27], v[178:179], off
	global_load_dwordx4 v[28:31], v[180:181], off
	global_load_dwordx4 v[42:45], v[80:81], off offset:512
	s_waitcnt vmcnt(3)
	v_mov_b32_e32 v46, v128
	v_mov_b32_e32 v47, v129
	v_sub_f32_e32 v55, v55, v46
	v_sub_f32_e32 v54, v54, v46
	v_sub_f32_e32 v53, v53, v46
	v_sub_f32_e32 v52, v52, v46
	v_pk_mul_f32 v[52:53], v[52:53], v[46:47] op_sel:[0,1]
	v_pk_mul_f32 v[46:47], v[54:55], v[46:47] op_sel:[0,1]
	s_waitcnt vmcnt(1)
	v_pk_fma_f32 v[24:25], v[24:25], v[52:53], v[28:29]
	v_pk_fma_f32 v[26:27], v[26:27], v[46:47], v[30:31]
	v_pk_mul_f32 v[24:25], v[24:25], s[44:45] op_sel_hi:[1,0]
	v_pk_mul_f32 v[26:27], v[26:27], s[44:45] op_sel_hi:[1,0]
	s_waitcnt vmcnt(0)
	v_pk_fma_f32 v[20:21], v[20:21], v[42:43], v[24:25]
	v_pk_fma_f32 v[22:23], v[22:23], v[44:45], v[26:27]
	global_store_dwordx4 v[60:61], v[20:23], off offset:512
	s_nop 0
	s_nop 0
	global_load_dwordx4 v[20:23], v[182:183], off
	global_load_dwordx4 v[24:27], v[184:185], off
	global_load_dwordx4 v[28:31], v[80:81], off offset:576
	v_lshl_add_u64 v[44:45], v[82:83], 3, s[62:63]
	s_waitcnt vmcnt(3)
	v_mov_b32_e32 v42, v128
	v_mov_b32_e32 v43, v129
	v_sub_f32_e32 v47, v51, v42
	v_sub_f32_e32 v46, v50, v42
	v_sub_f32_e32 v49, v49, v42
	v_sub_f32_e32 v48, v48, v42
	v_pk_mul_f32 v[48:49], v[48:49], v[42:43] op_sel:[0,1]
	v_pk_mul_f32 v[42:43], v[46:47], v[42:43] op_sel:[0,1]
	s_waitcnt vmcnt(1)
	v_pk_fma_f32 v[20:21], v[20:21], v[48:49], v[24:25]
	v_pk_fma_f32 v[22:23], v[22:23], v[42:43], v[26:27]
	v_pk_mul_f32 v[20:21], v[20:21], s[44:45] op_sel_hi:[1,0]
	v_pk_mul_f32 v[22:23], v[22:23], s[44:45] op_sel_hi:[1,0]
	s_waitcnt vmcnt(0)
	v_pk_fma_f32 v[16:17], v[16:17], v[28:29], v[20:21]
	v_pk_fma_f32 v[18:19], v[18:19], v[30:31], v[22:23]
	global_store_dwordx4 v[60:61], v[16:19], off offset:576
	global_load_dwordx2 v[28:29], v[44:45], off
	v_cndmask_b32_e64 v24, v88, 4, vcc
	v_mul_hi_i32_i24_e32 v25, 0x6000, v24
	v_mul_i32_i24_e32 v24, 0x6000, v24
	global_load_dwordx4 v[16:19], v[174:175], off
	global_load_dwordx4 v[20:23], v[176:177], off
	v_lshl_add_u64 v[24:25], s[0:1], 0, v[24:25]
	v_lshl_add_u64 v[30:31], v[24:25], 0, v[172:173]
	global_load_dwordx4 v[24:27], v[30:31], off
	s_andn2_b64 vcc, exec, s[8:9]
	s_waitcnt vmcnt(3)
	v_mov_b32_e32 v128, v28
	v_mov_b32_e32 v129, v29
	v_sub_f32_e32 v43, v73, v28
	v_sub_f32_e32 v42, v72, v28
	v_sub_f32_e32 v47, v71, v28
	v_sub_f32_e32 v46, v70, v28
	v_pk_mul_f32 v[46:47], v[46:47], v[28:29] op_sel:[0,1]
	v_pk_mul_f32 v[28:29], v[42:43], v[28:29] op_sel:[0,1]
	s_waitcnt vmcnt(1)
	v_pk_fma_f32 v[16:17], v[16:17], v[46:47], v[20:21]
	v_pk_fma_f32 v[18:19], v[18:19], v[28:29], v[22:23]
	v_pk_mul_f32 v[16:17], v[16:17], s[44:45] op_sel_hi:[1,0]
	v_pk_mul_f32 v[18:19], v[18:19], s[44:45] op_sel_hi:[1,0]
	s_waitcnt vmcnt(0)
	v_pk_fma_f32 v[12:13], v[12:13], v[24:25], v[16:17]
	v_pk_fma_f32 v[14:15], v[14:15], v[26:27], v[18:19]
	global_store_dwordx4 v[40:41], v[12:15], off
	s_nop 0
	s_nop 0
	global_load_dwordx4 v[12:15], v[124:125], off
	global_load_dwordx4 v[16:19], v[126:127], off
	global_load_dwordx4 v[20:23], v[30:31], off offset:64
	s_waitcnt vmcnt(3)
	v_mov_b32_e32 v24, v128
	v_mov_b32_e32 v25, v129
	v_sub_f32_e32 v27, v77, v24
	v_sub_f32_e32 v26, v76, v24
	v_sub_f32_e32 v29, v75, v24
	v_sub_f32_e32 v28, v74, v24
	v_pk_mul_f32 v[28:29], v[28:29], v[24:25] op_sel:[0,1]
	v_pk_mul_f32 v[24:25], v[26:27], v[24:25] op_sel:[0,1]
	s_waitcnt vmcnt(1)
	v_pk_fma_f32 v[12:13], v[12:13], v[28:29], v[16:17]
	v_pk_fma_f32 v[14:15], v[14:15], v[24:25], v[18:19]
	v_pk_mul_f32 v[12:13], v[12:13], s[44:45] op_sel_hi:[1,0]
	v_pk_mul_f32 v[14:15], v[14:15], s[44:45] op_sel_hi:[1,0]
	s_waitcnt vmcnt(0)
	v_pk_fma_f32 v[8:9], v[8:9], v[20:21], v[12:13]
	v_pk_fma_f32 v[10:11], v[10:11], v[22:23], v[14:15]
	global_store_dwordx4 v[40:41], v[8:11], off offset:64
	s_nop 0
	s_nop 0
	global_load_dwordx4 v[8:11], v[178:179], off
	global_load_dwordx4 v[12:15], v[180:181], off
	global_load_dwordx4 v[16:19], v[30:31], off offset:512
	s_waitcnt vmcnt(3)
	v_mov_b32_e32 v20, v128
	v_mov_b32_e32 v21, v129
	v_sub_f32_e32 v23, v39, v20
	v_sub_f32_e32 v22, v38, v20
	v_sub_f32_e32 v25, v37, v20
	v_sub_f32_e32 v24, v36, v20
	v_pk_mul_f32 v[24:25], v[24:25], v[20:21] op_sel:[0,1]
	v_pk_mul_f32 v[20:21], v[22:23], v[20:21] op_sel:[0,1]
	s_waitcnt vmcnt(1)
	v_pk_fma_f32 v[8:9], v[8:9], v[24:25], v[12:13]
	v_pk_fma_f32 v[10:11], v[10:11], v[20:21], v[14:15]
	v_pk_mul_f32 v[8:9], v[8:9], s[44:45] op_sel_hi:[1,0]
	v_pk_mul_f32 v[10:11], v[10:11], s[44:45] op_sel_hi:[1,0]
	s_waitcnt vmcnt(0)
	v_pk_fma_f32 v[4:5], v[4:5], v[16:17], v[8:9]
	v_pk_fma_f32 v[6:7], v[6:7], v[18:19], v[10:11]
	global_store_dwordx4 v[40:41], v[4:7], off offset:512
	s_nop 0
	s_nop 0
	global_load_dwordx4 v[4:7], v[182:183], off
	global_load_dwordx4 v[8:11], v[184:185], off
	global_load_dwordx4 v[12:15], v[30:31], off offset:576
	s_waitcnt vmcnt(3)
	v_mov_b32_e32 v16, v128
	v_mov_b32_e32 v17, v129
	v_sub_f32_e32 v19, v35, v16
	v_sub_f32_e32 v18, v34, v16
	v_sub_f32_e32 v21, v33, v16
	v_sub_f32_e32 v20, v32, v16
	v_pk_mul_f32 v[20:21], v[20:21], v[16:17] op_sel:[0,1]
	v_pk_mul_f32 v[16:17], v[18:19], v[16:17] op_sel:[0,1]
	s_waitcnt vmcnt(1)
	v_pk_fma_f32 v[4:5], v[4:5], v[20:21], v[8:9]
	v_pk_fma_f32 v[6:7], v[6:7], v[16:17], v[10:11]
	v_pk_mul_f32 v[4:5], v[4:5], s[44:45] op_sel_hi:[1,0]
	v_pk_mul_f32 v[6:7], v[6:7], s[44:45] op_sel_hi:[1,0]
	s_waitcnt vmcnt(0)
	v_pk_fma_f32 v[0:1], v[0:1], v[12:13], v[4:5]
	v_pk_fma_f32 v[2:3], v[2:3], v[14:15], v[6:7]
	global_store_dwordx4 v[40:41], v[0:3], off offset:576
	s_cbranch_vccnz .LBB0_1758
	s_andn2_b64 vcc, exec, s[14:15]
	s_cbranch_vccnz .LBB0_1757
	s_barrier
	s_branch .LBB0_1757

.LBB0_1997:
	v_lshl_add_u32 v186, s66, 8, v153
	v_mul_hi_i32 v128, v186, s67
	v_lshrrev_b32_e32 v129, 31, v128
	v_ashrrev_i32_e32 v128, 11, v128
	v_add_u32_e32 v132, v128, v129
	v_mad_i32_i24 v128, v132, s74, v186
	v_lshl_add_u32 v129, v132, 13, v215
	v_lshlrev_b32_e32 v130, 8, v132
	v_cmp_gt_i32_e32 vcc, s52, v128
	v_readlane_b32 s20, v254, 28
	v_readlane_b32 s21, v254, 29
	v_cndmask_b32_e32 v129, v129, v130, vcc
	v_readlane_b32 s22, v254, 30
	v_readlane_b32 s23, v254, 31
	v_readlane_b32 s24, v254, 32
	v_readlane_b32 s25, v254, 33
	v_add_u32_e32 v128, v129, v128
	v_readlane_b32 s26, v254, 34
	v_readlane_b32 s27, v254, 35
	s_mov_b64 s[20:21], s[24:25]
	v_lshl_or_b32 v232, s77, 8, v198
	v_mov_b32_e32 v216, s21
	v_mov_b32_e32 v217, s71
	v_mov_b32_e32 v218, s20
	v_mov_b32_e32 v219, s70
	v_ashrrev_i32_e32 v129, 31, v128
	v_cndmask_b32_e32 v131, v216, v217, vcc
	v_cndmask_b32_e32 v130, v218, v219, vcc
	v_lshlrev_b64 v[128:129], 12, v[128:129]
	v_ashrrev_i32_e32 v233, 31, v232
	v_lshl_add_u64 v[128:129], v[130:131], 0, v[128:129]
	v_lshlrev_b64 v[172:173], 2, v[232:233]
	v_ashrrev_i32_e32 v187, 31, v186
	v_lshl_add_u64 v[192:193], v[128:129], 0, v[172:173]
	v_lshl_add_u64 v[188:189], v[186:187], 3, s[62:63]
	global_load_dwordx4 v[178:181], v[192:193], off
	global_load_dwordx4 v[228:231], v[192:193], off offset:64
	global_load_dwordx2 v[234:235], v[188:189], off
	v_cndmask_b32_e64 v128, v132, 4, vcc
	v_mul_hi_i32_i24_e32 v129, 0x6000, v128
	v_lshl_add_u64 v[174:175], s[14:15], 0, v[172:173]
	v_lshl_add_u64 v[176:177], s[18:19], 0, v[172:173]
	v_mul_i32_i24_e32 v128, 0x6000, v128
	global_load_dwordx4 v[182:185], v[174:175], off
	global_load_dwordx4 v[220:223], v[176:177], off
	v_lshl_add_u64 v[128:129], s[0:1], 0, v[128:129]
	v_lshl_add_u64 v[236:237], v[128:129], 0, v[172:173]
	global_load_dwordx4 v[224:227], v[236:237], off
	v_or_b32_e32 v240, 16, v186
	v_mul_hi_i32 v128, v240, s67
	v_lshrrev_b32_e32 v129, 31, v128
	v_ashrrev_i32_e32 v128, 11, v128
	v_add_u32_e32 v187, v128, v129
	v_mad_i32_i24 v128, v187, s74, v240
	v_lshl_add_u32 v129, v187, 13, v215
	v_lshlrev_b32_e32 v130, 8, v187
	v_cmp_gt_i32_e32 vcc, s52, v128
	v_or_b32_e32 v238, 16, v232
	v_ashrrev_i32_e32 v239, 31, v238
	v_cndmask_b32_e32 v129, v129, v130, vcc
	v_add_u32_e32 v128, v129, v128
	v_ashrrev_i32_e32 v129, 31, v128
	v_cndmask_b32_e32 v131, v216, v217, vcc
	v_cndmask_b32_e32 v130, v218, v219, vcc
	v_lshlrev_b64 v[128:129], 12, v[128:129]
	v_lshl_add_u64 v[128:129], v[130:131], 0, v[128:129]
	v_lshl_add_u64 v[190:191], v[128:129], 0, v[172:173]
	global_load_dwordx4 v[140:143], v[190:191], off
	global_load_dwordx4 v[136:139], v[190:191], off offset:64
	global_load_dwordx4 v[132:135], v[190:191], off offset:512
	global_load_dwordx4 v[128:131], v[190:191], off offset:576
	v_ashrrev_i32_e32 v241, 31, v240
	v_or_b32_e32 v242, 32, v186
	v_ashrrev_i32_e32 v243, 31, v242
	s_mov_b64 s[4:5], -1
	s_mov_b64 s[22:23], s[26:27]
	s_waitcnt vmcnt(0)
	v_sub_f32_e32 v181, v181, v234
	v_sub_f32_e32 v180, v180, v234
	v_sub_f32_e32 v179, v179, v234
	v_sub_f32_e32 v178, v178, v234
	v_pk_mul_f32 v[178:179], v[178:179], v[234:235] op_sel:[0,1]
	v_pk_mul_f32 v[180:181], v[180:181], v[234:235] op_sel:[0,1]
	v_pk_fma_f32 v[178:179], v[182:183], v[178:179], v[220:221]
	v_pk_fma_f32 v[180:181], v[184:185], v[180:181], v[222:223]
	v_pk_mul_f32 v[178:179], v[178:179], s[44:45] op_sel_hi:[1,0]
	v_pk_mul_f32 v[180:181], v[180:181], s[44:45] op_sel_hi:[1,0]
	v_pk_fma_f32 v[124:125], v[124:125], v[224:225], v[178:179]
	v_pk_fma_f32 v[126:127], v[126:127], v[226:227], v[180:181]
	global_store_dwordx4 v[192:193], v[124:127], off
	s_nop 0
	s_waitcnt vmcnt(1)
	v_sub_f32_e32 v231, v231, v234
	v_lshlrev_b64 v[126:127], 2, v[238:239]
	v_lshl_add_u64 v[124:125], s[14:15], 0, v[126:127]
	v_lshl_add_u64 v[126:127], s[18:19], 0, v[126:127]
	global_load_dwordx4 v[178:181], v[124:125], off
	global_load_dwordx4 v[182:185], v[126:127], off
	global_load_dwordx4 v[220:223], v[236:237], off offset:64
	v_sub_f32_e32 v230, v230, v234
	v_sub_f32_e32 v229, v229, v234
	v_sub_f32_e32 v228, v228, v234
	v_pk_mul_f32 v[228:229], v[228:229], v[234:235] op_sel:[0,1]
	v_pk_mul_f32 v[230:231], v[230:231], v[234:235] op_sel:[0,1]
	v_or_b32_e32 v238, 0x80, v232
	global_load_dwordx4 v[224:227], v[192:193], off offset:512
	v_ashrrev_i32_e32 v239, 31, v238
	v_or_b32_e32 v232, 0x90, v232
	v_ashrrev_i32_e32 v233, 31, v232
	s_waitcnt vmcnt(2)
	v_pk_fma_f32 v[180:181], v[180:181], v[230:231], v[184:185]
	v_pk_fma_f32 v[178:179], v[178:179], v[228:229], v[182:183]
	v_pk_mul_f32 v[180:181], v[180:181], s[44:45] op_sel_hi:[1,0]
	v_pk_mul_f32 v[178:179], v[178:179], s[44:45] op_sel_hi:[1,0]
	s_waitcnt vmcnt(1)
	v_pk_fma_f32 v[122:123], v[122:123], v[222:223], v[180:181]
	v_pk_fma_f32 v[120:121], v[120:121], v[220:221], v[178:179]
	global_store_dwordx4 v[192:193], v[120:123], off offset:64
	s_nop 0
	s_waitcnt vmcnt(1)
	v_sub_f32_e32 v227, v227, v234
	v_lshlrev_b64 v[120:121], 2, v[238:239]
	v_lshl_add_u64 v[178:179], s[14:15], 0, v[120:121]
	v_lshl_add_u64 v[180:181], s[18:19], 0, v[120:121]
	global_load_dwordx4 v[120:123], v[178:179], off
	global_load_dwordx4 v[182:185], v[180:181], off
	global_load_dwordx4 v[220:223], v[236:237], off offset:512
	v_sub_f32_e32 v226, v226, v234
	v_sub_f32_e32 v225, v225, v234
	v_sub_f32_e32 v224, v224, v234
	v_pk_mul_f32 v[224:225], v[224:225], v[234:235] op_sel:[0,1]
	v_pk_mul_f32 v[226:227], v[226:227], v[234:235] op_sel:[0,1]
	global_load_dwordx4 v[228:231], v[192:193], off offset:576
	s_waitcnt vmcnt(2)
	v_pk_fma_f32 v[122:123], v[122:123], v[226:227], v[184:185]
	v_pk_fma_f32 v[120:121], v[120:121], v[224:225], v[182:183]
	v_pk_mul_f32 v[122:123], v[122:123], s[44:45] op_sel_hi:[1,0]
	v_pk_mul_f32 v[120:121], v[120:121], s[44:45] op_sel_hi:[1,0]
	s_waitcnt vmcnt(1)
	v_pk_fma_f32 v[118:119], v[118:119], v[222:223], v[122:123]
	v_pk_fma_f32 v[116:117], v[116:117], v[220:221], v[120:121]
	global_store_dwordx4 v[192:193], v[116:119], off offset:512
	s_nop 0
	s_waitcnt vmcnt(1)
	v_mov_b32_e32 v224, v234
	v_mov_b32_e32 v225, v235
	v_sub_f32_e32 v227, v231, v224
	v_lshlrev_b64 v[116:117], 2, v[232:233]
	v_lshl_add_u64 v[182:183], s[14:15], 0, v[116:117]
	v_lshl_add_u64 v[184:185], s[18:19], 0, v[116:117]
	global_load_dwordx4 v[116:119], v[182:183], off
	global_load_dwordx4 v[120:123], v[184:185], off
	global_load_dwordx4 v[220:223], v[236:237], off offset:576
	v_sub_f32_e32 v226, v230, v224
	v_sub_f32_e32 v229, v229, v224
	v_sub_f32_e32 v228, v228, v224
	v_pk_mul_f32 v[228:229], v[228:229], v[224:225] op_sel:[0,1]
	v_pk_mul_f32 v[224:225], v[226:227], v[224:225] op_sel:[0,1]
	v_lshl_add_u64 v[236:237], v[240:241], 3, s[62:63]
	s_waitcnt vmcnt(1)
	v_pk_fma_f32 v[118:119], v[118:119], v[224:225], v[122:123]
	v_pk_fma_f32 v[116:117], v[116:117], v[228:229], v[120:121]
	v_pk_mul_f32 v[118:119], v[118:119], s[44:45] op_sel_hi:[1,0]
	v_pk_mul_f32 v[116:117], v[116:117], s[44:45] op_sel_hi:[1,0]
	s_waitcnt vmcnt(0)
	v_pk_fma_f32 v[114:115], v[114:115], v[222:223], v[118:119]
	v_pk_fma_f32 v[112:113], v[112:113], v[220:221], v[116:117]
	global_store_dwordx4 v[192:193], v[112:115], off offset:576
	global_load_dwordx2 v[238:239], v[236:237], off
	global_load_dwordx4 v[220:223], v[174:175], off
	global_load_dwordx4 v[224:227], v[176:177], off
	v_cndmask_b32_e64 v112, v187, 4, vcc
	v_mul_hi_i32_i24_e32 v113, 0x6000, v112
	v_mul_i32_i24_e32 v112, 0x6000, v112
	v_lshl_add_u64 v[112:113], s[0:1], 0, v[112:113]
	v_lshl_add_u64 v[240:241], v[112:113], 0, v[172:173]
	global_load_dwordx4 v[228:231], v[240:241], off
	v_mul_hi_i32 v112, v242, s67
	v_lshrrev_b32_e32 v113, 31, v112
	v_ashrrev_i32_e32 v112, 11, v112
	v_add_u32_e32 v187, v112, v113
	v_mad_i32_i24 v112, v187, s74, v242
	v_lshl_add_u32 v113, v187, 13, v215
	v_lshlrev_b32_e32 v114, 8, v187
	v_cmp_gt_i32_e32 vcc, s52, v112
	s_waitcnt vmcnt(3)
	v_sub_f32_e32 v143, v143, v238
	v_cndmask_b32_e32 v113, v113, v114, vcc
	v_add_u32_e32 v112, v113, v112
	v_sub_f32_e32 v142, v142, v238
	v_sub_f32_e32 v141, v141, v238
	v_sub_f32_e32 v140, v140, v238
	v_ashrrev_i32_e32 v113, 31, v112
	v_pk_mul_f32 v[140:141], v[140:141], v[238:239] op_sel:[0,1]
	v_pk_mul_f32 v[142:143], v[142:143], v[238:239] op_sel:[0,1]
	v_cndmask_b32_e32 v115, v216, v217, vcc
	v_cndmask_b32_e32 v114, v218, v219, vcc
	v_lshlrev_b64 v[112:113], 12, v[112:113]
	s_waitcnt vmcnt(1)
	v_pk_fma_f32 v[142:143], v[222:223], v[142:143], v[226:227]
	v_pk_fma_f32 v[140:141], v[220:221], v[140:141], v[224:225]
	v_lshl_add_u64 v[112:113], v[114:115], 0, v[112:113]
	v_pk_mul_f32 v[140:141], v[140:141], s[44:45] op_sel_hi:[1,0]
	v_pk_mul_f32 v[142:143], v[142:143], s[44:45] op_sel_hi:[1,0]
	v_lshl_add_u64 v[192:193], v[112:113], 0, v[172:173]
	s_waitcnt vmcnt(0)
	v_pk_fma_f32 v[110:111], v[110:111], v[230:231], v[142:143]
	v_pk_fma_f32 v[108:109], v[108:109], v[228:229], v[140:141]
	global_load_dwordx4 v[232:235], v[192:193], off
	global_load_dwordx4 v[120:123], v[192:193], off offset:64
	global_load_dwordx4 v[116:119], v[192:193], off offset:512
	global_load_dwordx4 v[112:115], v[192:193], off offset:576
	s_nop 0
	global_store_dwordx4 v[190:191], v[108:111], off
	s_nop 0
	s_nop 0
	global_load_dwordx4 v[108:111], v[124:125], off
	global_load_dwordx4 v[140:143], v[126:127], off
	global_load_dwordx4 v[220:223], v[240:241], off offset:64
	s_waitcnt vmcnt(3)
	v_mov_b32_e32 v224, v238
	v_mov_b32_e32 v225, v239
	v_sub_f32_e32 v139, v139, v224
	v_sub_f32_e32 v138, v138, v224
	v_sub_f32_e32 v137, v137, v224
	v_sub_f32_e32 v136, v136, v224
	v_pk_mul_f32 v[136:137], v[136:137], v[224:225] op_sel:[0,1]
	v_pk_mul_f32 v[138:139], v[138:139], v[224:225] op_sel:[0,1]
	s_waitcnt vmcnt(1)
	v_pk_fma_f32 v[108:109], v[108:109], v[136:137], v[140:141]
	v_pk_fma_f32 v[110:111], v[110:111], v[138:139], v[142:143]
	v_pk_mul_f32 v[108:109], v[108:109], s[44:45] op_sel_hi:[1,0]
	v_pk_mul_f32 v[110:111], v[110:111], s[44:45] op_sel_hi:[1,0]
	s_waitcnt vmcnt(0)
	v_pk_fma_f32 v[104:105], v[104:105], v[220:221], v[108:109]
	v_pk_fma_f32 v[106:107], v[106:107], v[222:223], v[110:111]
	global_store_dwordx4 v[190:191], v[104:107], off offset:64
	s_nop 0
	s_nop 0
	global_load_dwordx4 v[104:107], v[178:179], off
	global_load_dwordx4 v[108:111], v[180:181], off
	global_load_dwordx4 v[136:139], v[240:241], off offset:512
	v_lshl_add_u64 v[220:221], v[242:243], 3, s[62:63]
	v_or_b32_e32 v222, 48, v186
	v_ashrrev_i32_e32 v223, 31, v222
	s_waitcnt vmcnt(3)
	v_mov_b32_e32 v140, v238
	v_mov_b32_e32 v141, v239
	v_sub_f32_e32 v135, v135, v140
	v_sub_f32_e32 v134, v134, v140
	v_sub_f32_e32 v133, v133, v140
	v_sub_f32_e32 v132, v132, v140
	v_pk_mul_f32 v[132:133], v[132:133], v[140:141] op_sel:[0,1]
	v_pk_mul_f32 v[134:135], v[134:135], v[140:141] op_sel:[0,1]
	s_waitcnt vmcnt(1)
	v_pk_fma_f32 v[104:105], v[104:105], v[132:133], v[108:109]
	v_pk_fma_f32 v[106:107], v[106:107], v[134:135], v[110:111]
	v_pk_mul_f32 v[104:105], v[104:105], s[44:45] op_sel_hi:[1,0]
	v_pk_mul_f32 v[106:107], v[106:107], s[44:45] op_sel_hi:[1,0]
	s_waitcnt vmcnt(0)
	v_pk_fma_f32 v[100:101], v[100:101], v[136:137], v[104:105]
	v_pk_fma_f32 v[102:103], v[102:103], v[138:139], v[106:107]
	global_store_dwordx4 v[190:191], v[100:103], off offset:512
	s_nop 0
	s_nop 0
	global_load_dwordx4 v[100:103], v[182:183], off
	global_load_dwordx4 v[104:107], v[184:185], off
	global_load_dwordx4 v[108:111], v[240:241], off offset:576
	s_waitcnt vmcnt(3)
	v_mov_b32_e32 v132, v238
	v_mov_b32_e32 v133, v239
	v_sub_f32_e32 v131, v131, v132
	v_sub_f32_e32 v130, v130, v132
	v_sub_f32_e32 v129, v129, v132
	v_sub_f32_e32 v128, v128, v132
	v_pk_mul_f32 v[128:129], v[128:129], v[132:133] op_sel:[0,1]
	v_pk_mul_f32 v[130:131], v[130:131], v[132:133] op_sel:[0,1]
	s_waitcnt vmcnt(1)
	v_pk_fma_f32 v[100:101], v[100:101], v[128:129], v[104:105]
	v_pk_fma_f32 v[102:103], v[102:103], v[130:131], v[106:107]
	v_pk_mul_f32 v[100:101], v[100:101], s[44:45] op_sel_hi:[1,0]
	v_pk_mul_f32 v[102:103], v[102:103], s[44:45] op_sel_hi:[1,0]
	s_waitcnt vmcnt(0)
	v_pk_fma_f32 v[96:97], v[96:97], v[108:109], v[100:101]
	v_pk_fma_f32 v[98:99], v[98:99], v[110:111], v[102:103]
	global_store_dwordx4 v[190:191], v[96:99], off offset:576
	global_load_dwordx2 v[110:111], v[220:221], off
	global_load_dwordx4 v[128:131], v[174:175], off
	global_load_dwordx4 v[132:135], v[176:177], off
	v_cndmask_b32_e64 v96, v187, 4, vcc
	v_mul_hi_i32_i24_e32 v97, 0x6000, v96
	v_mul_i32_i24_e32 v96, 0x6000, v96
	v_lshl_add_u64 v[96:97], s[0:1], 0, v[96:97]
	v_lshl_add_u64 v[190:191], v[96:97], 0, v[172:173]
	global_load_dwordx4 v[136:139], v[190:191], off
	v_mul_hi_i32 v96, v222, s67
	v_lshrrev_b32_e32 v97, 31, v96
	v_ashrrev_i32_e32 v96, 11, v96
	v_add_u32_e32 v187, v96, v97
	v_mad_i32_i24 v96, v187, s74, v222
	v_lshl_add_u32 v97, v187, 13, v215
	v_lshlrev_b32_e32 v98, 8, v187
	v_cmp_gt_i32_e32 vcc, s52, v96
	s_waitcnt vmcnt(3)
	v_mov_b32_e32 v228, v110
	v_mov_b32_e32 v229, v111
	v_sub_f32_e32 v225, v235, v110
	v_cndmask_b32_e32 v97, v97, v98, vcc
	v_add_u32_e32 v96, v97, v96
	v_sub_f32_e32 v224, v234, v110
	v_sub_f32_e32 v227, v233, v110
	v_sub_f32_e32 v226, v232, v110
	v_ashrrev_i32_e32 v97, 31, v96
	v_pk_mul_f32 v[226:227], v[226:227], v[110:111] op_sel:[0,1]
	v_pk_mul_f32 v[110:111], v[224:225], v[110:111] op_sel:[0,1]
	v_cndmask_b32_e32 v99, v216, v217, vcc
	v_cndmask_b32_e32 v98, v218, v219, vcc
	v_lshlrev_b64 v[96:97], 12, v[96:97]
	s_waitcnt vmcnt(1)
	v_pk_fma_f32 v[110:111], v[130:131], v[110:111], v[134:135]
	v_pk_fma_f32 v[128:129], v[128:129], v[226:227], v[132:133]
	v_lshl_add_u64 v[96:97], v[98:99], 0, v[96:97]
	v_pk_mul_f32 v[128:129], v[128:129], s[44:45] op_sel_hi:[1,0]
	v_pk_mul_f32 v[110:111], v[110:111], s[44:45] op_sel_hi:[1,0]
	v_lshl_add_u64 v[108:109], v[96:97], 0, v[172:173]
	s_waitcnt vmcnt(0)
	v_pk_fma_f32 v[94:95], v[94:95], v[138:139], v[110:111]
	v_pk_fma_f32 v[92:93], v[92:93], v[136:137], v[128:129]
	global_load_dwordx4 v[140:143], v[108:109], off
	global_load_dwordx4 v[104:107], v[108:109], off offset:64
	global_load_dwordx4 v[100:103], v[108:109], off offset:512
	global_load_dwordx4 v[96:99], v[108:109], off offset:576
	s_nop 0
	global_store_dwordx4 v[192:193], v[92:95], off
	s_nop 0
	s_nop 0
	global_load_dwordx4 v[92:95], v[124:125], off
	global_load_dwordx4 v[128:131], v[126:127], off
	global_load_dwordx4 v[132:135], v[190:191], off offset:64
	s_waitcnt vmcnt(3)
	v_mov_b32_e32 v110, v228
	v_mov_b32_e32 v111, v229
	v_sub_f32_e32 v123, v123, v110
	v_sub_f32_e32 v122, v122, v110
	v_sub_f32_e32 v121, v121, v110
	v_sub_f32_e32 v120, v120, v110
	v_pk_mul_f32 v[120:121], v[120:121], v[110:111] op_sel:[0,1]
	v_pk_mul_f32 v[110:111], v[122:123], v[110:111] op_sel:[0,1]
	s_waitcnt vmcnt(1)
	v_pk_fma_f32 v[92:93], v[92:93], v[120:121], v[128:129]
	v_pk_fma_f32 v[94:95], v[94:95], v[110:111], v[130:131]
	v_pk_mul_f32 v[92:93], v[92:93], s[44:45] op_sel_hi:[1,0]
	v_pk_mul_f32 v[94:95], v[94:95], s[44:45] op_sel_hi:[1,0]
	s_waitcnt vmcnt(0)
	v_pk_fma_f32 v[88:89], v[88:89], v[132:133], v[92:93]
	v_pk_fma_f32 v[90:91], v[90:91], v[134:135], v[94:95]
	global_store_dwordx4 v[192:193], v[88:91], off offset:64
	s_nop 0
	s_nop 0
	global_load_dwordx4 v[88:91], v[178:179], off
	global_load_dwordx4 v[92:95], v[180:181], off
	global_load_dwordx4 v[120:123], v[190:191], off offset:512
	s_waitcnt vmcnt(3)
	v_mov_b32_e32 v110, v228
	v_mov_b32_e32 v111, v229
	v_sub_f32_e32 v119, v119, v110
	v_sub_f32_e32 v118, v118, v110
	v_sub_f32_e32 v117, v117, v110
	v_sub_f32_e32 v116, v116, v110
	v_pk_mul_f32 v[116:117], v[116:117], v[110:111] op_sel:[0,1]
	v_pk_mul_f32 v[110:111], v[118:119], v[110:111] op_sel:[0,1]
	s_waitcnt vmcnt(1)
	v_pk_fma_f32 v[88:89], v[88:89], v[116:117], v[92:93]
	v_pk_fma_f32 v[90:91], v[90:91], v[110:111], v[94:95]
	v_pk_mul_f32 v[88:89], v[88:89], s[44:45] op_sel_hi:[1,0]
	v_pk_mul_f32 v[90:91], v[90:91], s[44:45] op_sel_hi:[1,0]
	s_waitcnt vmcnt(0)
	v_pk_fma_f32 v[84:85], v[84:85], v[120:121], v[88:89]
	v_pk_fma_f32 v[86:87], v[86:87], v[122:123], v[90:91]
	global_store_dwordx4 v[192:193], v[84:87], off offset:512
	s_nop 0
	s_nop 0
	global_load_dwordx4 v[84:87], v[182:183], off
	global_load_dwordx4 v[88:91], v[184:185], off
	global_load_dwordx4 v[92:95], v[190:191], off offset:576
	v_lshl_add_u64 v[122:123], v[222:223], 3, s[62:63]
	s_waitcnt vmcnt(3)
	v_mov_b32_e32 v110, v228
	v_mov_b32_e32 v111, v229
	v_sub_f32_e32 v115, v115, v110
	v_sub_f32_e32 v114, v114, v110
	v_sub_f32_e32 v113, v113, v110
	v_sub_f32_e32 v112, v112, v110
	v_pk_mul_f32 v[112:113], v[112:113], v[110:111] op_sel:[0,1]
	v_pk_mul_f32 v[110:111], v[114:115], v[110:111] op_sel:[0,1]
	s_waitcnt vmcnt(1)
	v_pk_fma_f32 v[84:85], v[84:85], v[112:113], v[88:89]
	v_pk_fma_f32 v[86:87], v[86:87], v[110:111], v[90:91]
	v_pk_mul_f32 v[84:85], v[84:85], s[44:45] op_sel_hi:[1,0]
	v_pk_mul_f32 v[86:87], v[86:87], s[44:45] op_sel_hi:[1,0]
	s_waitcnt vmcnt(0)
	v_pk_fma_f32 v[80:81], v[80:81], v[92:93], v[84:85]
	v_pk_fma_f32 v[82:83], v[82:83], v[94:95], v[86:87]
	global_store_dwordx4 v[192:193], v[80:83], off offset:576
	global_load_dwordx2 v[94:95], v[122:123], off
	global_load_dwordx4 v[110:113], v[174:175], off
	global_load_dwordx4 v[114:117], v[176:177], off
	v_cndmask_b32_e64 v80, v187, 4, vcc
	v_mul_hi_i32_i24_e32 v81, 0x6000, v80
	v_mul_i32_i24_e32 v80, 0x6000, v80
	v_lshl_add_u64 v[80:81], s[0:1], 0, v[80:81]
	v_lshl_add_u64 v[132:133], v[80:81], 0, v[172:173]
	global_load_dwordx4 v[118:121], v[132:133], off
	v_add_u32_e32 v80, 0x80, v186
	v_mul_hi_i32 v81, v80, s67
	v_lshrrev_b32_e32 v82, 31, v81
	v_ashrrev_i32_e32 v81, 11, v81
	v_add_u32_e32 v138, v81, v82
	v_mad_i32_i24 v80, v138, s74, v80
	v_lshl_add_u32 v81, v138, 13, v215
	v_lshlrev_b32_e32 v82, 8, v138
	v_cmp_gt_i32_e32 vcc, s52, v80
	s_waitcnt vmcnt(3)
	v_mov_b32_e32 v190, v94
	v_mov_b32_e32 v191, v95
	v_sub_f32_e32 v135, v143, v94
	v_cndmask_b32_e32 v81, v81, v82, vcc
	v_add_u32_e32 v80, v81, v80
	v_sub_f32_e32 v134, v142, v94
	v_sub_f32_e32 v137, v141, v94
	v_sub_f32_e32 v136, v140, v94
	v_ashrrev_i32_e32 v81, 31, v80
	v_pk_mul_f32 v[136:137], v[136:137], v[94:95] op_sel:[0,1]
	v_pk_mul_f32 v[94:95], v[134:135], v[94:95] op_sel:[0,1]
	v_cndmask_b32_e32 v83, v216, v217, vcc
	v_cndmask_b32_e32 v82, v218, v219, vcc
	v_lshlrev_b64 v[80:81], 12, v[80:81]
	s_waitcnt vmcnt(1)
	v_pk_fma_f32 v[94:95], v[112:113], v[94:95], v[116:117]
	v_pk_fma_f32 v[110:111], v[110:111], v[136:137], v[114:115]
	v_lshl_add_u64 v[80:81], v[82:83], 0, v[80:81]
	v_pk_mul_f32 v[110:111], v[110:111], s[44:45] op_sel_hi:[1,0]
	v_pk_mul_f32 v[94:95], v[94:95], s[44:45] op_sel_hi:[1,0]
	v_lshl_add_u64 v[92:93], v[80:81], 0, v[172:173]
	s_waitcnt vmcnt(0)
	v_pk_fma_f32 v[78:79], v[78:79], v[120:121], v[94:95]
	v_pk_fma_f32 v[76:77], v[76:77], v[118:119], v[110:111]
	global_load_dwordx4 v[128:131], v[92:93], off
	global_load_dwordx4 v[88:91], v[92:93], off offset:64
	global_load_dwordx4 v[84:87], v[92:93], off offset:512
	global_load_dwordx4 v[80:83], v[92:93], off offset:576
	s_nop 0
	global_store_dwordx4 v[108:109], v[76:79], off
	s_nop 0
	s_nop 0
	global_load_dwordx4 v[76:79], v[124:125], off
	global_load_dwordx4 v[110:113], v[126:127], off
	global_load_dwordx4 v[114:117], v[132:133], off offset:64
	s_waitcnt vmcnt(3)
	v_mov_b32_e32 v94, v190
	v_mov_b32_e32 v95, v191
	v_sub_f32_e32 v107, v107, v94
	v_sub_f32_e32 v106, v106, v94
	v_sub_f32_e32 v105, v105, v94
	v_sub_f32_e32 v104, v104, v94
	v_pk_mul_f32 v[104:105], v[104:105], v[94:95] op_sel:[0,1]
	v_pk_mul_f32 v[94:95], v[106:107], v[94:95] op_sel:[0,1]
	s_waitcnt vmcnt(1)
	v_pk_fma_f32 v[76:77], v[76:77], v[104:105], v[110:111]
	v_pk_fma_f32 v[78:79], v[78:79], v[94:95], v[112:113]
	v_pk_mul_f32 v[76:77], v[76:77], s[44:45] op_sel_hi:[1,0]
	v_pk_mul_f32 v[78:79], v[78:79], s[44:45] op_sel_hi:[1,0]
	s_waitcnt vmcnt(0)
	v_pk_fma_f32 v[72:73], v[72:73], v[114:115], v[76:77]
	v_pk_fma_f32 v[74:75], v[74:75], v[116:117], v[78:79]
	global_store_dwordx4 v[108:109], v[72:75], off offset:64
	s_nop 0
	s_nop 0
	global_load_dwordx4 v[72:75], v[178:179], off
	global_load_dwordx4 v[76:79], v[180:181], off
	global_load_dwordx4 v[104:107], v[132:133], off offset:512
	v_add_u32_e32 v112, 0x90, v186
	v_ashrrev_i32_e32 v113, 31, v112
	s_waitcnt vmcnt(3)
	v_mov_b32_e32 v94, v190
	v_mov_b32_e32 v95, v191
	v_sub_f32_e32 v103, v103, v94
	v_sub_f32_e32 v102, v102, v94
	v_sub_f32_e32 v101, v101, v94
	v_sub_f32_e32 v100, v100, v94
	v_pk_mul_f32 v[100:101], v[100:101], v[94:95] op_sel:[0,1]
	v_pk_mul_f32 v[94:95], v[102:103], v[94:95] op_sel:[0,1]
	s_waitcnt vmcnt(1)
	v_pk_fma_f32 v[72:73], v[72:73], v[100:101], v[76:77]
	v_pk_fma_f32 v[74:75], v[74:75], v[94:95], v[78:79]
	v_pk_mul_f32 v[72:73], v[72:73], s[44:45] op_sel_hi:[1,0]
	v_pk_mul_f32 v[74:75], v[74:75], s[44:45] op_sel_hi:[1,0]
	s_waitcnt vmcnt(0)
	v_pk_fma_f32 v[68:69], v[68:69], v[104:105], v[72:73]
	v_pk_fma_f32 v[70:71], v[70:71], v[106:107], v[74:75]
	global_store_dwordx4 v[108:109], v[68:71], off offset:512
	s_nop 0
	s_nop 0
	global_load_dwordx4 v[68:71], v[182:183], off
	global_load_dwordx4 v[72:75], v[184:185], off
	global_load_dwordx4 v[76:79], v[132:133], off offset:576
	s_waitcnt vmcnt(3)
	v_mov_b32_e32 v94, v190
	v_mov_b32_e32 v95, v191
	v_sub_f32_e32 v99, v99, v94
	v_sub_f32_e32 v98, v98, v94
	v_sub_f32_e32 v97, v97, v94
	v_sub_f32_e32 v96, v96, v94
	v_pk_mul_f32 v[96:97], v[96:97], v[94:95] op_sel:[0,1]
	v_pk_mul_f32 v[94:95], v[98:99], v[94:95] op_sel:[0,1]
	s_waitcnt vmcnt(1)
	v_pk_fma_f32 v[68:69], v[68:69], v[96:97], v[72:73]
	v_pk_fma_f32 v[70:71], v[70:71], v[94:95], v[74:75]
	v_pk_mul_f32 v[68:69], v[68:69], s[44:45] op_sel_hi:[1,0]
	v_pk_mul_f32 v[70:71], v[70:71], s[44:45] op_sel_hi:[1,0]
	s_waitcnt vmcnt(0)
	v_pk_fma_f32 v[64:65], v[64:65], v[76:77], v[68:69]
	v_pk_fma_f32 v[66:67], v[66:67], v[78:79], v[70:71]
	global_store_dwordx4 v[108:109], v[64:67], off offset:576
	global_load_dwordx2 v[78:79], v[188:189], off offset:1024
	global_load_dwordx4 v[94:97], v[174:175], off
	global_load_dwordx4 v[98:101], v[176:177], off
	v_cndmask_b32_e64 v64, v138, 4, vcc
	v_mul_hi_i32_i24_e32 v65, 0x6000, v64
	v_mul_i32_i24_e32 v64, 0x6000, v64
	v_lshl_add_u64 v[64:65], s[0:1], 0, v[64:65]
	v_lshl_add_u64 v[110:111], v[64:65], 0, v[172:173]
	global_load_dwordx4 v[102:105], v[110:111], off
	v_mul_hi_i32 v64, v112, s67
	v_lshrrev_b32_e32 v65, 31, v64
	v_ashrrev_i32_e32 v64, 11, v64
	v_add_u32_e32 v118, v64, v65
	v_mad_i32_i24 v64, v118, s74, v112
	v_lshl_add_u32 v65, v118, 13, v215
	v_lshlrev_b32_e32 v66, 8, v118
	v_cmp_gt_i32_e32 vcc, s52, v64
	s_waitcnt vmcnt(3)
	v_sub_f32_e32 v115, v131, v78
	v_cndmask_b32_e32 v65, v65, v66, vcc
	v_add_u32_e32 v64, v65, v64
	v_sub_f32_e32 v114, v130, v78
	v_sub_f32_e32 v117, v129, v78
	v_sub_f32_e32 v116, v128, v78
	v_ashrrev_i32_e32 v65, 31, v64
	v_pk_mul_f32 v[116:117], v[116:117], v[78:79] op_sel:[0,1]
	v_pk_mul_f32 v[78:79], v[114:115], v[78:79] op_sel:[0,1]
	v_cndmask_b32_e32 v67, v216, v217, vcc
	v_cndmask_b32_e32 v66, v218, v219, vcc
	v_lshlrev_b64 v[64:65], 12, v[64:65]
	s_waitcnt vmcnt(1)
	v_pk_fma_f32 v[78:79], v[96:97], v[78:79], v[100:101]
	v_pk_fma_f32 v[94:95], v[94:95], v[116:117], v[98:99]
	v_lshl_add_u64 v[64:65], v[66:67], 0, v[64:65]
	v_pk_mul_f32 v[94:95], v[94:95], s[44:45] op_sel_hi:[1,0]
	v_pk_mul_f32 v[78:79], v[78:79], s[44:45] op_sel_hi:[1,0]
	v_lshl_add_u64 v[76:77], v[64:65], 0, v[172:173]
	s_waitcnt vmcnt(0)
	v_pk_fma_f32 v[62:63], v[62:63], v[104:105], v[78:79]
	v_pk_fma_f32 v[60:61], v[60:61], v[102:103], v[94:95]
	global_load_dwordx4 v[106:109], v[76:77], off
	global_load_dwordx4 v[72:75], v[76:77], off offset:64
	global_load_dwordx4 v[68:71], v[76:77], off offset:512
	global_load_dwordx4 v[64:67], v[76:77], off offset:576
	s_nop 0
	global_store_dwordx4 v[92:93], v[60:63], off
	global_load_dwordx2 v[78:79], v[188:189], off offset:1024
	s_nop 0
	global_load_dwordx4 v[60:63], v[124:125], off
	global_load_dwordx4 v[94:97], v[126:127], off
	global_load_dwordx4 v[98:101], v[110:111], off offset:64
	s_waitcnt vmcnt(3)
	v_sub_f32_e32 v91, v91, v78
	v_sub_f32_e32 v90, v90, v78
	v_sub_f32_e32 v89, v89, v78
	v_sub_f32_e32 v88, v88, v78
	v_pk_mul_f32 v[88:89], v[88:89], v[78:79] op_sel:[0,1]
	v_pk_mul_f32 v[78:79], v[90:91], v[78:79] op_sel:[0,1]
	s_waitcnt vmcnt(1)
	v_pk_fma_f32 v[60:61], v[60:61], v[88:89], v[94:95]
	v_pk_fma_f32 v[62:63], v[62:63], v[78:79], v[96:97]
	v_pk_mul_f32 v[60:61], v[60:61], s[44:45] op_sel_hi:[1,0]
	v_pk_mul_f32 v[62:63], v[62:63], s[44:45] op_sel_hi:[1,0]
	s_waitcnt vmcnt(0)
	v_pk_fma_f32 v[56:57], v[56:57], v[98:99], v[60:61]
	v_pk_fma_f32 v[58:59], v[58:59], v[100:101], v[62:63]
	global_store_dwordx4 v[92:93], v[56:59], off offset:64
	global_load_dwordx2 v[78:79], v[188:189], off offset:1024
	s_nop 0
	global_load_dwordx4 v[56:59], v[178:179], off
	global_load_dwordx4 v[60:63], v[180:181], off
	global_load_dwordx4 v[88:91], v[110:111], off offset:512
	v_lshl_add_u64 v[94:95], v[112:113], 3, s[62:63]
	v_add_u32_e32 v98, 0xa0, v186
	v_ashrrev_i32_e32 v99, 31, v98
	s_waitcnt vmcnt(3)
	v_sub_f32_e32 v87, v87, v78
	v_sub_f32_e32 v86, v86, v78
	v_sub_f32_e32 v85, v85, v78
	v_sub_f32_e32 v84, v84, v78
	v_pk_mul_f32 v[84:85], v[84:85], v[78:79] op_sel:[0,1]
	v_pk_mul_f32 v[78:79], v[86:87], v[78:79] op_sel:[0,1]
	s_waitcnt vmcnt(1)
	v_pk_fma_f32 v[56:57], v[56:57], v[84:85], v[60:61]
	v_pk_fma_f32 v[58:59], v[58:59], v[78:79], v[62:63]
	v_pk_mul_f32 v[56:57], v[56:57], s[44:45] op_sel_hi:[1,0]
	v_pk_mul_f32 v[58:59], v[58:59], s[44:45] op_sel_hi:[1,0]
	s_waitcnt vmcnt(0)
	v_pk_fma_f32 v[52:53], v[52:53], v[88:89], v[56:57]
	v_pk_fma_f32 v[54:55], v[54:55], v[90:91], v[58:59]
	global_store_dwordx4 v[92:93], v[52:55], off offset:512
	global_load_dwordx2 v[78:79], v[188:189], off offset:1024
	s_nop 0
	global_load_dwordx4 v[52:55], v[182:183], off
	global_load_dwordx4 v[56:59], v[184:185], off
	global_load_dwordx4 v[60:63], v[110:111], off offset:576
	s_waitcnt vmcnt(3)
	v_sub_f32_e32 v83, v83, v78
	v_sub_f32_e32 v82, v82, v78
	v_sub_f32_e32 v81, v81, v78
	v_sub_f32_e32 v80, v80, v78
	v_pk_mul_f32 v[80:81], v[80:81], v[78:79] op_sel:[0,1]
	v_pk_mul_f32 v[78:79], v[82:83], v[78:79] op_sel:[0,1]
	s_waitcnt vmcnt(1)
	v_pk_fma_f32 v[52:53], v[52:53], v[80:81], v[56:57]
	v_pk_fma_f32 v[54:55], v[54:55], v[78:79], v[58:59]
	v_pk_mul_f32 v[52:53], v[52:53], s[44:45] op_sel_hi:[1,0]
	v_pk_mul_f32 v[54:55], v[54:55], s[44:45] op_sel_hi:[1,0]
	s_waitcnt vmcnt(0)
	v_pk_fma_f32 v[48:49], v[48:49], v[60:61], v[52:53]
	v_pk_fma_f32 v[50:51], v[50:51], v[62:63], v[54:55]
	global_store_dwordx4 v[92:93], v[48:51], off offset:576
	global_load_dwordx2 v[62:63], v[94:95], off
	global_load_dwordx4 v[78:81], v[174:175], off
	global_load_dwordx4 v[82:85], v[176:177], off
	v_cndmask_b32_e64 v48, v118, 4, vcc
	v_mul_hi_i32_i24_e32 v49, 0x6000, v48
	v_mul_i32_i24_e32 v48, 0x6000, v48
	v_lshl_add_u64 v[48:49], s[0:1], 0, v[48:49]
	v_lshl_add_u64 v[96:97], v[48:49], 0, v[172:173]
	global_load_dwordx4 v[86:89], v[96:97], off
	v_mul_hi_i32 v48, v98, s67
	v_lshrrev_b32_e32 v49, 31, v48
	v_ashrrev_i32_e32 v48, 11, v48
	v_add_u32_e32 v104, v48, v49
	v_mad_i32_i24 v48, v104, s74, v98
	v_lshl_add_u32 v49, v104, 13, v215
	v_lshlrev_b32_e32 v50, 8, v104
	v_cmp_gt_i32_e32 vcc, s52, v48
	s_waitcnt vmcnt(3)
	v_mov_b32_e32 v128, v62
	v_mov_b32_e32 v129, v63
	v_sub_f32_e32 v101, v109, v62
	v_cndmask_b32_e32 v49, v49, v50, vcc
	v_add_u32_e32 v48, v49, v48
	v_sub_f32_e32 v100, v108, v62
	v_sub_f32_e32 v103, v107, v62
	v_sub_f32_e32 v102, v106, v62
	v_ashrrev_i32_e32 v49, 31, v48
	v_pk_mul_f32 v[102:103], v[102:103], v[62:63] op_sel:[0,1]
	v_pk_mul_f32 v[62:63], v[100:101], v[62:63] op_sel:[0,1]
	v_cndmask_b32_e32 v51, v216, v217, vcc
	v_cndmask_b32_e32 v50, v218, v219, vcc
	v_lshlrev_b64 v[48:49], 12, v[48:49]
	s_waitcnt vmcnt(1)
	v_pk_fma_f32 v[62:63], v[80:81], v[62:63], v[84:85]
	v_pk_fma_f32 v[78:79], v[78:79], v[102:103], v[82:83]
	v_lshl_add_u64 v[48:49], v[50:51], 0, v[48:49]
	v_pk_mul_f32 v[78:79], v[78:79], s[44:45] op_sel_hi:[1,0]
	v_pk_mul_f32 v[62:63], v[62:63], s[44:45] op_sel_hi:[1,0]
	v_lshl_add_u64 v[60:61], v[48:49], 0, v[172:173]
	s_waitcnt vmcnt(0)
	v_pk_fma_f32 v[46:47], v[46:47], v[88:89], v[62:63]
	v_pk_fma_f32 v[44:45], v[44:45], v[86:87], v[78:79]
	global_load_dwordx4 v[90:93], v[60:61], off
	global_load_dwordx4 v[56:59], v[60:61], off offset:64
	global_load_dwordx4 v[52:55], v[60:61], off offset:512
	global_load_dwordx4 v[48:51], v[60:61], off offset:576
	s_nop 0
	global_store_dwordx4 v[76:77], v[44:47], off
	s_nop 0
	s_nop 0
	global_load_dwordx4 v[44:47], v[124:125], off
	global_load_dwordx4 v[78:81], v[126:127], off
	global_load_dwordx4 v[82:85], v[96:97], off offset:64
	s_waitcnt vmcnt(3)
	v_mov_b32_e32 v62, v128
	v_mov_b32_e32 v63, v129
	v_sub_f32_e32 v75, v75, v62
	v_sub_f32_e32 v74, v74, v62
	v_sub_f32_e32 v73, v73, v62
	v_sub_f32_e32 v72, v72, v62
	v_pk_mul_f32 v[72:73], v[72:73], v[62:63] op_sel:[0,1]
	v_pk_mul_f32 v[62:63], v[74:75], v[62:63] op_sel:[0,1]
	s_waitcnt vmcnt(1)
	v_pk_fma_f32 v[44:45], v[44:45], v[72:73], v[78:79]
	v_pk_fma_f32 v[46:47], v[46:47], v[62:63], v[80:81]
	v_pk_mul_f32 v[44:45], v[44:45], s[44:45] op_sel_hi:[1,0]
	v_pk_mul_f32 v[46:47], v[46:47], s[44:45] op_sel_hi:[1,0]
	s_waitcnt vmcnt(0)
	v_pk_fma_f32 v[40:41], v[40:41], v[82:83], v[44:45]
	v_pk_fma_f32 v[42:43], v[42:43], v[84:85], v[46:47]
	global_store_dwordx4 v[76:77], v[40:43], off offset:64
	s_nop 0
	s_nop 0
	global_load_dwordx4 v[40:43], v[178:179], off
	global_load_dwordx4 v[44:47], v[180:181], off
	global_load_dwordx4 v[72:75], v[96:97], off offset:512
	v_lshl_add_u64 v[78:79], v[98:99], 3, s[62:63]
	v_add_u32_e32 v82, 0xb0, v186
	v_ashrrev_i32_e32 v83, 31, v82
	s_waitcnt vmcnt(3)
	v_mov_b32_e32 v62, v128
	v_mov_b32_e32 v63, v129
	v_sub_f32_e32 v71, v71, v62
	v_sub_f32_e32 v70, v70, v62
	v_sub_f32_e32 v69, v69, v62
	v_sub_f32_e32 v68, v68, v62
	v_pk_mul_f32 v[68:69], v[68:69], v[62:63] op_sel:[0,1]
	v_pk_mul_f32 v[62:63], v[70:71], v[62:63] op_sel:[0,1]
	s_waitcnt vmcnt(1)
	v_pk_fma_f32 v[40:41], v[40:41], v[68:69], v[44:45]
	v_pk_fma_f32 v[42:43], v[42:43], v[62:63], v[46:47]
	v_pk_mul_f32 v[40:41], v[40:41], s[44:45] op_sel_hi:[1,0]
	v_pk_mul_f32 v[42:43], v[42:43], s[44:45] op_sel_hi:[1,0]
	s_waitcnt vmcnt(0)
	v_pk_fma_f32 v[36:37], v[36:37], v[72:73], v[40:41]
	v_pk_fma_f32 v[38:39], v[38:39], v[74:75], v[42:43]
	global_store_dwordx4 v[76:77], v[36:39], off offset:512
	s_nop 0
	s_nop 0
	global_load_dwordx4 v[36:39], v[182:183], off
	global_load_dwordx4 v[40:43], v[184:185], off
	global_load_dwordx4 v[44:47], v[96:97], off offset:576
	s_waitcnt vmcnt(3)
	v_mov_b32_e32 v62, v128
	v_mov_b32_e32 v63, v129
	v_sub_f32_e32 v67, v67, v62
	v_sub_f32_e32 v66, v66, v62
	v_sub_f32_e32 v65, v65, v62
	v_sub_f32_e32 v64, v64, v62
	v_pk_mul_f32 v[64:65], v[64:65], v[62:63] op_sel:[0,1]
	v_pk_mul_f32 v[62:63], v[66:67], v[62:63] op_sel:[0,1]
	s_waitcnt vmcnt(1)
	v_pk_fma_f32 v[36:37], v[36:37], v[64:65], v[40:41]
	v_pk_fma_f32 v[38:39], v[38:39], v[62:63], v[42:43]
	v_pk_mul_f32 v[36:37], v[36:37], s[44:45] op_sel_hi:[1,0]
	v_pk_mul_f32 v[38:39], v[38:39], s[44:45] op_sel_hi:[1,0]
	s_waitcnt vmcnt(0)
	v_pk_fma_f32 v[32:33], v[32:33], v[44:45], v[36:37]
	v_pk_fma_f32 v[34:35], v[34:35], v[46:47], v[38:39]
	global_store_dwordx4 v[76:77], v[32:35], off offset:576
	global_load_dwordx2 v[46:47], v[78:79], off
	global_load_dwordx4 v[42:45], v[174:175], off
	global_load_dwordx4 v[62:65], v[176:177], off
	v_cndmask_b32_e64 v32, v104, 4, vcc
	v_mul_hi_i32_i24_e32 v33, 0x6000, v32
	v_mul_i32_i24_e32 v32, 0x6000, v32
	v_lshl_add_u64 v[32:33], s[0:1], 0, v[32:33]
	v_lshl_add_u64 v[80:81], v[32:33], 0, v[172:173]
	global_load_dwordx4 v[66:69], v[80:81], off
	v_mul_hi_i32 v32, v82, s67
	v_lshrrev_b32_e32 v33, 31, v32
	v_ashrrev_i32_e32 v32, 11, v32
	v_add_u32_e32 v88, v32, v33
	v_mad_i32_i24 v32, v88, s74, v82
	v_lshl_add_u32 v33, v88, 13, v215
	v_lshlrev_b32_e32 v34, 8, v88
	v_cmp_gt_i32_e32 vcc, s52, v32
	s_waitcnt vmcnt(3)
	v_mov_b32_e32 v128, v46
	v_mov_b32_e32 v129, v47
	v_sub_f32_e32 v85, v93, v46
	v_cndmask_b32_e32 v33, v33, v34, vcc
	v_add_u32_e32 v32, v33, v32
	v_sub_f32_e32 v84, v92, v46
	v_sub_f32_e32 v87, v91, v46
	v_sub_f32_e32 v86, v90, v46
	v_ashrrev_i32_e32 v33, 31, v32
	v_pk_mul_f32 v[86:87], v[86:87], v[46:47] op_sel:[0,1]
	v_pk_mul_f32 v[46:47], v[84:85], v[46:47] op_sel:[0,1]
	v_cndmask_b32_e32 v35, v216, v217, vcc
	v_cndmask_b32_e32 v34, v218, v219, vcc
	v_lshlrev_b64 v[32:33], 12, v[32:33]
	s_waitcnt vmcnt(1)
	v_pk_fma_f32 v[44:45], v[44:45], v[46:47], v[64:65]
	v_pk_fma_f32 v[42:43], v[42:43], v[86:87], v[62:63]
	v_lshl_add_u64 v[32:33], v[34:35], 0, v[32:33]
	v_pk_mul_f32 v[42:43], v[42:43], s[44:45] op_sel_hi:[1,0]
	v_pk_mul_f32 v[44:45], v[44:45], s[44:45] op_sel_hi:[1,0]
	v_lshl_add_u64 v[40:41], v[32:33], 0, v[172:173]
	s_waitcnt vmcnt(0)
	v_pk_fma_f32 v[30:31], v[30:31], v[68:69], v[44:45]
	v_pk_fma_f32 v[28:29], v[28:29], v[66:67], v[42:43]
	global_load_dwordx4 v[70:73], v[40:41], off
	global_load_dwordx4 v[74:77], v[40:41], off offset:64
	global_load_dwordx4 v[36:39], v[40:41], off offset:512
	global_load_dwordx4 v[32:35], v[40:41], off offset:576
	s_nop 0
	global_store_dwordx4 v[60:61], v[28:31], off
	s_nop 0
	s_nop 0
	global_load_dwordx4 v[28:31], v[124:125], off
	global_load_dwordx4 v[42:45], v[126:127], off
	global_load_dwordx4 v[62:65], v[80:81], off offset:64
	s_waitcnt vmcnt(3)
	v_mov_b32_e32 v46, v128
	v_mov_b32_e32 v47, v129
	v_sub_f32_e32 v59, v59, v46
	v_sub_f32_e32 v58, v58, v46
	v_sub_f32_e32 v57, v57, v46
	v_sub_f32_e32 v56, v56, v46
	v_pk_mul_f32 v[56:57], v[56:57], v[46:47] op_sel:[0,1]
	v_pk_mul_f32 v[46:47], v[58:59], v[46:47] op_sel:[0,1]
	s_waitcnt vmcnt(1)
	v_pk_fma_f32 v[28:29], v[28:29], v[56:57], v[42:43]
	v_pk_fma_f32 v[30:31], v[30:31], v[46:47], v[44:45]
	v_pk_mul_f32 v[28:29], v[28:29], s[44:45] op_sel_hi:[1,0]
	v_pk_mul_f32 v[30:31], v[30:31], s[44:45] op_sel_hi:[1,0]
	s_waitcnt vmcnt(0)
	v_pk_fma_f32 v[24:25], v[24:25], v[62:63], v[28:29]
	v_pk_fma_f32 v[26:27], v[26:27], v[64:65], v[30:31]
	global_store_dwordx4 v[60:61], v[24:27], off offset:64
	s_nop 0
	s_nop 0
	global_load_dwordx4 v[24:27], v[178:179], off
	global_load_dwordx4 v[28:31], v[180:181], off
	global_load_dwordx4 v[42:45], v[80:81], off offset:512
	s_waitcnt vmcnt(3)
	v_mov_b32_e32 v46, v128
	v_mov_b32_e32 v47, v129
	v_sub_f32_e32 v55, v55, v46
	v_sub_f32_e32 v54, v54, v46
	v_sub_f32_e32 v53, v53, v46
	v_sub_f32_e32 v52, v52, v46
	v_pk_mul_f32 v[52:53], v[52:53], v[46:47] op_sel:[0,1]
	v_pk_mul_f32 v[46:47], v[54:55], v[46:47] op_sel:[0,1]
	s_waitcnt vmcnt(1)
	v_pk_fma_f32 v[24:25], v[24:25], v[52:53], v[28:29]
	v_pk_fma_f32 v[26:27], v[26:27], v[46:47], v[30:31]
	v_pk_mul_f32 v[24:25], v[24:25], s[44:45] op_sel_hi:[1,0]
	v_pk_mul_f32 v[26:27], v[26:27], s[44:45] op_sel_hi:[1,0]
	s_waitcnt vmcnt(0)
	v_pk_fma_f32 v[20:21], v[20:21], v[42:43], v[24:25]
	v_pk_fma_f32 v[22:23], v[22:23], v[44:45], v[26:27]
	global_store_dwordx4 v[60:61], v[20:23], off offset:512
	s_nop 0
	s_nop 0
	global_load_dwordx4 v[20:23], v[182:183], off
	global_load_dwordx4 v[24:27], v[184:185], off
	global_load_dwordx4 v[28:31], v[80:81], off offset:576
	v_lshl_add_u64 v[44:45], v[82:83], 3, s[62:63]
	s_waitcnt vmcnt(3)
	v_mov_b32_e32 v42, v128
	v_mov_b32_e32 v43, v129
	v_sub_f32_e32 v47, v51, v42
	v_sub_f32_e32 v46, v50, v42
	v_sub_f32_e32 v49, v49, v42
	v_sub_f32_e32 v48, v48, v42
	v_pk_mul_f32 v[48:49], v[48:49], v[42:43] op_sel:[0,1]
	v_pk_mul_f32 v[42:43], v[46:47], v[42:43] op_sel:[0,1]
	s_waitcnt vmcnt(1)
	v_pk_fma_f32 v[20:21], v[20:21], v[48:49], v[24:25]
	v_pk_fma_f32 v[22:23], v[22:23], v[42:43], v[26:27]
	v_pk_mul_f32 v[20:21], v[20:21], s[44:45] op_sel_hi:[1,0]
	v_pk_mul_f32 v[22:23], v[22:23], s[44:45] op_sel_hi:[1,0]
	s_waitcnt vmcnt(0)
	v_pk_fma_f32 v[16:17], v[16:17], v[28:29], v[20:21]
	v_pk_fma_f32 v[18:19], v[18:19], v[30:31], v[22:23]
	global_store_dwordx4 v[60:61], v[16:19], off offset:576
	global_load_dwordx2 v[28:29], v[44:45], off
	v_cndmask_b32_e64 v24, v88, 4, vcc
	v_mul_hi_i32_i24_e32 v25, 0x6000, v24
	v_mul_i32_i24_e32 v24, 0x6000, v24
	global_load_dwordx4 v[16:19], v[174:175], off
	global_load_dwordx4 v[20:23], v[176:177], off
	v_lshl_add_u64 v[24:25], s[0:1], 0, v[24:25]
	v_lshl_add_u64 v[30:31], v[24:25], 0, v[172:173]
	global_load_dwordx4 v[24:27], v[30:31], off
	s_and_b64 vcc, exec, s[10:11]
	s_waitcnt vmcnt(3)
	v_mov_b32_e32 v128, v28
	v_mov_b32_e32 v129, v29
	v_sub_f32_e32 v43, v73, v28
	v_sub_f32_e32 v42, v72, v28
	v_sub_f32_e32 v47, v71, v28
	v_sub_f32_e32 v46, v70, v28
	v_pk_mul_f32 v[46:47], v[46:47], v[28:29] op_sel:[0,1]
	v_pk_mul_f32 v[28:29], v[42:43], v[28:29] op_sel:[0,1]
	s_waitcnt vmcnt(1)
	v_pk_fma_f32 v[16:17], v[16:17], v[46:47], v[20:21]
	v_pk_fma_f32 v[18:19], v[18:19], v[28:29], v[22:23]
	v_pk_mul_f32 v[16:17], v[16:17], s[44:45] op_sel_hi:[1,0]
	v_pk_mul_f32 v[18:19], v[18:19], s[44:45] op_sel_hi:[1,0]
	s_waitcnt vmcnt(0)
	v_pk_fma_f32 v[12:13], v[12:13], v[24:25], v[16:17]
	v_pk_fma_f32 v[14:15], v[14:15], v[26:27], v[18:19]
	global_store_dwordx4 v[40:41], v[12:15], off
	s_nop 0
	s_nop 0
	global_load_dwordx4 v[12:15], v[124:125], off
	global_load_dwordx4 v[16:19], v[126:127], off
	global_load_dwordx4 v[20:23], v[30:31], off offset:64
	s_waitcnt vmcnt(3)
	v_mov_b32_e32 v24, v128
	v_mov_b32_e32 v25, v129
	v_sub_f32_e32 v27, v77, v24
	v_sub_f32_e32 v26, v76, v24
	v_sub_f32_e32 v29, v75, v24
	v_sub_f32_e32 v28, v74, v24
	v_pk_mul_f32 v[28:29], v[28:29], v[24:25] op_sel:[0,1]
	v_pk_mul_f32 v[24:25], v[26:27], v[24:25] op_sel:[0,1]
	s_waitcnt vmcnt(1)
	v_pk_fma_f32 v[12:13], v[12:13], v[28:29], v[16:17]
	v_pk_fma_f32 v[14:15], v[14:15], v[24:25], v[18:19]
	v_pk_mul_f32 v[12:13], v[12:13], s[44:45] op_sel_hi:[1,0]
	v_pk_mul_f32 v[14:15], v[14:15], s[44:45] op_sel_hi:[1,0]
	s_waitcnt vmcnt(0)
	v_pk_fma_f32 v[8:9], v[8:9], v[20:21], v[12:13]
	v_pk_fma_f32 v[10:11], v[10:11], v[22:23], v[14:15]
	global_store_dwordx4 v[40:41], v[8:11], off offset:64
	s_nop 0
	s_nop 0
	global_load_dwordx4 v[8:11], v[178:179], off
	global_load_dwordx4 v[12:15], v[180:181], off
	global_load_dwordx4 v[16:19], v[30:31], off offset:512
	s_waitcnt vmcnt(3)
	v_mov_b32_e32 v20, v128
	v_mov_b32_e32 v21, v129
	v_sub_f32_e32 v23, v39, v20
	v_sub_f32_e32 v22, v38, v20
	v_sub_f32_e32 v25, v37, v20
	v_sub_f32_e32 v24, v36, v20
	v_pk_mul_f32 v[24:25], v[24:25], v[20:21] op_sel:[0,1]
	v_pk_mul_f32 v[20:21], v[22:23], v[20:21] op_sel:[0,1]
	s_waitcnt vmcnt(1)
	v_pk_fma_f32 v[8:9], v[8:9], v[24:25], v[12:13]
	v_pk_fma_f32 v[10:11], v[10:11], v[20:21], v[14:15]
	v_pk_mul_f32 v[8:9], v[8:9], s[44:45] op_sel_hi:[1,0]
	v_pk_mul_f32 v[10:11], v[10:11], s[44:45] op_sel_hi:[1,0]
	s_waitcnt vmcnt(0)
	v_pk_fma_f32 v[4:5], v[4:5], v[16:17], v[8:9]
	v_pk_fma_f32 v[6:7], v[6:7], v[18:19], v[10:11]
	global_store_dwordx4 v[40:41], v[4:7], off offset:512
	s_nop 0
	s_nop 0
	global_load_dwordx4 v[4:7], v[182:183], off
	global_load_dwordx4 v[8:11], v[184:185], off
	global_load_dwordx4 v[12:15], v[30:31], off offset:576
	s_waitcnt vmcnt(3)
	v_mov_b32_e32 v16, v128
	v_mov_b32_e32 v17, v129
	v_sub_f32_e32 v19, v35, v16
	v_sub_f32_e32 v18, v34, v16
	v_sub_f32_e32 v21, v33, v16
	v_sub_f32_e32 v20, v32, v16
	v_pk_mul_f32 v[20:21], v[20:21], v[16:17] op_sel:[0,1]
	v_pk_mul_f32 v[16:17], v[18:19], v[16:17] op_sel:[0,1]
	s_waitcnt vmcnt(1)
	v_pk_fma_f32 v[4:5], v[4:5], v[20:21], v[8:9]
	v_pk_fma_f32 v[6:7], v[6:7], v[16:17], v[10:11]
	v_pk_mul_f32 v[4:5], v[4:5], s[44:45] op_sel_hi:[1,0]
	v_pk_mul_f32 v[6:7], v[6:7], s[44:45] op_sel_hi:[1,0]
	s_waitcnt vmcnt(0)
	v_pk_fma_f32 v[0:1], v[0:1], v[12:13], v[4:5]
	v_pk_fma_f32 v[2:3], v[2:3], v[14:15], v[6:7]
	global_store_dwordx4 v[40:41], v[0:3], off offset:576
	s_cbranch_vccnz .LBB0_1982
	s_andn2_b64 vcc, exec, s[38:39]
	s_cbranch_vccnz .LBB0_1981
	s_barrier
	s_branch .LBB0_1981

.LBB0_2804:
	v_lshl_add_u32 v184, s42, 8, v153
	v_mul_hi_i32 v128, v184, s61
	v_lshrrev_b32_e32 v129, 31, v128
	v_ashrrev_i32_e32 v128, 11, v128
	v_add_u32_e32 v132, v128, v129
	v_mad_i32_i24 v128, v132, s64, v184
	v_lshl_add_u32 v129, v132, 13, v211
	v_lshlrev_b32_e32 v130, 8, v132
	v_cmp_gt_i32_e32 vcc, s43, v128
	v_lshl_or_b32 v228, s65, 8, v193
	v_mov_b32_e32 v212, s89
	v_cndmask_b32_e32 v129, v129, v130, vcc
	v_add_u32_e32 v128, v129, v128
	v_mov_b32_e32 v213, s71
	v_mov_b32_e32 v214, s88
	v_mov_b32_e32 v215, s70
	v_ashrrev_i32_e32 v129, 31, v128
	v_cndmask_b32_e32 v131, v212, v213, vcc
	v_cndmask_b32_e32 v130, v214, v215, vcc
	v_lshlrev_b64 v[128:129], 12, v[128:129]
	v_ashrrev_i32_e32 v229, 31, v228
	v_lshl_add_u64 v[128:129], v[130:131], 0, v[128:129]
	v_lshlrev_b64 v[170:171], 2, v[228:229]
	v_ashrrev_i32_e32 v185, 31, v184
	v_lshl_add_u64 v[190:191], v[128:129], 0, v[170:171]
	v_lshl_add_u64 v[186:187], v[184:185], 3, s[62:63]
	global_load_dwordx4 v[176:179], v[190:191], off
	global_load_dwordx4 v[224:227], v[190:191], off offset:64
	global_load_dwordx2 v[230:231], v[186:187], off
	v_cndmask_b32_e64 v128, v132, 4, vcc
	v_mul_hi_i32_i24_e32 v129, 0x6000, v128
	v_lshl_add_u64 v[172:173], s[12:13], 0, v[170:171]
	v_lshl_add_u64 v[174:175], s[14:15], 0, v[170:171]
	v_mul_i32_i24_e32 v128, 0x6000, v128
	global_load_dwordx4 v[180:183], v[172:173], off
	global_load_dwordx4 v[216:219], v[174:175], off
	v_lshl_add_u64 v[128:129], s[0:1], 0, v[128:129]
	v_lshl_add_u64 v[232:233], v[128:129], 0, v[170:171]
	global_load_dwordx4 v[220:223], v[232:233], off
	v_or_b32_e32 v236, 16, v184
	v_mul_hi_i32 v128, v236, s61
	v_lshrrev_b32_e32 v129, 31, v128
	v_ashrrev_i32_e32 v128, 11, v128
	v_add_u32_e32 v185, v128, v129
	v_mad_i32_i24 v128, v185, s64, v236
	v_lshl_add_u32 v129, v185, 13, v211
	v_lshlrev_b32_e32 v130, 8, v185
	v_cmp_gt_i32_e32 vcc, s43, v128
	v_or_b32_e32 v234, 16, v228
	v_ashrrev_i32_e32 v235, 31, v234
	v_cndmask_b32_e32 v129, v129, v130, vcc
	v_add_u32_e32 v128, v129, v128
	v_ashrrev_i32_e32 v129, 31, v128
	v_cndmask_b32_e32 v131, v212, v213, vcc
	v_cndmask_b32_e32 v130, v214, v215, vcc
	v_lshlrev_b64 v[128:129], 12, v[128:129]
	v_lshl_add_u64 v[128:129], v[130:131], 0, v[128:129]
	v_lshl_add_u64 v[188:189], v[128:129], 0, v[170:171]
	global_load_dwordx4 v[140:143], v[188:189], off
	global_load_dwordx4 v[136:139], v[188:189], off offset:64
	global_load_dwordx4 v[132:135], v[188:189], off offset:512
	global_load_dwordx4 v[128:131], v[188:189], off offset:576
	v_ashrrev_i32_e32 v237, 31, v236
	v_or_b32_e32 v238, 32, v184
	v_ashrrev_i32_e32 v239, 31, v238
	v_readlane_b32 s66, v255, 41
	s_mov_b64 s[4:5], -1
	v_readlane_b32 s67, v255, 42
	s_waitcnt vmcnt(0)
	v_sub_f32_e32 v179, v179, v230
	v_sub_f32_e32 v178, v178, v230
	v_sub_f32_e32 v177, v177, v230
	v_sub_f32_e32 v176, v176, v230
	v_pk_mul_f32 v[176:177], v[176:177], v[230:231] op_sel:[0,1]
	v_pk_mul_f32 v[178:179], v[178:179], v[230:231] op_sel:[0,1]
	v_pk_fma_f32 v[176:177], v[180:181], v[176:177], v[216:217]
	v_pk_fma_f32 v[178:179], v[182:183], v[178:179], v[218:219]
	v_pk_mul_f32 v[176:177], v[176:177], s[22:23] op_sel_hi:[1,0]
	v_pk_mul_f32 v[178:179], v[178:179], s[22:23] op_sel_hi:[1,0]
	v_pk_fma_f32 v[124:125], v[124:125], v[220:221], v[176:177]
	v_pk_fma_f32 v[126:127], v[126:127], v[222:223], v[178:179]
	global_store_dwordx4 v[190:191], v[124:127], off
	s_nop 0
	s_waitcnt vmcnt(1)
	v_sub_f32_e32 v227, v227, v230
	v_lshlrev_b64 v[126:127], 2, v[234:235]
	v_lshl_add_u64 v[124:125], s[12:13], 0, v[126:127]
	v_lshl_add_u64 v[126:127], s[14:15], 0, v[126:127]
	global_load_dwordx4 v[176:179], v[124:125], off
	global_load_dwordx4 v[180:183], v[126:127], off
	global_load_dwordx4 v[216:219], v[232:233], off offset:64
	v_sub_f32_e32 v226, v226, v230
	v_sub_f32_e32 v225, v225, v230
	v_sub_f32_e32 v224, v224, v230
	v_pk_mul_f32 v[224:225], v[224:225], v[230:231] op_sel:[0,1]
	v_pk_mul_f32 v[226:227], v[226:227], v[230:231] op_sel:[0,1]
	v_or_b32_e32 v234, 0x80, v228
	global_load_dwordx4 v[220:223], v[190:191], off offset:512
	v_ashrrev_i32_e32 v235, 31, v234
	v_or_b32_e32 v228, 0x90, v228
	v_ashrrev_i32_e32 v229, 31, v228
	s_waitcnt vmcnt(2)
	v_pk_fma_f32 v[178:179], v[178:179], v[226:227], v[182:183]
	v_pk_fma_f32 v[176:177], v[176:177], v[224:225], v[180:181]
	v_pk_mul_f32 v[178:179], v[178:179], s[22:23] op_sel_hi:[1,0]
	v_pk_mul_f32 v[176:177], v[176:177], s[22:23] op_sel_hi:[1,0]
	s_waitcnt vmcnt(1)
	v_pk_fma_f32 v[122:123], v[122:123], v[218:219], v[178:179]
	v_pk_fma_f32 v[120:121], v[120:121], v[216:217], v[176:177]
	global_store_dwordx4 v[190:191], v[120:123], off offset:64
	s_nop 0
	s_waitcnt vmcnt(1)
	v_sub_f32_e32 v223, v223, v230
	v_lshlrev_b64 v[120:121], 2, v[234:235]
	v_lshl_add_u64 v[176:177], s[12:13], 0, v[120:121]
	v_lshl_add_u64 v[178:179], s[14:15], 0, v[120:121]
	global_load_dwordx4 v[120:123], v[176:177], off
	global_load_dwordx4 v[180:183], v[178:179], off
	global_load_dwordx4 v[216:219], v[232:233], off offset:512
	v_sub_f32_e32 v222, v222, v230
	v_sub_f32_e32 v221, v221, v230
	v_sub_f32_e32 v220, v220, v230
	v_pk_mul_f32 v[220:221], v[220:221], v[230:231] op_sel:[0,1]
	v_pk_mul_f32 v[222:223], v[222:223], v[230:231] op_sel:[0,1]
	global_load_dwordx4 v[224:227], v[190:191], off offset:576
	s_waitcnt vmcnt(2)
	v_pk_fma_f32 v[122:123], v[122:123], v[222:223], v[182:183]
	v_pk_fma_f32 v[120:121], v[120:121], v[220:221], v[180:181]
	v_pk_mul_f32 v[122:123], v[122:123], s[22:23] op_sel_hi:[1,0]
	v_pk_mul_f32 v[120:121], v[120:121], s[22:23] op_sel_hi:[1,0]
	s_waitcnt vmcnt(1)
	v_pk_fma_f32 v[118:119], v[118:119], v[218:219], v[122:123]
	v_pk_fma_f32 v[116:117], v[116:117], v[216:217], v[120:121]
	global_store_dwordx4 v[190:191], v[116:119], off offset:512
	s_nop 0
	s_waitcnt vmcnt(1)
	v_mov_b32_e32 v220, v230
	v_mov_b32_e32 v221, v231
	v_sub_f32_e32 v223, v227, v220
	v_lshlrev_b64 v[116:117], 2, v[228:229]
	v_lshl_add_u64 v[180:181], s[12:13], 0, v[116:117]
	v_lshl_add_u64 v[182:183], s[14:15], 0, v[116:117]
	global_load_dwordx4 v[116:119], v[180:181], off
	global_load_dwordx4 v[120:123], v[182:183], off
	global_load_dwordx4 v[216:219], v[232:233], off offset:576
	v_sub_f32_e32 v222, v226, v220
	v_sub_f32_e32 v225, v225, v220
	v_sub_f32_e32 v224, v224, v220
	v_pk_mul_f32 v[224:225], v[224:225], v[220:221] op_sel:[0,1]
	v_pk_mul_f32 v[220:221], v[222:223], v[220:221] op_sel:[0,1]
	v_lshl_add_u64 v[232:233], v[236:237], 3, s[62:63]
	s_waitcnt vmcnt(1)
	v_pk_fma_f32 v[118:119], v[118:119], v[220:221], v[122:123]
	v_pk_fma_f32 v[116:117], v[116:117], v[224:225], v[120:121]
	v_pk_mul_f32 v[118:119], v[118:119], s[22:23] op_sel_hi:[1,0]
	v_pk_mul_f32 v[116:117], v[116:117], s[22:23] op_sel_hi:[1,0]
	s_waitcnt vmcnt(0)
	v_pk_fma_f32 v[114:115], v[114:115], v[218:219], v[118:119]
	v_pk_fma_f32 v[112:113], v[112:113], v[216:217], v[116:117]
	global_store_dwordx4 v[190:191], v[112:115], off offset:576
	global_load_dwordx2 v[234:235], v[232:233], off
	global_load_dwordx4 v[216:219], v[172:173], off
	global_load_dwordx4 v[220:223], v[174:175], off
	v_cndmask_b32_e64 v112, v185, 4, vcc
	v_mul_hi_i32_i24_e32 v113, 0x6000, v112
	v_mul_i32_i24_e32 v112, 0x6000, v112
	v_lshl_add_u64 v[112:113], s[0:1], 0, v[112:113]
	v_lshl_add_u64 v[236:237], v[112:113], 0, v[170:171]
	global_load_dwordx4 v[224:227], v[236:237], off
	v_mul_hi_i32 v112, v238, s61
	v_lshrrev_b32_e32 v113, 31, v112
	v_ashrrev_i32_e32 v112, 11, v112
	v_add_u32_e32 v185, v112, v113
	v_mad_i32_i24 v112, v185, s64, v238
	v_lshl_add_u32 v113, v185, 13, v211
	v_lshlrev_b32_e32 v114, 8, v185
	v_cmp_gt_i32_e32 vcc, s43, v112
	s_waitcnt vmcnt(3)
	v_sub_f32_e32 v143, v143, v234
	v_cndmask_b32_e32 v113, v113, v114, vcc
	v_add_u32_e32 v112, v113, v112
	v_sub_f32_e32 v142, v142, v234
	v_sub_f32_e32 v141, v141, v234
	v_sub_f32_e32 v140, v140, v234
	v_ashrrev_i32_e32 v113, 31, v112
	v_pk_mul_f32 v[140:141], v[140:141], v[234:235] op_sel:[0,1]
	v_pk_mul_f32 v[142:143], v[142:143], v[234:235] op_sel:[0,1]
	v_cndmask_b32_e32 v115, v212, v213, vcc
	v_cndmask_b32_e32 v114, v214, v215, vcc
	v_lshlrev_b64 v[112:113], 12, v[112:113]
	s_waitcnt vmcnt(1)
	v_pk_fma_f32 v[142:143], v[218:219], v[142:143], v[222:223]
	v_pk_fma_f32 v[140:141], v[216:217], v[140:141], v[220:221]
	v_lshl_add_u64 v[112:113], v[114:115], 0, v[112:113]
	v_pk_mul_f32 v[140:141], v[140:141], s[22:23] op_sel_hi:[1,0]
	v_pk_mul_f32 v[142:143], v[142:143], s[22:23] op_sel_hi:[1,0]
	v_lshl_add_u64 v[190:191], v[112:113], 0, v[170:171]
	s_waitcnt vmcnt(0)
	v_pk_fma_f32 v[110:111], v[110:111], v[226:227], v[142:143]
	v_pk_fma_f32 v[108:109], v[108:109], v[224:225], v[140:141]
	global_load_dwordx4 v[228:231], v[190:191], off
	global_load_dwordx4 v[120:123], v[190:191], off offset:64
	global_load_dwordx4 v[116:119], v[190:191], off offset:512
	global_load_dwordx4 v[112:115], v[190:191], off offset:576
	s_nop 0
	global_store_dwordx4 v[188:189], v[108:111], off
	s_nop 0
	s_nop 0
	global_load_dwordx4 v[108:111], v[124:125], off
	global_load_dwordx4 v[140:143], v[126:127], off
	global_load_dwordx4 v[216:219], v[236:237], off offset:64
	s_waitcnt vmcnt(3)
	v_mov_b32_e32 v220, v234
	v_mov_b32_e32 v221, v235
	v_sub_f32_e32 v139, v139, v220
	v_sub_f32_e32 v138, v138, v220
	v_sub_f32_e32 v137, v137, v220
	v_sub_f32_e32 v136, v136, v220
	v_pk_mul_f32 v[136:137], v[136:137], v[220:221] op_sel:[0,1]
	v_pk_mul_f32 v[138:139], v[138:139], v[220:221] op_sel:[0,1]
	s_waitcnt vmcnt(1)
	v_pk_fma_f32 v[108:109], v[108:109], v[136:137], v[140:141]
	v_pk_fma_f32 v[110:111], v[110:111], v[138:139], v[142:143]
	v_pk_mul_f32 v[108:109], v[108:109], s[22:23] op_sel_hi:[1,0]
	v_pk_mul_f32 v[110:111], v[110:111], s[22:23] op_sel_hi:[1,0]
	s_waitcnt vmcnt(0)
	v_pk_fma_f32 v[104:105], v[104:105], v[216:217], v[108:109]
	v_pk_fma_f32 v[106:107], v[106:107], v[218:219], v[110:111]
	global_store_dwordx4 v[188:189], v[104:107], off offset:64
	s_nop 0
	s_nop 0
	global_load_dwordx4 v[104:107], v[176:177], off
	global_load_dwordx4 v[108:111], v[178:179], off
	global_load_dwordx4 v[136:139], v[236:237], off offset:512
	v_lshl_add_u64 v[216:217], v[238:239], 3, s[62:63]
	v_or_b32_e32 v218, 48, v184
	v_ashrrev_i32_e32 v219, 31, v218
	s_waitcnt vmcnt(3)
	v_mov_b32_e32 v140, v234
	v_mov_b32_e32 v141, v235
	v_sub_f32_e32 v135, v135, v140
	v_sub_f32_e32 v134, v134, v140
	v_sub_f32_e32 v133, v133, v140
	v_sub_f32_e32 v132, v132, v140
	v_pk_mul_f32 v[132:133], v[132:133], v[140:141] op_sel:[0,1]
	v_pk_mul_f32 v[134:135], v[134:135], v[140:141] op_sel:[0,1]
	s_waitcnt vmcnt(1)
	v_pk_fma_f32 v[104:105], v[104:105], v[132:133], v[108:109]
	v_pk_fma_f32 v[106:107], v[106:107], v[134:135], v[110:111]
	v_pk_mul_f32 v[104:105], v[104:105], s[22:23] op_sel_hi:[1,0]
	v_pk_mul_f32 v[106:107], v[106:107], s[22:23] op_sel_hi:[1,0]
	s_waitcnt vmcnt(0)
	v_pk_fma_f32 v[100:101], v[100:101], v[136:137], v[104:105]
	v_pk_fma_f32 v[102:103], v[102:103], v[138:139], v[106:107]
	global_store_dwordx4 v[188:189], v[100:103], off offset:512
	s_nop 0
	s_nop 0
	global_load_dwordx4 v[100:103], v[180:181], off
	global_load_dwordx4 v[104:107], v[182:183], off
	global_load_dwordx4 v[108:111], v[236:237], off offset:576
	s_waitcnt vmcnt(3)
	v_mov_b32_e32 v132, v234
	v_mov_b32_e32 v133, v235
	v_sub_f32_e32 v131, v131, v132
	v_sub_f32_e32 v130, v130, v132
	v_sub_f32_e32 v129, v129, v132
	v_sub_f32_e32 v128, v128, v132
	v_pk_mul_f32 v[128:129], v[128:129], v[132:133] op_sel:[0,1]
	v_pk_mul_f32 v[130:131], v[130:131], v[132:133] op_sel:[0,1]
	s_waitcnt vmcnt(1)
	v_pk_fma_f32 v[100:101], v[100:101], v[128:129], v[104:105]
	v_pk_fma_f32 v[102:103], v[102:103], v[130:131], v[106:107]
	v_pk_mul_f32 v[100:101], v[100:101], s[22:23] op_sel_hi:[1,0]
	v_pk_mul_f32 v[102:103], v[102:103], s[22:23] op_sel_hi:[1,0]
	s_waitcnt vmcnt(0)
	v_pk_fma_f32 v[96:97], v[96:97], v[108:109], v[100:101]
	v_pk_fma_f32 v[98:99], v[98:99], v[110:111], v[102:103]
	global_store_dwordx4 v[188:189], v[96:99], off offset:576
	global_load_dwordx2 v[110:111], v[216:217], off
	global_load_dwordx4 v[128:131], v[172:173], off
	global_load_dwordx4 v[132:135], v[174:175], off
	v_cndmask_b32_e64 v96, v185, 4, vcc
	v_mul_hi_i32_i24_e32 v97, 0x6000, v96
	v_mul_i32_i24_e32 v96, 0x6000, v96
	v_lshl_add_u64 v[96:97], s[0:1], 0, v[96:97]
	v_lshl_add_u64 v[188:189], v[96:97], 0, v[170:171]
	global_load_dwordx4 v[136:139], v[188:189], off
	v_mul_hi_i32 v96, v218, s61
	v_lshrrev_b32_e32 v97, 31, v96
	v_ashrrev_i32_e32 v96, 11, v96
	v_add_u32_e32 v185, v96, v97
	v_mad_i32_i24 v96, v185, s64, v218
	v_lshl_add_u32 v97, v185, 13, v211
	v_lshlrev_b32_e32 v98, 8, v185
	v_cmp_gt_i32_e32 vcc, s43, v96
	s_waitcnt vmcnt(3)
	v_mov_b32_e32 v224, v110
	v_mov_b32_e32 v225, v111
	v_sub_f32_e32 v221, v231, v110
	v_cndmask_b32_e32 v97, v97, v98, vcc
	v_add_u32_e32 v96, v97, v96
	v_sub_f32_e32 v220, v230, v110
	v_sub_f32_e32 v223, v229, v110
	v_sub_f32_e32 v222, v228, v110
	v_ashrrev_i32_e32 v97, 31, v96
	v_pk_mul_f32 v[222:223], v[222:223], v[110:111] op_sel:[0,1]
	v_pk_mul_f32 v[110:111], v[220:221], v[110:111] op_sel:[0,1]
	v_cndmask_b32_e32 v99, v212, v213, vcc
	v_cndmask_b32_e32 v98, v214, v215, vcc
	v_lshlrev_b64 v[96:97], 12, v[96:97]
	s_waitcnt vmcnt(1)
	v_pk_fma_f32 v[110:111], v[130:131], v[110:111], v[134:135]
	v_pk_fma_f32 v[128:129], v[128:129], v[222:223], v[132:133]
	v_lshl_add_u64 v[96:97], v[98:99], 0, v[96:97]
	v_pk_mul_f32 v[128:129], v[128:129], s[22:23] op_sel_hi:[1,0]
	v_pk_mul_f32 v[110:111], v[110:111], s[22:23] op_sel_hi:[1,0]
	v_lshl_add_u64 v[108:109], v[96:97], 0, v[170:171]
	s_waitcnt vmcnt(0)
	v_pk_fma_f32 v[94:95], v[94:95], v[138:139], v[110:111]
	v_pk_fma_f32 v[92:93], v[92:93], v[136:137], v[128:129]
	global_load_dwordx4 v[140:143], v[108:109], off
	global_load_dwordx4 v[104:107], v[108:109], off offset:64
	global_load_dwordx4 v[100:103], v[108:109], off offset:512
	global_load_dwordx4 v[96:99], v[108:109], off offset:576
	s_nop 0
	global_store_dwordx4 v[190:191], v[92:95], off
	s_nop 0
	s_nop 0
	global_load_dwordx4 v[92:95], v[124:125], off
	global_load_dwordx4 v[128:131], v[126:127], off
	global_load_dwordx4 v[132:135], v[188:189], off offset:64
	s_waitcnt vmcnt(3)
	v_mov_b32_e32 v110, v224
	v_mov_b32_e32 v111, v225
	v_sub_f32_e32 v123, v123, v110
	v_sub_f32_e32 v122, v122, v110
	v_sub_f32_e32 v121, v121, v110
	v_sub_f32_e32 v120, v120, v110
	v_pk_mul_f32 v[120:121], v[120:121], v[110:111] op_sel:[0,1]
	v_pk_mul_f32 v[110:111], v[122:123], v[110:111] op_sel:[0,1]
	s_waitcnt vmcnt(1)
	v_pk_fma_f32 v[92:93], v[92:93], v[120:121], v[128:129]
	v_pk_fma_f32 v[94:95], v[94:95], v[110:111], v[130:131]
	v_pk_mul_f32 v[92:93], v[92:93], s[22:23] op_sel_hi:[1,0]
	v_pk_mul_f32 v[94:95], v[94:95], s[22:23] op_sel_hi:[1,0]
	s_waitcnt vmcnt(0)
	v_pk_fma_f32 v[88:89], v[88:89], v[132:133], v[92:93]
	v_pk_fma_f32 v[90:91], v[90:91], v[134:135], v[94:95]
	global_store_dwordx4 v[190:191], v[88:91], off offset:64
	s_nop 0
	s_nop 0
	global_load_dwordx4 v[88:91], v[176:177], off
	global_load_dwordx4 v[92:95], v[178:179], off
	global_load_dwordx4 v[120:123], v[188:189], off offset:512
	s_waitcnt vmcnt(3)
	v_mov_b32_e32 v110, v224
	v_mov_b32_e32 v111, v225
	v_sub_f32_e32 v119, v119, v110
	v_sub_f32_e32 v118, v118, v110
	v_sub_f32_e32 v117, v117, v110
	v_sub_f32_e32 v116, v116, v110
	v_pk_mul_f32 v[116:117], v[116:117], v[110:111] op_sel:[0,1]
	v_pk_mul_f32 v[110:111], v[118:119], v[110:111] op_sel:[0,1]
	s_waitcnt vmcnt(1)
	v_pk_fma_f32 v[88:89], v[88:89], v[116:117], v[92:93]
	v_pk_fma_f32 v[90:91], v[90:91], v[110:111], v[94:95]
	v_pk_mul_f32 v[88:89], v[88:89], s[22:23] op_sel_hi:[1,0]
	v_pk_mul_f32 v[90:91], v[90:91], s[22:23] op_sel_hi:[1,0]
	s_waitcnt vmcnt(0)
	v_pk_fma_f32 v[84:85], v[84:85], v[120:121], v[88:89]
	v_pk_fma_f32 v[86:87], v[86:87], v[122:123], v[90:91]
	global_store_dwordx4 v[190:191], v[84:87], off offset:512
	s_nop 0
	s_nop 0
	global_load_dwordx4 v[84:87], v[180:181], off
	global_load_dwordx4 v[88:91], v[182:183], off
	global_load_dwordx4 v[92:95], v[188:189], off offset:576
	v_lshl_add_u64 v[122:123], v[218:219], 3, s[62:63]
	s_waitcnt vmcnt(3)
	v_mov_b32_e32 v110, v224
	v_mov_b32_e32 v111, v225
	v_sub_f32_e32 v115, v115, v110
	v_sub_f32_e32 v114, v114, v110
	v_sub_f32_e32 v113, v113, v110
	v_sub_f32_e32 v112, v112, v110
	v_pk_mul_f32 v[112:113], v[112:113], v[110:111] op_sel:[0,1]
	v_pk_mul_f32 v[110:111], v[114:115], v[110:111] op_sel:[0,1]
	s_waitcnt vmcnt(1)
	v_pk_fma_f32 v[84:85], v[84:85], v[112:113], v[88:89]
	v_pk_fma_f32 v[86:87], v[86:87], v[110:111], v[90:91]
	v_pk_mul_f32 v[84:85], v[84:85], s[22:23] op_sel_hi:[1,0]
	v_pk_mul_f32 v[86:87], v[86:87], s[22:23] op_sel_hi:[1,0]
	s_waitcnt vmcnt(0)
	v_pk_fma_f32 v[80:81], v[80:81], v[92:93], v[84:85]
	v_pk_fma_f32 v[82:83], v[82:83], v[94:95], v[86:87]
	global_store_dwordx4 v[190:191], v[80:83], off offset:576
	global_load_dwordx2 v[94:95], v[122:123], off
	global_load_dwordx4 v[110:113], v[172:173], off
	global_load_dwordx4 v[114:117], v[174:175], off
	v_cndmask_b32_e64 v80, v185, 4, vcc
	v_mul_hi_i32_i24_e32 v81, 0x6000, v80
	v_mul_i32_i24_e32 v80, 0x6000, v80
	v_lshl_add_u64 v[80:81], s[0:1], 0, v[80:81]
	v_lshl_add_u64 v[132:133], v[80:81], 0, v[170:171]
	global_load_dwordx4 v[118:121], v[132:133], off
	v_add_u32_e32 v80, 0x80, v184
	v_mul_hi_i32 v81, v80, s61
	v_lshrrev_b32_e32 v82, 31, v81
	v_ashrrev_i32_e32 v81, 11, v81
	v_add_u32_e32 v138, v81, v82
	v_mad_i32_i24 v80, v138, s64, v80
	v_lshl_add_u32 v81, v138, 13, v211
	v_lshlrev_b32_e32 v82, 8, v138
	v_cmp_gt_i32_e32 vcc, s43, v80
	s_waitcnt vmcnt(3)
	v_mov_b32_e32 v188, v94
	v_mov_b32_e32 v189, v95
	v_sub_f32_e32 v135, v143, v94
	v_cndmask_b32_e32 v81, v81, v82, vcc
	v_add_u32_e32 v80, v81, v80
	v_sub_f32_e32 v134, v142, v94
	v_sub_f32_e32 v137, v141, v94
	v_sub_f32_e32 v136, v140, v94
	v_ashrrev_i32_e32 v81, 31, v80
	v_pk_mul_f32 v[136:137], v[136:137], v[94:95] op_sel:[0,1]
	v_pk_mul_f32 v[94:95], v[134:135], v[94:95] op_sel:[0,1]
	v_cndmask_b32_e32 v83, v212, v213, vcc
	v_cndmask_b32_e32 v82, v214, v215, vcc
	v_lshlrev_b64 v[80:81], 12, v[80:81]
	s_waitcnt vmcnt(1)
	v_pk_fma_f32 v[94:95], v[112:113], v[94:95], v[116:117]
	v_pk_fma_f32 v[110:111], v[110:111], v[136:137], v[114:115]
	v_lshl_add_u64 v[80:81], v[82:83], 0, v[80:81]
	v_pk_mul_f32 v[110:111], v[110:111], s[22:23] op_sel_hi:[1,0]
	v_pk_mul_f32 v[94:95], v[94:95], s[22:23] op_sel_hi:[1,0]
	v_lshl_add_u64 v[92:93], v[80:81], 0, v[170:171]
	s_waitcnt vmcnt(0)
	v_pk_fma_f32 v[78:79], v[78:79], v[120:121], v[94:95]
	v_pk_fma_f32 v[76:77], v[76:77], v[118:119], v[110:111]
	global_load_dwordx4 v[128:131], v[92:93], off
	global_load_dwordx4 v[88:91], v[92:93], off offset:64
	global_load_dwordx4 v[84:87], v[92:93], off offset:512
	global_load_dwordx4 v[80:83], v[92:93], off offset:576
	s_nop 0
	global_store_dwordx4 v[108:109], v[76:79], off
	s_nop 0
	s_nop 0
	global_load_dwordx4 v[76:79], v[124:125], off
	global_load_dwordx4 v[110:113], v[126:127], off
	global_load_dwordx4 v[114:117], v[132:133], off offset:64
	s_waitcnt vmcnt(3)
	v_mov_b32_e32 v94, v188
	v_mov_b32_e32 v95, v189
	v_sub_f32_e32 v107, v107, v94
	v_sub_f32_e32 v106, v106, v94
	v_sub_f32_e32 v105, v105, v94
	v_sub_f32_e32 v104, v104, v94
	v_pk_mul_f32 v[104:105], v[104:105], v[94:95] op_sel:[0,1]
	v_pk_mul_f32 v[94:95], v[106:107], v[94:95] op_sel:[0,1]
	s_waitcnt vmcnt(1)
	v_pk_fma_f32 v[76:77], v[76:77], v[104:105], v[110:111]
	v_pk_fma_f32 v[78:79], v[78:79], v[94:95], v[112:113]
	v_pk_mul_f32 v[76:77], v[76:77], s[22:23] op_sel_hi:[1,0]
	v_pk_mul_f32 v[78:79], v[78:79], s[22:23] op_sel_hi:[1,0]
	s_waitcnt vmcnt(0)
	v_pk_fma_f32 v[72:73], v[72:73], v[114:115], v[76:77]
	v_pk_fma_f32 v[74:75], v[74:75], v[116:117], v[78:79]
	global_store_dwordx4 v[108:109], v[72:75], off offset:64
	s_nop 0
	s_nop 0
	global_load_dwordx4 v[72:75], v[176:177], off
	global_load_dwordx4 v[76:79], v[178:179], off
	global_load_dwordx4 v[104:107], v[132:133], off offset:512
	v_add_u32_e32 v112, 0x90, v184
	v_ashrrev_i32_e32 v113, 31, v112
	s_waitcnt vmcnt(3)
	v_mov_b32_e32 v94, v188
	v_mov_b32_e32 v95, v189
	v_sub_f32_e32 v103, v103, v94
	v_sub_f32_e32 v102, v102, v94
	v_sub_f32_e32 v101, v101, v94
	v_sub_f32_e32 v100, v100, v94
	v_pk_mul_f32 v[100:101], v[100:101], v[94:95] op_sel:[0,1]
	v_pk_mul_f32 v[94:95], v[102:103], v[94:95] op_sel:[0,1]
	s_waitcnt vmcnt(1)
	v_pk_fma_f32 v[72:73], v[72:73], v[100:101], v[76:77]
	v_pk_fma_f32 v[74:75], v[74:75], v[94:95], v[78:79]
	v_pk_mul_f32 v[72:73], v[72:73], s[22:23] op_sel_hi:[1,0]
	v_pk_mul_f32 v[74:75], v[74:75], s[22:23] op_sel_hi:[1,0]
	s_waitcnt vmcnt(0)
	v_pk_fma_f32 v[68:69], v[68:69], v[104:105], v[72:73]
	v_pk_fma_f32 v[70:71], v[70:71], v[106:107], v[74:75]
	global_store_dwordx4 v[108:109], v[68:71], off offset:512
	s_nop 0
	s_nop 0
	global_load_dwordx4 v[68:71], v[180:181], off
	global_load_dwordx4 v[72:75], v[182:183], off
	global_load_dwordx4 v[76:79], v[132:133], off offset:576
	s_waitcnt vmcnt(3)
	v_mov_b32_e32 v94, v188
	v_mov_b32_e32 v95, v189
	v_sub_f32_e32 v99, v99, v94
	v_sub_f32_e32 v98, v98, v94
	v_sub_f32_e32 v97, v97, v94
	v_sub_f32_e32 v96, v96, v94
	v_pk_mul_f32 v[96:97], v[96:97], v[94:95] op_sel:[0,1]
	v_pk_mul_f32 v[94:95], v[98:99], v[94:95] op_sel:[0,1]
	s_waitcnt vmcnt(1)
	v_pk_fma_f32 v[68:69], v[68:69], v[96:97], v[72:73]
	v_pk_fma_f32 v[70:71], v[70:71], v[94:95], v[74:75]
	v_pk_mul_f32 v[68:69], v[68:69], s[22:23] op_sel_hi:[1,0]
	v_pk_mul_f32 v[70:71], v[70:71], s[22:23] op_sel_hi:[1,0]
	s_waitcnt vmcnt(0)
	v_pk_fma_f32 v[64:65], v[64:65], v[76:77], v[68:69]
	v_pk_fma_f32 v[66:67], v[66:67], v[78:79], v[70:71]
	global_store_dwordx4 v[108:109], v[64:67], off offset:576
	global_load_dwordx2 v[78:79], v[186:187], off offset:1024
	global_load_dwordx4 v[94:97], v[172:173], off
	global_load_dwordx4 v[98:101], v[174:175], off
	v_cndmask_b32_e64 v64, v138, 4, vcc
	v_mul_hi_i32_i24_e32 v65, 0x6000, v64
	v_mul_i32_i24_e32 v64, 0x6000, v64
	v_lshl_add_u64 v[64:65], s[0:1], 0, v[64:65]
	v_lshl_add_u64 v[110:111], v[64:65], 0, v[170:171]
	global_load_dwordx4 v[102:105], v[110:111], off
	v_mul_hi_i32 v64, v112, s61
	v_lshrrev_b32_e32 v65, 31, v64
	v_ashrrev_i32_e32 v64, 11, v64
	v_add_u32_e32 v118, v64, v65
	v_mad_i32_i24 v64, v118, s64, v112
	v_lshl_add_u32 v65, v118, 13, v211
	v_lshlrev_b32_e32 v66, 8, v118
	v_cmp_gt_i32_e32 vcc, s43, v64
	s_waitcnt vmcnt(3)
	v_sub_f32_e32 v115, v131, v78
	v_cndmask_b32_e32 v65, v65, v66, vcc
	v_add_u32_e32 v64, v65, v64
	v_sub_f32_e32 v114, v130, v78
	v_sub_f32_e32 v117, v129, v78
	v_sub_f32_e32 v116, v128, v78
	v_ashrrev_i32_e32 v65, 31, v64
	v_pk_mul_f32 v[116:117], v[116:117], v[78:79] op_sel:[0,1]
	v_pk_mul_f32 v[78:79], v[114:115], v[78:79] op_sel:[0,1]
	v_cndmask_b32_e32 v67, v212, v213, vcc
	v_cndmask_b32_e32 v66, v214, v215, vcc
	v_lshlrev_b64 v[64:65], 12, v[64:65]
	s_waitcnt vmcnt(1)
	v_pk_fma_f32 v[78:79], v[96:97], v[78:79], v[100:101]
	v_pk_fma_f32 v[94:95], v[94:95], v[116:117], v[98:99]
	v_lshl_add_u64 v[64:65], v[66:67], 0, v[64:65]
	v_pk_mul_f32 v[94:95], v[94:95], s[22:23] op_sel_hi:[1,0]
	v_pk_mul_f32 v[78:79], v[78:79], s[22:23] op_sel_hi:[1,0]
	v_lshl_add_u64 v[76:77], v[64:65], 0, v[170:171]
	s_waitcnt vmcnt(0)
	v_pk_fma_f32 v[62:63], v[62:63], v[104:105], v[78:79]
	v_pk_fma_f32 v[60:61], v[60:61], v[102:103], v[94:95]
	global_load_dwordx4 v[106:109], v[76:77], off
	global_load_dwordx4 v[72:75], v[76:77], off offset:64
	global_load_dwordx4 v[68:71], v[76:77], off offset:512
	global_load_dwordx4 v[64:67], v[76:77], off offset:576
	s_nop 0
	global_store_dwordx4 v[92:93], v[60:63], off
	global_load_dwordx2 v[78:79], v[186:187], off offset:1024
	s_nop 0
	global_load_dwordx4 v[60:63], v[124:125], off
	global_load_dwordx4 v[94:97], v[126:127], off
	global_load_dwordx4 v[98:101], v[110:111], off offset:64
	s_waitcnt vmcnt(3)
	v_sub_f32_e32 v91, v91, v78
	v_sub_f32_e32 v90, v90, v78
	v_sub_f32_e32 v89, v89, v78
	v_sub_f32_e32 v88, v88, v78
	v_pk_mul_f32 v[88:89], v[88:89], v[78:79] op_sel:[0,1]
	v_pk_mul_f32 v[78:79], v[90:91], v[78:79] op_sel:[0,1]
	s_waitcnt vmcnt(1)
	v_pk_fma_f32 v[60:61], v[60:61], v[88:89], v[94:95]
	v_pk_fma_f32 v[62:63], v[62:63], v[78:79], v[96:97]
	v_pk_mul_f32 v[60:61], v[60:61], s[22:23] op_sel_hi:[1,0]
	v_pk_mul_f32 v[62:63], v[62:63], s[22:23] op_sel_hi:[1,0]
	s_waitcnt vmcnt(0)
	v_pk_fma_f32 v[56:57], v[56:57], v[98:99], v[60:61]
	v_pk_fma_f32 v[58:59], v[58:59], v[100:101], v[62:63]
	global_store_dwordx4 v[92:93], v[56:59], off offset:64
	global_load_dwordx2 v[78:79], v[186:187], off offset:1024
	s_nop 0
	global_load_dwordx4 v[56:59], v[176:177], off
	global_load_dwordx4 v[60:63], v[178:179], off
	global_load_dwordx4 v[88:91], v[110:111], off offset:512
	v_lshl_add_u64 v[94:95], v[112:113], 3, s[62:63]
	v_add_u32_e32 v98, 0xa0, v184
	v_ashrrev_i32_e32 v99, 31, v98
	s_waitcnt vmcnt(3)
	v_sub_f32_e32 v87, v87, v78
	v_sub_f32_e32 v86, v86, v78
	v_sub_f32_e32 v85, v85, v78
	v_sub_f32_e32 v84, v84, v78
	v_pk_mul_f32 v[84:85], v[84:85], v[78:79] op_sel:[0,1]
	v_pk_mul_f32 v[78:79], v[86:87], v[78:79] op_sel:[0,1]
	s_waitcnt vmcnt(1)
	v_pk_fma_f32 v[56:57], v[56:57], v[84:85], v[60:61]
	v_pk_fma_f32 v[58:59], v[58:59], v[78:79], v[62:63]
	v_pk_mul_f32 v[56:57], v[56:57], s[22:23] op_sel_hi:[1,0]
	v_pk_mul_f32 v[58:59], v[58:59], s[22:23] op_sel_hi:[1,0]
	s_waitcnt vmcnt(0)
	v_pk_fma_f32 v[52:53], v[52:53], v[88:89], v[56:57]
	v_pk_fma_f32 v[54:55], v[54:55], v[90:91], v[58:59]
	global_store_dwordx4 v[92:93], v[52:55], off offset:512
	global_load_dwordx2 v[78:79], v[186:187], off offset:1024
	s_nop 0
	global_load_dwordx4 v[52:55], v[180:181], off
	global_load_dwordx4 v[56:59], v[182:183], off
	global_load_dwordx4 v[60:63], v[110:111], off offset:576
	s_waitcnt vmcnt(3)
	v_sub_f32_e32 v83, v83, v78
	v_sub_f32_e32 v82, v82, v78
	v_sub_f32_e32 v81, v81, v78
	v_sub_f32_e32 v80, v80, v78
	v_pk_mul_f32 v[80:81], v[80:81], v[78:79] op_sel:[0,1]
	v_pk_mul_f32 v[78:79], v[82:83], v[78:79] op_sel:[0,1]
	s_waitcnt vmcnt(1)
	v_pk_fma_f32 v[52:53], v[52:53], v[80:81], v[56:57]
	v_pk_fma_f32 v[54:55], v[54:55], v[78:79], v[58:59]
	v_pk_mul_f32 v[52:53], v[52:53], s[22:23] op_sel_hi:[1,0]
	v_pk_mul_f32 v[54:55], v[54:55], s[22:23] op_sel_hi:[1,0]
	s_waitcnt vmcnt(0)
	v_pk_fma_f32 v[48:49], v[48:49], v[60:61], v[52:53]
	v_pk_fma_f32 v[50:51], v[50:51], v[62:63], v[54:55]
	global_store_dwordx4 v[92:93], v[48:51], off offset:576
	global_load_dwordx2 v[62:63], v[94:95], off
	global_load_dwordx4 v[78:81], v[172:173], off
	global_load_dwordx4 v[82:85], v[174:175], off
	v_cndmask_b32_e64 v48, v118, 4, vcc
	v_mul_hi_i32_i24_e32 v49, 0x6000, v48
	v_mul_i32_i24_e32 v48, 0x6000, v48
	v_lshl_add_u64 v[48:49], s[0:1], 0, v[48:49]
	v_lshl_add_u64 v[96:97], v[48:49], 0, v[170:171]
	global_load_dwordx4 v[86:89], v[96:97], off
	v_mul_hi_i32 v48, v98, s61
	v_lshrrev_b32_e32 v49, 31, v48
	v_ashrrev_i32_e32 v48, 11, v48
	v_add_u32_e32 v104, v48, v49
	v_mad_i32_i24 v48, v104, s64, v98
	v_lshl_add_u32 v49, v104, 13, v211
	v_lshlrev_b32_e32 v50, 8, v104
	v_cmp_gt_i32_e32 vcc, s43, v48
	s_waitcnt vmcnt(3)
	v_mov_b32_e32 v128, v62
	v_mov_b32_e32 v129, v63
	v_sub_f32_e32 v101, v109, v62
	v_cndmask_b32_e32 v49, v49, v50, vcc
	v_add_u32_e32 v48, v49, v48
	v_sub_f32_e32 v100, v108, v62
	v_sub_f32_e32 v103, v107, v62
	v_sub_f32_e32 v102, v106, v62
	v_ashrrev_i32_e32 v49, 31, v48
	v_pk_mul_f32 v[102:103], v[102:103], v[62:63] op_sel:[0,1]
	v_pk_mul_f32 v[62:63], v[100:101], v[62:63] op_sel:[0,1]
	v_cndmask_b32_e32 v51, v212, v213, vcc
	v_cndmask_b32_e32 v50, v214, v215, vcc
	v_lshlrev_b64 v[48:49], 12, v[48:49]
	s_waitcnt vmcnt(1)
	v_pk_fma_f32 v[62:63], v[80:81], v[62:63], v[84:85]
	v_pk_fma_f32 v[78:79], v[78:79], v[102:103], v[82:83]
	v_lshl_add_u64 v[48:49], v[50:51], 0, v[48:49]
	v_pk_mul_f32 v[78:79], v[78:79], s[22:23] op_sel_hi:[1,0]
	v_pk_mul_f32 v[62:63], v[62:63], s[22:23] op_sel_hi:[1,0]
	v_lshl_add_u64 v[60:61], v[48:49], 0, v[170:171]
	s_waitcnt vmcnt(0)
	v_pk_fma_f32 v[46:47], v[46:47], v[88:89], v[62:63]
	v_pk_fma_f32 v[44:45], v[44:45], v[86:87], v[78:79]
	global_load_dwordx4 v[90:93], v[60:61], off
	global_load_dwordx4 v[56:59], v[60:61], off offset:64
	global_load_dwordx4 v[52:55], v[60:61], off offset:512
	global_load_dwordx4 v[48:51], v[60:61], off offset:576
	s_nop 0
	global_store_dwordx4 v[76:77], v[44:47], off
	s_nop 0
	s_nop 0
	global_load_dwordx4 v[44:47], v[124:125], off
	global_load_dwordx4 v[78:81], v[126:127], off
	global_load_dwordx4 v[82:85], v[96:97], off offset:64
	s_waitcnt vmcnt(3)
	v_mov_b32_e32 v62, v128
	v_mov_b32_e32 v63, v129
	v_sub_f32_e32 v75, v75, v62
	v_sub_f32_e32 v74, v74, v62
	v_sub_f32_e32 v73, v73, v62
	v_sub_f32_e32 v72, v72, v62
	v_pk_mul_f32 v[72:73], v[72:73], v[62:63] op_sel:[0,1]
	v_pk_mul_f32 v[62:63], v[74:75], v[62:63] op_sel:[0,1]
	s_waitcnt vmcnt(1)
	v_pk_fma_f32 v[44:45], v[44:45], v[72:73], v[78:79]
	v_pk_fma_f32 v[46:47], v[46:47], v[62:63], v[80:81]
	v_pk_mul_f32 v[44:45], v[44:45], s[22:23] op_sel_hi:[1,0]
	v_pk_mul_f32 v[46:47], v[46:47], s[22:23] op_sel_hi:[1,0]
	s_waitcnt vmcnt(0)
	v_pk_fma_f32 v[40:41], v[40:41], v[82:83], v[44:45]
	v_pk_fma_f32 v[42:43], v[42:43], v[84:85], v[46:47]
	global_store_dwordx4 v[76:77], v[40:43], off offset:64
	s_nop 0
	s_nop 0
	global_load_dwordx4 v[40:43], v[176:177], off
	global_load_dwordx4 v[44:47], v[178:179], off
	global_load_dwordx4 v[72:75], v[96:97], off offset:512
	v_lshl_add_u64 v[78:79], v[98:99], 3, s[62:63]
	v_add_u32_e32 v82, 0xb0, v184
	v_ashrrev_i32_e32 v83, 31, v82
	s_waitcnt vmcnt(3)
	v_mov_b32_e32 v62, v128
	v_mov_b32_e32 v63, v129
	v_sub_f32_e32 v71, v71, v62
	v_sub_f32_e32 v70, v70, v62
	v_sub_f32_e32 v69, v69, v62
	v_sub_f32_e32 v68, v68, v62
	v_pk_mul_f32 v[68:69], v[68:69], v[62:63] op_sel:[0,1]
	v_pk_mul_f32 v[62:63], v[70:71], v[62:63] op_sel:[0,1]
	s_waitcnt vmcnt(1)
	v_pk_fma_f32 v[40:41], v[40:41], v[68:69], v[44:45]
	v_pk_fma_f32 v[42:43], v[42:43], v[62:63], v[46:47]
	v_pk_mul_f32 v[40:41], v[40:41], s[22:23] op_sel_hi:[1,0]
	v_pk_mul_f32 v[42:43], v[42:43], s[22:23] op_sel_hi:[1,0]
	s_waitcnt vmcnt(0)
	v_pk_fma_f32 v[36:37], v[36:37], v[72:73], v[40:41]
	v_pk_fma_f32 v[38:39], v[38:39], v[74:75], v[42:43]
	global_store_dwordx4 v[76:77], v[36:39], off offset:512
	s_nop 0
	s_nop 0
	global_load_dwordx4 v[36:39], v[180:181], off
	global_load_dwordx4 v[40:43], v[182:183], off
	global_load_dwordx4 v[44:47], v[96:97], off offset:576
	s_waitcnt vmcnt(3)
	v_mov_b32_e32 v62, v128
	v_mov_b32_e32 v63, v129
	v_sub_f32_e32 v67, v67, v62
	v_sub_f32_e32 v66, v66, v62
	v_sub_f32_e32 v65, v65, v62
	v_sub_f32_e32 v64, v64, v62
	v_pk_mul_f32 v[64:65], v[64:65], v[62:63] op_sel:[0,1]
	v_pk_mul_f32 v[62:63], v[66:67], v[62:63] op_sel:[0,1]
	s_waitcnt vmcnt(1)
	v_pk_fma_f32 v[36:37], v[36:37], v[64:65], v[40:41]
	v_pk_fma_f32 v[38:39], v[38:39], v[62:63], v[42:43]
	v_pk_mul_f32 v[36:37], v[36:37], s[22:23] op_sel_hi:[1,0]
	v_pk_mul_f32 v[38:39], v[38:39], s[22:23] op_sel_hi:[1,0]
	s_waitcnt vmcnt(0)
	v_pk_fma_f32 v[32:33], v[32:33], v[44:45], v[36:37]
	v_pk_fma_f32 v[34:35], v[34:35], v[46:47], v[38:39]
	global_store_dwordx4 v[76:77], v[32:35], off offset:576
	global_load_dwordx2 v[46:47], v[78:79], off
	global_load_dwordx4 v[42:45], v[172:173], off
	global_load_dwordx4 v[62:65], v[174:175], off
	v_cndmask_b32_e64 v32, v104, 4, vcc
	v_mul_hi_i32_i24_e32 v33, 0x6000, v32
	v_mul_i32_i24_e32 v32, 0x6000, v32
	v_lshl_add_u64 v[32:33], s[0:1], 0, v[32:33]
	v_lshl_add_u64 v[80:81], v[32:33], 0, v[170:171]
	global_load_dwordx4 v[66:69], v[80:81], off
	v_mul_hi_i32 v32, v82, s61
	v_lshrrev_b32_e32 v33, 31, v32
	v_ashrrev_i32_e32 v32, 11, v32
	v_add_u32_e32 v88, v32, v33
	v_mad_i32_i24 v32, v88, s64, v82
	v_lshl_add_u32 v33, v88, 13, v211
	v_lshlrev_b32_e32 v34, 8, v88
	v_cmp_gt_i32_e32 vcc, s43, v32
	s_waitcnt vmcnt(3)
	v_mov_b32_e32 v128, v46
	v_mov_b32_e32 v129, v47
	v_sub_f32_e32 v85, v93, v46
	v_cndmask_b32_e32 v33, v33, v34, vcc
	v_add_u32_e32 v32, v33, v32
	v_sub_f32_e32 v84, v92, v46
	v_sub_f32_e32 v87, v91, v46
	v_sub_f32_e32 v86, v90, v46
	v_ashrrev_i32_e32 v33, 31, v32
	v_pk_mul_f32 v[86:87], v[86:87], v[46:47] op_sel:[0,1]
	v_pk_mul_f32 v[46:47], v[84:85], v[46:47] op_sel:[0,1]
	v_cndmask_b32_e32 v35, v212, v213, vcc
	v_cndmask_b32_e32 v34, v214, v215, vcc
	v_lshlrev_b64 v[32:33], 12, v[32:33]
	s_waitcnt vmcnt(1)
	v_pk_fma_f32 v[44:45], v[44:45], v[46:47], v[64:65]
	v_pk_fma_f32 v[42:43], v[42:43], v[86:87], v[62:63]
	v_lshl_add_u64 v[32:33], v[34:35], 0, v[32:33]
	v_pk_mul_f32 v[42:43], v[42:43], s[22:23] op_sel_hi:[1,0]
	v_pk_mul_f32 v[44:45], v[44:45], s[22:23] op_sel_hi:[1,0]
	v_lshl_add_u64 v[40:41], v[32:33], 0, v[170:171]
	s_waitcnt vmcnt(0)
	v_pk_fma_f32 v[30:31], v[30:31], v[68:69], v[44:45]
	v_pk_fma_f32 v[28:29], v[28:29], v[66:67], v[42:43]
	global_load_dwordx4 v[70:73], v[40:41], off
	global_load_dwordx4 v[74:77], v[40:41], off offset:64
	global_load_dwordx4 v[36:39], v[40:41], off offset:512
	global_load_dwordx4 v[32:35], v[40:41], off offset:576
	s_nop 0
	global_store_dwordx4 v[60:61], v[28:31], off
	s_nop 0
	s_nop 0
	global_load_dwordx4 v[28:31], v[124:125], off
	global_load_dwordx4 v[42:45], v[126:127], off
	global_load_dwordx4 v[62:65], v[80:81], off offset:64
	s_waitcnt vmcnt(3)
	v_mov_b32_e32 v46, v128
	v_mov_b32_e32 v47, v129
	v_sub_f32_e32 v59, v59, v46
	v_sub_f32_e32 v58, v58, v46
	v_sub_f32_e32 v57, v57, v46
	v_sub_f32_e32 v56, v56, v46
	v_pk_mul_f32 v[56:57], v[56:57], v[46:47] op_sel:[0,1]
	v_pk_mul_f32 v[46:47], v[58:59], v[46:47] op_sel:[0,1]
	s_waitcnt vmcnt(1)
	v_pk_fma_f32 v[28:29], v[28:29], v[56:57], v[42:43]
	v_pk_fma_f32 v[30:31], v[30:31], v[46:47], v[44:45]
	v_pk_mul_f32 v[28:29], v[28:29], s[22:23] op_sel_hi:[1,0]
	v_pk_mul_f32 v[30:31], v[30:31], s[22:23] op_sel_hi:[1,0]
	s_waitcnt vmcnt(0)
	v_pk_fma_f32 v[24:25], v[24:25], v[62:63], v[28:29]
	v_pk_fma_f32 v[26:27], v[26:27], v[64:65], v[30:31]
	global_store_dwordx4 v[60:61], v[24:27], off offset:64
	s_nop 0
	s_nop 0
	global_load_dwordx4 v[24:27], v[176:177], off
	global_load_dwordx4 v[28:31], v[178:179], off
	global_load_dwordx4 v[42:45], v[80:81], off offset:512
	s_waitcnt vmcnt(3)
	v_mov_b32_e32 v46, v128
	v_mov_b32_e32 v47, v129
	v_sub_f32_e32 v55, v55, v46
	v_sub_f32_e32 v54, v54, v46
	v_sub_f32_e32 v53, v53, v46
	v_sub_f32_e32 v52, v52, v46
	v_pk_mul_f32 v[52:53], v[52:53], v[46:47] op_sel:[0,1]
	v_pk_mul_f32 v[46:47], v[54:55], v[46:47] op_sel:[0,1]
	s_waitcnt vmcnt(1)
	v_pk_fma_f32 v[24:25], v[24:25], v[52:53], v[28:29]
	v_pk_fma_f32 v[26:27], v[26:27], v[46:47], v[30:31]
	v_pk_mul_f32 v[24:25], v[24:25], s[22:23] op_sel_hi:[1,0]
	v_pk_mul_f32 v[26:27], v[26:27], s[22:23] op_sel_hi:[1,0]
	s_waitcnt vmcnt(0)
	v_pk_fma_f32 v[20:21], v[20:21], v[42:43], v[24:25]
	v_pk_fma_f32 v[22:23], v[22:23], v[44:45], v[26:27]
	global_store_dwordx4 v[60:61], v[20:23], off offset:512
	s_nop 0
	s_nop 0
	global_load_dwordx4 v[20:23], v[180:181], off
	global_load_dwordx4 v[24:27], v[182:183], off
	global_load_dwordx4 v[28:31], v[80:81], off offset:576
	v_lshl_add_u64 v[44:45], v[82:83], 3, s[62:63]
	s_waitcnt vmcnt(3)
	v_mov_b32_e32 v42, v128
	v_mov_b32_e32 v43, v129
	v_sub_f32_e32 v47, v51, v42
	v_sub_f32_e32 v46, v50, v42
	v_sub_f32_e32 v49, v49, v42
	v_sub_f32_e32 v48, v48, v42
	v_pk_mul_f32 v[48:49], v[48:49], v[42:43] op_sel:[0,1]
	v_pk_mul_f32 v[42:43], v[46:47], v[42:43] op_sel:[0,1]
	s_waitcnt vmcnt(1)
	v_pk_fma_f32 v[20:21], v[20:21], v[48:49], v[24:25]
	v_pk_fma_f32 v[22:23], v[22:23], v[42:43], v[26:27]
	v_pk_mul_f32 v[20:21], v[20:21], s[22:23] op_sel_hi:[1,0]
	v_pk_mul_f32 v[22:23], v[22:23], s[22:23] op_sel_hi:[1,0]
	s_waitcnt vmcnt(0)
	v_pk_fma_f32 v[16:17], v[16:17], v[28:29], v[20:21]
	v_pk_fma_f32 v[18:19], v[18:19], v[30:31], v[22:23]
	global_store_dwordx4 v[60:61], v[16:19], off offset:576
	global_load_dwordx2 v[28:29], v[44:45], off
	v_cndmask_b32_e64 v24, v88, 4, vcc
	v_mul_hi_i32_i24_e32 v25, 0x6000, v24
	v_mul_i32_i24_e32 v24, 0x6000, v24
	global_load_dwordx4 v[16:19], v[172:173], off
	global_load_dwordx4 v[20:23], v[174:175], off
	v_lshl_add_u64 v[24:25], s[0:1], 0, v[24:25]
	v_lshl_add_u64 v[30:31], v[24:25], 0, v[170:171]
	global_load_dwordx4 v[24:27], v[30:31], off
	s_andn2_b64 vcc, exec, s[10:11]
	s_waitcnt vmcnt(3)
	v_mov_b32_e32 v128, v28
	v_mov_b32_e32 v129, v29
	v_sub_f32_e32 v43, v73, v28
	v_sub_f32_e32 v42, v72, v28
	v_sub_f32_e32 v47, v71, v28
	v_sub_f32_e32 v46, v70, v28
	v_pk_mul_f32 v[46:47], v[46:47], v[28:29] op_sel:[0,1]
	v_pk_mul_f32 v[28:29], v[42:43], v[28:29] op_sel:[0,1]
	s_waitcnt vmcnt(1)
	v_pk_fma_f32 v[16:17], v[16:17], v[46:47], v[20:21]
	v_pk_fma_f32 v[18:19], v[18:19], v[28:29], v[22:23]
	v_pk_mul_f32 v[16:17], v[16:17], s[22:23] op_sel_hi:[1,0]
	v_pk_mul_f32 v[18:19], v[18:19], s[22:23] op_sel_hi:[1,0]
	s_waitcnt vmcnt(0)
	v_pk_fma_f32 v[12:13], v[12:13], v[24:25], v[16:17]
	v_pk_fma_f32 v[14:15], v[14:15], v[26:27], v[18:19]
	global_store_dwordx4 v[40:41], v[12:15], off
	s_nop 0
	s_nop 0
	global_load_dwordx4 v[12:15], v[124:125], off
	global_load_dwordx4 v[16:19], v[126:127], off
	global_load_dwordx4 v[20:23], v[30:31], off offset:64
	s_waitcnt vmcnt(3)
	v_mov_b32_e32 v24, v128
	v_mov_b32_e32 v25, v129
	v_sub_f32_e32 v27, v77, v24
	v_sub_f32_e32 v26, v76, v24
	v_sub_f32_e32 v29, v75, v24
	v_sub_f32_e32 v28, v74, v24
	v_pk_mul_f32 v[28:29], v[28:29], v[24:25] op_sel:[0,1]
	v_pk_mul_f32 v[24:25], v[26:27], v[24:25] op_sel:[0,1]
	s_waitcnt vmcnt(1)
	v_pk_fma_f32 v[12:13], v[12:13], v[28:29], v[16:17]
	v_pk_fma_f32 v[14:15], v[14:15], v[24:25], v[18:19]
	v_pk_mul_f32 v[12:13], v[12:13], s[22:23] op_sel_hi:[1,0]
	v_pk_mul_f32 v[14:15], v[14:15], s[22:23] op_sel_hi:[1,0]
	s_waitcnt vmcnt(0)
	v_pk_fma_f32 v[8:9], v[8:9], v[20:21], v[12:13]
	v_pk_fma_f32 v[10:11], v[10:11], v[22:23], v[14:15]
	global_store_dwordx4 v[40:41], v[8:11], off offset:64
	s_nop 0
	s_nop 0
	global_load_dwordx4 v[8:11], v[176:177], off
	global_load_dwordx4 v[12:15], v[178:179], off
	global_load_dwordx4 v[16:19], v[30:31], off offset:512
	s_waitcnt vmcnt(3)
	v_mov_b32_e32 v20, v128
	v_mov_b32_e32 v21, v129
	v_sub_f32_e32 v23, v39, v20
	v_sub_f32_e32 v22, v38, v20
	v_sub_f32_e32 v25, v37, v20
	v_sub_f32_e32 v24, v36, v20
	v_pk_mul_f32 v[24:25], v[24:25], v[20:21] op_sel:[0,1]
	v_pk_mul_f32 v[20:21], v[22:23], v[20:21] op_sel:[0,1]
	s_waitcnt vmcnt(1)
	v_pk_fma_f32 v[8:9], v[8:9], v[24:25], v[12:13]
	v_pk_fma_f32 v[10:11], v[10:11], v[20:21], v[14:15]
	v_pk_mul_f32 v[8:9], v[8:9], s[22:23] op_sel_hi:[1,0]
	v_pk_mul_f32 v[10:11], v[10:11], s[22:23] op_sel_hi:[1,0]
	s_waitcnt vmcnt(0)
	v_pk_fma_f32 v[4:5], v[4:5], v[16:17], v[8:9]
	v_pk_fma_f32 v[6:7], v[6:7], v[18:19], v[10:11]
	global_store_dwordx4 v[40:41], v[4:7], off offset:512
	s_nop 0
	s_nop 0
	global_load_dwordx4 v[4:7], v[180:181], off
	global_load_dwordx4 v[8:11], v[182:183], off
	global_load_dwordx4 v[12:15], v[30:31], off offset:576
	s_waitcnt vmcnt(3)
	v_mov_b32_e32 v16, v128
	v_mov_b32_e32 v17, v129
	v_sub_f32_e32 v19, v35, v16
	v_sub_f32_e32 v18, v34, v16
	v_sub_f32_e32 v21, v33, v16
	v_sub_f32_e32 v20, v32, v16
	v_pk_mul_f32 v[20:21], v[20:21], v[16:17] op_sel:[0,1]
	v_pk_mul_f32 v[16:17], v[18:19], v[16:17] op_sel:[0,1]
	s_waitcnt vmcnt(1)
	v_pk_fma_f32 v[4:5], v[4:5], v[20:21], v[8:9]
	v_pk_fma_f32 v[6:7], v[6:7], v[16:17], v[10:11]
	v_pk_mul_f32 v[4:5], v[4:5], s[22:23] op_sel_hi:[1,0]
	v_pk_mul_f32 v[6:7], v[6:7], s[22:23] op_sel_hi:[1,0]
	s_waitcnt vmcnt(0)
	v_pk_fma_f32 v[0:1], v[0:1], v[12:13], v[4:5]
	v_pk_fma_f32 v[2:3], v[2:3], v[14:15], v[6:7]
	global_store_dwordx4 v[40:41], v[0:3], off offset:576
	s_cbranch_vccnz .LBB0_2793
	s_andn2_b64 vcc, exec, s[16:17]
	s_cbranch_vccnz .LBB0_2792
	s_barrier
	s_branch .LBB0_2792

.LBB0_3032:
	v_lshl_add_u32 v184, s60, 8, v153
	v_mul_hi_i32 v128, v184, s52
	v_lshrrev_b32_e32 v129, 31, v128
	v_ashrrev_i32_e32 v128, 11, v128
	v_add_u32_e32 v132, v128, v129
	v_mad_i32_i24 v128, v132, s53, v184
	v_lshl_add_u32 v129, v132, 13, v211
	v_lshlrev_b32_e32 v130, 8, v132
	v_cmp_gt_i32_e32 vcc, s46, v128
	v_lshl_or_b32 v228, s61, 8, v193
	v_mov_b32_e32 v212, s89
	v_cndmask_b32_e32 v129, v129, v130, vcc
	v_add_u32_e32 v128, v129, v128
	v_mov_b32_e32 v213, s71
	v_mov_b32_e32 v214, s88
	v_mov_b32_e32 v215, s70
	v_ashrrev_i32_e32 v129, 31, v128
	v_cndmask_b32_e32 v131, v212, v213, vcc
	v_cndmask_b32_e32 v130, v214, v215, vcc
	v_lshlrev_b64 v[128:129], 12, v[128:129]
	v_ashrrev_i32_e32 v229, 31, v228
	v_lshl_add_u64 v[128:129], v[130:131], 0, v[128:129]
	v_lshlrev_b64 v[170:171], 2, v[228:229]
	v_ashrrev_i32_e32 v185, 31, v184
	v_lshl_add_u64 v[190:191], v[128:129], 0, v[170:171]
	v_lshl_add_u64 v[186:187], v[184:185], 3, s[62:63]
	global_load_dwordx4 v[176:179], v[190:191], off
	global_load_dwordx4 v[224:227], v[190:191], off offset:64
	global_load_dwordx2 v[230:231], v[186:187], off
	v_cndmask_b32_e64 v128, v132, 4, vcc
	v_mul_hi_i32_i24_e32 v129, 0x6000, v128
	v_lshl_add_u64 v[172:173], s[12:13], 0, v[170:171]
	v_lshl_add_u64 v[174:175], s[14:15], 0, v[170:171]
	v_mul_i32_i24_e32 v128, 0x6000, v128
	global_load_dwordx4 v[180:183], v[172:173], off
	global_load_dwordx4 v[216:219], v[174:175], off
	v_lshl_add_u64 v[128:129], s[0:1], 0, v[128:129]
	v_lshl_add_u64 v[232:233], v[128:129], 0, v[170:171]
	global_load_dwordx4 v[220:223], v[232:233], off
	v_or_b32_e32 v236, 16, v184
	v_mul_hi_i32 v128, v236, s52
	v_lshrrev_b32_e32 v129, 31, v128
	v_ashrrev_i32_e32 v128, 11, v128
	v_add_u32_e32 v185, v128, v129
	v_mad_i32_i24 v128, v185, s53, v236
	v_lshl_add_u32 v129, v185, 13, v211
	v_lshlrev_b32_e32 v130, 8, v185
	v_cmp_gt_i32_e32 vcc, s46, v128
	v_or_b32_e32 v234, 16, v228
	v_ashrrev_i32_e32 v235, 31, v234
	v_cndmask_b32_e32 v129, v129, v130, vcc
	v_add_u32_e32 v128, v129, v128
	v_ashrrev_i32_e32 v129, 31, v128
	v_cndmask_b32_e32 v131, v212, v213, vcc
	v_cndmask_b32_e32 v130, v214, v215, vcc
	v_lshlrev_b64 v[128:129], 12, v[128:129]
	v_lshl_add_u64 v[128:129], v[130:131], 0, v[128:129]
	v_lshl_add_u64 v[188:189], v[128:129], 0, v[170:171]
	global_load_dwordx4 v[140:143], v[188:189], off
	global_load_dwordx4 v[136:139], v[188:189], off offset:64
	global_load_dwordx4 v[132:135], v[188:189], off offset:512
	global_load_dwordx4 v[128:131], v[188:189], off offset:576
	v_ashrrev_i32_e32 v237, 31, v236
	v_or_b32_e32 v238, 32, v184
	v_ashrrev_i32_e32 v239, 31, v238
	s_mov_b64 s[4:5], -1
	s_waitcnt vmcnt(0)
	v_sub_f32_e32 v179, v179, v230
	v_sub_f32_e32 v178, v178, v230
	v_sub_f32_e32 v177, v177, v230
	v_sub_f32_e32 v176, v176, v230
	v_pk_mul_f32 v[176:177], v[176:177], v[230:231] op_sel:[0,1]
	v_pk_mul_f32 v[178:179], v[178:179], v[230:231] op_sel:[0,1]
	v_pk_fma_f32 v[176:177], v[180:181], v[176:177], v[216:217]
	v_pk_fma_f32 v[178:179], v[182:183], v[178:179], v[218:219]
	v_pk_mul_f32 v[176:177], v[176:177], s[22:23] op_sel_hi:[1,0]
	v_pk_mul_f32 v[178:179], v[178:179], s[22:23] op_sel_hi:[1,0]
	v_pk_fma_f32 v[124:125], v[124:125], v[220:221], v[176:177]
	v_pk_fma_f32 v[126:127], v[126:127], v[222:223], v[178:179]
	global_store_dwordx4 v[190:191], v[124:127], off
	s_nop 0
	s_waitcnt vmcnt(1)
	v_sub_f32_e32 v227, v227, v230
	v_lshlrev_b64 v[126:127], 2, v[234:235]
	v_lshl_add_u64 v[124:125], s[12:13], 0, v[126:127]
	v_lshl_add_u64 v[126:127], s[14:15], 0, v[126:127]
	global_load_dwordx4 v[176:179], v[124:125], off
	global_load_dwordx4 v[180:183], v[126:127], off
	global_load_dwordx4 v[216:219], v[232:233], off offset:64
	v_sub_f32_e32 v226, v226, v230
	v_sub_f32_e32 v225, v225, v230
	v_sub_f32_e32 v224, v224, v230
	v_pk_mul_f32 v[224:225], v[224:225], v[230:231] op_sel:[0,1]
	v_pk_mul_f32 v[226:227], v[226:227], v[230:231] op_sel:[0,1]
	v_or_b32_e32 v234, 0x80, v228
	global_load_dwordx4 v[220:223], v[190:191], off offset:512
	v_ashrrev_i32_e32 v235, 31, v234
	v_or_b32_e32 v228, 0x90, v228
	v_ashrrev_i32_e32 v229, 31, v228
	s_waitcnt vmcnt(2)
	v_pk_fma_f32 v[178:179], v[178:179], v[226:227], v[182:183]
	v_pk_fma_f32 v[176:177], v[176:177], v[224:225], v[180:181]
	v_pk_mul_f32 v[178:179], v[178:179], s[22:23] op_sel_hi:[1,0]
	v_pk_mul_f32 v[176:177], v[176:177], s[22:23] op_sel_hi:[1,0]
	s_waitcnt vmcnt(1)
	v_pk_fma_f32 v[122:123], v[122:123], v[218:219], v[178:179]
	v_pk_fma_f32 v[120:121], v[120:121], v[216:217], v[176:177]
	global_store_dwordx4 v[190:191], v[120:123], off offset:64
	s_nop 0
	s_waitcnt vmcnt(1)
	v_sub_f32_e32 v223, v223, v230
	v_lshlrev_b64 v[120:121], 2, v[234:235]
	v_lshl_add_u64 v[176:177], s[12:13], 0, v[120:121]
	v_lshl_add_u64 v[178:179], s[14:15], 0, v[120:121]
	global_load_dwordx4 v[120:123], v[176:177], off
	global_load_dwordx4 v[180:183], v[178:179], off
	global_load_dwordx4 v[216:219], v[232:233], off offset:512
	v_sub_f32_e32 v222, v222, v230
	v_sub_f32_e32 v221, v221, v230
	v_sub_f32_e32 v220, v220, v230
	v_pk_mul_f32 v[220:221], v[220:221], v[230:231] op_sel:[0,1]
	v_pk_mul_f32 v[222:223], v[222:223], v[230:231] op_sel:[0,1]
	global_load_dwordx4 v[224:227], v[190:191], off offset:576
	s_waitcnt vmcnt(2)
	v_pk_fma_f32 v[122:123], v[122:123], v[222:223], v[182:183]
	v_pk_fma_f32 v[120:121], v[120:121], v[220:221], v[180:181]
	v_pk_mul_f32 v[122:123], v[122:123], s[22:23] op_sel_hi:[1,0]
	v_pk_mul_f32 v[120:121], v[120:121], s[22:23] op_sel_hi:[1,0]
	s_waitcnt vmcnt(1)
	v_pk_fma_f32 v[118:119], v[118:119], v[218:219], v[122:123]
	v_pk_fma_f32 v[116:117], v[116:117], v[216:217], v[120:121]
	global_store_dwordx4 v[190:191], v[116:119], off offset:512
	s_nop 0
	s_waitcnt vmcnt(1)
	v_mov_b32_e32 v220, v230
	v_mov_b32_e32 v221, v231
	v_sub_f32_e32 v223, v227, v220
	v_lshlrev_b64 v[116:117], 2, v[228:229]
	v_lshl_add_u64 v[180:181], s[12:13], 0, v[116:117]
	v_lshl_add_u64 v[182:183], s[14:15], 0, v[116:117]
	global_load_dwordx4 v[116:119], v[180:181], off
	global_load_dwordx4 v[120:123], v[182:183], off
	global_load_dwordx4 v[216:219], v[232:233], off offset:576
	v_sub_f32_e32 v222, v226, v220
	v_sub_f32_e32 v225, v225, v220
	v_sub_f32_e32 v224, v224, v220
	v_pk_mul_f32 v[224:225], v[224:225], v[220:221] op_sel:[0,1]
	v_pk_mul_f32 v[220:221], v[222:223], v[220:221] op_sel:[0,1]
	v_lshl_add_u64 v[232:233], v[236:237], 3, s[62:63]
	s_waitcnt vmcnt(1)
	v_pk_fma_f32 v[118:119], v[118:119], v[220:221], v[122:123]
	v_pk_fma_f32 v[116:117], v[116:117], v[224:225], v[120:121]
	v_pk_mul_f32 v[118:119], v[118:119], s[22:23] op_sel_hi:[1,0]
	v_pk_mul_f32 v[116:117], v[116:117], s[22:23] op_sel_hi:[1,0]
	s_waitcnt vmcnt(0)
	v_pk_fma_f32 v[114:115], v[114:115], v[218:219], v[118:119]
	v_pk_fma_f32 v[112:113], v[112:113], v[216:217], v[116:117]
	global_store_dwordx4 v[190:191], v[112:115], off offset:576
	global_load_dwordx2 v[234:235], v[232:233], off
	global_load_dwordx4 v[216:219], v[172:173], off
	global_load_dwordx4 v[220:223], v[174:175], off
	v_cndmask_b32_e64 v112, v185, 4, vcc
	v_mul_hi_i32_i24_e32 v113, 0x6000, v112
	v_mul_i32_i24_e32 v112, 0x6000, v112
	v_lshl_add_u64 v[112:113], s[0:1], 0, v[112:113]
	v_lshl_add_u64 v[236:237], v[112:113], 0, v[170:171]
	global_load_dwordx4 v[224:227], v[236:237], off
	v_mul_hi_i32 v112, v238, s52
	v_lshrrev_b32_e32 v113, 31, v112
	v_ashrrev_i32_e32 v112, 11, v112
	v_add_u32_e32 v185, v112, v113
	v_mad_i32_i24 v112, v185, s53, v238
	v_lshl_add_u32 v113, v185, 13, v211
	v_lshlrev_b32_e32 v114, 8, v185
	v_cmp_gt_i32_e32 vcc, s46, v112
	s_waitcnt vmcnt(3)
	v_sub_f32_e32 v143, v143, v234
	v_cndmask_b32_e32 v113, v113, v114, vcc
	v_add_u32_e32 v112, v113, v112
	v_sub_f32_e32 v142, v142, v234
	v_sub_f32_e32 v141, v141, v234
	v_sub_f32_e32 v140, v140, v234
	v_ashrrev_i32_e32 v113, 31, v112
	v_pk_mul_f32 v[140:141], v[140:141], v[234:235] op_sel:[0,1]
	v_pk_mul_f32 v[142:143], v[142:143], v[234:235] op_sel:[0,1]
	v_cndmask_b32_e32 v115, v212, v213, vcc
	v_cndmask_b32_e32 v114, v214, v215, vcc
	v_lshlrev_b64 v[112:113], 12, v[112:113]
	s_waitcnt vmcnt(1)
	v_pk_fma_f32 v[142:143], v[218:219], v[142:143], v[222:223]
	v_pk_fma_f32 v[140:141], v[216:217], v[140:141], v[220:221]
	v_lshl_add_u64 v[112:113], v[114:115], 0, v[112:113]
	v_pk_mul_f32 v[140:141], v[140:141], s[22:23] op_sel_hi:[1,0]
	v_pk_mul_f32 v[142:143], v[142:143], s[22:23] op_sel_hi:[1,0]
	v_lshl_add_u64 v[190:191], v[112:113], 0, v[170:171]
	s_waitcnt vmcnt(0)
	v_pk_fma_f32 v[110:111], v[110:111], v[226:227], v[142:143]
	v_pk_fma_f32 v[108:109], v[108:109], v[224:225], v[140:141]
	global_load_dwordx4 v[228:231], v[190:191], off
	global_load_dwordx4 v[120:123], v[190:191], off offset:64
	global_load_dwordx4 v[116:119], v[190:191], off offset:512
	global_load_dwordx4 v[112:115], v[190:191], off offset:576
	s_nop 0
	global_store_dwordx4 v[188:189], v[108:111], off
	s_nop 0
	s_nop 0
	global_load_dwordx4 v[108:111], v[124:125], off
	global_load_dwordx4 v[140:143], v[126:127], off
	global_load_dwordx4 v[216:219], v[236:237], off offset:64
	s_waitcnt vmcnt(3)
	v_mov_b32_e32 v220, v234
	v_mov_b32_e32 v221, v235
	v_sub_f32_e32 v139, v139, v220
	v_sub_f32_e32 v138, v138, v220
	v_sub_f32_e32 v137, v137, v220
	v_sub_f32_e32 v136, v136, v220
	v_pk_mul_f32 v[136:137], v[136:137], v[220:221] op_sel:[0,1]
	v_pk_mul_f32 v[138:139], v[138:139], v[220:221] op_sel:[0,1]
	s_waitcnt vmcnt(1)
	v_pk_fma_f32 v[108:109], v[108:109], v[136:137], v[140:141]
	v_pk_fma_f32 v[110:111], v[110:111], v[138:139], v[142:143]
	v_pk_mul_f32 v[108:109], v[108:109], s[22:23] op_sel_hi:[1,0]
	v_pk_mul_f32 v[110:111], v[110:111], s[22:23] op_sel_hi:[1,0]
	s_waitcnt vmcnt(0)
	v_pk_fma_f32 v[104:105], v[104:105], v[216:217], v[108:109]
	v_pk_fma_f32 v[106:107], v[106:107], v[218:219], v[110:111]
	global_store_dwordx4 v[188:189], v[104:107], off offset:64
	s_nop 0
	s_nop 0
	global_load_dwordx4 v[104:107], v[176:177], off
	global_load_dwordx4 v[108:111], v[178:179], off
	global_load_dwordx4 v[136:139], v[236:237], off offset:512
	v_lshl_add_u64 v[216:217], v[238:239], 3, s[62:63]
	v_or_b32_e32 v218, 48, v184
	v_ashrrev_i32_e32 v219, 31, v218
	s_waitcnt vmcnt(3)
	v_mov_b32_e32 v140, v234
	v_mov_b32_e32 v141, v235
	v_sub_f32_e32 v135, v135, v140
	v_sub_f32_e32 v134, v134, v140
	v_sub_f32_e32 v133, v133, v140
	v_sub_f32_e32 v132, v132, v140
	v_pk_mul_f32 v[132:133], v[132:133], v[140:141] op_sel:[0,1]
	v_pk_mul_f32 v[134:135], v[134:135], v[140:141] op_sel:[0,1]
	s_waitcnt vmcnt(1)
	v_pk_fma_f32 v[104:105], v[104:105], v[132:133], v[108:109]
	v_pk_fma_f32 v[106:107], v[106:107], v[134:135], v[110:111]
	v_pk_mul_f32 v[104:105], v[104:105], s[22:23] op_sel_hi:[1,0]
	v_pk_mul_f32 v[106:107], v[106:107], s[22:23] op_sel_hi:[1,0]
	s_waitcnt vmcnt(0)
	v_pk_fma_f32 v[100:101], v[100:101], v[136:137], v[104:105]
	v_pk_fma_f32 v[102:103], v[102:103], v[138:139], v[106:107]
	global_store_dwordx4 v[188:189], v[100:103], off offset:512
	s_nop 0
	s_nop 0
	global_load_dwordx4 v[100:103], v[180:181], off
	global_load_dwordx4 v[104:107], v[182:183], off
	global_load_dwordx4 v[108:111], v[236:237], off offset:576
	s_waitcnt vmcnt(3)
	v_mov_b32_e32 v132, v234
	v_mov_b32_e32 v133, v235
	v_sub_f32_e32 v131, v131, v132
	v_sub_f32_e32 v130, v130, v132
	v_sub_f32_e32 v129, v129, v132
	v_sub_f32_e32 v128, v128, v132
	v_pk_mul_f32 v[128:129], v[128:129], v[132:133] op_sel:[0,1]
	v_pk_mul_f32 v[130:131], v[130:131], v[132:133] op_sel:[0,1]
	s_waitcnt vmcnt(1)
	v_pk_fma_f32 v[100:101], v[100:101], v[128:129], v[104:105]
	v_pk_fma_f32 v[102:103], v[102:103], v[130:131], v[106:107]
	v_pk_mul_f32 v[100:101], v[100:101], s[22:23] op_sel_hi:[1,0]
	v_pk_mul_f32 v[102:103], v[102:103], s[22:23] op_sel_hi:[1,0]
	s_waitcnt vmcnt(0)
	v_pk_fma_f32 v[96:97], v[96:97], v[108:109], v[100:101]
	v_pk_fma_f32 v[98:99], v[98:99], v[110:111], v[102:103]
	global_store_dwordx4 v[188:189], v[96:99], off offset:576
	global_load_dwordx2 v[110:111], v[216:217], off
	global_load_dwordx4 v[128:131], v[172:173], off
	global_load_dwordx4 v[132:135], v[174:175], off
	v_cndmask_b32_e64 v96, v185, 4, vcc
	v_mul_hi_i32_i24_e32 v97, 0x6000, v96
	v_mul_i32_i24_e32 v96, 0x6000, v96
	v_lshl_add_u64 v[96:97], s[0:1], 0, v[96:97]
	v_lshl_add_u64 v[188:189], v[96:97], 0, v[170:171]
	global_load_dwordx4 v[136:139], v[188:189], off
	v_mul_hi_i32 v96, v218, s52
	v_lshrrev_b32_e32 v97, 31, v96
	v_ashrrev_i32_e32 v96, 11, v96
	v_add_u32_e32 v185, v96, v97
	v_mad_i32_i24 v96, v185, s53, v218
	v_lshl_add_u32 v97, v185, 13, v211
	v_lshlrev_b32_e32 v98, 8, v185
	v_cmp_gt_i32_e32 vcc, s46, v96
	s_waitcnt vmcnt(3)
	v_mov_b32_e32 v224, v110
	v_mov_b32_e32 v225, v111
	v_sub_f32_e32 v221, v231, v110
	v_cndmask_b32_e32 v97, v97, v98, vcc
	v_add_u32_e32 v96, v97, v96
	v_sub_f32_e32 v220, v230, v110
	v_sub_f32_e32 v223, v229, v110
	v_sub_f32_e32 v222, v228, v110
	v_ashrrev_i32_e32 v97, 31, v96
	v_pk_mul_f32 v[222:223], v[222:223], v[110:111] op_sel:[0,1]
	v_pk_mul_f32 v[110:111], v[220:221], v[110:111] op_sel:[0,1]
	v_cndmask_b32_e32 v99, v212, v213, vcc
	v_cndmask_b32_e32 v98, v214, v215, vcc
	v_lshlrev_b64 v[96:97], 12, v[96:97]
	s_waitcnt vmcnt(1)
	v_pk_fma_f32 v[110:111], v[130:131], v[110:111], v[134:135]
	v_pk_fma_f32 v[128:129], v[128:129], v[222:223], v[132:133]
	v_lshl_add_u64 v[96:97], v[98:99], 0, v[96:97]
	v_pk_mul_f32 v[128:129], v[128:129], s[22:23] op_sel_hi:[1,0]
	v_pk_mul_f32 v[110:111], v[110:111], s[22:23] op_sel_hi:[1,0]
	v_lshl_add_u64 v[108:109], v[96:97], 0, v[170:171]
	s_waitcnt vmcnt(0)
	v_pk_fma_f32 v[94:95], v[94:95], v[138:139], v[110:111]
	v_pk_fma_f32 v[92:93], v[92:93], v[136:137], v[128:129]
	global_load_dwordx4 v[140:143], v[108:109], off
	global_load_dwordx4 v[104:107], v[108:109], off offset:64
	global_load_dwordx4 v[100:103], v[108:109], off offset:512
	global_load_dwordx4 v[96:99], v[108:109], off offset:576
	s_nop 0
	global_store_dwordx4 v[190:191], v[92:95], off
	s_nop 0
	s_nop 0
	global_load_dwordx4 v[92:95], v[124:125], off
	global_load_dwordx4 v[128:131], v[126:127], off
	global_load_dwordx4 v[132:135], v[188:189], off offset:64
	s_waitcnt vmcnt(3)
	v_mov_b32_e32 v110, v224
	v_mov_b32_e32 v111, v225
	v_sub_f32_e32 v123, v123, v110
	v_sub_f32_e32 v122, v122, v110
	v_sub_f32_e32 v121, v121, v110
	v_sub_f32_e32 v120, v120, v110
	v_pk_mul_f32 v[120:121], v[120:121], v[110:111] op_sel:[0,1]
	v_pk_mul_f32 v[110:111], v[122:123], v[110:111] op_sel:[0,1]
	s_waitcnt vmcnt(1)
	v_pk_fma_f32 v[92:93], v[92:93], v[120:121], v[128:129]
	v_pk_fma_f32 v[94:95], v[94:95], v[110:111], v[130:131]
	v_pk_mul_f32 v[92:93], v[92:93], s[22:23] op_sel_hi:[1,0]
	v_pk_mul_f32 v[94:95], v[94:95], s[22:23] op_sel_hi:[1,0]
	s_waitcnt vmcnt(0)
	v_pk_fma_f32 v[88:89], v[88:89], v[132:133], v[92:93]
	v_pk_fma_f32 v[90:91], v[90:91], v[134:135], v[94:95]
	global_store_dwordx4 v[190:191], v[88:91], off offset:64
	s_nop 0
	s_nop 0
	global_load_dwordx4 v[88:91], v[176:177], off
	global_load_dwordx4 v[92:95], v[178:179], off
	global_load_dwordx4 v[120:123], v[188:189], off offset:512
	s_waitcnt vmcnt(3)
	v_mov_b32_e32 v110, v224
	v_mov_b32_e32 v111, v225
	v_sub_f32_e32 v119, v119, v110
	v_sub_f32_e32 v118, v118, v110
	v_sub_f32_e32 v117, v117, v110
	v_sub_f32_e32 v116, v116, v110
	v_pk_mul_f32 v[116:117], v[116:117], v[110:111] op_sel:[0,1]
	v_pk_mul_f32 v[110:111], v[118:119], v[110:111] op_sel:[0,1]
	s_waitcnt vmcnt(1)
	v_pk_fma_f32 v[88:89], v[88:89], v[116:117], v[92:93]
	v_pk_fma_f32 v[90:91], v[90:91], v[110:111], v[94:95]
	v_pk_mul_f32 v[88:89], v[88:89], s[22:23] op_sel_hi:[1,0]
	v_pk_mul_f32 v[90:91], v[90:91], s[22:23] op_sel_hi:[1,0]
	s_waitcnt vmcnt(0)
	v_pk_fma_f32 v[84:85], v[84:85], v[120:121], v[88:89]
	v_pk_fma_f32 v[86:87], v[86:87], v[122:123], v[90:91]
	global_store_dwordx4 v[190:191], v[84:87], off offset:512
	s_nop 0
	s_nop 0
	global_load_dwordx4 v[84:87], v[180:181], off
	global_load_dwordx4 v[88:91], v[182:183], off
	global_load_dwordx4 v[92:95], v[188:189], off offset:576
	v_lshl_add_u64 v[122:123], v[218:219], 3, s[62:63]
	s_waitcnt vmcnt(3)
	v_mov_b32_e32 v110, v224
	v_mov_b32_e32 v111, v225
	v_sub_f32_e32 v115, v115, v110
	v_sub_f32_e32 v114, v114, v110
	v_sub_f32_e32 v113, v113, v110
	v_sub_f32_e32 v112, v112, v110
	v_pk_mul_f32 v[112:113], v[112:113], v[110:111] op_sel:[0,1]
	v_pk_mul_f32 v[110:111], v[114:115], v[110:111] op_sel:[0,1]
	s_waitcnt vmcnt(1)
	v_pk_fma_f32 v[84:85], v[84:85], v[112:113], v[88:89]
	v_pk_fma_f32 v[86:87], v[86:87], v[110:111], v[90:91]
	v_pk_mul_f32 v[84:85], v[84:85], s[22:23] op_sel_hi:[1,0]
	v_pk_mul_f32 v[86:87], v[86:87], s[22:23] op_sel_hi:[1,0]
	s_waitcnt vmcnt(0)
	v_pk_fma_f32 v[80:81], v[80:81], v[92:93], v[84:85]
	v_pk_fma_f32 v[82:83], v[82:83], v[94:95], v[86:87]
	global_store_dwordx4 v[190:191], v[80:83], off offset:576
	global_load_dwordx2 v[94:95], v[122:123], off
	global_load_dwordx4 v[110:113], v[172:173], off
	global_load_dwordx4 v[114:117], v[174:175], off
	v_cndmask_b32_e64 v80, v185, 4, vcc
	v_mul_hi_i32_i24_e32 v81, 0x6000, v80
	v_mul_i32_i24_e32 v80, 0x6000, v80
	v_lshl_add_u64 v[80:81], s[0:1], 0, v[80:81]
	v_lshl_add_u64 v[132:133], v[80:81], 0, v[170:171]
	global_load_dwordx4 v[118:121], v[132:133], off
	v_add_u32_e32 v80, 0x80, v184
	v_mul_hi_i32 v81, v80, s52
	v_lshrrev_b32_e32 v82, 31, v81
	v_ashrrev_i32_e32 v81, 11, v81
	v_add_u32_e32 v138, v81, v82
	v_mad_i32_i24 v80, v138, s53, v80
	v_lshl_add_u32 v81, v138, 13, v211
	v_lshlrev_b32_e32 v82, 8, v138
	v_cmp_gt_i32_e32 vcc, s46, v80
	s_waitcnt vmcnt(3)
	v_mov_b32_e32 v188, v94
	v_mov_b32_e32 v189, v95
	v_sub_f32_e32 v135, v143, v94
	v_cndmask_b32_e32 v81, v81, v82, vcc
	v_add_u32_e32 v80, v81, v80
	v_sub_f32_e32 v134, v142, v94
	v_sub_f32_e32 v137, v141, v94
	v_sub_f32_e32 v136, v140, v94
	v_ashrrev_i32_e32 v81, 31, v80
	v_pk_mul_f32 v[136:137], v[136:137], v[94:95] op_sel:[0,1]
	v_pk_mul_f32 v[94:95], v[134:135], v[94:95] op_sel:[0,1]
	v_cndmask_b32_e32 v83, v212, v213, vcc
	v_cndmask_b32_e32 v82, v214, v215, vcc
	v_lshlrev_b64 v[80:81], 12, v[80:81]
	s_waitcnt vmcnt(1)
	v_pk_fma_f32 v[94:95], v[112:113], v[94:95], v[116:117]
	v_pk_fma_f32 v[110:111], v[110:111], v[136:137], v[114:115]
	v_lshl_add_u64 v[80:81], v[82:83], 0, v[80:81]
	v_pk_mul_f32 v[110:111], v[110:111], s[22:23] op_sel_hi:[1,0]
	v_pk_mul_f32 v[94:95], v[94:95], s[22:23] op_sel_hi:[1,0]
	v_lshl_add_u64 v[92:93], v[80:81], 0, v[170:171]
	s_waitcnt vmcnt(0)
	v_pk_fma_f32 v[78:79], v[78:79], v[120:121], v[94:95]
	v_pk_fma_f32 v[76:77], v[76:77], v[118:119], v[110:111]
	global_load_dwordx4 v[128:131], v[92:93], off
	global_load_dwordx4 v[88:91], v[92:93], off offset:64
	global_load_dwordx4 v[84:87], v[92:93], off offset:512
	global_load_dwordx4 v[80:83], v[92:93], off offset:576
	s_nop 0
	global_store_dwordx4 v[108:109], v[76:79], off
	s_nop 0
	s_nop 0
	global_load_dwordx4 v[76:79], v[124:125], off
	global_load_dwordx4 v[110:113], v[126:127], off
	global_load_dwordx4 v[114:117], v[132:133], off offset:64
	s_waitcnt vmcnt(3)
	v_mov_b32_e32 v94, v188
	v_mov_b32_e32 v95, v189
	v_sub_f32_e32 v107, v107, v94
	v_sub_f32_e32 v106, v106, v94
	v_sub_f32_e32 v105, v105, v94
	v_sub_f32_e32 v104, v104, v94
	v_pk_mul_f32 v[104:105], v[104:105], v[94:95] op_sel:[0,1]
	v_pk_mul_f32 v[94:95], v[106:107], v[94:95] op_sel:[0,1]
	s_waitcnt vmcnt(1)
	v_pk_fma_f32 v[76:77], v[76:77], v[104:105], v[110:111]
	v_pk_fma_f32 v[78:79], v[78:79], v[94:95], v[112:113]
	v_pk_mul_f32 v[76:77], v[76:77], s[22:23] op_sel_hi:[1,0]
	v_pk_mul_f32 v[78:79], v[78:79], s[22:23] op_sel_hi:[1,0]
	s_waitcnt vmcnt(0)
	v_pk_fma_f32 v[72:73], v[72:73], v[114:115], v[76:77]
	v_pk_fma_f32 v[74:75], v[74:75], v[116:117], v[78:79]
	global_store_dwordx4 v[108:109], v[72:75], off offset:64
	s_nop 0
	s_nop 0
	global_load_dwordx4 v[72:75], v[176:177], off
	global_load_dwordx4 v[76:79], v[178:179], off
	global_load_dwordx4 v[104:107], v[132:133], off offset:512
	v_add_u32_e32 v112, 0x90, v184
	v_ashrrev_i32_e32 v113, 31, v112
	s_waitcnt vmcnt(3)
	v_mov_b32_e32 v94, v188
	v_mov_b32_e32 v95, v189
	v_sub_f32_e32 v103, v103, v94
	v_sub_f32_e32 v102, v102, v94
	v_sub_f32_e32 v101, v101, v94
	v_sub_f32_e32 v100, v100, v94
	v_pk_mul_f32 v[100:101], v[100:101], v[94:95] op_sel:[0,1]
	v_pk_mul_f32 v[94:95], v[102:103], v[94:95] op_sel:[0,1]
	s_waitcnt vmcnt(1)
	v_pk_fma_f32 v[72:73], v[72:73], v[100:101], v[76:77]
	v_pk_fma_f32 v[74:75], v[74:75], v[94:95], v[78:79]
	v_pk_mul_f32 v[72:73], v[72:73], s[22:23] op_sel_hi:[1,0]
	v_pk_mul_f32 v[74:75], v[74:75], s[22:23] op_sel_hi:[1,0]
	s_waitcnt vmcnt(0)
	v_pk_fma_f32 v[68:69], v[68:69], v[104:105], v[72:73]
	v_pk_fma_f32 v[70:71], v[70:71], v[106:107], v[74:75]
	global_store_dwordx4 v[108:109], v[68:71], off offset:512
	s_nop 0
	s_nop 0
	global_load_dwordx4 v[68:71], v[180:181], off
	global_load_dwordx4 v[72:75], v[182:183], off
	global_load_dwordx4 v[76:79], v[132:133], off offset:576
	s_waitcnt vmcnt(3)
	v_mov_b32_e32 v94, v188
	v_mov_b32_e32 v95, v189
	v_sub_f32_e32 v99, v99, v94
	v_sub_f32_e32 v98, v98, v94
	v_sub_f32_e32 v97, v97, v94
	v_sub_f32_e32 v96, v96, v94
	v_pk_mul_f32 v[96:97], v[96:97], v[94:95] op_sel:[0,1]
	v_pk_mul_f32 v[94:95], v[98:99], v[94:95] op_sel:[0,1]
	s_waitcnt vmcnt(1)
	v_pk_fma_f32 v[68:69], v[68:69], v[96:97], v[72:73]
	v_pk_fma_f32 v[70:71], v[70:71], v[94:95], v[74:75]
	v_pk_mul_f32 v[68:69], v[68:69], s[22:23] op_sel_hi:[1,0]
	v_pk_mul_f32 v[70:71], v[70:71], s[22:23] op_sel_hi:[1,0]
	s_waitcnt vmcnt(0)
	v_pk_fma_f32 v[64:65], v[64:65], v[76:77], v[68:69]
	v_pk_fma_f32 v[66:67], v[66:67], v[78:79], v[70:71]
	global_store_dwordx4 v[108:109], v[64:67], off offset:576
	global_load_dwordx2 v[78:79], v[186:187], off offset:1024
	global_load_dwordx4 v[94:97], v[172:173], off
	global_load_dwordx4 v[98:101], v[174:175], off
	v_cndmask_b32_e64 v64, v138, 4, vcc
	v_mul_hi_i32_i24_e32 v65, 0x6000, v64
	v_mul_i32_i24_e32 v64, 0x6000, v64
	v_lshl_add_u64 v[64:65], s[0:1], 0, v[64:65]
	v_lshl_add_u64 v[110:111], v[64:65], 0, v[170:171]
	global_load_dwordx4 v[102:105], v[110:111], off
	v_mul_hi_i32 v64, v112, s52
	v_lshrrev_b32_e32 v65, 31, v64
	v_ashrrev_i32_e32 v64, 11, v64
	v_add_u32_e32 v118, v64, v65
	v_mad_i32_i24 v64, v118, s53, v112
	v_lshl_add_u32 v65, v118, 13, v211
	v_lshlrev_b32_e32 v66, 8, v118
	v_cmp_gt_i32_e32 vcc, s46, v64
	s_waitcnt vmcnt(3)
	v_sub_f32_e32 v115, v131, v78
	v_cndmask_b32_e32 v65, v65, v66, vcc
	v_add_u32_e32 v64, v65, v64
	v_sub_f32_e32 v114, v130, v78
	v_sub_f32_e32 v117, v129, v78
	v_sub_f32_e32 v116, v128, v78
	v_ashrrev_i32_e32 v65, 31, v64
	v_pk_mul_f32 v[116:117], v[116:117], v[78:79] op_sel:[0,1]
	v_pk_mul_f32 v[78:79], v[114:115], v[78:79] op_sel:[0,1]
	v_cndmask_b32_e32 v67, v212, v213, vcc
	v_cndmask_b32_e32 v66, v214, v215, vcc
	v_lshlrev_b64 v[64:65], 12, v[64:65]
	s_waitcnt vmcnt(1)
	v_pk_fma_f32 v[78:79], v[96:97], v[78:79], v[100:101]
	v_pk_fma_f32 v[94:95], v[94:95], v[116:117], v[98:99]
	v_lshl_add_u64 v[64:65], v[66:67], 0, v[64:65]
	v_pk_mul_f32 v[94:95], v[94:95], s[22:23] op_sel_hi:[1,0]
	v_pk_mul_f32 v[78:79], v[78:79], s[22:23] op_sel_hi:[1,0]
	v_lshl_add_u64 v[76:77], v[64:65], 0, v[170:171]
	s_waitcnt vmcnt(0)
	v_pk_fma_f32 v[62:63], v[62:63], v[104:105], v[78:79]
	v_pk_fma_f32 v[60:61], v[60:61], v[102:103], v[94:95]
	global_load_dwordx4 v[106:109], v[76:77], off
	global_load_dwordx4 v[72:75], v[76:77], off offset:64
	global_load_dwordx4 v[68:71], v[76:77], off offset:512
	global_load_dwordx4 v[64:67], v[76:77], off offset:576
	s_nop 0
	global_store_dwordx4 v[92:93], v[60:63], off
	global_load_dwordx2 v[78:79], v[186:187], off offset:1024
	s_nop 0
	global_load_dwordx4 v[60:63], v[124:125], off
	global_load_dwordx4 v[94:97], v[126:127], off
	global_load_dwordx4 v[98:101], v[110:111], off offset:64
	s_waitcnt vmcnt(3)
	v_sub_f32_e32 v91, v91, v78
	v_sub_f32_e32 v90, v90, v78
	v_sub_f32_e32 v89, v89, v78
	v_sub_f32_e32 v88, v88, v78
	v_pk_mul_f32 v[88:89], v[88:89], v[78:79] op_sel:[0,1]
	v_pk_mul_f32 v[78:79], v[90:91], v[78:79] op_sel:[0,1]
	s_waitcnt vmcnt(1)
	v_pk_fma_f32 v[60:61], v[60:61], v[88:89], v[94:95]
	v_pk_fma_f32 v[62:63], v[62:63], v[78:79], v[96:97]
	v_pk_mul_f32 v[60:61], v[60:61], s[22:23] op_sel_hi:[1,0]
	v_pk_mul_f32 v[62:63], v[62:63], s[22:23] op_sel_hi:[1,0]
	s_waitcnt vmcnt(0)
	v_pk_fma_f32 v[56:57], v[56:57], v[98:99], v[60:61]
	v_pk_fma_f32 v[58:59], v[58:59], v[100:101], v[62:63]
	global_store_dwordx4 v[92:93], v[56:59], off offset:64
	global_load_dwordx2 v[78:79], v[186:187], off offset:1024
	s_nop 0
	global_load_dwordx4 v[56:59], v[176:177], off
	global_load_dwordx4 v[60:63], v[178:179], off
	global_load_dwordx4 v[88:91], v[110:111], off offset:512
	v_lshl_add_u64 v[94:95], v[112:113], 3, s[62:63]
	v_add_u32_e32 v98, 0xa0, v184
	v_ashrrev_i32_e32 v99, 31, v98
	s_waitcnt vmcnt(3)
	v_sub_f32_e32 v87, v87, v78
	v_sub_f32_e32 v86, v86, v78
	v_sub_f32_e32 v85, v85, v78
	v_sub_f32_e32 v84, v84, v78
	v_pk_mul_f32 v[84:85], v[84:85], v[78:79] op_sel:[0,1]
	v_pk_mul_f32 v[78:79], v[86:87], v[78:79] op_sel:[0,1]
	s_waitcnt vmcnt(1)
	v_pk_fma_f32 v[56:57], v[56:57], v[84:85], v[60:61]
	v_pk_fma_f32 v[58:59], v[58:59], v[78:79], v[62:63]
	v_pk_mul_f32 v[56:57], v[56:57], s[22:23] op_sel_hi:[1,0]
	v_pk_mul_f32 v[58:59], v[58:59], s[22:23] op_sel_hi:[1,0]
	s_waitcnt vmcnt(0)
	v_pk_fma_f32 v[52:53], v[52:53], v[88:89], v[56:57]
	v_pk_fma_f32 v[54:55], v[54:55], v[90:91], v[58:59]
	global_store_dwordx4 v[92:93], v[52:55], off offset:512
	global_load_dwordx2 v[78:79], v[186:187], off offset:1024
	s_nop 0
	global_load_dwordx4 v[52:55], v[180:181], off
	global_load_dwordx4 v[56:59], v[182:183], off
	global_load_dwordx4 v[60:63], v[110:111], off offset:576
	s_waitcnt vmcnt(3)
	v_sub_f32_e32 v83, v83, v78
	v_sub_f32_e32 v82, v82, v78
	v_sub_f32_e32 v81, v81, v78
	v_sub_f32_e32 v80, v80, v78
	v_pk_mul_f32 v[80:81], v[80:81], v[78:79] op_sel:[0,1]
	v_pk_mul_f32 v[78:79], v[82:83], v[78:79] op_sel:[0,1]
	s_waitcnt vmcnt(1)
	v_pk_fma_f32 v[52:53], v[52:53], v[80:81], v[56:57]
	v_pk_fma_f32 v[54:55], v[54:55], v[78:79], v[58:59]
	v_pk_mul_f32 v[52:53], v[52:53], s[22:23] op_sel_hi:[1,0]
	v_pk_mul_f32 v[54:55], v[54:55], s[22:23] op_sel_hi:[1,0]
	s_waitcnt vmcnt(0)
	v_pk_fma_f32 v[48:49], v[48:49], v[60:61], v[52:53]
	v_pk_fma_f32 v[50:51], v[50:51], v[62:63], v[54:55]
	global_store_dwordx4 v[92:93], v[48:51], off offset:576
	global_load_dwordx2 v[62:63], v[94:95], off
	global_load_dwordx4 v[78:81], v[172:173], off
	global_load_dwordx4 v[82:85], v[174:175], off
	v_cndmask_b32_e64 v48, v118, 4, vcc
	v_mul_hi_i32_i24_e32 v49, 0x6000, v48
	v_mul_i32_i24_e32 v48, 0x6000, v48
	v_lshl_add_u64 v[48:49], s[0:1], 0, v[48:49]
	v_lshl_add_u64 v[96:97], v[48:49], 0, v[170:171]
	global_load_dwordx4 v[86:89], v[96:97], off
	v_mul_hi_i32 v48, v98, s52
	v_lshrrev_b32_e32 v49, 31, v48
	v_ashrrev_i32_e32 v48, 11, v48
	v_add_u32_e32 v104, v48, v49
	v_mad_i32_i24 v48, v104, s53, v98
	v_lshl_add_u32 v49, v104, 13, v211
	v_lshlrev_b32_e32 v50, 8, v104
	v_cmp_gt_i32_e32 vcc, s46, v48
	s_waitcnt vmcnt(3)
	v_mov_b32_e32 v128, v62
	v_mov_b32_e32 v129, v63
	v_sub_f32_e32 v101, v109, v62
	v_cndmask_b32_e32 v49, v49, v50, vcc
	v_add_u32_e32 v48, v49, v48
	v_sub_f32_e32 v100, v108, v62
	v_sub_f32_e32 v103, v107, v62
	v_sub_f32_e32 v102, v106, v62
	v_ashrrev_i32_e32 v49, 31, v48
	v_pk_mul_f32 v[102:103], v[102:103], v[62:63] op_sel:[0,1]
	v_pk_mul_f32 v[62:63], v[100:101], v[62:63] op_sel:[0,1]
	v_cndmask_b32_e32 v51, v212, v213, vcc
	v_cndmask_b32_e32 v50, v214, v215, vcc
	v_lshlrev_b64 v[48:49], 12, v[48:49]
	s_waitcnt vmcnt(1)
	v_pk_fma_f32 v[62:63], v[80:81], v[62:63], v[84:85]
	v_pk_fma_f32 v[78:79], v[78:79], v[102:103], v[82:83]
	v_lshl_add_u64 v[48:49], v[50:51], 0, v[48:49]
	v_pk_mul_f32 v[78:79], v[78:79], s[22:23] op_sel_hi:[1,0]
	v_pk_mul_f32 v[62:63], v[62:63], s[22:23] op_sel_hi:[1,0]
	v_lshl_add_u64 v[60:61], v[48:49], 0, v[170:171]
	s_waitcnt vmcnt(0)
	v_pk_fma_f32 v[46:47], v[46:47], v[88:89], v[62:63]
	v_pk_fma_f32 v[44:45], v[44:45], v[86:87], v[78:79]
	global_load_dwordx4 v[90:93], v[60:61], off
	global_load_dwordx4 v[56:59], v[60:61], off offset:64
	global_load_dwordx4 v[52:55], v[60:61], off offset:512
	global_load_dwordx4 v[48:51], v[60:61], off offset:576
	s_nop 0
	global_store_dwordx4 v[76:77], v[44:47], off
	s_nop 0
	s_nop 0
	global_load_dwordx4 v[44:47], v[124:125], off
	global_load_dwordx4 v[78:81], v[126:127], off
	global_load_dwordx4 v[82:85], v[96:97], off offset:64
	s_waitcnt vmcnt(3)
	v_mov_b32_e32 v62, v128
	v_mov_b32_e32 v63, v129
	v_sub_f32_e32 v75, v75, v62
	v_sub_f32_e32 v74, v74, v62
	v_sub_f32_e32 v73, v73, v62
	v_sub_f32_e32 v72, v72, v62
	v_pk_mul_f32 v[72:73], v[72:73], v[62:63] op_sel:[0,1]
	v_pk_mul_f32 v[62:63], v[74:75], v[62:63] op_sel:[0,1]
	s_waitcnt vmcnt(1)
	v_pk_fma_f32 v[44:45], v[44:45], v[72:73], v[78:79]
	v_pk_fma_f32 v[46:47], v[46:47], v[62:63], v[80:81]
	v_pk_mul_f32 v[44:45], v[44:45], s[22:23] op_sel_hi:[1,0]
	v_pk_mul_f32 v[46:47], v[46:47], s[22:23] op_sel_hi:[1,0]
	s_waitcnt vmcnt(0)
	v_pk_fma_f32 v[40:41], v[40:41], v[82:83], v[44:45]
	v_pk_fma_f32 v[42:43], v[42:43], v[84:85], v[46:47]
	global_store_dwordx4 v[76:77], v[40:43], off offset:64
	s_nop 0
	s_nop 0
	global_load_dwordx4 v[40:43], v[176:177], off
	global_load_dwordx4 v[44:47], v[178:179], off
	global_load_dwordx4 v[72:75], v[96:97], off offset:512
	v_lshl_add_u64 v[78:79], v[98:99], 3, s[62:63]
	v_add_u32_e32 v82, 0xb0, v184
	v_ashrrev_i32_e32 v83, 31, v82
	s_waitcnt vmcnt(3)
	v_mov_b32_e32 v62, v128
	v_mov_b32_e32 v63, v129
	v_sub_f32_e32 v71, v71, v62
	v_sub_f32_e32 v70, v70, v62
	v_sub_f32_e32 v69, v69, v62
	v_sub_f32_e32 v68, v68, v62
	v_pk_mul_f32 v[68:69], v[68:69], v[62:63] op_sel:[0,1]
	v_pk_mul_f32 v[62:63], v[70:71], v[62:63] op_sel:[0,1]
	s_waitcnt vmcnt(1)
	v_pk_fma_f32 v[40:41], v[40:41], v[68:69], v[44:45]
	v_pk_fma_f32 v[42:43], v[42:43], v[62:63], v[46:47]
	v_pk_mul_f32 v[40:41], v[40:41], s[22:23] op_sel_hi:[1,0]
	v_pk_mul_f32 v[42:43], v[42:43], s[22:23] op_sel_hi:[1,0]
	s_waitcnt vmcnt(0)
	v_pk_fma_f32 v[36:37], v[36:37], v[72:73], v[40:41]
	v_pk_fma_f32 v[38:39], v[38:39], v[74:75], v[42:43]
	global_store_dwordx4 v[76:77], v[36:39], off offset:512
	s_nop 0
	s_nop 0
	global_load_dwordx4 v[36:39], v[180:181], off
	global_load_dwordx4 v[40:43], v[182:183], off
	global_load_dwordx4 v[44:47], v[96:97], off offset:576
	s_waitcnt vmcnt(3)
	v_mov_b32_e32 v62, v128
	v_mov_b32_e32 v63, v129
	v_sub_f32_e32 v67, v67, v62
	v_sub_f32_e32 v66, v66, v62
	v_sub_f32_e32 v65, v65, v62
	v_sub_f32_e32 v64, v64, v62
	v_pk_mul_f32 v[64:65], v[64:65], v[62:63] op_sel:[0,1]
	v_pk_mul_f32 v[62:63], v[66:67], v[62:63] op_sel:[0,1]
	s_waitcnt vmcnt(1)
	v_pk_fma_f32 v[36:37], v[36:37], v[64:65], v[40:41]
	v_pk_fma_f32 v[38:39], v[38:39], v[62:63], v[42:43]
	v_pk_mul_f32 v[36:37], v[36:37], s[22:23] op_sel_hi:[1,0]
	v_pk_mul_f32 v[38:39], v[38:39], s[22:23] op_sel_hi:[1,0]
	s_waitcnt vmcnt(0)
	v_pk_fma_f32 v[32:33], v[32:33], v[44:45], v[36:37]
	v_pk_fma_f32 v[34:35], v[34:35], v[46:47], v[38:39]
	global_store_dwordx4 v[76:77], v[32:35], off offset:576
	global_load_dwordx2 v[46:47], v[78:79], off
	global_load_dwordx4 v[42:45], v[172:173], off
	global_load_dwordx4 v[62:65], v[174:175], off
	v_cndmask_b32_e64 v32, v104, 4, vcc
	v_mul_hi_i32_i24_e32 v33, 0x6000, v32
	v_mul_i32_i24_e32 v32, 0x6000, v32
	v_lshl_add_u64 v[32:33], s[0:1], 0, v[32:33]
	v_lshl_add_u64 v[80:81], v[32:33], 0, v[170:171]
	global_load_dwordx4 v[66:69], v[80:81], off
	v_mul_hi_i32 v32, v82, s52
	v_lshrrev_b32_e32 v33, 31, v32
	v_ashrrev_i32_e32 v32, 11, v32
	v_add_u32_e32 v88, v32, v33
	v_mad_i32_i24 v32, v88, s53, v82
	v_lshl_add_u32 v33, v88, 13, v211
	v_lshlrev_b32_e32 v34, 8, v88
	v_cmp_gt_i32_e32 vcc, s46, v32
	s_waitcnt vmcnt(3)
	v_mov_b32_e32 v128, v46
	v_mov_b32_e32 v129, v47
	v_sub_f32_e32 v85, v93, v46
	v_cndmask_b32_e32 v33, v33, v34, vcc
	v_add_u32_e32 v32, v33, v32
	v_sub_f32_e32 v84, v92, v46
	v_sub_f32_e32 v87, v91, v46
	v_sub_f32_e32 v86, v90, v46
	v_ashrrev_i32_e32 v33, 31, v32
	v_pk_mul_f32 v[86:87], v[86:87], v[46:47] op_sel:[0,1]
	v_pk_mul_f32 v[46:47], v[84:85], v[46:47] op_sel:[0,1]
	v_cndmask_b32_e32 v35, v212, v213, vcc
	v_cndmask_b32_e32 v34, v214, v215, vcc
	v_lshlrev_b64 v[32:33], 12, v[32:33]
	s_waitcnt vmcnt(1)
	v_pk_fma_f32 v[44:45], v[44:45], v[46:47], v[64:65]
	v_pk_fma_f32 v[42:43], v[42:43], v[86:87], v[62:63]
	v_lshl_add_u64 v[32:33], v[34:35], 0, v[32:33]
	v_pk_mul_f32 v[42:43], v[42:43], s[22:23] op_sel_hi:[1,0]
	v_pk_mul_f32 v[44:45], v[44:45], s[22:23] op_sel_hi:[1,0]
	v_lshl_add_u64 v[40:41], v[32:33], 0, v[170:171]
	s_waitcnt vmcnt(0)
	v_pk_fma_f32 v[30:31], v[30:31], v[68:69], v[44:45]
	v_pk_fma_f32 v[28:29], v[28:29], v[66:67], v[42:43]
	global_load_dwordx4 v[70:73], v[40:41], off
	global_load_dwordx4 v[74:77], v[40:41], off offset:64
	global_load_dwordx4 v[36:39], v[40:41], off offset:512
	global_load_dwordx4 v[32:35], v[40:41], off offset:576
	s_nop 0
	global_store_dwordx4 v[60:61], v[28:31], off
	s_nop 0
	s_nop 0
	global_load_dwordx4 v[28:31], v[124:125], off
	global_load_dwordx4 v[42:45], v[126:127], off
	global_load_dwordx4 v[62:65], v[80:81], off offset:64
	s_waitcnt vmcnt(3)
	v_mov_b32_e32 v46, v128
	v_mov_b32_e32 v47, v129
	v_sub_f32_e32 v59, v59, v46
	v_sub_f32_e32 v58, v58, v46
	v_sub_f32_e32 v57, v57, v46
	v_sub_f32_e32 v56, v56, v46
	v_pk_mul_f32 v[56:57], v[56:57], v[46:47] op_sel:[0,1]
	v_pk_mul_f32 v[46:47], v[58:59], v[46:47] op_sel:[0,1]
	s_waitcnt vmcnt(1)
	v_pk_fma_f32 v[28:29], v[28:29], v[56:57], v[42:43]
	v_pk_fma_f32 v[30:31], v[30:31], v[46:47], v[44:45]
	v_pk_mul_f32 v[28:29], v[28:29], s[22:23] op_sel_hi:[1,0]
	v_pk_mul_f32 v[30:31], v[30:31], s[22:23] op_sel_hi:[1,0]
	s_waitcnt vmcnt(0)
	v_pk_fma_f32 v[24:25], v[24:25], v[62:63], v[28:29]
	v_pk_fma_f32 v[26:27], v[26:27], v[64:65], v[30:31]
	global_store_dwordx4 v[60:61], v[24:27], off offset:64
	s_nop 0
	s_nop 0
	global_load_dwordx4 v[24:27], v[176:177], off
	global_load_dwordx4 v[28:31], v[178:179], off
	global_load_dwordx4 v[42:45], v[80:81], off offset:512
	s_waitcnt vmcnt(3)
	v_mov_b32_e32 v46, v128
	v_mov_b32_e32 v47, v129
	v_sub_f32_e32 v55, v55, v46
	v_sub_f32_e32 v54, v54, v46
	v_sub_f32_e32 v53, v53, v46
	v_sub_f32_e32 v52, v52, v46
	v_pk_mul_f32 v[52:53], v[52:53], v[46:47] op_sel:[0,1]
	v_pk_mul_f32 v[46:47], v[54:55], v[46:47] op_sel:[0,1]
	s_waitcnt vmcnt(1)
	v_pk_fma_f32 v[24:25], v[24:25], v[52:53], v[28:29]
	v_pk_fma_f32 v[26:27], v[26:27], v[46:47], v[30:31]
	v_pk_mul_f32 v[24:25], v[24:25], s[22:23] op_sel_hi:[1,0]
	v_pk_mul_f32 v[26:27], v[26:27], s[22:23] op_sel_hi:[1,0]
	s_waitcnt vmcnt(0)
	v_pk_fma_f32 v[20:21], v[20:21], v[42:43], v[24:25]
	v_pk_fma_f32 v[22:23], v[22:23], v[44:45], v[26:27]
	global_store_dwordx4 v[60:61], v[20:23], off offset:512
	s_nop 0
	s_nop 0
	global_load_dwordx4 v[20:23], v[180:181], off
	global_load_dwordx4 v[24:27], v[182:183], off
	global_load_dwordx4 v[28:31], v[80:81], off offset:576
	v_lshl_add_u64 v[44:45], v[82:83], 3, s[62:63]
	s_waitcnt vmcnt(3)
	v_mov_b32_e32 v42, v128
	v_mov_b32_e32 v43, v129
	v_sub_f32_e32 v47, v51, v42
	v_sub_f32_e32 v46, v50, v42
	v_sub_f32_e32 v49, v49, v42
	v_sub_f32_e32 v48, v48, v42
	v_pk_mul_f32 v[48:49], v[48:49], v[42:43] op_sel:[0,1]
	v_pk_mul_f32 v[42:43], v[46:47], v[42:43] op_sel:[0,1]
	s_waitcnt vmcnt(1)
	v_pk_fma_f32 v[20:21], v[20:21], v[48:49], v[24:25]
	v_pk_fma_f32 v[22:23], v[22:23], v[42:43], v[26:27]
	v_pk_mul_f32 v[20:21], v[20:21], s[22:23] op_sel_hi:[1,0]
	v_pk_mul_f32 v[22:23], v[22:23], s[22:23] op_sel_hi:[1,0]
	s_waitcnt vmcnt(0)
	v_pk_fma_f32 v[16:17], v[16:17], v[28:29], v[20:21]
	v_pk_fma_f32 v[18:19], v[18:19], v[30:31], v[22:23]
	global_store_dwordx4 v[60:61], v[16:19], off offset:576
	global_load_dwordx2 v[28:29], v[44:45], off
	v_cndmask_b32_e64 v24, v88, 4, vcc
	v_mul_hi_i32_i24_e32 v25, 0x6000, v24
	v_mul_i32_i24_e32 v24, 0x6000, v24
	global_load_dwordx4 v[16:19], v[172:173], off
	global_load_dwordx4 v[20:23], v[174:175], off
	v_lshl_add_u64 v[24:25], s[0:1], 0, v[24:25]
	v_lshl_add_u64 v[30:31], v[24:25], 0, v[170:171]
	global_load_dwordx4 v[24:27], v[30:31], off
	s_and_b64 vcc, exec, s[8:9]
	s_waitcnt vmcnt(3)
	v_mov_b32_e32 v128, v28
	v_mov_b32_e32 v129, v29
	v_sub_f32_e32 v43, v73, v28
	v_sub_f32_e32 v42, v72, v28
	v_sub_f32_e32 v47, v71, v28
	v_sub_f32_e32 v46, v70, v28
	v_pk_mul_f32 v[46:47], v[46:47], v[28:29] op_sel:[0,1]
	v_pk_mul_f32 v[28:29], v[42:43], v[28:29] op_sel:[0,1]
	s_waitcnt vmcnt(1)
	v_pk_fma_f32 v[16:17], v[16:17], v[46:47], v[20:21]
	v_pk_fma_f32 v[18:19], v[18:19], v[28:29], v[22:23]
	v_pk_mul_f32 v[16:17], v[16:17], s[22:23] op_sel_hi:[1,0]
	v_pk_mul_f32 v[18:19], v[18:19], s[22:23] op_sel_hi:[1,0]
	s_waitcnt vmcnt(0)
	v_pk_fma_f32 v[12:13], v[12:13], v[24:25], v[16:17]
	v_pk_fma_f32 v[14:15], v[14:15], v[26:27], v[18:19]
	global_store_dwordx4 v[40:41], v[12:15], off
	s_nop 0
	s_nop 0
	global_load_dwordx4 v[12:15], v[124:125], off
	global_load_dwordx4 v[16:19], v[126:127], off
	global_load_dwordx4 v[20:23], v[30:31], off offset:64
	s_waitcnt vmcnt(3)
	v_mov_b32_e32 v24, v128
	v_mov_b32_e32 v25, v129
	v_sub_f32_e32 v27, v77, v24
	v_sub_f32_e32 v26, v76, v24
	v_sub_f32_e32 v29, v75, v24
	v_sub_f32_e32 v28, v74, v24
	v_pk_mul_f32 v[28:29], v[28:29], v[24:25] op_sel:[0,1]
	v_pk_mul_f32 v[24:25], v[26:27], v[24:25] op_sel:[0,1]
	s_waitcnt vmcnt(1)
	v_pk_fma_f32 v[12:13], v[12:13], v[28:29], v[16:17]
	v_pk_fma_f32 v[14:15], v[14:15], v[24:25], v[18:19]
	v_pk_mul_f32 v[12:13], v[12:13], s[22:23] op_sel_hi:[1,0]
	v_pk_mul_f32 v[14:15], v[14:15], s[22:23] op_sel_hi:[1,0]
	s_waitcnt vmcnt(0)
	v_pk_fma_f32 v[8:9], v[8:9], v[20:21], v[12:13]
	v_pk_fma_f32 v[10:11], v[10:11], v[22:23], v[14:15]
	global_store_dwordx4 v[40:41], v[8:11], off offset:64
	s_nop 0
	s_nop 0
	global_load_dwordx4 v[8:11], v[176:177], off
	global_load_dwordx4 v[12:15], v[178:179], off
	global_load_dwordx4 v[16:19], v[30:31], off offset:512
	s_waitcnt vmcnt(3)
	v_mov_b32_e32 v20, v128
	v_mov_b32_e32 v21, v129
	v_sub_f32_e32 v23, v39, v20
	v_sub_f32_e32 v22, v38, v20
	v_sub_f32_e32 v25, v37, v20
	v_sub_f32_e32 v24, v36, v20
	v_pk_mul_f32 v[24:25], v[24:25], v[20:21] op_sel:[0,1]
	v_pk_mul_f32 v[20:21], v[22:23], v[20:21] op_sel:[0,1]
	s_waitcnt vmcnt(1)
	v_pk_fma_f32 v[8:9], v[8:9], v[24:25], v[12:13]
	v_pk_fma_f32 v[10:11], v[10:11], v[20:21], v[14:15]
	v_pk_mul_f32 v[8:9], v[8:9], s[22:23] op_sel_hi:[1,0]
	v_pk_mul_f32 v[10:11], v[10:11], s[22:23] op_sel_hi:[1,0]
	s_waitcnt vmcnt(0)
	v_pk_fma_f32 v[4:5], v[4:5], v[16:17], v[8:9]
	v_pk_fma_f32 v[6:7], v[6:7], v[18:19], v[10:11]
	global_store_dwordx4 v[40:41], v[4:7], off offset:512
	s_nop 0
	s_nop 0
	global_load_dwordx4 v[4:7], v[180:181], off
	global_load_dwordx4 v[8:11], v[182:183], off
	global_load_dwordx4 v[12:15], v[30:31], off offset:576
	s_waitcnt vmcnt(3)
	v_mov_b32_e32 v16, v128
	v_mov_b32_e32 v17, v129
	v_sub_f32_e32 v19, v35, v16
	v_sub_f32_e32 v18, v34, v16
	v_sub_f32_e32 v21, v33, v16
	v_sub_f32_e32 v20, v32, v16
	v_pk_mul_f32 v[20:21], v[20:21], v[16:17] op_sel:[0,1]
	v_pk_mul_f32 v[16:17], v[18:19], v[16:17] op_sel:[0,1]
	s_waitcnt vmcnt(1)
	v_pk_fma_f32 v[4:5], v[4:5], v[20:21], v[8:9]
	v_pk_fma_f32 v[6:7], v[6:7], v[16:17], v[10:11]
	v_pk_mul_f32 v[4:5], v[4:5], s[22:23] op_sel_hi:[1,0]
	v_pk_mul_f32 v[6:7], v[6:7], s[22:23] op_sel_hi:[1,0]
	s_waitcnt vmcnt(0)
	v_pk_fma_f32 v[0:1], v[0:1], v[12:13], v[4:5]
	v_pk_fma_f32 v[2:3], v[2:3], v[14:15], v[6:7]
	global_store_dwordx4 v[40:41], v[0:3], off offset:576
	s_cbranch_vccnz .LBB0_3017
	s_andn2_b64 vcc, exec, s[16:17]
	s_cbranch_vccnz .LBB0_3016
	s_barrier
	s_branch .LBB0_3016

.LBB0_3537:
	v_lshl_add_u32 v180, s28, 8, v147
	v_mul_hi_i32 v128, v180, s61
	v_lshrrev_b32_e32 v129, 31, v128
	v_ashrrev_i32_e32 v128, 11, v128
	v_add_u32_e32 v132, v128, v129
	v_mad_i32_i24 v128, v132, s64, v180
	v_lshl_add_u32 v129, v132, 13, v204
	v_lshlrev_b32_e32 v130, 8, v132
	v_cmp_gt_i32_e32 vcc, s51, v128
	v_lshl_or_b32 v222, s65, 8, v153
	v_mov_b32_e32 v205, s89
	v_cndmask_b32_e32 v129, v129, v130, vcc
	v_add_u32_e32 v128, v129, v128
	v_mov_b32_e32 v206, s71
	v_mov_b32_e32 v207, s88
	v_mov_b32_e32 v208, s70
	v_ashrrev_i32_e32 v129, 31, v128
	v_cndmask_b32_e32 v131, v205, v206, vcc
	v_cndmask_b32_e32 v130, v207, v208, vcc
	v_lshlrev_b64 v[128:129], 12, v[128:129]
	v_ashrrev_i32_e32 v223, 31, v222
	v_lshl_add_u64 v[128:129], v[130:131], 0, v[128:129]
	v_lshlrev_b64 v[166:167], 2, v[222:223]
	v_ashrrev_i32_e32 v181, 31, v180
	v_lshl_add_u64 v[186:187], v[128:129], 0, v[166:167]
	v_lshl_add_u64 v[182:183], v[180:181], 3, s[62:63]
	global_load_dwordx4 v[172:175], v[186:187], off
	global_load_dwordx4 v[218:221], v[186:187], off offset:64
	global_load_dwordx2 v[224:225], v[182:183], off
	v_cndmask_b32_e64 v128, v132, 4, vcc
	v_mul_hi_i32_i24_e32 v129, 0x6000, v128
	v_lshl_add_u64 v[168:169], s[10:11], 0, v[166:167]
	v_lshl_add_u64 v[170:171], s[12:13], 0, v[166:167]
	v_mul_i32_i24_e32 v128, 0x6000, v128
	global_load_dwordx4 v[176:179], v[168:169], off
	global_load_dwordx4 v[210:213], v[170:171], off
	v_lshl_add_u64 v[128:129], s[8:9], 0, v[128:129]
	v_lshl_add_u64 v[226:227], v[128:129], 0, v[166:167]
	global_load_dwordx4 v[214:217], v[226:227], off
	v_or_b32_e32 v230, 16, v180
	v_mul_hi_i32 v128, v230, s61
	v_lshrrev_b32_e32 v129, 31, v128
	v_ashrrev_i32_e32 v128, 11, v128
	v_add_u32_e32 v181, v128, v129
	v_mad_i32_i24 v128, v181, s64, v230
	v_lshl_add_u32 v129, v181, 13, v204
	v_lshlrev_b32_e32 v130, 8, v181
	v_cmp_gt_i32_e32 vcc, s51, v128
	v_or_b32_e32 v228, 16, v222
	v_ashrrev_i32_e32 v229, 31, v228
	v_cndmask_b32_e32 v129, v129, v130, vcc
	v_add_u32_e32 v128, v129, v128
	v_ashrrev_i32_e32 v129, 31, v128
	v_cndmask_b32_e32 v131, v205, v206, vcc
	v_cndmask_b32_e32 v130, v207, v208, vcc
	v_lshlrev_b64 v[128:129], 12, v[128:129]
	v_lshl_add_u64 v[128:129], v[130:131], 0, v[128:129]
	v_lshl_add_u64 v[184:185], v[128:129], 0, v[166:167]
	global_load_dwordx4 v[140:143], v[184:185], off
	global_load_dwordx4 v[136:139], v[184:185], off offset:64
	global_load_dwordx4 v[132:135], v[184:185], off offset:512
	global_load_dwordx4 v[128:131], v[184:185], off offset:576
	v_ashrrev_i32_e32 v231, 31, v230
	v_or_b32_e32 v232, 32, v180
	v_ashrrev_i32_e32 v233, 31, v232
	s_mov_b64 s[4:5], -1
	s_waitcnt vmcnt(0)
	v_sub_f32_e32 v175, v175, v224
	v_sub_f32_e32 v174, v174, v224
	v_sub_f32_e32 v173, v173, v224
	v_sub_f32_e32 v172, v172, v224
	v_pk_mul_f32 v[172:173], v[172:173], v[224:225] op_sel:[0,1]
	v_pk_mul_f32 v[174:175], v[174:175], v[224:225] op_sel:[0,1]
	v_pk_fma_f32 v[172:173], v[176:177], v[172:173], v[210:211]
	v_pk_fma_f32 v[174:175], v[178:179], v[174:175], v[212:213]
	v_pk_mul_f32 v[172:173], v[172:173], s[18:19] op_sel_hi:[1,0]
	v_pk_mul_f32 v[174:175], v[174:175], s[18:19] op_sel_hi:[1,0]
	v_pk_fma_f32 v[124:125], v[124:125], v[214:215], v[172:173]
	v_pk_fma_f32 v[126:127], v[126:127], v[216:217], v[174:175]
	global_store_dwordx4 v[186:187], v[124:127], off
	s_nop 0
	s_waitcnt vmcnt(1)
	v_sub_f32_e32 v221, v221, v224
	v_lshlrev_b64 v[126:127], 2, v[228:229]
	v_lshl_add_u64 v[124:125], s[10:11], 0, v[126:127]
	v_lshl_add_u64 v[126:127], s[12:13], 0, v[126:127]
	global_load_dwordx4 v[172:175], v[124:125], off
	global_load_dwordx4 v[176:179], v[126:127], off
	global_load_dwordx4 v[210:213], v[226:227], off offset:64
	v_sub_f32_e32 v220, v220, v224
	v_sub_f32_e32 v219, v219, v224
	v_sub_f32_e32 v218, v218, v224
	v_pk_mul_f32 v[218:219], v[218:219], v[224:225] op_sel:[0,1]
	v_pk_mul_f32 v[220:221], v[220:221], v[224:225] op_sel:[0,1]
	v_or_b32_e32 v228, 0x80, v222
	global_load_dwordx4 v[214:217], v[186:187], off offset:512
	v_ashrrev_i32_e32 v229, 31, v228
	v_or_b32_e32 v222, 0x90, v222
	v_ashrrev_i32_e32 v223, 31, v222
	s_waitcnt vmcnt(2)
	v_pk_fma_f32 v[174:175], v[174:175], v[220:221], v[178:179]
	v_pk_fma_f32 v[172:173], v[172:173], v[218:219], v[176:177]
	v_pk_mul_f32 v[174:175], v[174:175], s[18:19] op_sel_hi:[1,0]
	v_pk_mul_f32 v[172:173], v[172:173], s[18:19] op_sel_hi:[1,0]
	s_waitcnt vmcnt(1)
	v_pk_fma_f32 v[122:123], v[122:123], v[212:213], v[174:175]
	v_pk_fma_f32 v[120:121], v[120:121], v[210:211], v[172:173]
	global_store_dwordx4 v[186:187], v[120:123], off offset:64
	s_nop 0
	s_waitcnt vmcnt(1)
	v_sub_f32_e32 v217, v217, v224
	v_lshlrev_b64 v[120:121], 2, v[228:229]
	v_lshl_add_u64 v[172:173], s[10:11], 0, v[120:121]
	v_lshl_add_u64 v[174:175], s[12:13], 0, v[120:121]
	global_load_dwordx4 v[120:123], v[172:173], off
	global_load_dwordx4 v[176:179], v[174:175], off
	global_load_dwordx4 v[210:213], v[226:227], off offset:512
	v_sub_f32_e32 v216, v216, v224
	v_sub_f32_e32 v215, v215, v224
	v_sub_f32_e32 v214, v214, v224
	v_pk_mul_f32 v[214:215], v[214:215], v[224:225] op_sel:[0,1]
	v_pk_mul_f32 v[216:217], v[216:217], v[224:225] op_sel:[0,1]
	global_load_dwordx4 v[218:221], v[186:187], off offset:576
	s_waitcnt vmcnt(2)
	v_pk_fma_f32 v[122:123], v[122:123], v[216:217], v[178:179]
	v_pk_fma_f32 v[120:121], v[120:121], v[214:215], v[176:177]
	v_pk_mul_f32 v[122:123], v[122:123], s[18:19] op_sel_hi:[1,0]
	v_pk_mul_f32 v[120:121], v[120:121], s[18:19] op_sel_hi:[1,0]
	s_waitcnt vmcnt(1)
	v_pk_fma_f32 v[118:119], v[118:119], v[212:213], v[122:123]
	v_pk_fma_f32 v[116:117], v[116:117], v[210:211], v[120:121]
	global_store_dwordx4 v[186:187], v[116:119], off offset:512
	s_nop 0
	s_waitcnt vmcnt(1)
	v_mov_b32_e32 v214, v224
	v_mov_b32_e32 v215, v225
	v_sub_f32_e32 v217, v221, v214
	v_lshlrev_b64 v[116:117], 2, v[222:223]
	v_lshl_add_u64 v[176:177], s[10:11], 0, v[116:117]
	v_lshl_add_u64 v[178:179], s[12:13], 0, v[116:117]
	global_load_dwordx4 v[116:119], v[176:177], off
	global_load_dwordx4 v[120:123], v[178:179], off
	global_load_dwordx4 v[210:213], v[226:227], off offset:576
	v_sub_f32_e32 v216, v220, v214
	v_sub_f32_e32 v219, v219, v214
	v_sub_f32_e32 v218, v218, v214
	v_pk_mul_f32 v[218:219], v[218:219], v[214:215] op_sel:[0,1]
	v_pk_mul_f32 v[214:215], v[216:217], v[214:215] op_sel:[0,1]
	v_lshl_add_u64 v[226:227], v[230:231], 3, s[62:63]
	s_waitcnt vmcnt(1)
	v_pk_fma_f32 v[118:119], v[118:119], v[214:215], v[122:123]
	v_pk_fma_f32 v[116:117], v[116:117], v[218:219], v[120:121]
	v_pk_mul_f32 v[118:119], v[118:119], s[18:19] op_sel_hi:[1,0]
	v_pk_mul_f32 v[116:117], v[116:117], s[18:19] op_sel_hi:[1,0]
	s_waitcnt vmcnt(0)
	v_pk_fma_f32 v[114:115], v[114:115], v[212:213], v[118:119]
	v_pk_fma_f32 v[112:113], v[112:113], v[210:211], v[116:117]
	global_store_dwordx4 v[186:187], v[112:115], off offset:576
	global_load_dwordx2 v[228:229], v[226:227], off
	global_load_dwordx4 v[210:213], v[168:169], off
	global_load_dwordx4 v[214:217], v[170:171], off
	v_cndmask_b32_e64 v112, v181, 4, vcc
	v_mul_hi_i32_i24_e32 v113, 0x6000, v112
	v_mul_i32_i24_e32 v112, 0x6000, v112
	v_lshl_add_u64 v[112:113], s[8:9], 0, v[112:113]
	v_lshl_add_u64 v[230:231], v[112:113], 0, v[166:167]
	global_load_dwordx4 v[218:221], v[230:231], off
	v_mul_hi_i32 v112, v232, s61
	v_lshrrev_b32_e32 v113, 31, v112
	v_ashrrev_i32_e32 v112, 11, v112
	v_add_u32_e32 v181, v112, v113
	v_mad_i32_i24 v112, v181, s64, v232
	v_lshl_add_u32 v113, v181, 13, v204
	v_lshlrev_b32_e32 v114, 8, v181
	v_cmp_gt_i32_e32 vcc, s51, v112
	s_waitcnt vmcnt(3)
	v_sub_f32_e32 v143, v143, v228
	v_cndmask_b32_e32 v113, v113, v114, vcc
	v_add_u32_e32 v112, v113, v112
	v_sub_f32_e32 v142, v142, v228
	v_sub_f32_e32 v141, v141, v228
	v_sub_f32_e32 v140, v140, v228
	v_ashrrev_i32_e32 v113, 31, v112
	v_pk_mul_f32 v[140:141], v[140:141], v[228:229] op_sel:[0,1]
	v_pk_mul_f32 v[142:143], v[142:143], v[228:229] op_sel:[0,1]
	v_cndmask_b32_e32 v115, v205, v206, vcc
	v_cndmask_b32_e32 v114, v207, v208, vcc
	v_lshlrev_b64 v[112:113], 12, v[112:113]
	s_waitcnt vmcnt(1)
	v_pk_fma_f32 v[142:143], v[212:213], v[142:143], v[216:217]
	v_pk_fma_f32 v[140:141], v[210:211], v[140:141], v[214:215]
	v_lshl_add_u64 v[112:113], v[114:115], 0, v[112:113]
	v_pk_mul_f32 v[140:141], v[140:141], s[18:19] op_sel_hi:[1,0]
	v_pk_mul_f32 v[142:143], v[142:143], s[18:19] op_sel_hi:[1,0]
	v_lshl_add_u64 v[186:187], v[112:113], 0, v[166:167]
	s_waitcnt vmcnt(0)
	v_pk_fma_f32 v[110:111], v[110:111], v[220:221], v[142:143]
	v_pk_fma_f32 v[108:109], v[108:109], v[218:219], v[140:141]
	global_load_dwordx4 v[222:225], v[186:187], off
	global_load_dwordx4 v[120:123], v[186:187], off offset:64
	global_load_dwordx4 v[116:119], v[186:187], off offset:512
	global_load_dwordx4 v[112:115], v[186:187], off offset:576
	s_nop 0
	global_store_dwordx4 v[184:185], v[108:111], off
	s_nop 0
	s_nop 0
	global_load_dwordx4 v[108:111], v[124:125], off
	global_load_dwordx4 v[140:143], v[126:127], off
	global_load_dwordx4 v[210:213], v[230:231], off offset:64
	s_waitcnt vmcnt(3)
	v_mov_b32_e32 v214, v228
	v_mov_b32_e32 v215, v229
	v_sub_f32_e32 v139, v139, v214
	v_sub_f32_e32 v138, v138, v214
	v_sub_f32_e32 v137, v137, v214
	v_sub_f32_e32 v136, v136, v214
	v_pk_mul_f32 v[136:137], v[136:137], v[214:215] op_sel:[0,1]
	v_pk_mul_f32 v[138:139], v[138:139], v[214:215] op_sel:[0,1]
	s_waitcnt vmcnt(1)
	v_pk_fma_f32 v[108:109], v[108:109], v[136:137], v[140:141]
	v_pk_fma_f32 v[110:111], v[110:111], v[138:139], v[142:143]
	v_pk_mul_f32 v[108:109], v[108:109], s[18:19] op_sel_hi:[1,0]
	v_pk_mul_f32 v[110:111], v[110:111], s[18:19] op_sel_hi:[1,0]
	s_waitcnt vmcnt(0)
	v_pk_fma_f32 v[104:105], v[104:105], v[210:211], v[108:109]
	v_pk_fma_f32 v[106:107], v[106:107], v[212:213], v[110:111]
	global_store_dwordx4 v[184:185], v[104:107], off offset:64
	s_nop 0
	s_nop 0
	global_load_dwordx4 v[104:107], v[172:173], off
	global_load_dwordx4 v[108:111], v[174:175], off
	global_load_dwordx4 v[136:139], v[230:231], off offset:512
	v_lshl_add_u64 v[210:211], v[232:233], 3, s[62:63]
	v_or_b32_e32 v212, 48, v180
	v_ashrrev_i32_e32 v213, 31, v212
	s_waitcnt vmcnt(3)
	v_mov_b32_e32 v140, v228
	v_mov_b32_e32 v141, v229
	v_sub_f32_e32 v135, v135, v140
	v_sub_f32_e32 v134, v134, v140
	v_sub_f32_e32 v133, v133, v140
	v_sub_f32_e32 v132, v132, v140
	v_pk_mul_f32 v[132:133], v[132:133], v[140:141] op_sel:[0,1]
	v_pk_mul_f32 v[134:135], v[134:135], v[140:141] op_sel:[0,1]
	s_waitcnt vmcnt(1)
	v_pk_fma_f32 v[104:105], v[104:105], v[132:133], v[108:109]
	v_pk_fma_f32 v[106:107], v[106:107], v[134:135], v[110:111]
	v_pk_mul_f32 v[104:105], v[104:105], s[18:19] op_sel_hi:[1,0]
	v_pk_mul_f32 v[106:107], v[106:107], s[18:19] op_sel_hi:[1,0]
	s_waitcnt vmcnt(0)
	v_pk_fma_f32 v[100:101], v[100:101], v[136:137], v[104:105]
	v_pk_fma_f32 v[102:103], v[102:103], v[138:139], v[106:107]
	global_store_dwordx4 v[184:185], v[100:103], off offset:512
	s_nop 0
	s_nop 0
	global_load_dwordx4 v[100:103], v[176:177], off
	global_load_dwordx4 v[104:107], v[178:179], off
	global_load_dwordx4 v[108:111], v[230:231], off offset:576
	s_waitcnt vmcnt(3)
	v_mov_b32_e32 v132, v228
	v_mov_b32_e32 v133, v229
	v_sub_f32_e32 v131, v131, v132
	v_sub_f32_e32 v130, v130, v132
	v_sub_f32_e32 v129, v129, v132
	v_sub_f32_e32 v128, v128, v132
	v_pk_mul_f32 v[128:129], v[128:129], v[132:133] op_sel:[0,1]
	v_pk_mul_f32 v[130:131], v[130:131], v[132:133] op_sel:[0,1]
	s_waitcnt vmcnt(1)
	v_pk_fma_f32 v[100:101], v[100:101], v[128:129], v[104:105]
	v_pk_fma_f32 v[102:103], v[102:103], v[130:131], v[106:107]
	v_pk_mul_f32 v[100:101], v[100:101], s[18:19] op_sel_hi:[1,0]
	v_pk_mul_f32 v[102:103], v[102:103], s[18:19] op_sel_hi:[1,0]
	s_waitcnt vmcnt(0)
	v_pk_fma_f32 v[96:97], v[96:97], v[108:109], v[100:101]
	v_pk_fma_f32 v[98:99], v[98:99], v[110:111], v[102:103]
	global_store_dwordx4 v[184:185], v[96:99], off offset:576
	global_load_dwordx2 v[110:111], v[210:211], off
	global_load_dwordx4 v[128:131], v[168:169], off
	global_load_dwordx4 v[132:135], v[170:171], off
	v_cndmask_b32_e64 v96, v181, 4, vcc
	v_mul_hi_i32_i24_e32 v97, 0x6000, v96
	v_mul_i32_i24_e32 v96, 0x6000, v96
	v_lshl_add_u64 v[96:97], s[8:9], 0, v[96:97]
	v_lshl_add_u64 v[184:185], v[96:97], 0, v[166:167]
	global_load_dwordx4 v[136:139], v[184:185], off
	v_mul_hi_i32 v96, v212, s61
	v_lshrrev_b32_e32 v97, 31, v96
	v_ashrrev_i32_e32 v96, 11, v96
	v_add_u32_e32 v181, v96, v97
	v_mad_i32_i24 v96, v181, s64, v212
	v_lshl_add_u32 v97, v181, 13, v204
	v_lshlrev_b32_e32 v98, 8, v181
	v_cmp_gt_i32_e32 vcc, s51, v96
	s_waitcnt vmcnt(3)
	v_mov_b32_e32 v218, v110
	v_mov_b32_e32 v219, v111
	v_sub_f32_e32 v215, v225, v110
	v_cndmask_b32_e32 v97, v97, v98, vcc
	v_add_u32_e32 v96, v97, v96
	v_sub_f32_e32 v214, v224, v110
	v_sub_f32_e32 v217, v223, v110
	v_sub_f32_e32 v216, v222, v110
	v_ashrrev_i32_e32 v97, 31, v96
	v_pk_mul_f32 v[216:217], v[216:217], v[110:111] op_sel:[0,1]
	v_pk_mul_f32 v[110:111], v[214:215], v[110:111] op_sel:[0,1]
	v_cndmask_b32_e32 v99, v205, v206, vcc
	v_cndmask_b32_e32 v98, v207, v208, vcc
	v_lshlrev_b64 v[96:97], 12, v[96:97]
	s_waitcnt vmcnt(1)
	v_pk_fma_f32 v[110:111], v[130:131], v[110:111], v[134:135]
	v_pk_fma_f32 v[128:129], v[128:129], v[216:217], v[132:133]
	v_lshl_add_u64 v[96:97], v[98:99], 0, v[96:97]
	v_pk_mul_f32 v[128:129], v[128:129], s[18:19] op_sel_hi:[1,0]
	v_pk_mul_f32 v[110:111], v[110:111], s[18:19] op_sel_hi:[1,0]
	v_lshl_add_u64 v[108:109], v[96:97], 0, v[166:167]
	s_waitcnt vmcnt(0)
	v_pk_fma_f32 v[94:95], v[94:95], v[138:139], v[110:111]
	v_pk_fma_f32 v[92:93], v[92:93], v[136:137], v[128:129]
	global_load_dwordx4 v[140:143], v[108:109], off
	global_load_dwordx4 v[104:107], v[108:109], off offset:64
	global_load_dwordx4 v[100:103], v[108:109], off offset:512
	global_load_dwordx4 v[96:99], v[108:109], off offset:576
	s_nop 0
	global_store_dwordx4 v[186:187], v[92:95], off
	s_nop 0
	s_nop 0
	global_load_dwordx4 v[92:95], v[124:125], off
	global_load_dwordx4 v[128:131], v[126:127], off
	global_load_dwordx4 v[132:135], v[184:185], off offset:64
	s_waitcnt vmcnt(3)
	v_mov_b32_e32 v110, v218
	v_mov_b32_e32 v111, v219
	v_sub_f32_e32 v123, v123, v110
	v_sub_f32_e32 v122, v122, v110
	v_sub_f32_e32 v121, v121, v110
	v_sub_f32_e32 v120, v120, v110
	v_pk_mul_f32 v[120:121], v[120:121], v[110:111] op_sel:[0,1]
	v_pk_mul_f32 v[110:111], v[122:123], v[110:111] op_sel:[0,1]
	s_waitcnt vmcnt(1)
	v_pk_fma_f32 v[92:93], v[92:93], v[120:121], v[128:129]
	v_pk_fma_f32 v[94:95], v[94:95], v[110:111], v[130:131]
	v_pk_mul_f32 v[92:93], v[92:93], s[18:19] op_sel_hi:[1,0]
	v_pk_mul_f32 v[94:95], v[94:95], s[18:19] op_sel_hi:[1,0]
	s_waitcnt vmcnt(0)
	v_pk_fma_f32 v[88:89], v[88:89], v[132:133], v[92:93]
	v_pk_fma_f32 v[90:91], v[90:91], v[134:135], v[94:95]
	global_store_dwordx4 v[186:187], v[88:91], off offset:64
	s_nop 0
	s_nop 0
	global_load_dwordx4 v[88:91], v[172:173], off
	global_load_dwordx4 v[92:95], v[174:175], off
	global_load_dwordx4 v[120:123], v[184:185], off offset:512
	s_waitcnt vmcnt(3)
	v_mov_b32_e32 v110, v218
	v_mov_b32_e32 v111, v219
	v_sub_f32_e32 v119, v119, v110
	v_sub_f32_e32 v118, v118, v110
	v_sub_f32_e32 v117, v117, v110
	v_sub_f32_e32 v116, v116, v110
	v_pk_mul_f32 v[116:117], v[116:117], v[110:111] op_sel:[0,1]
	v_pk_mul_f32 v[110:111], v[118:119], v[110:111] op_sel:[0,1]
	s_waitcnt vmcnt(1)
	v_pk_fma_f32 v[88:89], v[88:89], v[116:117], v[92:93]
	v_pk_fma_f32 v[90:91], v[90:91], v[110:111], v[94:95]
	v_pk_mul_f32 v[88:89], v[88:89], s[18:19] op_sel_hi:[1,0]
	v_pk_mul_f32 v[90:91], v[90:91], s[18:19] op_sel_hi:[1,0]
	s_waitcnt vmcnt(0)
	v_pk_fma_f32 v[84:85], v[84:85], v[120:121], v[88:89]
	v_pk_fma_f32 v[86:87], v[86:87], v[122:123], v[90:91]
	global_store_dwordx4 v[186:187], v[84:87], off offset:512
	s_nop 0
	s_nop 0
	global_load_dwordx4 v[84:87], v[176:177], off
	global_load_dwordx4 v[88:91], v[178:179], off
	global_load_dwordx4 v[92:95], v[184:185], off offset:576
	v_lshl_add_u64 v[122:123], v[212:213], 3, s[62:63]
	s_waitcnt vmcnt(3)
	v_mov_b32_e32 v110, v218
	v_mov_b32_e32 v111, v219
	v_sub_f32_e32 v115, v115, v110
	v_sub_f32_e32 v114, v114, v110
	v_sub_f32_e32 v113, v113, v110
	v_sub_f32_e32 v112, v112, v110
	v_pk_mul_f32 v[112:113], v[112:113], v[110:111] op_sel:[0,1]
	v_pk_mul_f32 v[110:111], v[114:115], v[110:111] op_sel:[0,1]
	s_waitcnt vmcnt(1)
	v_pk_fma_f32 v[84:85], v[84:85], v[112:113], v[88:89]
	v_pk_fma_f32 v[86:87], v[86:87], v[110:111], v[90:91]
	v_pk_mul_f32 v[84:85], v[84:85], s[18:19] op_sel_hi:[1,0]
	v_pk_mul_f32 v[86:87], v[86:87], s[18:19] op_sel_hi:[1,0]
	s_waitcnt vmcnt(0)
	v_pk_fma_f32 v[80:81], v[80:81], v[92:93], v[84:85]
	v_pk_fma_f32 v[82:83], v[82:83], v[94:95], v[86:87]
	global_store_dwordx4 v[186:187], v[80:83], off offset:576
	global_load_dwordx2 v[94:95], v[122:123], off
	global_load_dwordx4 v[110:113], v[168:169], off
	global_load_dwordx4 v[114:117], v[170:171], off
	v_cndmask_b32_e64 v80, v181, 4, vcc
	v_mul_hi_i32_i24_e32 v81, 0x6000, v80
	v_mul_i32_i24_e32 v80, 0x6000, v80
	v_lshl_add_u64 v[80:81], s[8:9], 0, v[80:81]
	v_lshl_add_u64 v[132:133], v[80:81], 0, v[166:167]
	global_load_dwordx4 v[118:121], v[132:133], off
	v_add_u32_e32 v80, 0x80, v180
	v_mul_hi_i32 v81, v80, s61
	v_lshrrev_b32_e32 v82, 31, v81
	v_ashrrev_i32_e32 v81, 11, v81
	v_add_u32_e32 v138, v81, v82
	v_mad_i32_i24 v80, v138, s64, v80
	v_lshl_add_u32 v81, v138, 13, v204
	v_lshlrev_b32_e32 v82, 8, v138
	v_cmp_gt_i32_e32 vcc, s51, v80
	s_waitcnt vmcnt(3)
	v_mov_b32_e32 v184, v94
	v_mov_b32_e32 v185, v95
	v_sub_f32_e32 v135, v143, v94
	v_cndmask_b32_e32 v81, v81, v82, vcc
	v_add_u32_e32 v80, v81, v80
	v_sub_f32_e32 v134, v142, v94
	v_sub_f32_e32 v137, v141, v94
	v_sub_f32_e32 v136, v140, v94
	v_ashrrev_i32_e32 v81, 31, v80
	v_pk_mul_f32 v[136:137], v[136:137], v[94:95] op_sel:[0,1]
	v_pk_mul_f32 v[94:95], v[134:135], v[94:95] op_sel:[0,1]
	v_cndmask_b32_e32 v83, v205, v206, vcc
	v_cndmask_b32_e32 v82, v207, v208, vcc
	v_lshlrev_b64 v[80:81], 12, v[80:81]
	s_waitcnt vmcnt(1)
	v_pk_fma_f32 v[94:95], v[112:113], v[94:95], v[116:117]
	v_pk_fma_f32 v[110:111], v[110:111], v[136:137], v[114:115]
	v_lshl_add_u64 v[80:81], v[82:83], 0, v[80:81]
	v_pk_mul_f32 v[110:111], v[110:111], s[18:19] op_sel_hi:[1,0]
	v_pk_mul_f32 v[94:95], v[94:95], s[18:19] op_sel_hi:[1,0]
	v_lshl_add_u64 v[92:93], v[80:81], 0, v[166:167]
	s_waitcnt vmcnt(0)
	v_pk_fma_f32 v[78:79], v[78:79], v[120:121], v[94:95]
	v_pk_fma_f32 v[76:77], v[76:77], v[118:119], v[110:111]
	global_load_dwordx4 v[128:131], v[92:93], off
	global_load_dwordx4 v[88:91], v[92:93], off offset:64
	global_load_dwordx4 v[84:87], v[92:93], off offset:512
	global_load_dwordx4 v[80:83], v[92:93], off offset:576
	s_nop 0
	global_store_dwordx4 v[108:109], v[76:79], off
	s_nop 0
	s_nop 0
	global_load_dwordx4 v[76:79], v[124:125], off
	global_load_dwordx4 v[110:113], v[126:127], off
	global_load_dwordx4 v[114:117], v[132:133], off offset:64
	s_waitcnt vmcnt(3)
	v_mov_b32_e32 v94, v184
	v_mov_b32_e32 v95, v185
	v_sub_f32_e32 v107, v107, v94
	v_sub_f32_e32 v106, v106, v94
	v_sub_f32_e32 v105, v105, v94
	v_sub_f32_e32 v104, v104, v94
	v_pk_mul_f32 v[104:105], v[104:105], v[94:95] op_sel:[0,1]
	v_pk_mul_f32 v[94:95], v[106:107], v[94:95] op_sel:[0,1]
	s_waitcnt vmcnt(1)
	v_pk_fma_f32 v[76:77], v[76:77], v[104:105], v[110:111]
	v_pk_fma_f32 v[78:79], v[78:79], v[94:95], v[112:113]
	v_pk_mul_f32 v[76:77], v[76:77], s[18:19] op_sel_hi:[1,0]
	v_pk_mul_f32 v[78:79], v[78:79], s[18:19] op_sel_hi:[1,0]
	s_waitcnt vmcnt(0)
	v_pk_fma_f32 v[72:73], v[72:73], v[114:115], v[76:77]
	v_pk_fma_f32 v[74:75], v[74:75], v[116:117], v[78:79]
	global_store_dwordx4 v[108:109], v[72:75], off offset:64
	s_nop 0
	s_nop 0
	global_load_dwordx4 v[72:75], v[172:173], off
	global_load_dwordx4 v[76:79], v[174:175], off
	global_load_dwordx4 v[104:107], v[132:133], off offset:512
	v_add_u32_e32 v112, 0x90, v180
	v_ashrrev_i32_e32 v113, 31, v112
	s_waitcnt vmcnt(3)
	v_mov_b32_e32 v94, v184
	v_mov_b32_e32 v95, v185
	v_sub_f32_e32 v103, v103, v94
	v_sub_f32_e32 v102, v102, v94
	v_sub_f32_e32 v101, v101, v94
	v_sub_f32_e32 v100, v100, v94
	v_pk_mul_f32 v[100:101], v[100:101], v[94:95] op_sel:[0,1]
	v_pk_mul_f32 v[94:95], v[102:103], v[94:95] op_sel:[0,1]
	s_waitcnt vmcnt(1)
	v_pk_fma_f32 v[72:73], v[72:73], v[100:101], v[76:77]
	v_pk_fma_f32 v[74:75], v[74:75], v[94:95], v[78:79]
	v_pk_mul_f32 v[72:73], v[72:73], s[18:19] op_sel_hi:[1,0]
	v_pk_mul_f32 v[74:75], v[74:75], s[18:19] op_sel_hi:[1,0]
	s_waitcnt vmcnt(0)
	v_pk_fma_f32 v[68:69], v[68:69], v[104:105], v[72:73]
	v_pk_fma_f32 v[70:71], v[70:71], v[106:107], v[74:75]
	global_store_dwordx4 v[108:109], v[68:71], off offset:512
	s_nop 0
	s_nop 0
	global_load_dwordx4 v[68:71], v[176:177], off
	global_load_dwordx4 v[72:75], v[178:179], off
	global_load_dwordx4 v[76:79], v[132:133], off offset:576
	s_waitcnt vmcnt(3)
	v_mov_b32_e32 v94, v184
	v_mov_b32_e32 v95, v185
	v_sub_f32_e32 v99, v99, v94
	v_sub_f32_e32 v98, v98, v94
	v_sub_f32_e32 v97, v97, v94
	v_sub_f32_e32 v96, v96, v94
	v_pk_mul_f32 v[96:97], v[96:97], v[94:95] op_sel:[0,1]
	v_pk_mul_f32 v[94:95], v[98:99], v[94:95] op_sel:[0,1]
	s_waitcnt vmcnt(1)
	v_pk_fma_f32 v[68:69], v[68:69], v[96:97], v[72:73]
	v_pk_fma_f32 v[70:71], v[70:71], v[94:95], v[74:75]
	v_pk_mul_f32 v[68:69], v[68:69], s[18:19] op_sel_hi:[1,0]
	v_pk_mul_f32 v[70:71], v[70:71], s[18:19] op_sel_hi:[1,0]
	s_waitcnt vmcnt(0)
	v_pk_fma_f32 v[64:65], v[64:65], v[76:77], v[68:69]
	v_pk_fma_f32 v[66:67], v[66:67], v[78:79], v[70:71]
	global_store_dwordx4 v[108:109], v[64:67], off offset:576
	global_load_dwordx2 v[78:79], v[182:183], off offset:1024
	global_load_dwordx4 v[94:97], v[168:169], off
	global_load_dwordx4 v[98:101], v[170:171], off
	v_cndmask_b32_e64 v64, v138, 4, vcc
	v_mul_hi_i32_i24_e32 v65, 0x6000, v64
	v_mul_i32_i24_e32 v64, 0x6000, v64
	v_lshl_add_u64 v[64:65], s[8:9], 0, v[64:65]
	v_lshl_add_u64 v[110:111], v[64:65], 0, v[166:167]
	global_load_dwordx4 v[102:105], v[110:111], off
	v_mul_hi_i32 v64, v112, s61
	v_lshrrev_b32_e32 v65, 31, v64
	v_ashrrev_i32_e32 v64, 11, v64
	v_add_u32_e32 v118, v64, v65
	v_mad_i32_i24 v64, v118, s64, v112
	v_lshl_add_u32 v65, v118, 13, v204
	v_lshlrev_b32_e32 v66, 8, v118
	v_cmp_gt_i32_e32 vcc, s51, v64
	s_waitcnt vmcnt(3)
	v_sub_f32_e32 v115, v131, v78
	v_cndmask_b32_e32 v65, v65, v66, vcc
	v_add_u32_e32 v64, v65, v64
	v_sub_f32_e32 v114, v130, v78
	v_sub_f32_e32 v117, v129, v78
	v_sub_f32_e32 v116, v128, v78
	v_ashrrev_i32_e32 v65, 31, v64
	v_pk_mul_f32 v[116:117], v[116:117], v[78:79] op_sel:[0,1]
	v_pk_mul_f32 v[78:79], v[114:115], v[78:79] op_sel:[0,1]
	v_cndmask_b32_e32 v67, v205, v206, vcc
	v_cndmask_b32_e32 v66, v207, v208, vcc
	v_lshlrev_b64 v[64:65], 12, v[64:65]
	s_waitcnt vmcnt(1)
	v_pk_fma_f32 v[78:79], v[96:97], v[78:79], v[100:101]
	v_pk_fma_f32 v[94:95], v[94:95], v[116:117], v[98:99]
	v_lshl_add_u64 v[64:65], v[66:67], 0, v[64:65]
	v_pk_mul_f32 v[94:95], v[94:95], s[18:19] op_sel_hi:[1,0]
	v_pk_mul_f32 v[78:79], v[78:79], s[18:19] op_sel_hi:[1,0]
	v_lshl_add_u64 v[76:77], v[64:65], 0, v[166:167]
	s_waitcnt vmcnt(0)
	v_pk_fma_f32 v[62:63], v[62:63], v[104:105], v[78:79]
	v_pk_fma_f32 v[60:61], v[60:61], v[102:103], v[94:95]
	global_load_dwordx4 v[106:109], v[76:77], off
	global_load_dwordx4 v[72:75], v[76:77], off offset:64
	global_load_dwordx4 v[68:71], v[76:77], off offset:512
	global_load_dwordx4 v[64:67], v[76:77], off offset:576
	s_nop 0
	global_store_dwordx4 v[92:93], v[60:63], off
	global_load_dwordx2 v[78:79], v[182:183], off offset:1024
	s_nop 0
	global_load_dwordx4 v[60:63], v[124:125], off
	global_load_dwordx4 v[94:97], v[126:127], off
	global_load_dwordx4 v[98:101], v[110:111], off offset:64
	s_waitcnt vmcnt(3)
	v_sub_f32_e32 v91, v91, v78
	v_sub_f32_e32 v90, v90, v78
	v_sub_f32_e32 v89, v89, v78
	v_sub_f32_e32 v88, v88, v78
	v_pk_mul_f32 v[88:89], v[88:89], v[78:79] op_sel:[0,1]
	v_pk_mul_f32 v[78:79], v[90:91], v[78:79] op_sel:[0,1]
	s_waitcnt vmcnt(1)
	v_pk_fma_f32 v[60:61], v[60:61], v[88:89], v[94:95]
	v_pk_fma_f32 v[62:63], v[62:63], v[78:79], v[96:97]
	v_pk_mul_f32 v[60:61], v[60:61], s[18:19] op_sel_hi:[1,0]
	v_pk_mul_f32 v[62:63], v[62:63], s[18:19] op_sel_hi:[1,0]
	s_waitcnt vmcnt(0)
	v_pk_fma_f32 v[56:57], v[56:57], v[98:99], v[60:61]
	v_pk_fma_f32 v[58:59], v[58:59], v[100:101], v[62:63]
	global_store_dwordx4 v[92:93], v[56:59], off offset:64
	global_load_dwordx2 v[78:79], v[182:183], off offset:1024
	s_nop 0
	global_load_dwordx4 v[56:59], v[172:173], off
	global_load_dwordx4 v[60:63], v[174:175], off
	global_load_dwordx4 v[88:91], v[110:111], off offset:512
	v_lshl_add_u64 v[94:95], v[112:113], 3, s[62:63]
	v_add_u32_e32 v98, 0xa0, v180
	v_ashrrev_i32_e32 v99, 31, v98
	s_waitcnt vmcnt(3)
	v_sub_f32_e32 v87, v87, v78
	v_sub_f32_e32 v86, v86, v78
	v_sub_f32_e32 v85, v85, v78
	v_sub_f32_e32 v84, v84, v78
	v_pk_mul_f32 v[84:85], v[84:85], v[78:79] op_sel:[0,1]
	v_pk_mul_f32 v[78:79], v[86:87], v[78:79] op_sel:[0,1]
	s_waitcnt vmcnt(1)
	v_pk_fma_f32 v[56:57], v[56:57], v[84:85], v[60:61]
	v_pk_fma_f32 v[58:59], v[58:59], v[78:79], v[62:63]
	v_pk_mul_f32 v[56:57], v[56:57], s[18:19] op_sel_hi:[1,0]
	v_pk_mul_f32 v[58:59], v[58:59], s[18:19] op_sel_hi:[1,0]
	s_waitcnt vmcnt(0)
	v_pk_fma_f32 v[52:53], v[52:53], v[88:89], v[56:57]
	v_pk_fma_f32 v[54:55], v[54:55], v[90:91], v[58:59]
	global_store_dwordx4 v[92:93], v[52:55], off offset:512
	global_load_dwordx2 v[78:79], v[182:183], off offset:1024
	s_nop 0
	global_load_dwordx4 v[52:55], v[176:177], off
	global_load_dwordx4 v[56:59], v[178:179], off
	global_load_dwordx4 v[60:63], v[110:111], off offset:576
	s_waitcnt vmcnt(3)
	v_sub_f32_e32 v83, v83, v78
	v_sub_f32_e32 v82, v82, v78
	v_sub_f32_e32 v81, v81, v78
	v_sub_f32_e32 v80, v80, v78
	v_pk_mul_f32 v[80:81], v[80:81], v[78:79] op_sel:[0,1]
	v_pk_mul_f32 v[78:79], v[82:83], v[78:79] op_sel:[0,1]
	s_waitcnt vmcnt(1)
	v_pk_fma_f32 v[52:53], v[52:53], v[80:81], v[56:57]
	v_pk_fma_f32 v[54:55], v[54:55], v[78:79], v[58:59]
	v_pk_mul_f32 v[52:53], v[52:53], s[18:19] op_sel_hi:[1,0]
	v_pk_mul_f32 v[54:55], v[54:55], s[18:19] op_sel_hi:[1,0]
	s_waitcnt vmcnt(0)
	v_pk_fma_f32 v[48:49], v[48:49], v[60:61], v[52:53]
	v_pk_fma_f32 v[50:51], v[50:51], v[62:63], v[54:55]
	global_store_dwordx4 v[92:93], v[48:51], off offset:576
	global_load_dwordx2 v[62:63], v[94:95], off
	global_load_dwordx4 v[78:81], v[168:169], off
	global_load_dwordx4 v[82:85], v[170:171], off
	v_cndmask_b32_e64 v48, v118, 4, vcc
	v_mul_hi_i32_i24_e32 v49, 0x6000, v48
	v_mul_i32_i24_e32 v48, 0x6000, v48
	v_lshl_add_u64 v[48:49], s[8:9], 0, v[48:49]
	v_lshl_add_u64 v[96:97], v[48:49], 0, v[166:167]
	global_load_dwordx4 v[86:89], v[96:97], off
	v_mul_hi_i32 v48, v98, s61
	v_lshrrev_b32_e32 v49, 31, v48
	v_ashrrev_i32_e32 v48, 11, v48
	v_add_u32_e32 v104, v48, v49
	v_mad_i32_i24 v48, v104, s64, v98
	v_lshl_add_u32 v49, v104, 13, v204
	v_lshlrev_b32_e32 v50, 8, v104
	v_cmp_gt_i32_e32 vcc, s51, v48
	s_waitcnt vmcnt(3)
	v_mov_b32_e32 v128, v62
	v_mov_b32_e32 v129, v63
	v_sub_f32_e32 v101, v109, v62
	v_cndmask_b32_e32 v49, v49, v50, vcc
	v_add_u32_e32 v48, v49, v48
	v_sub_f32_e32 v100, v108, v62
	v_sub_f32_e32 v103, v107, v62
	v_sub_f32_e32 v102, v106, v62
	v_ashrrev_i32_e32 v49, 31, v48
	v_pk_mul_f32 v[102:103], v[102:103], v[62:63] op_sel:[0,1]
	v_pk_mul_f32 v[62:63], v[100:101], v[62:63] op_sel:[0,1]
	v_cndmask_b32_e32 v51, v205, v206, vcc
	v_cndmask_b32_e32 v50, v207, v208, vcc
	v_lshlrev_b64 v[48:49], 12, v[48:49]
	s_waitcnt vmcnt(1)
	v_pk_fma_f32 v[62:63], v[80:81], v[62:63], v[84:85]
	v_pk_fma_f32 v[78:79], v[78:79], v[102:103], v[82:83]
	v_lshl_add_u64 v[48:49], v[50:51], 0, v[48:49]
	v_pk_mul_f32 v[78:79], v[78:79], s[18:19] op_sel_hi:[1,0]
	v_pk_mul_f32 v[62:63], v[62:63], s[18:19] op_sel_hi:[1,0]
	v_lshl_add_u64 v[60:61], v[48:49], 0, v[166:167]
	s_waitcnt vmcnt(0)
	v_pk_fma_f32 v[46:47], v[46:47], v[88:89], v[62:63]
	v_pk_fma_f32 v[44:45], v[44:45], v[86:87], v[78:79]
	global_load_dwordx4 v[90:93], v[60:61], off
	global_load_dwordx4 v[56:59], v[60:61], off offset:64
	global_load_dwordx4 v[52:55], v[60:61], off offset:512
	global_load_dwordx4 v[48:51], v[60:61], off offset:576
	s_nop 0
	global_store_dwordx4 v[76:77], v[44:47], off
	s_nop 0
	s_nop 0
	global_load_dwordx4 v[44:47], v[124:125], off
	global_load_dwordx4 v[78:81], v[126:127], off
	global_load_dwordx4 v[82:85], v[96:97], off offset:64
	s_waitcnt vmcnt(3)
	v_mov_b32_e32 v62, v128
	v_mov_b32_e32 v63, v129
	v_sub_f32_e32 v75, v75, v62
	v_sub_f32_e32 v74, v74, v62
	v_sub_f32_e32 v73, v73, v62
	v_sub_f32_e32 v72, v72, v62
	v_pk_mul_f32 v[72:73], v[72:73], v[62:63] op_sel:[0,1]
	v_pk_mul_f32 v[62:63], v[74:75], v[62:63] op_sel:[0,1]
	s_waitcnt vmcnt(1)
	v_pk_fma_f32 v[44:45], v[44:45], v[72:73], v[78:79]
	v_pk_fma_f32 v[46:47], v[46:47], v[62:63], v[80:81]
	v_pk_mul_f32 v[44:45], v[44:45], s[18:19] op_sel_hi:[1,0]
	v_pk_mul_f32 v[46:47], v[46:47], s[18:19] op_sel_hi:[1,0]
	s_waitcnt vmcnt(0)
	v_pk_fma_f32 v[40:41], v[40:41], v[82:83], v[44:45]
	v_pk_fma_f32 v[42:43], v[42:43], v[84:85], v[46:47]
	global_store_dwordx4 v[76:77], v[40:43], off offset:64
	s_nop 0
	s_nop 0
	global_load_dwordx4 v[40:43], v[172:173], off
	global_load_dwordx4 v[44:47], v[174:175], off
	global_load_dwordx4 v[72:75], v[96:97], off offset:512
	v_lshl_add_u64 v[78:79], v[98:99], 3, s[62:63]
	v_add_u32_e32 v82, 0xb0, v180
	v_ashrrev_i32_e32 v83, 31, v82
	s_waitcnt vmcnt(3)
	v_mov_b32_e32 v62, v128
	v_mov_b32_e32 v63, v129
	v_sub_f32_e32 v71, v71, v62
	v_sub_f32_e32 v70, v70, v62
	v_sub_f32_e32 v69, v69, v62
	v_sub_f32_e32 v68, v68, v62
	v_pk_mul_f32 v[68:69], v[68:69], v[62:63] op_sel:[0,1]
	v_pk_mul_f32 v[62:63], v[70:71], v[62:63] op_sel:[0,1]
	s_waitcnt vmcnt(1)
	v_pk_fma_f32 v[40:41], v[40:41], v[68:69], v[44:45]
	v_pk_fma_f32 v[42:43], v[42:43], v[62:63], v[46:47]
	v_pk_mul_f32 v[40:41], v[40:41], s[18:19] op_sel_hi:[1,0]
	v_pk_mul_f32 v[42:43], v[42:43], s[18:19] op_sel_hi:[1,0]
	s_waitcnt vmcnt(0)
	v_pk_fma_f32 v[36:37], v[36:37], v[72:73], v[40:41]
	v_pk_fma_f32 v[38:39], v[38:39], v[74:75], v[42:43]
	global_store_dwordx4 v[76:77], v[36:39], off offset:512
	s_nop 0
	s_nop 0
	global_load_dwordx4 v[36:39], v[176:177], off
	global_load_dwordx4 v[40:43], v[178:179], off
	global_load_dwordx4 v[44:47], v[96:97], off offset:576
	s_waitcnt vmcnt(3)
	v_mov_b32_e32 v62, v128
	v_mov_b32_e32 v63, v129
	v_sub_f32_e32 v67, v67, v62
	v_sub_f32_e32 v66, v66, v62
	v_sub_f32_e32 v65, v65, v62
	v_sub_f32_e32 v64, v64, v62
	v_pk_mul_f32 v[64:65], v[64:65], v[62:63] op_sel:[0,1]
	v_pk_mul_f32 v[62:63], v[66:67], v[62:63] op_sel:[0,1]
	s_waitcnt vmcnt(1)
	v_pk_fma_f32 v[36:37], v[36:37], v[64:65], v[40:41]
	v_pk_fma_f32 v[38:39], v[38:39], v[62:63], v[42:43]
	v_pk_mul_f32 v[36:37], v[36:37], s[18:19] op_sel_hi:[1,0]
	v_pk_mul_f32 v[38:39], v[38:39], s[18:19] op_sel_hi:[1,0]
	s_waitcnt vmcnt(0)
	v_pk_fma_f32 v[32:33], v[32:33], v[44:45], v[36:37]
	v_pk_fma_f32 v[34:35], v[34:35], v[46:47], v[38:39]
	global_store_dwordx4 v[76:77], v[32:35], off offset:576
	global_load_dwordx2 v[46:47], v[78:79], off
	global_load_dwordx4 v[42:45], v[168:169], off
	global_load_dwordx4 v[62:65], v[170:171], off
	v_cndmask_b32_e64 v32, v104, 4, vcc
	v_mul_hi_i32_i24_e32 v33, 0x6000, v32
	v_mul_i32_i24_e32 v32, 0x6000, v32
	v_lshl_add_u64 v[32:33], s[8:9], 0, v[32:33]
	v_lshl_add_u64 v[80:81], v[32:33], 0, v[166:167]
	global_load_dwordx4 v[66:69], v[80:81], off
	v_mul_hi_i32 v32, v82, s61
	v_lshrrev_b32_e32 v33, 31, v32
	v_ashrrev_i32_e32 v32, 11, v32
	v_add_u32_e32 v88, v32, v33
	v_mad_i32_i24 v32, v88, s64, v82
	v_lshl_add_u32 v33, v88, 13, v204
	v_lshlrev_b32_e32 v34, 8, v88
	v_cmp_gt_i32_e32 vcc, s51, v32
	s_waitcnt vmcnt(3)
	v_mov_b32_e32 v128, v46
	v_mov_b32_e32 v129, v47
	v_sub_f32_e32 v85, v93, v46
	v_cndmask_b32_e32 v33, v33, v34, vcc
	v_add_u32_e32 v32, v33, v32
	v_sub_f32_e32 v84, v92, v46
	v_sub_f32_e32 v87, v91, v46
	v_sub_f32_e32 v86, v90, v46
	v_ashrrev_i32_e32 v33, 31, v32
	v_pk_mul_f32 v[86:87], v[86:87], v[46:47] op_sel:[0,1]
	v_pk_mul_f32 v[46:47], v[84:85], v[46:47] op_sel:[0,1]
	v_cndmask_b32_e32 v35, v205, v206, vcc
	v_cndmask_b32_e32 v34, v207, v208, vcc
	v_lshlrev_b64 v[32:33], 12, v[32:33]
	s_waitcnt vmcnt(1)
	v_pk_fma_f32 v[44:45], v[44:45], v[46:47], v[64:65]
	v_pk_fma_f32 v[42:43], v[42:43], v[86:87], v[62:63]
	v_lshl_add_u64 v[32:33], v[34:35], 0, v[32:33]
	v_pk_mul_f32 v[42:43], v[42:43], s[18:19] op_sel_hi:[1,0]
	v_pk_mul_f32 v[44:45], v[44:45], s[18:19] op_sel_hi:[1,0]
	v_lshl_add_u64 v[40:41], v[32:33], 0, v[166:167]
	s_waitcnt vmcnt(0)
	v_pk_fma_f32 v[30:31], v[30:31], v[68:69], v[44:45]
	v_pk_fma_f32 v[28:29], v[28:29], v[66:67], v[42:43]
	global_load_dwordx4 v[70:73], v[40:41], off
	global_load_dwordx4 v[74:77], v[40:41], off offset:64
	global_load_dwordx4 v[36:39], v[40:41], off offset:512
	global_load_dwordx4 v[32:35], v[40:41], off offset:576
	s_nop 0
	global_store_dwordx4 v[60:61], v[28:31], off
	s_nop 0
	s_nop 0
	global_load_dwordx4 v[28:31], v[124:125], off
	global_load_dwordx4 v[42:45], v[126:127], off
	global_load_dwordx4 v[62:65], v[80:81], off offset:64
	s_waitcnt vmcnt(3)
	v_mov_b32_e32 v46, v128
	v_mov_b32_e32 v47, v129
	v_sub_f32_e32 v59, v59, v46
	v_sub_f32_e32 v58, v58, v46
	v_sub_f32_e32 v57, v57, v46
	v_sub_f32_e32 v56, v56, v46
	v_pk_mul_f32 v[56:57], v[56:57], v[46:47] op_sel:[0,1]
	v_pk_mul_f32 v[46:47], v[58:59], v[46:47] op_sel:[0,1]
	s_waitcnt vmcnt(1)
	v_pk_fma_f32 v[28:29], v[28:29], v[56:57], v[42:43]
	v_pk_fma_f32 v[30:31], v[30:31], v[46:47], v[44:45]
	v_pk_mul_f32 v[28:29], v[28:29], s[18:19] op_sel_hi:[1,0]
	v_pk_mul_f32 v[30:31], v[30:31], s[18:19] op_sel_hi:[1,0]
	s_waitcnt vmcnt(0)
	v_pk_fma_f32 v[24:25], v[24:25], v[62:63], v[28:29]
	v_pk_fma_f32 v[26:27], v[26:27], v[64:65], v[30:31]
	global_store_dwordx4 v[60:61], v[24:27], off offset:64
	s_nop 0
	s_nop 0
	global_load_dwordx4 v[24:27], v[172:173], off
	global_load_dwordx4 v[28:31], v[174:175], off
	global_load_dwordx4 v[42:45], v[80:81], off offset:512
	s_waitcnt vmcnt(3)
	v_mov_b32_e32 v46, v128
	v_mov_b32_e32 v47, v129
	v_sub_f32_e32 v55, v55, v46
	v_sub_f32_e32 v54, v54, v46
	v_sub_f32_e32 v53, v53, v46
	v_sub_f32_e32 v52, v52, v46
	v_pk_mul_f32 v[52:53], v[52:53], v[46:47] op_sel:[0,1]
	v_pk_mul_f32 v[46:47], v[54:55], v[46:47] op_sel:[0,1]
	s_waitcnt vmcnt(1)
	v_pk_fma_f32 v[24:25], v[24:25], v[52:53], v[28:29]
	v_pk_fma_f32 v[26:27], v[26:27], v[46:47], v[30:31]
	v_pk_mul_f32 v[24:25], v[24:25], s[18:19] op_sel_hi:[1,0]
	v_pk_mul_f32 v[26:27], v[26:27], s[18:19] op_sel_hi:[1,0]
	s_waitcnt vmcnt(0)
	v_pk_fma_f32 v[20:21], v[20:21], v[42:43], v[24:25]
	v_pk_fma_f32 v[22:23], v[22:23], v[44:45], v[26:27]
	global_store_dwordx4 v[60:61], v[20:23], off offset:512
	s_nop 0
	s_nop 0
	global_load_dwordx4 v[20:23], v[176:177], off
	global_load_dwordx4 v[24:27], v[178:179], off
	global_load_dwordx4 v[28:31], v[80:81], off offset:576
	v_lshl_add_u64 v[44:45], v[82:83], 3, s[62:63]
	s_waitcnt vmcnt(3)
	v_mov_b32_e32 v42, v128
	v_mov_b32_e32 v43, v129
	v_sub_f32_e32 v47, v51, v42
	v_sub_f32_e32 v46, v50, v42
	v_sub_f32_e32 v49, v49, v42
	v_sub_f32_e32 v48, v48, v42
	v_pk_mul_f32 v[48:49], v[48:49], v[42:43] op_sel:[0,1]
	v_pk_mul_f32 v[42:43], v[46:47], v[42:43] op_sel:[0,1]
	s_waitcnt vmcnt(1)
	v_pk_fma_f32 v[20:21], v[20:21], v[48:49], v[24:25]
	v_pk_fma_f32 v[22:23], v[22:23], v[42:43], v[26:27]
	v_pk_mul_f32 v[20:21], v[20:21], s[18:19] op_sel_hi:[1,0]
	v_pk_mul_f32 v[22:23], v[22:23], s[18:19] op_sel_hi:[1,0]
	s_waitcnt vmcnt(0)
	v_pk_fma_f32 v[16:17], v[16:17], v[28:29], v[20:21]
	v_pk_fma_f32 v[18:19], v[18:19], v[30:31], v[22:23]
	global_store_dwordx4 v[60:61], v[16:19], off offset:576
	global_load_dwordx2 v[28:29], v[44:45], off
	v_cndmask_b32_e64 v24, v88, 4, vcc
	v_mul_hi_i32_i24_e32 v25, 0x6000, v24
	v_mul_i32_i24_e32 v24, 0x6000, v24
	global_load_dwordx4 v[16:19], v[168:169], off
	global_load_dwordx4 v[20:23], v[170:171], off
	v_lshl_add_u64 v[24:25], s[8:9], 0, v[24:25]
	v_lshl_add_u64 v[30:31], v[24:25], 0, v[166:167]
	global_load_dwordx4 v[24:27], v[30:31], off
	s_andn2_b64 vcc, exec, s[6:7]
	s_waitcnt vmcnt(3)
	v_mov_b32_e32 v128, v28
	v_mov_b32_e32 v129, v29
	v_sub_f32_e32 v43, v73, v28
	v_sub_f32_e32 v42, v72, v28
	v_sub_f32_e32 v47, v71, v28
	v_sub_f32_e32 v46, v70, v28
	v_pk_mul_f32 v[46:47], v[46:47], v[28:29] op_sel:[0,1]
	v_pk_mul_f32 v[28:29], v[42:43], v[28:29] op_sel:[0,1]
	s_waitcnt vmcnt(1)
	v_pk_fma_f32 v[16:17], v[16:17], v[46:47], v[20:21]
	v_pk_fma_f32 v[18:19], v[18:19], v[28:29], v[22:23]
	v_pk_mul_f32 v[16:17], v[16:17], s[18:19] op_sel_hi:[1,0]
	v_pk_mul_f32 v[18:19], v[18:19], s[18:19] op_sel_hi:[1,0]
	s_waitcnt vmcnt(0)
	v_pk_fma_f32 v[12:13], v[12:13], v[24:25], v[16:17]
	v_pk_fma_f32 v[14:15], v[14:15], v[26:27], v[18:19]
	global_store_dwordx4 v[40:41], v[12:15], off
	s_nop 0
	s_nop 0
	global_load_dwordx4 v[12:15], v[124:125], off
	global_load_dwordx4 v[16:19], v[126:127], off
	global_load_dwordx4 v[20:23], v[30:31], off offset:64
	s_waitcnt vmcnt(3)
	v_mov_b32_e32 v24, v128
	v_mov_b32_e32 v25, v129
	v_sub_f32_e32 v27, v77, v24
	v_sub_f32_e32 v26, v76, v24
	v_sub_f32_e32 v29, v75, v24
	v_sub_f32_e32 v28, v74, v24
	v_pk_mul_f32 v[28:29], v[28:29], v[24:25] op_sel:[0,1]
	v_pk_mul_f32 v[24:25], v[26:27], v[24:25] op_sel:[0,1]
	s_waitcnt vmcnt(1)
	v_pk_fma_f32 v[12:13], v[12:13], v[28:29], v[16:17]
	v_pk_fma_f32 v[14:15], v[14:15], v[24:25], v[18:19]
	v_pk_mul_f32 v[12:13], v[12:13], s[18:19] op_sel_hi:[1,0]
	v_pk_mul_f32 v[14:15], v[14:15], s[18:19] op_sel_hi:[1,0]
	s_waitcnt vmcnt(0)
	v_pk_fma_f32 v[8:9], v[8:9], v[20:21], v[12:13]
	v_pk_fma_f32 v[10:11], v[10:11], v[22:23], v[14:15]
	global_store_dwordx4 v[40:41], v[8:11], off offset:64
	s_nop 0
	s_nop 0
	global_load_dwordx4 v[8:11], v[172:173], off
	global_load_dwordx4 v[12:15], v[174:175], off
	global_load_dwordx4 v[16:19], v[30:31], off offset:512
	s_waitcnt vmcnt(3)
	v_mov_b32_e32 v20, v128
	v_mov_b32_e32 v21, v129
	v_sub_f32_e32 v23, v39, v20
	v_sub_f32_e32 v22, v38, v20
	v_sub_f32_e32 v25, v37, v20
	v_sub_f32_e32 v24, v36, v20
	v_pk_mul_f32 v[24:25], v[24:25], v[20:21] op_sel:[0,1]
	v_pk_mul_f32 v[20:21], v[22:23], v[20:21] op_sel:[0,1]
	s_waitcnt vmcnt(1)
	v_pk_fma_f32 v[8:9], v[8:9], v[24:25], v[12:13]
	v_pk_fma_f32 v[10:11], v[10:11], v[20:21], v[14:15]
	v_pk_mul_f32 v[8:9], v[8:9], s[18:19] op_sel_hi:[1,0]
	v_pk_mul_f32 v[10:11], v[10:11], s[18:19] op_sel_hi:[1,0]
	s_waitcnt vmcnt(0)
	v_pk_fma_f32 v[4:5], v[4:5], v[16:17], v[8:9]
	v_pk_fma_f32 v[6:7], v[6:7], v[18:19], v[10:11]
	global_store_dwordx4 v[40:41], v[4:7], off offset:512
	s_nop 0
	s_nop 0
	global_load_dwordx4 v[4:7], v[176:177], off
	global_load_dwordx4 v[8:11], v[178:179], off
	global_load_dwordx4 v[12:15], v[30:31], off offset:576
	s_waitcnt vmcnt(3)
	v_mov_b32_e32 v16, v128
	v_mov_b32_e32 v17, v129
	v_sub_f32_e32 v19, v35, v16
	v_sub_f32_e32 v18, v34, v16
	v_sub_f32_e32 v21, v33, v16
	v_sub_f32_e32 v20, v32, v16
	v_pk_mul_f32 v[20:21], v[20:21], v[16:17] op_sel:[0,1]
	v_pk_mul_f32 v[16:17], v[18:19], v[16:17] op_sel:[0,1]
	s_waitcnt vmcnt(1)
	v_pk_fma_f32 v[4:5], v[4:5], v[20:21], v[8:9]
	v_pk_fma_f32 v[6:7], v[6:7], v[16:17], v[10:11]
	v_pk_mul_f32 v[4:5], v[4:5], s[18:19] op_sel_hi:[1,0]
	v_pk_mul_f32 v[6:7], v[6:7], s[18:19] op_sel_hi:[1,0]
	s_waitcnt vmcnt(0)
	v_pk_fma_f32 v[0:1], v[0:1], v[12:13], v[4:5]
	v_pk_fma_f32 v[2:3], v[2:3], v[14:15], v[6:7]
	global_store_dwordx4 v[40:41], v[0:3], off offset:576
	s_cbranch_vccnz .LBB0_3526
	s_andn2_b64 vcc, exec, s[0:1]
	s_cbranch_vccnz .LBB0_3525
	s_barrier
	s_branch .LBB0_3525

.LBB0_3746:
	v_lshl_add_u32 v176, s54, 8, v151
	v_mul_hi_i32 v128, v176, s50
	v_lshrrev_b32_e32 v129, 31, v128
	v_ashrrev_i32_e32 v128, 11, v128
	v_add_u32_e32 v132, v128, v129
	v_mad_i32_i24 v128, v132, s51, v176
	v_lshl_add_u32 v129, v132, 13, v201
	v_lshlrev_b32_e32 v130, 8, v132
	v_cmp_gt_i32_e32 vcc, s44, v128
	v_lshl_or_b32 v218, s55, 8, v184
	v_mov_b32_e32 v202, s89
	v_cndmask_b32_e32 v129, v129, v130, vcc
	v_add_u32_e32 v128, v129, v128
	v_mov_b32_e32 v203, s71
	v_mov_b32_e32 v204, s88
	v_mov_b32_e32 v205, s70
	v_ashrrev_i32_e32 v129, 31, v128
	v_cndmask_b32_e32 v131, v202, v203, vcc
	v_cndmask_b32_e32 v130, v204, v205, vcc
	v_lshlrev_b64 v[128:129], 12, v[128:129]
	v_ashrrev_i32_e32 v219, 31, v218
	v_lshl_add_u64 v[128:129], v[130:131], 0, v[128:129]
	v_lshlrev_b64 v[162:163], 2, v[218:219]
	v_ashrrev_i32_e32 v177, 31, v176
	v_lshl_add_u64 v[182:183], v[128:129], 0, v[162:163]
	v_lshl_add_u64 v[178:179], v[176:177], 3, s[62:63]
	global_load_dwordx4 v[168:171], v[182:183], off
	global_load_dwordx4 v[214:217], v[182:183], off offset:64
	global_load_dwordx2 v[220:221], v[178:179], off
	v_cndmask_b32_e64 v128, v132, 4, vcc
	v_mul_hi_i32_i24_e32 v129, 0x6000, v128
	v_lshl_add_u64 v[164:165], s[12:13], 0, v[162:163]
	v_lshl_add_u64 v[166:167], s[14:15], 0, v[162:163]
	v_mul_i32_i24_e32 v128, 0x6000, v128
	global_load_dwordx4 v[172:175], v[164:165], off
	global_load_dwordx4 v[206:209], v[166:167], off
	v_lshl_add_u64 v[128:129], s[10:11], 0, v[128:129]
	v_lshl_add_u64 v[222:223], v[128:129], 0, v[162:163]
	global_load_dwordx4 v[210:213], v[222:223], off
	v_or_b32_e32 v226, 16, v176
	v_mul_hi_i32 v128, v226, s50
	v_lshrrev_b32_e32 v129, 31, v128
	v_ashrrev_i32_e32 v128, 11, v128
	v_add_u32_e32 v177, v128, v129
	v_mad_i32_i24 v128, v177, s51, v226
	v_lshl_add_u32 v129, v177, 13, v201
	v_lshlrev_b32_e32 v130, 8, v177
	v_cmp_gt_i32_e32 vcc, s44, v128
	v_or_b32_e32 v224, 16, v218
	v_ashrrev_i32_e32 v225, 31, v224
	v_cndmask_b32_e32 v129, v129, v130, vcc
	v_add_u32_e32 v128, v129, v128
	v_ashrrev_i32_e32 v129, 31, v128
	v_cndmask_b32_e32 v131, v202, v203, vcc
	v_cndmask_b32_e32 v130, v204, v205, vcc
	v_lshlrev_b64 v[128:129], 12, v[128:129]
	v_lshl_add_u64 v[128:129], v[130:131], 0, v[128:129]
	v_lshl_add_u64 v[180:181], v[128:129], 0, v[162:163]
	global_load_dwordx4 v[140:143], v[180:181], off
	global_load_dwordx4 v[136:139], v[180:181], off offset:64
	global_load_dwordx4 v[132:135], v[180:181], off offset:512
	global_load_dwordx4 v[128:131], v[180:181], off offset:576
	v_ashrrev_i32_e32 v227, 31, v226
	v_or_b32_e32 v228, 32, v176
	v_ashrrev_i32_e32 v229, 31, v228
	s_waitcnt vmcnt(0)
	v_sub_f32_e32 v171, v171, v220
	v_sub_f32_e32 v170, v170, v220
	v_sub_f32_e32 v169, v169, v220
	v_sub_f32_e32 v168, v168, v220
	v_pk_mul_f32 v[168:169], v[168:169], v[220:221] op_sel:[0,1]
	v_pk_mul_f32 v[170:171], v[170:171], v[220:221] op_sel:[0,1]
	v_pk_fma_f32 v[168:169], v[172:173], v[168:169], v[206:207]
	v_pk_fma_f32 v[170:171], v[174:175], v[170:171], v[208:209]
	v_pk_mul_f32 v[168:169], v[168:169], s[20:21] op_sel_hi:[1,0]
	v_pk_mul_f32 v[170:171], v[170:171], s[20:21] op_sel_hi:[1,0]
	v_pk_fma_f32 v[124:125], v[124:125], v[210:211], v[168:169]
	v_pk_fma_f32 v[126:127], v[126:127], v[212:213], v[170:171]
	global_store_dwordx4 v[182:183], v[124:127], off
	s_nop 0
	s_waitcnt vmcnt(1)
	v_sub_f32_e32 v217, v217, v220
	v_lshlrev_b64 v[126:127], 2, v[224:225]
	v_lshl_add_u64 v[124:125], s[12:13], 0, v[126:127]
	v_lshl_add_u64 v[126:127], s[14:15], 0, v[126:127]
	global_load_dwordx4 v[168:171], v[124:125], off
	global_load_dwordx4 v[172:175], v[126:127], off
	global_load_dwordx4 v[206:209], v[222:223], off offset:64
	v_sub_f32_e32 v216, v216, v220
	v_sub_f32_e32 v215, v215, v220
	v_sub_f32_e32 v214, v214, v220
	v_pk_mul_f32 v[214:215], v[214:215], v[220:221] op_sel:[0,1]
	v_pk_mul_f32 v[216:217], v[216:217], v[220:221] op_sel:[0,1]
	v_or_b32_e32 v224, 0x80, v218
	global_load_dwordx4 v[210:213], v[182:183], off offset:512
	v_ashrrev_i32_e32 v225, 31, v224
	v_or_b32_e32 v218, 0x90, v218
	v_ashrrev_i32_e32 v219, 31, v218
	s_waitcnt vmcnt(2)
	v_pk_fma_f32 v[170:171], v[170:171], v[216:217], v[174:175]
	v_pk_fma_f32 v[168:169], v[168:169], v[214:215], v[172:173]
	v_pk_mul_f32 v[170:171], v[170:171], s[20:21] op_sel_hi:[1,0]
	v_pk_mul_f32 v[168:169], v[168:169], s[20:21] op_sel_hi:[1,0]
	s_waitcnt vmcnt(1)
	v_pk_fma_f32 v[122:123], v[122:123], v[208:209], v[170:171]
	v_pk_fma_f32 v[120:121], v[120:121], v[206:207], v[168:169]
	global_store_dwordx4 v[182:183], v[120:123], off offset:64
	s_nop 0
	s_waitcnt vmcnt(1)
	v_sub_f32_e32 v213, v213, v220
	v_lshlrev_b64 v[120:121], 2, v[224:225]
	v_lshl_add_u64 v[168:169], s[12:13], 0, v[120:121]
	v_lshl_add_u64 v[170:171], s[14:15], 0, v[120:121]
	global_load_dwordx4 v[120:123], v[168:169], off
	global_load_dwordx4 v[172:175], v[170:171], off
	global_load_dwordx4 v[206:209], v[222:223], off offset:512
	v_sub_f32_e32 v212, v212, v220
	v_sub_f32_e32 v211, v211, v220
	v_sub_f32_e32 v210, v210, v220
	v_pk_mul_f32 v[210:211], v[210:211], v[220:221] op_sel:[0,1]
	v_pk_mul_f32 v[212:213], v[212:213], v[220:221] op_sel:[0,1]
	global_load_dwordx4 v[214:217], v[182:183], off offset:576
	s_waitcnt vmcnt(2)
	v_pk_fma_f32 v[122:123], v[122:123], v[212:213], v[174:175]
	v_pk_fma_f32 v[120:121], v[120:121], v[210:211], v[172:173]
	v_pk_mul_f32 v[122:123], v[122:123], s[20:21] op_sel_hi:[1,0]
	v_pk_mul_f32 v[120:121], v[120:121], s[20:21] op_sel_hi:[1,0]
	s_waitcnt vmcnt(1)
	v_pk_fma_f32 v[118:119], v[118:119], v[208:209], v[122:123]
	v_pk_fma_f32 v[116:117], v[116:117], v[206:207], v[120:121]
	global_store_dwordx4 v[182:183], v[116:119], off offset:512
	s_nop 0
	s_waitcnt vmcnt(1)
	v_mov_b32_e32 v210, v220
	v_mov_b32_e32 v211, v221
	v_sub_f32_e32 v213, v217, v210
	v_lshlrev_b64 v[116:117], 2, v[218:219]
	v_lshl_add_u64 v[172:173], s[12:13], 0, v[116:117]
	v_lshl_add_u64 v[174:175], s[14:15], 0, v[116:117]
	global_load_dwordx4 v[116:119], v[172:173], off
	global_load_dwordx4 v[120:123], v[174:175], off
	global_load_dwordx4 v[206:209], v[222:223], off offset:576
	v_sub_f32_e32 v212, v216, v210
	v_sub_f32_e32 v215, v215, v210
	v_sub_f32_e32 v214, v214, v210
	v_pk_mul_f32 v[214:215], v[214:215], v[210:211] op_sel:[0,1]
	v_pk_mul_f32 v[210:211], v[212:213], v[210:211] op_sel:[0,1]
	v_lshl_add_u64 v[222:223], v[226:227], 3, s[62:63]
	s_waitcnt vmcnt(1)
	v_pk_fma_f32 v[118:119], v[118:119], v[210:211], v[122:123]
	v_pk_fma_f32 v[116:117], v[116:117], v[214:215], v[120:121]
	v_pk_mul_f32 v[118:119], v[118:119], s[20:21] op_sel_hi:[1,0]
	v_pk_mul_f32 v[116:117], v[116:117], s[20:21] op_sel_hi:[1,0]
	s_waitcnt vmcnt(0)
	v_pk_fma_f32 v[114:115], v[114:115], v[208:209], v[118:119]
	v_pk_fma_f32 v[112:113], v[112:113], v[206:207], v[116:117]
	global_store_dwordx4 v[182:183], v[112:115], off offset:576
	global_load_dwordx2 v[224:225], v[222:223], off
	global_load_dwordx4 v[206:209], v[164:165], off
	global_load_dwordx4 v[210:213], v[166:167], off
	v_cndmask_b32_e64 v112, v177, 4, vcc
	v_mul_hi_i32_i24_e32 v113, 0x6000, v112
	v_mul_i32_i24_e32 v112, 0x6000, v112
	v_lshl_add_u64 v[112:113], s[10:11], 0, v[112:113]
	v_lshl_add_u64 v[226:227], v[112:113], 0, v[162:163]
	global_load_dwordx4 v[214:217], v[226:227], off
	v_mul_hi_i32 v112, v228, s50
	v_lshrrev_b32_e32 v113, 31, v112
	v_ashrrev_i32_e32 v112, 11, v112
	v_add_u32_e32 v177, v112, v113
	v_mad_i32_i24 v112, v177, s51, v228
	v_lshl_add_u32 v113, v177, 13, v201
	v_lshlrev_b32_e32 v114, 8, v177
	v_cmp_gt_i32_e32 vcc, s44, v112
	s_waitcnt vmcnt(3)
	v_sub_f32_e32 v143, v143, v224
	v_cndmask_b32_e32 v113, v113, v114, vcc
	v_add_u32_e32 v112, v113, v112
	v_sub_f32_e32 v142, v142, v224
	v_sub_f32_e32 v141, v141, v224
	v_sub_f32_e32 v140, v140, v224
	v_ashrrev_i32_e32 v113, 31, v112
	v_pk_mul_f32 v[140:141], v[140:141], v[224:225] op_sel:[0,1]
	v_pk_mul_f32 v[142:143], v[142:143], v[224:225] op_sel:[0,1]
	v_cndmask_b32_e32 v115, v202, v203, vcc
	v_cndmask_b32_e32 v114, v204, v205, vcc
	v_lshlrev_b64 v[112:113], 12, v[112:113]
	s_waitcnt vmcnt(1)
	v_pk_fma_f32 v[142:143], v[208:209], v[142:143], v[212:213]
	v_pk_fma_f32 v[140:141], v[206:207], v[140:141], v[210:211]
	v_lshl_add_u64 v[112:113], v[114:115], 0, v[112:113]
	v_pk_mul_f32 v[140:141], v[140:141], s[20:21] op_sel_hi:[1,0]
	v_pk_mul_f32 v[142:143], v[142:143], s[20:21] op_sel_hi:[1,0]
	v_lshl_add_u64 v[182:183], v[112:113], 0, v[162:163]
	s_waitcnt vmcnt(0)
	v_pk_fma_f32 v[110:111], v[110:111], v[216:217], v[142:143]
	v_pk_fma_f32 v[108:109], v[108:109], v[214:215], v[140:141]
	global_load_dwordx4 v[218:221], v[182:183], off
	global_load_dwordx4 v[120:123], v[182:183], off offset:64
	global_load_dwordx4 v[116:119], v[182:183], off offset:512
	global_load_dwordx4 v[112:115], v[182:183], off offset:576
	s_nop 0
	global_store_dwordx4 v[180:181], v[108:111], off
	s_nop 0
	s_nop 0
	global_load_dwordx4 v[108:111], v[124:125], off
	global_load_dwordx4 v[140:143], v[126:127], off
	global_load_dwordx4 v[206:209], v[226:227], off offset:64
	s_waitcnt vmcnt(3)
	v_mov_b32_e32 v210, v224
	v_mov_b32_e32 v211, v225
	v_sub_f32_e32 v139, v139, v210
	v_sub_f32_e32 v138, v138, v210
	v_sub_f32_e32 v137, v137, v210
	v_sub_f32_e32 v136, v136, v210
	v_pk_mul_f32 v[136:137], v[136:137], v[210:211] op_sel:[0,1]
	v_pk_mul_f32 v[138:139], v[138:139], v[210:211] op_sel:[0,1]
	s_waitcnt vmcnt(1)
	v_pk_fma_f32 v[108:109], v[108:109], v[136:137], v[140:141]
	v_pk_fma_f32 v[110:111], v[110:111], v[138:139], v[142:143]
	v_pk_mul_f32 v[108:109], v[108:109], s[20:21] op_sel_hi:[1,0]
	v_pk_mul_f32 v[110:111], v[110:111], s[20:21] op_sel_hi:[1,0]
	s_waitcnt vmcnt(0)
	v_pk_fma_f32 v[104:105], v[104:105], v[206:207], v[108:109]
	v_pk_fma_f32 v[106:107], v[106:107], v[208:209], v[110:111]
	global_store_dwordx4 v[180:181], v[104:107], off offset:64
	s_nop 0
	s_nop 0
	global_load_dwordx4 v[104:107], v[168:169], off
	global_load_dwordx4 v[108:111], v[170:171], off
	global_load_dwordx4 v[136:139], v[226:227], off offset:512
	v_lshl_add_u64 v[206:207], v[228:229], 3, s[62:63]
	v_or_b32_e32 v208, 48, v176
	v_ashrrev_i32_e32 v209, 31, v208
	s_waitcnt vmcnt(3)
	v_mov_b32_e32 v140, v224
	v_mov_b32_e32 v141, v225
	v_sub_f32_e32 v135, v135, v140
	v_sub_f32_e32 v134, v134, v140
	v_sub_f32_e32 v133, v133, v140
	v_sub_f32_e32 v132, v132, v140
	v_pk_mul_f32 v[132:133], v[132:133], v[140:141] op_sel:[0,1]
	v_pk_mul_f32 v[134:135], v[134:135], v[140:141] op_sel:[0,1]
	s_waitcnt vmcnt(1)
	v_pk_fma_f32 v[104:105], v[104:105], v[132:133], v[108:109]
	v_pk_fma_f32 v[106:107], v[106:107], v[134:135], v[110:111]
	v_pk_mul_f32 v[104:105], v[104:105], s[20:21] op_sel_hi:[1,0]
	v_pk_mul_f32 v[106:107], v[106:107], s[20:21] op_sel_hi:[1,0]
	s_waitcnt vmcnt(0)
	v_pk_fma_f32 v[100:101], v[100:101], v[136:137], v[104:105]
	v_pk_fma_f32 v[102:103], v[102:103], v[138:139], v[106:107]
	global_store_dwordx4 v[180:181], v[100:103], off offset:512
	s_nop 0
	s_nop 0
	global_load_dwordx4 v[100:103], v[172:173], off
	global_load_dwordx4 v[104:107], v[174:175], off
	global_load_dwordx4 v[108:111], v[226:227], off offset:576
	s_waitcnt vmcnt(3)
	v_mov_b32_e32 v132, v224
	v_mov_b32_e32 v133, v225
	v_sub_f32_e32 v131, v131, v132
	v_sub_f32_e32 v130, v130, v132
	v_sub_f32_e32 v129, v129, v132
	v_sub_f32_e32 v128, v128, v132
	v_pk_mul_f32 v[128:129], v[128:129], v[132:133] op_sel:[0,1]
	v_pk_mul_f32 v[130:131], v[130:131], v[132:133] op_sel:[0,1]
	s_waitcnt vmcnt(1)
	v_pk_fma_f32 v[100:101], v[100:101], v[128:129], v[104:105]
	v_pk_fma_f32 v[102:103], v[102:103], v[130:131], v[106:107]
	v_pk_mul_f32 v[100:101], v[100:101], s[20:21] op_sel_hi:[1,0]
	v_pk_mul_f32 v[102:103], v[102:103], s[20:21] op_sel_hi:[1,0]
	s_waitcnt vmcnt(0)
	v_pk_fma_f32 v[96:97], v[96:97], v[108:109], v[100:101]
	v_pk_fma_f32 v[98:99], v[98:99], v[110:111], v[102:103]
	global_store_dwordx4 v[180:181], v[96:99], off offset:576
	global_load_dwordx2 v[110:111], v[206:207], off
	global_load_dwordx4 v[128:131], v[164:165], off
	global_load_dwordx4 v[132:135], v[166:167], off
	v_cndmask_b32_e64 v96, v177, 4, vcc
	v_mul_hi_i32_i24_e32 v97, 0x6000, v96
	v_mul_i32_i24_e32 v96, 0x6000, v96
	v_lshl_add_u64 v[96:97], s[10:11], 0, v[96:97]
	v_lshl_add_u64 v[180:181], v[96:97], 0, v[162:163]
	global_load_dwordx4 v[136:139], v[180:181], off
	v_mul_hi_i32 v96, v208, s50
	v_lshrrev_b32_e32 v97, 31, v96
	v_ashrrev_i32_e32 v96, 11, v96
	v_add_u32_e32 v177, v96, v97
	v_mad_i32_i24 v96, v177, s51, v208
	v_lshl_add_u32 v97, v177, 13, v201
	v_lshlrev_b32_e32 v98, 8, v177
	v_cmp_gt_i32_e32 vcc, s44, v96
	s_waitcnt vmcnt(3)
	v_mov_b32_e32 v214, v110
	v_mov_b32_e32 v215, v111
	v_sub_f32_e32 v211, v221, v110
	v_cndmask_b32_e32 v97, v97, v98, vcc
	v_add_u32_e32 v96, v97, v96
	v_sub_f32_e32 v210, v220, v110
	v_sub_f32_e32 v213, v219, v110
	v_sub_f32_e32 v212, v218, v110
	v_ashrrev_i32_e32 v97, 31, v96
	v_pk_mul_f32 v[212:213], v[212:213], v[110:111] op_sel:[0,1]
	v_pk_mul_f32 v[110:111], v[210:211], v[110:111] op_sel:[0,1]
	v_cndmask_b32_e32 v99, v202, v203, vcc
	v_cndmask_b32_e32 v98, v204, v205, vcc
	v_lshlrev_b64 v[96:97], 12, v[96:97]
	s_waitcnt vmcnt(1)
	v_pk_fma_f32 v[110:111], v[130:131], v[110:111], v[134:135]
	v_pk_fma_f32 v[128:129], v[128:129], v[212:213], v[132:133]
	v_lshl_add_u64 v[96:97], v[98:99], 0, v[96:97]
	v_pk_mul_f32 v[128:129], v[128:129], s[20:21] op_sel_hi:[1,0]
	v_pk_mul_f32 v[110:111], v[110:111], s[20:21] op_sel_hi:[1,0]
	v_lshl_add_u64 v[108:109], v[96:97], 0, v[162:163]
	s_waitcnt vmcnt(0)
	v_pk_fma_f32 v[94:95], v[94:95], v[138:139], v[110:111]
	v_pk_fma_f32 v[92:93], v[92:93], v[136:137], v[128:129]
	global_load_dwordx4 v[140:143], v[108:109], off
	global_load_dwordx4 v[104:107], v[108:109], off offset:64
	global_load_dwordx4 v[100:103], v[108:109], off offset:512
	global_load_dwordx4 v[96:99], v[108:109], off offset:576
	s_nop 0
	global_store_dwordx4 v[182:183], v[92:95], off
	s_nop 0
	s_nop 0
	global_load_dwordx4 v[92:95], v[124:125], off
	global_load_dwordx4 v[128:131], v[126:127], off
	global_load_dwordx4 v[132:135], v[180:181], off offset:64
	s_waitcnt vmcnt(3)
	v_mov_b32_e32 v110, v214
	v_mov_b32_e32 v111, v215
	v_sub_f32_e32 v123, v123, v110
	v_sub_f32_e32 v122, v122, v110
	v_sub_f32_e32 v121, v121, v110
	v_sub_f32_e32 v120, v120, v110
	v_pk_mul_f32 v[120:121], v[120:121], v[110:111] op_sel:[0,1]
	v_pk_mul_f32 v[110:111], v[122:123], v[110:111] op_sel:[0,1]
	s_waitcnt vmcnt(1)
	v_pk_fma_f32 v[92:93], v[92:93], v[120:121], v[128:129]
	v_pk_fma_f32 v[94:95], v[94:95], v[110:111], v[130:131]
	v_pk_mul_f32 v[92:93], v[92:93], s[20:21] op_sel_hi:[1,0]
	v_pk_mul_f32 v[94:95], v[94:95], s[20:21] op_sel_hi:[1,0]
	s_waitcnt vmcnt(0)
	v_pk_fma_f32 v[88:89], v[88:89], v[132:133], v[92:93]
	v_pk_fma_f32 v[90:91], v[90:91], v[134:135], v[94:95]
	global_store_dwordx4 v[182:183], v[88:91], off offset:64
	s_nop 0
	s_nop 0
	global_load_dwordx4 v[88:91], v[168:169], off
	global_load_dwordx4 v[92:95], v[170:171], off
	global_load_dwordx4 v[120:123], v[180:181], off offset:512
	s_waitcnt vmcnt(3)
	v_mov_b32_e32 v110, v214
	v_mov_b32_e32 v111, v215
	v_sub_f32_e32 v119, v119, v110
	v_sub_f32_e32 v118, v118, v110
	v_sub_f32_e32 v117, v117, v110
	v_sub_f32_e32 v116, v116, v110
	v_pk_mul_f32 v[116:117], v[116:117], v[110:111] op_sel:[0,1]
	v_pk_mul_f32 v[110:111], v[118:119], v[110:111] op_sel:[0,1]
	s_waitcnt vmcnt(1)
	v_pk_fma_f32 v[88:89], v[88:89], v[116:117], v[92:93]
	v_pk_fma_f32 v[90:91], v[90:91], v[110:111], v[94:95]
	v_pk_mul_f32 v[88:89], v[88:89], s[20:21] op_sel_hi:[1,0]
	v_pk_mul_f32 v[90:91], v[90:91], s[20:21] op_sel_hi:[1,0]
	s_waitcnt vmcnt(0)
	v_pk_fma_f32 v[84:85], v[84:85], v[120:121], v[88:89]
	v_pk_fma_f32 v[86:87], v[86:87], v[122:123], v[90:91]
	global_store_dwordx4 v[182:183], v[84:87], off offset:512
	s_nop 0
	s_nop 0
	global_load_dwordx4 v[84:87], v[172:173], off
	global_load_dwordx4 v[88:91], v[174:175], off
	global_load_dwordx4 v[92:95], v[180:181], off offset:576
	v_lshl_add_u64 v[122:123], v[208:209], 3, s[62:63]
	s_waitcnt vmcnt(3)
	v_mov_b32_e32 v110, v214
	v_mov_b32_e32 v111, v215
	v_sub_f32_e32 v115, v115, v110
	v_sub_f32_e32 v114, v114, v110
	v_sub_f32_e32 v113, v113, v110
	v_sub_f32_e32 v112, v112, v110
	v_pk_mul_f32 v[112:113], v[112:113], v[110:111] op_sel:[0,1]
	v_pk_mul_f32 v[110:111], v[114:115], v[110:111] op_sel:[0,1]
	s_waitcnt vmcnt(1)
	v_pk_fma_f32 v[84:85], v[84:85], v[112:113], v[88:89]
	v_pk_fma_f32 v[86:87], v[86:87], v[110:111], v[90:91]
	v_pk_mul_f32 v[84:85], v[84:85], s[20:21] op_sel_hi:[1,0]
	v_pk_mul_f32 v[86:87], v[86:87], s[20:21] op_sel_hi:[1,0]
	s_waitcnt vmcnt(0)
	v_pk_fma_f32 v[80:81], v[80:81], v[92:93], v[84:85]
	v_pk_fma_f32 v[82:83], v[82:83], v[94:95], v[86:87]
	global_store_dwordx4 v[182:183], v[80:83], off offset:576
	global_load_dwordx2 v[94:95], v[122:123], off
	global_load_dwordx4 v[110:113], v[164:165], off
	global_load_dwordx4 v[114:117], v[166:167], off
	v_cndmask_b32_e64 v80, v177, 4, vcc
	v_mul_hi_i32_i24_e32 v81, 0x6000, v80
	v_mul_i32_i24_e32 v80, 0x6000, v80
	v_lshl_add_u64 v[80:81], s[10:11], 0, v[80:81]
	v_lshl_add_u64 v[132:133], v[80:81], 0, v[162:163]
	global_load_dwordx4 v[118:121], v[132:133], off
	v_add_u32_e32 v80, 0x80, v176
	v_mul_hi_i32 v81, v80, s50
	v_lshrrev_b32_e32 v82, 31, v81
	v_ashrrev_i32_e32 v81, 11, v81
	v_add_u32_e32 v138, v81, v82
	v_mad_i32_i24 v80, v138, s51, v80
	v_lshl_add_u32 v81, v138, 13, v201
	v_lshlrev_b32_e32 v82, 8, v138
	v_cmp_gt_i32_e32 vcc, s44, v80
	s_waitcnt vmcnt(3)
	v_mov_b32_e32 v180, v94
	v_mov_b32_e32 v181, v95
	v_sub_f32_e32 v135, v143, v94
	v_cndmask_b32_e32 v81, v81, v82, vcc
	v_add_u32_e32 v80, v81, v80
	v_sub_f32_e32 v134, v142, v94
	v_sub_f32_e32 v137, v141, v94
	v_sub_f32_e32 v136, v140, v94
	v_ashrrev_i32_e32 v81, 31, v80
	v_pk_mul_f32 v[136:137], v[136:137], v[94:95] op_sel:[0,1]
	v_pk_mul_f32 v[94:95], v[134:135], v[94:95] op_sel:[0,1]
	v_cndmask_b32_e32 v83, v202, v203, vcc
	v_cndmask_b32_e32 v82, v204, v205, vcc
	v_lshlrev_b64 v[80:81], 12, v[80:81]
	s_waitcnt vmcnt(1)
	v_pk_fma_f32 v[94:95], v[112:113], v[94:95], v[116:117]
	v_pk_fma_f32 v[110:111], v[110:111], v[136:137], v[114:115]
	v_lshl_add_u64 v[80:81], v[82:83], 0, v[80:81]
	v_pk_mul_f32 v[110:111], v[110:111], s[20:21] op_sel_hi:[1,0]
	v_pk_mul_f32 v[94:95], v[94:95], s[20:21] op_sel_hi:[1,0]
	v_lshl_add_u64 v[92:93], v[80:81], 0, v[162:163]
	s_waitcnt vmcnt(0)
	v_pk_fma_f32 v[78:79], v[78:79], v[120:121], v[94:95]
	v_pk_fma_f32 v[76:77], v[76:77], v[118:119], v[110:111]
	global_load_dwordx4 v[128:131], v[92:93], off
	global_load_dwordx4 v[88:91], v[92:93], off offset:64
	global_load_dwordx4 v[84:87], v[92:93], off offset:512
	global_load_dwordx4 v[80:83], v[92:93], off offset:576
	s_nop 0
	global_store_dwordx4 v[108:109], v[76:79], off
	s_nop 0
	s_nop 0
	global_load_dwordx4 v[76:79], v[124:125], off
	global_load_dwordx4 v[110:113], v[126:127], off
	global_load_dwordx4 v[114:117], v[132:133], off offset:64
	s_waitcnt vmcnt(3)
	v_mov_b32_e32 v94, v180
	v_mov_b32_e32 v95, v181
	v_sub_f32_e32 v107, v107, v94
	v_sub_f32_e32 v106, v106, v94
	v_sub_f32_e32 v105, v105, v94
	v_sub_f32_e32 v104, v104, v94
	v_pk_mul_f32 v[104:105], v[104:105], v[94:95] op_sel:[0,1]
	v_pk_mul_f32 v[94:95], v[106:107], v[94:95] op_sel:[0,1]
	s_waitcnt vmcnt(1)
	v_pk_fma_f32 v[76:77], v[76:77], v[104:105], v[110:111]
	v_pk_fma_f32 v[78:79], v[78:79], v[94:95], v[112:113]
	v_pk_mul_f32 v[76:77], v[76:77], s[20:21] op_sel_hi:[1,0]
	v_pk_mul_f32 v[78:79], v[78:79], s[20:21] op_sel_hi:[1,0]
	s_waitcnt vmcnt(0)
	v_pk_fma_f32 v[72:73], v[72:73], v[114:115], v[76:77]
	v_pk_fma_f32 v[74:75], v[74:75], v[116:117], v[78:79]
	global_store_dwordx4 v[108:109], v[72:75], off offset:64
	s_nop 0
	s_nop 0
	global_load_dwordx4 v[72:75], v[168:169], off
	global_load_dwordx4 v[76:79], v[170:171], off
	global_load_dwordx4 v[104:107], v[132:133], off offset:512
	v_add_u32_e32 v112, 0x90, v176
	v_ashrrev_i32_e32 v113, 31, v112
	s_waitcnt vmcnt(3)
	v_mov_b32_e32 v94, v180
	v_mov_b32_e32 v95, v181
	v_sub_f32_e32 v103, v103, v94
	v_sub_f32_e32 v102, v102, v94
	v_sub_f32_e32 v101, v101, v94
	v_sub_f32_e32 v100, v100, v94
	v_pk_mul_f32 v[100:101], v[100:101], v[94:95] op_sel:[0,1]
	v_pk_mul_f32 v[94:95], v[102:103], v[94:95] op_sel:[0,1]
	s_waitcnt vmcnt(1)
	v_pk_fma_f32 v[72:73], v[72:73], v[100:101], v[76:77]
	v_pk_fma_f32 v[74:75], v[74:75], v[94:95], v[78:79]
	v_pk_mul_f32 v[72:73], v[72:73], s[20:21] op_sel_hi:[1,0]
	v_pk_mul_f32 v[74:75], v[74:75], s[20:21] op_sel_hi:[1,0]
	s_waitcnt vmcnt(0)
	v_pk_fma_f32 v[68:69], v[68:69], v[104:105], v[72:73]
	v_pk_fma_f32 v[70:71], v[70:71], v[106:107], v[74:75]
	global_store_dwordx4 v[108:109], v[68:71], off offset:512
	s_nop 0
	s_nop 0
	global_load_dwordx4 v[68:71], v[172:173], off
	global_load_dwordx4 v[72:75], v[174:175], off
	global_load_dwordx4 v[76:79], v[132:133], off offset:576
	s_waitcnt vmcnt(3)
	v_mov_b32_e32 v94, v180
	v_mov_b32_e32 v95, v181
	v_sub_f32_e32 v99, v99, v94
	v_sub_f32_e32 v98, v98, v94
	v_sub_f32_e32 v97, v97, v94
	v_sub_f32_e32 v96, v96, v94
	v_pk_mul_f32 v[96:97], v[96:97], v[94:95] op_sel:[0,1]
	v_pk_mul_f32 v[94:95], v[98:99], v[94:95] op_sel:[0,1]
	s_waitcnt vmcnt(1)
	v_pk_fma_f32 v[68:69], v[68:69], v[96:97], v[72:73]
	v_pk_fma_f32 v[70:71], v[70:71], v[94:95], v[74:75]
	v_pk_mul_f32 v[68:69], v[68:69], s[20:21] op_sel_hi:[1,0]
	v_pk_mul_f32 v[70:71], v[70:71], s[20:21] op_sel_hi:[1,0]
	s_waitcnt vmcnt(0)
	v_pk_fma_f32 v[64:65], v[64:65], v[76:77], v[68:69]
	v_pk_fma_f32 v[66:67], v[66:67], v[78:79], v[70:71]
	global_store_dwordx4 v[108:109], v[64:67], off offset:576
	global_load_dwordx2 v[78:79], v[178:179], off offset:1024
	global_load_dwordx4 v[94:97], v[164:165], off
	global_load_dwordx4 v[98:101], v[166:167], off
	v_cndmask_b32_e64 v64, v138, 4, vcc
	v_mul_hi_i32_i24_e32 v65, 0x6000, v64
	v_mul_i32_i24_e32 v64, 0x6000, v64
	v_lshl_add_u64 v[64:65], s[10:11], 0, v[64:65]
	v_lshl_add_u64 v[110:111], v[64:65], 0, v[162:163]
	global_load_dwordx4 v[102:105], v[110:111], off
	v_mul_hi_i32 v64, v112, s50
	v_lshrrev_b32_e32 v65, 31, v64
	v_ashrrev_i32_e32 v64, 11, v64
	v_add_u32_e32 v118, v64, v65
	v_mad_i32_i24 v64, v118, s51, v112
	v_lshl_add_u32 v65, v118, 13, v201
	v_lshlrev_b32_e32 v66, 8, v118
	v_cmp_gt_i32_e32 vcc, s44, v64
	s_waitcnt vmcnt(3)
	v_sub_f32_e32 v115, v131, v78
	v_cndmask_b32_e32 v65, v65, v66, vcc
	v_add_u32_e32 v64, v65, v64
	v_sub_f32_e32 v114, v130, v78
	v_sub_f32_e32 v117, v129, v78
	v_sub_f32_e32 v116, v128, v78
	v_ashrrev_i32_e32 v65, 31, v64
	v_pk_mul_f32 v[116:117], v[116:117], v[78:79] op_sel:[0,1]
	v_pk_mul_f32 v[78:79], v[114:115], v[78:79] op_sel:[0,1]
	v_cndmask_b32_e32 v67, v202, v203, vcc
	v_cndmask_b32_e32 v66, v204, v205, vcc
	v_lshlrev_b64 v[64:65], 12, v[64:65]
	s_waitcnt vmcnt(1)
	v_pk_fma_f32 v[78:79], v[96:97], v[78:79], v[100:101]
	v_pk_fma_f32 v[94:95], v[94:95], v[116:117], v[98:99]
	v_lshl_add_u64 v[64:65], v[66:67], 0, v[64:65]
	v_pk_mul_f32 v[94:95], v[94:95], s[20:21] op_sel_hi:[1,0]
	v_pk_mul_f32 v[78:79], v[78:79], s[20:21] op_sel_hi:[1,0]
	v_lshl_add_u64 v[76:77], v[64:65], 0, v[162:163]
	s_waitcnt vmcnt(0)
	v_pk_fma_f32 v[62:63], v[62:63], v[104:105], v[78:79]
	v_pk_fma_f32 v[60:61], v[60:61], v[102:103], v[94:95]
	global_load_dwordx4 v[106:109], v[76:77], off
	global_load_dwordx4 v[72:75], v[76:77], off offset:64
	global_load_dwordx4 v[68:71], v[76:77], off offset:512
	global_load_dwordx4 v[64:67], v[76:77], off offset:576
	s_nop 0
	global_store_dwordx4 v[92:93], v[60:63], off
	global_load_dwordx2 v[78:79], v[178:179], off offset:1024
	s_nop 0
	global_load_dwordx4 v[60:63], v[124:125], off
	global_load_dwordx4 v[94:97], v[126:127], off
	global_load_dwordx4 v[98:101], v[110:111], off offset:64
	s_waitcnt vmcnt(3)
	v_sub_f32_e32 v91, v91, v78
	v_sub_f32_e32 v90, v90, v78
	v_sub_f32_e32 v89, v89, v78
	v_sub_f32_e32 v88, v88, v78
	v_pk_mul_f32 v[88:89], v[88:89], v[78:79] op_sel:[0,1]
	v_pk_mul_f32 v[78:79], v[90:91], v[78:79] op_sel:[0,1]
	s_waitcnt vmcnt(1)
	v_pk_fma_f32 v[60:61], v[60:61], v[88:89], v[94:95]
	v_pk_fma_f32 v[62:63], v[62:63], v[78:79], v[96:97]
	v_pk_mul_f32 v[60:61], v[60:61], s[20:21] op_sel_hi:[1,0]
	v_pk_mul_f32 v[62:63], v[62:63], s[20:21] op_sel_hi:[1,0]
	s_waitcnt vmcnt(0)
	v_pk_fma_f32 v[56:57], v[56:57], v[98:99], v[60:61]
	v_pk_fma_f32 v[58:59], v[58:59], v[100:101], v[62:63]
	global_store_dwordx4 v[92:93], v[56:59], off offset:64
	global_load_dwordx2 v[78:79], v[178:179], off offset:1024
	s_nop 0
	global_load_dwordx4 v[56:59], v[168:169], off
	global_load_dwordx4 v[60:63], v[170:171], off
	global_load_dwordx4 v[88:91], v[110:111], off offset:512
	v_lshl_add_u64 v[94:95], v[112:113], 3, s[62:63]
	v_add_u32_e32 v98, 0xa0, v176
	v_ashrrev_i32_e32 v99, 31, v98
	s_waitcnt vmcnt(3)
	v_sub_f32_e32 v87, v87, v78
	v_sub_f32_e32 v86, v86, v78
	v_sub_f32_e32 v85, v85, v78
	v_sub_f32_e32 v84, v84, v78
	v_pk_mul_f32 v[84:85], v[84:85], v[78:79] op_sel:[0,1]
	v_pk_mul_f32 v[78:79], v[86:87], v[78:79] op_sel:[0,1]
	s_waitcnt vmcnt(1)
	v_pk_fma_f32 v[56:57], v[56:57], v[84:85], v[60:61]
	v_pk_fma_f32 v[58:59], v[58:59], v[78:79], v[62:63]
	v_pk_mul_f32 v[56:57], v[56:57], s[20:21] op_sel_hi:[1,0]
	v_pk_mul_f32 v[58:59], v[58:59], s[20:21] op_sel_hi:[1,0]
	s_waitcnt vmcnt(0)
	v_pk_fma_f32 v[52:53], v[52:53], v[88:89], v[56:57]
	v_pk_fma_f32 v[54:55], v[54:55], v[90:91], v[58:59]
	global_store_dwordx4 v[92:93], v[52:55], off offset:512
	global_load_dwordx2 v[78:79], v[178:179], off offset:1024
	s_nop 0
	global_load_dwordx4 v[52:55], v[172:173], off
	global_load_dwordx4 v[56:59], v[174:175], off
	global_load_dwordx4 v[60:63], v[110:111], off offset:576
	s_waitcnt vmcnt(3)
	v_sub_f32_e32 v83, v83, v78
	v_sub_f32_e32 v82, v82, v78
	v_sub_f32_e32 v81, v81, v78
	v_sub_f32_e32 v80, v80, v78
	v_pk_mul_f32 v[80:81], v[80:81], v[78:79] op_sel:[0,1]
	v_pk_mul_f32 v[78:79], v[82:83], v[78:79] op_sel:[0,1]
	s_waitcnt vmcnt(1)
	v_pk_fma_f32 v[52:53], v[52:53], v[80:81], v[56:57]
	v_pk_fma_f32 v[54:55], v[54:55], v[78:79], v[58:59]
	v_pk_mul_f32 v[52:53], v[52:53], s[20:21] op_sel_hi:[1,0]
	v_pk_mul_f32 v[54:55], v[54:55], s[20:21] op_sel_hi:[1,0]
	s_waitcnt vmcnt(0)
	v_pk_fma_f32 v[48:49], v[48:49], v[60:61], v[52:53]
	v_pk_fma_f32 v[50:51], v[50:51], v[62:63], v[54:55]
	global_store_dwordx4 v[92:93], v[48:51], off offset:576
	global_load_dwordx2 v[62:63], v[94:95], off
	global_load_dwordx4 v[78:81], v[164:165], off
	global_load_dwordx4 v[82:85], v[166:167], off
	v_cndmask_b32_e64 v48, v118, 4, vcc
	v_mul_hi_i32_i24_e32 v49, 0x6000, v48
	v_mul_i32_i24_e32 v48, 0x6000, v48
	v_lshl_add_u64 v[48:49], s[10:11], 0, v[48:49]
	v_lshl_add_u64 v[96:97], v[48:49], 0, v[162:163]
	global_load_dwordx4 v[86:89], v[96:97], off
	v_mul_hi_i32 v48, v98, s50
	v_lshrrev_b32_e32 v49, 31, v48
	v_ashrrev_i32_e32 v48, 11, v48
	v_add_u32_e32 v104, v48, v49
	v_mad_i32_i24 v48, v104, s51, v98
	v_lshl_add_u32 v49, v104, 13, v201
	v_lshlrev_b32_e32 v50, 8, v104
	v_cmp_gt_i32_e32 vcc, s44, v48
	s_waitcnt vmcnt(3)
	v_mov_b32_e32 v128, v62
	v_mov_b32_e32 v129, v63
	v_sub_f32_e32 v101, v109, v62
	v_cndmask_b32_e32 v49, v49, v50, vcc
	v_add_u32_e32 v48, v49, v48
	v_sub_f32_e32 v100, v108, v62
	v_sub_f32_e32 v103, v107, v62
	v_sub_f32_e32 v102, v106, v62
	v_ashrrev_i32_e32 v49, 31, v48
	v_pk_mul_f32 v[102:103], v[102:103], v[62:63] op_sel:[0,1]
	v_pk_mul_f32 v[62:63], v[100:101], v[62:63] op_sel:[0,1]
	v_cndmask_b32_e32 v51, v202, v203, vcc
	v_cndmask_b32_e32 v50, v204, v205, vcc
	v_lshlrev_b64 v[48:49], 12, v[48:49]
	s_waitcnt vmcnt(1)
	v_pk_fma_f32 v[62:63], v[80:81], v[62:63], v[84:85]
	v_pk_fma_f32 v[78:79], v[78:79], v[102:103], v[82:83]
	v_lshl_add_u64 v[48:49], v[50:51], 0, v[48:49]
	v_pk_mul_f32 v[78:79], v[78:79], s[20:21] op_sel_hi:[1,0]
	v_pk_mul_f32 v[62:63], v[62:63], s[20:21] op_sel_hi:[1,0]
	v_lshl_add_u64 v[60:61], v[48:49], 0, v[162:163]
	s_waitcnt vmcnt(0)
	v_pk_fma_f32 v[46:47], v[46:47], v[88:89], v[62:63]
	v_pk_fma_f32 v[44:45], v[44:45], v[86:87], v[78:79]
	global_load_dwordx4 v[90:93], v[60:61], off
	global_load_dwordx4 v[56:59], v[60:61], off offset:64
	global_load_dwordx4 v[52:55], v[60:61], off offset:512
	global_load_dwordx4 v[48:51], v[60:61], off offset:576
	s_nop 0
	global_store_dwordx4 v[76:77], v[44:47], off
	s_nop 0
	s_nop 0
	global_load_dwordx4 v[44:47], v[124:125], off
	global_load_dwordx4 v[78:81], v[126:127], off
	global_load_dwordx4 v[82:85], v[96:97], off offset:64
	s_waitcnt vmcnt(3)
	v_mov_b32_e32 v62, v128
	v_mov_b32_e32 v63, v129
	v_sub_f32_e32 v75, v75, v62
	v_sub_f32_e32 v74, v74, v62
	v_sub_f32_e32 v73, v73, v62
	v_sub_f32_e32 v72, v72, v62
	v_pk_mul_f32 v[72:73], v[72:73], v[62:63] op_sel:[0,1]
	v_pk_mul_f32 v[62:63], v[74:75], v[62:63] op_sel:[0,1]
	s_waitcnt vmcnt(1)
	v_pk_fma_f32 v[44:45], v[44:45], v[72:73], v[78:79]
	v_pk_fma_f32 v[46:47], v[46:47], v[62:63], v[80:81]
	v_pk_mul_f32 v[44:45], v[44:45], s[20:21] op_sel_hi:[1,0]
	v_pk_mul_f32 v[46:47], v[46:47], s[20:21] op_sel_hi:[1,0]
	s_waitcnt vmcnt(0)
	v_pk_fma_f32 v[40:41], v[40:41], v[82:83], v[44:45]
	v_pk_fma_f32 v[42:43], v[42:43], v[84:85], v[46:47]
	global_store_dwordx4 v[76:77], v[40:43], off offset:64
	s_nop 0
	s_nop 0
	global_load_dwordx4 v[40:43], v[168:169], off
	global_load_dwordx4 v[44:47], v[170:171], off
	global_load_dwordx4 v[72:75], v[96:97], off offset:512
	v_lshl_add_u64 v[78:79], v[98:99], 3, s[62:63]
	v_add_u32_e32 v82, 0xb0, v176
	v_ashrrev_i32_e32 v83, 31, v82
	s_waitcnt vmcnt(3)
	v_mov_b32_e32 v62, v128
	v_mov_b32_e32 v63, v129
	v_sub_f32_e32 v71, v71, v62
	v_sub_f32_e32 v70, v70, v62
	v_sub_f32_e32 v69, v69, v62
	v_sub_f32_e32 v68, v68, v62
	v_pk_mul_f32 v[68:69], v[68:69], v[62:63] op_sel:[0,1]
	v_pk_mul_f32 v[62:63], v[70:71], v[62:63] op_sel:[0,1]
	s_waitcnt vmcnt(1)
	v_pk_fma_f32 v[40:41], v[40:41], v[68:69], v[44:45]
	v_pk_fma_f32 v[42:43], v[42:43], v[62:63], v[46:47]
	v_pk_mul_f32 v[40:41], v[40:41], s[20:21] op_sel_hi:[1,0]
	v_pk_mul_f32 v[42:43], v[42:43], s[20:21] op_sel_hi:[1,0]
	s_waitcnt vmcnt(0)
	v_pk_fma_f32 v[36:37], v[36:37], v[72:73], v[40:41]
	v_pk_fma_f32 v[38:39], v[38:39], v[74:75], v[42:43]
	global_store_dwordx4 v[76:77], v[36:39], off offset:512
	s_nop 0
	s_nop 0
	global_load_dwordx4 v[36:39], v[172:173], off
	global_load_dwordx4 v[40:43], v[174:175], off
	global_load_dwordx4 v[44:47], v[96:97], off offset:576
	s_waitcnt vmcnt(3)
	v_mov_b32_e32 v62, v128
	v_mov_b32_e32 v63, v129
	v_sub_f32_e32 v67, v67, v62
	v_sub_f32_e32 v66, v66, v62
	v_sub_f32_e32 v65, v65, v62
	v_sub_f32_e32 v64, v64, v62
	v_pk_mul_f32 v[64:65], v[64:65], v[62:63] op_sel:[0,1]
	v_pk_mul_f32 v[62:63], v[66:67], v[62:63] op_sel:[0,1]
	s_waitcnt vmcnt(1)
	v_pk_fma_f32 v[36:37], v[36:37], v[64:65], v[40:41]
	v_pk_fma_f32 v[38:39], v[38:39], v[62:63], v[42:43]
	v_pk_mul_f32 v[36:37], v[36:37], s[20:21] op_sel_hi:[1,0]
	v_pk_mul_f32 v[38:39], v[38:39], s[20:21] op_sel_hi:[1,0]
	s_waitcnt vmcnt(0)
	v_pk_fma_f32 v[32:33], v[32:33], v[44:45], v[36:37]
	v_pk_fma_f32 v[34:35], v[34:35], v[46:47], v[38:39]
	global_store_dwordx4 v[76:77], v[32:35], off offset:576
	global_load_dwordx2 v[46:47], v[78:79], off
	global_load_dwordx4 v[42:45], v[164:165], off
	global_load_dwordx4 v[62:65], v[166:167], off
	v_cndmask_b32_e64 v32, v104, 4, vcc
	v_mul_hi_i32_i24_e32 v33, 0x6000, v32
	v_mul_i32_i24_e32 v32, 0x6000, v32
	v_lshl_add_u64 v[32:33], s[10:11], 0, v[32:33]
	v_lshl_add_u64 v[80:81], v[32:33], 0, v[162:163]
	global_load_dwordx4 v[66:69], v[80:81], off
	v_mul_hi_i32 v32, v82, s50
	v_lshrrev_b32_e32 v33, 31, v32
	v_ashrrev_i32_e32 v32, 11, v32
	v_add_u32_e32 v88, v32, v33
	v_mad_i32_i24 v32, v88, s51, v82
	v_lshl_add_u32 v33, v88, 13, v201
	v_lshlrev_b32_e32 v34, 8, v88
	v_cmp_gt_i32_e32 vcc, s44, v32
	s_waitcnt vmcnt(3)
	v_mov_b32_e32 v128, v46
	v_mov_b32_e32 v129, v47
	v_sub_f32_e32 v85, v93, v46
	v_cndmask_b32_e32 v33, v33, v34, vcc
	v_add_u32_e32 v32, v33, v32
	v_sub_f32_e32 v84, v92, v46
	v_sub_f32_e32 v87, v91, v46
	v_sub_f32_e32 v86, v90, v46
	v_ashrrev_i32_e32 v33, 31, v32
	v_pk_mul_f32 v[86:87], v[86:87], v[46:47] op_sel:[0,1]
	v_pk_mul_f32 v[46:47], v[84:85], v[46:47] op_sel:[0,1]
	v_cndmask_b32_e32 v35, v202, v203, vcc
	v_cndmask_b32_e32 v34, v204, v205, vcc
	v_lshlrev_b64 v[32:33], 12, v[32:33]
	s_waitcnt vmcnt(1)
	v_pk_fma_f32 v[44:45], v[44:45], v[46:47], v[64:65]
	v_pk_fma_f32 v[42:43], v[42:43], v[86:87], v[62:63]
	v_lshl_add_u64 v[32:33], v[34:35], 0, v[32:33]
	v_pk_mul_f32 v[42:43], v[42:43], s[20:21] op_sel_hi:[1,0]
	v_pk_mul_f32 v[44:45], v[44:45], s[20:21] op_sel_hi:[1,0]
	v_lshl_add_u64 v[40:41], v[32:33], 0, v[162:163]
	s_waitcnt vmcnt(0)
	v_pk_fma_f32 v[30:31], v[30:31], v[68:69], v[44:45]
	v_pk_fma_f32 v[28:29], v[28:29], v[66:67], v[42:43]
	global_load_dwordx4 v[70:73], v[40:41], off
	global_load_dwordx4 v[74:77], v[40:41], off offset:64
	global_load_dwordx4 v[36:39], v[40:41], off offset:512
	global_load_dwordx4 v[32:35], v[40:41], off offset:576
	s_nop 0
	global_store_dwordx4 v[60:61], v[28:31], off
	s_nop 0
	s_nop 0
	global_load_dwordx4 v[28:31], v[124:125], off
	global_load_dwordx4 v[42:45], v[126:127], off
	global_load_dwordx4 v[62:65], v[80:81], off offset:64
	s_waitcnt vmcnt(3)
	v_mov_b32_e32 v46, v128
	v_mov_b32_e32 v47, v129
	v_sub_f32_e32 v59, v59, v46
	v_sub_f32_e32 v58, v58, v46
	v_sub_f32_e32 v57, v57, v46
	v_sub_f32_e32 v56, v56, v46
	v_pk_mul_f32 v[56:57], v[56:57], v[46:47] op_sel:[0,1]
	v_pk_mul_f32 v[46:47], v[58:59], v[46:47] op_sel:[0,1]
	s_waitcnt vmcnt(1)
	v_pk_fma_f32 v[28:29], v[28:29], v[56:57], v[42:43]
	v_pk_fma_f32 v[30:31], v[30:31], v[46:47], v[44:45]
	v_pk_mul_f32 v[28:29], v[28:29], s[20:21] op_sel_hi:[1,0]
	v_pk_mul_f32 v[30:31], v[30:31], s[20:21] op_sel_hi:[1,0]
	s_waitcnt vmcnt(0)
	v_pk_fma_f32 v[24:25], v[24:25], v[62:63], v[28:29]
	v_pk_fma_f32 v[26:27], v[26:27], v[64:65], v[30:31]
	global_store_dwordx4 v[60:61], v[24:27], off offset:64
	s_nop 0
	s_nop 0
	global_load_dwordx4 v[24:27], v[168:169], off
	global_load_dwordx4 v[28:31], v[170:171], off
	global_load_dwordx4 v[42:45], v[80:81], off offset:512
	s_waitcnt vmcnt(3)
	v_mov_b32_e32 v46, v128
	v_mov_b32_e32 v47, v129
	v_sub_f32_e32 v55, v55, v46
	v_sub_f32_e32 v54, v54, v46
	v_sub_f32_e32 v53, v53, v46
	v_sub_f32_e32 v52, v52, v46
	v_pk_mul_f32 v[52:53], v[52:53], v[46:47] op_sel:[0,1]
	v_pk_mul_f32 v[46:47], v[54:55], v[46:47] op_sel:[0,1]
	s_waitcnt vmcnt(1)
	v_pk_fma_f32 v[24:25], v[24:25], v[52:53], v[28:29]
	v_pk_fma_f32 v[26:27], v[26:27], v[46:47], v[30:31]
	v_pk_mul_f32 v[24:25], v[24:25], s[20:21] op_sel_hi:[1,0]
	v_pk_mul_f32 v[26:27], v[26:27], s[20:21] op_sel_hi:[1,0]
	s_waitcnt vmcnt(0)
	v_pk_fma_f32 v[20:21], v[20:21], v[42:43], v[24:25]
	v_pk_fma_f32 v[22:23], v[22:23], v[44:45], v[26:27]
	global_store_dwordx4 v[60:61], v[20:23], off offset:512
	s_nop 0
	s_nop 0
	global_load_dwordx4 v[20:23], v[172:173], off
	global_load_dwordx4 v[24:27], v[174:175], off
	global_load_dwordx4 v[28:31], v[80:81], off offset:576
	v_lshl_add_u64 v[44:45], v[82:83], 3, s[62:63]
	s_waitcnt vmcnt(3)
	v_mov_b32_e32 v42, v128
	v_mov_b32_e32 v43, v129
	v_sub_f32_e32 v47, v51, v42
	v_sub_f32_e32 v46, v50, v42
	v_sub_f32_e32 v49, v49, v42
	v_sub_f32_e32 v48, v48, v42
	v_pk_mul_f32 v[48:49], v[48:49], v[42:43] op_sel:[0,1]
	v_pk_mul_f32 v[42:43], v[46:47], v[42:43] op_sel:[0,1]
	s_waitcnt vmcnt(1)
	v_pk_fma_f32 v[20:21], v[20:21], v[48:49], v[24:25]
	v_pk_fma_f32 v[22:23], v[22:23], v[42:43], v[26:27]
	v_pk_mul_f32 v[20:21], v[20:21], s[20:21] op_sel_hi:[1,0]
	v_pk_mul_f32 v[22:23], v[22:23], s[20:21] op_sel_hi:[1,0]
	s_waitcnt vmcnt(0)
	v_pk_fma_f32 v[16:17], v[16:17], v[28:29], v[20:21]
	v_pk_fma_f32 v[18:19], v[18:19], v[30:31], v[22:23]
	global_store_dwordx4 v[60:61], v[16:19], off offset:576
	global_load_dwordx2 v[28:29], v[44:45], off
	v_cndmask_b32_e64 v24, v88, 4, vcc
	v_mul_hi_i32_i24_e32 v25, 0x6000, v24
	v_mul_i32_i24_e32 v24, 0x6000, v24
	global_load_dwordx4 v[16:19], v[164:165], off
	global_load_dwordx4 v[20:23], v[166:167], off
	v_lshl_add_u64 v[24:25], s[10:11], 0, v[24:25]
	v_lshl_add_u64 v[30:31], v[24:25], 0, v[162:163]
	global_load_dwordx4 v[24:27], v[30:31], off
	s_and_b64 vcc, exec, s[0:1]
	s_mov_b64 s[0:1], -1
	s_waitcnt vmcnt(3)
	v_mov_b32_e32 v128, v28
	v_mov_b32_e32 v129, v29
	v_sub_f32_e32 v43, v73, v28
	v_sub_f32_e32 v42, v72, v28
	v_sub_f32_e32 v47, v71, v28
	v_sub_f32_e32 v46, v70, v28
	v_pk_mul_f32 v[46:47], v[46:47], v[28:29] op_sel:[0,1]
	v_pk_mul_f32 v[28:29], v[42:43], v[28:29] op_sel:[0,1]
	s_waitcnt vmcnt(1)
	v_pk_fma_f32 v[16:17], v[16:17], v[46:47], v[20:21]
	v_pk_fma_f32 v[18:19], v[18:19], v[28:29], v[22:23]
	v_pk_mul_f32 v[16:17], v[16:17], s[20:21] op_sel_hi:[1,0]
	v_pk_mul_f32 v[18:19], v[18:19], s[20:21] op_sel_hi:[1,0]
	s_waitcnt vmcnt(0)
	v_pk_fma_f32 v[12:13], v[12:13], v[24:25], v[16:17]
	v_pk_fma_f32 v[14:15], v[14:15], v[26:27], v[18:19]
	global_store_dwordx4 v[40:41], v[12:15], off
	s_nop 0
	s_nop 0
	global_load_dwordx4 v[12:15], v[124:125], off
	global_load_dwordx4 v[16:19], v[126:127], off
	global_load_dwordx4 v[20:23], v[30:31], off offset:64
	s_waitcnt vmcnt(3)
	v_mov_b32_e32 v24, v128
	v_mov_b32_e32 v25, v129
	v_sub_f32_e32 v27, v77, v24
	v_sub_f32_e32 v26, v76, v24
	v_sub_f32_e32 v29, v75, v24
	v_sub_f32_e32 v28, v74, v24
	v_pk_mul_f32 v[28:29], v[28:29], v[24:25] op_sel:[0,1]
	v_pk_mul_f32 v[24:25], v[26:27], v[24:25] op_sel:[0,1]
	s_waitcnt vmcnt(1)
	v_pk_fma_f32 v[12:13], v[12:13], v[28:29], v[16:17]
	v_pk_fma_f32 v[14:15], v[14:15], v[24:25], v[18:19]
	v_pk_mul_f32 v[12:13], v[12:13], s[20:21] op_sel_hi:[1,0]
	v_pk_mul_f32 v[14:15], v[14:15], s[20:21] op_sel_hi:[1,0]
	s_waitcnt vmcnt(0)
	v_pk_fma_f32 v[8:9], v[8:9], v[20:21], v[12:13]
	v_pk_fma_f32 v[10:11], v[10:11], v[22:23], v[14:15]
	global_store_dwordx4 v[40:41], v[8:11], off offset:64
	s_nop 0
	s_nop 0
	global_load_dwordx4 v[8:11], v[168:169], off
	global_load_dwordx4 v[12:15], v[170:171], off
	global_load_dwordx4 v[16:19], v[30:31], off offset:512
	s_waitcnt vmcnt(3)
	v_mov_b32_e32 v20, v128
	v_mov_b32_e32 v21, v129
	v_sub_f32_e32 v23, v39, v20
	v_sub_f32_e32 v22, v38, v20
	v_sub_f32_e32 v25, v37, v20
	v_sub_f32_e32 v24, v36, v20
	v_pk_mul_f32 v[24:25], v[24:25], v[20:21] op_sel:[0,1]
	v_pk_mul_f32 v[20:21], v[22:23], v[20:21] op_sel:[0,1]
	s_waitcnt vmcnt(1)
	v_pk_fma_f32 v[8:9], v[8:9], v[24:25], v[12:13]
	v_pk_fma_f32 v[10:11], v[10:11], v[20:21], v[14:15]
	v_pk_mul_f32 v[8:9], v[8:9], s[20:21] op_sel_hi:[1,0]
	v_pk_mul_f32 v[10:11], v[10:11], s[20:21] op_sel_hi:[1,0]
	s_waitcnt vmcnt(0)
	v_pk_fma_f32 v[4:5], v[4:5], v[16:17], v[8:9]
	v_pk_fma_f32 v[6:7], v[6:7], v[18:19], v[10:11]
	global_store_dwordx4 v[40:41], v[4:7], off offset:512
	s_nop 0
	s_nop 0
	global_load_dwordx4 v[4:7], v[172:173], off
	global_load_dwordx4 v[8:11], v[174:175], off
	global_load_dwordx4 v[12:15], v[30:31], off offset:576
	s_waitcnt vmcnt(3)
	v_mov_b32_e32 v16, v128
	v_mov_b32_e32 v17, v129
	v_sub_f32_e32 v19, v35, v16
	v_sub_f32_e32 v18, v34, v16
	v_sub_f32_e32 v21, v33, v16
	v_sub_f32_e32 v20, v32, v16
	v_pk_mul_f32 v[20:21], v[20:21], v[16:17] op_sel:[0,1]
	v_pk_mul_f32 v[16:17], v[18:19], v[16:17] op_sel:[0,1]
	s_waitcnt vmcnt(1)
	v_pk_fma_f32 v[4:5], v[4:5], v[20:21], v[8:9]
	v_pk_fma_f32 v[6:7], v[6:7], v[16:17], v[10:11]
	v_pk_mul_f32 v[4:5], v[4:5], s[20:21] op_sel_hi:[1,0]
	v_pk_mul_f32 v[6:7], v[6:7], s[20:21] op_sel_hi:[1,0]
	s_waitcnt vmcnt(0)
	v_pk_fma_f32 v[0:1], v[0:1], v[12:13], v[4:5]
	v_pk_fma_f32 v[2:3], v[2:3], v[14:15], v[6:7]
	global_store_dwordx4 v[40:41], v[0:3], off offset:576
	s_cbranch_vccnz .LBB0_3731
	s_andn2_b64 vcc, exec, s[8:9]
	s_cbranch_vccnz .LBB0_3730
	s_barrier
	s_branch .LBB0_3730
